# prompt-MLA attention loop: deep K-fragment prefetch into idle V registers in QK^T + exp/cvt/PV reschedule (first PV MFMA after 8 exps)
# speedup vs baseline: 1.0051x; 1.0051x over previous
; #define PG8_STAGE(bufoff, gbase, voff) do { _Pragma("unroll") for (int _i = 0; _i < 2; ++_i) \
;         __builtin_amdgcn_global_load_lds((const unsigned*)((const char*)(gbase) + (voff)[_i]), (PG8_LAS unsigned*)(lds + (bufoff) + ldsw + _i * 8192), 16, 0, 0); } while (0)
; #define PG8_WAIT_V(n) asm volatile("s_waitcnt vmcnt(" #n ")" ::: "memory")
; #define PG8_BAR __builtin_amdgcn_s_barrier()
; template <class Epi, class Sched, bool ALIGN_EPI = false, bool SP2 = false>
; __device__ __forceinline__ void gemm_phase(PG8_LAS unsigned char* lds, const Gemm g, const Sched& S, const Epi& E) {
;     ...
;     for (int i = 0; i < 2; ++i) { int R, C; stage_rc(tid * 16 + i * 8192, R, C); const int Rb = Epi::PERM ? ((R & ~31) + perm32(R & 31)) : R;
;         voffA[i] = (unsigned)(R * LD + C) * 2u; voffB[i] = (unsigned)(Rb * LD + C) * 2u; }
;     const size_t kstep = (size_t)(BK * 2);
;     const size_t hstep = (size_t)HALF * LD * 2;
;     const size_t tstep = 2 * hstep;
;     const unsigned ldsw = (unsigned)wid * 1024u;
;     const int aoff = lds_byte(wr * 64 + fr, fq * 8), boff = lds_byte(wc * 32 + fr, fq * 8);
;     ...
;         PG8_WAIT_V(2); PG8_BAR;
;         PG8_STAGE(PG8_SB(1, 0), cB + kstep, voffB); PG8_STAGE(PG8_SA(1, 0), cA + kstep, voffA); PG8_STAGE(PG8_SB(1, 1), cB + hstep + kstep, voffB);
;         PG8_WAIT_V(6); PG8_BAR;
.LBB0_184:
	s_lshl_b32 s15, s15, 5
	s_mov_b64 s[16:17], 0x80
	s_and_b32 s26, s15, 0x60
	s_add_i32 m0, s6, 0x18000
	v_lshl_add_u64 v[8:9], v[8:9], 0, s[16:17]
	s_lshl_b32 s19, s18, 13
	s_lshl_b32 s27, s26, 7
	s_waitcnt vmcnt(2)
	s_barrier
	global_load_lds_dwordx4 v[8:9], off
	v_lshl_add_u64 v[4:5], v[4:5], 0, s[16:17]
	s_add_i32 m0, s6, 0x1a000
	s_add_i32 s15, s6, 0x8000
	s_add_i32 s21, s6, 0xa000
	global_load_lds_dwordx4 v[4:5], off
	v_lshl_add_u64 v[2:3], v[2:3], 0, s[16:17]
	s_mov_b32 m0, s15
	s_add_u32 s24, s34, 0x40080
	global_load_lds_dwordx4 v[2:3], off
	v_lshl_add_u64 v[2:3], v[6:7], 0, s[16:17]
	s_mov_b32 m0, s21
	s_addc_u32 s25, s35, 0
	global_load_lds_dwordx4 v[2:3], off
	s_add_i32 m0, s6, 0x1c000
	v_lshl_add_u64 v[2:3], s[24:25], 0, v[136:137]
	global_load_lds_dwordx4 v[2:3], off
	v_lshl_add_u64 v[2:3], s[24:25], 0, v[132:133]
	s_add_i32 m0, s6, 0x1e000
	s_sext_i32_i8 s42, s4
	global_load_lds_dwordx4 v[2:3], off
	v_and_b32_e32 v2, 15, v198
	v_lshlrev_b32_e32 v3, 1, v13
	v_lshlrev_b32_e32 v4, 2, v198
	v_lshlrev_b32_e32 v5, 6, v198
	s_movk_i32 s4, 0x3c0
	v_lshl_or_b32 v1, s18, 6, v2
	v_lshl_or_b32 v2, v2, 6, v3
	v_and_b32_e32 v4, 32, v4
	v_and_or_b32 v3, v5, s4, v3
	v_bitop3_b32 v2, v2, s19, v4 bitop3:0xde
	v_bitop3_b32 v3, s27, v3, v4 bitop3:0xf6
	v_lshlrev_b32_e32 v4, 8, v198
	v_and_b32_e32 v4, 0x38000, v4
	v_lshlrev_b32_e32 v5, 11, v14
	v_or3_b32 v4, v11, v4, v5
	v_add_u32_e32 v140, v4, v12
	v_lshlrev_b32_e32 v4, 4, v10
	s_mov_b32 s4, 0x18000
	s_mov_b32 s24, 0x1c000
	s_waitcnt vmcnt(6)
	s_cmpk_lt_u32 s5, 0x100
	v_and_b32_e32 v4, 0x78000, v4
	s_cselect_b64 s[18:19], -1, 0
	v_or3_b32 v4, v11, v4, v5
	s_add_i32 s33, s22, 0x100
	s_add_i32 s38, s23, 0x100
	s_add_i32 s40, s4, 0x100
	s_add_i32 s41, s24, 0x100
	v_or_b32_e32 v131, s26, v13
	v_mov_b32_e32 v141, v137
	v_add_u32_e32 v142, v4, v12
	v_mov_b32_e32 v143, v137
	v_mov_b64_e32 v[144:145], 0x5d8
	v_mov_b64_e32 v[146:147], 0x5d7
	v_add_u32_e32 v148, s33, v3
	v_add_u32_e32 v149, s38, v3
	v_add_u32_e32 v150, 0x100, v2
	s_movk_i32 s39, 0x1600
	v_add_u32_e32 v151, s40, v3
	v_add_u32_e32 v152, s41, v3
	s_barrier
	s_branch .LBB0_187

;     __device__ __forceinline__ bool next(int i, Unit& u) const { const int L = i * G + c; if (L >= nunits) return false; const int t = L / S, ks = L % S; u.pm = pm0 + t / nN; u.pn = t % nN; u.ko = ks * Ksub; return true; }
; #define PG8_STAGE(bufoff, gbase, voff) do { _Pragma("unroll") for (int _i = 0; _i < 2; ++_i) \
;         __builtin_amdgcn_global_load_lds((const unsigned*)((const char*)(gbase) + (voff)[_i]), (PG8_LAS unsigned*)(lds + (bufoff) + ldsw + _i * 8192), 16, 0, 0); } while (0)
; #define PG8_LDA(dst, b, h) do { _Pragma("unroll") for (int m = 0; m < 4; ++m) _Pragma("unroll") for (int k = 0; k < 2; ++k) dst[m][k] = *(const PG8_LAS bf16x8*)(lds + PG8_SA(b, h) + aoff + m * 2048 + k * 1024); } while (0)
; #define PG8_LDB(dst, b, h) do { _Pragma("unroll") for (int n = 0; n < 2; ++n) _Pragma("unroll") for (int k = 0; k < 2; ++k) dst[n][k] = *(const PG8_LAS bf16x8*)(lds + PG8_SB(b, h) + boff + n * 2048 + k * 1024); } while (0)
; template <class Epi, class Sched, bool ALIGN_EPI = false, bool SP2 = false>
; __device__ __forceinline__ void gemm_phase(PG8_LAS unsigned char* lds, const Gemm g, const Sched& S, const Epi& E) {
;     ...
;         const bool has_next = S.next(ui + 1, nxt);
;         const char* nA = has_next ? (const char*)g.A + (size_t)nxt.pm * tstep + (size_t)nxt.ko * 2 : cA; const char* nB = has_next ? (const char*)g.Bt + (size_t)nxt.pn * tstep + (size_t)nxt.ko * 2 : cB;
;         for (int t = 0; t < nt; t += 2) {
;             const bool last = (t == nt - 2);
;             const char* a1 = cA + (size_t)(t + 1) * kstep;
;             const char* a2 = last ? nA : cA + (size_t)(t + 2) * kstep; const char* b2 = last ? nB : cB + (size_t)(t + 2) * kstep;
;             const char* a3 = a2 + kstep; const char* b3 = b2 + kstep;
;             if (last && has_next) S.a_ready(nxt);
;             if constexpr (SP2) {
;             PG8_LDB(B0, 0, 0); PG8_LDB(B1, 0, 1); PG8_SCHED; PG8_LDA(At, 0, 0); PG8_STAGE(PG8_SA(1, 1), a1 + hstep, voffA);
;             PG8_WAIT_V(8); PG8_WAIT_L(0); PG8_BAR; PG8_MMA(0, 0, At, B0); PG8_MMA(0, 1, At, B1); PG8_BAR; PG8_SCHED;
;             PG8_LDA(At, 0, 1); PG8_STAGE(PG8_SB(0, 0), b2, voffB); PG8_STAGE(PG8_SB(0, 1), b2 + hstep, voffB); PG8_STAGE(PG8_SA(0, 0), a2, voffA);
;             PG8_WAIT_V(8); PG8_WAIT_L(0); PG8_BAR; PG8_MMA(1, 0, At, B0); PG8_MMA(1, 1, At, B1); PG8_BAR; PG8_SCHED;
.LBB0_190:
	ds_read_b128 v[154:157], v148
	ds_read_b128 v[158:161], v148 offset:1024
	ds_read_b128 v[162:165], v148 offset:2048
	ds_read_b128 v[166:169], v148 offset:3072
	ds_read_b128 v[170:173], v149
	ds_read_b128 v[174:177], v149 offset:1024
	ds_read_b128 v[178:181], v149 offset:2048
	ds_read_b128 v[182:185], v149 offset:3072
	s_add_u32 s34, s30, 0xfffc0080
	s_addc_u32 s35, s31, -1
	s_cmp_eq_u32 s47, 12
	s_cselect_b32 s37, s25, s35
	s_cselect_b32 s36, s43, s34
	s_cselect_b32 s35, s23, s46
	s_cselect_b32 s34, s44, s45
	v_lshl_add_u64 v[204:205], s[30:31], 0, v[140:141]
	s_add_i32 m0, s6, 0xc000
	ds_read_b128 v[186:189], v150
	ds_read_b128 v[190:193], v150 offset:1024
	ds_read_b128 v[194:197], v150 offset:2048
	ds_read_b128 v[200:203], v150 offset:3072
	ds_read_b128 v[208:211], v150 offset:4096
	ds_read_b128 v[212:215], v150 offset:5120
	ds_read_b128 v[216:219], v150 offset:6144
	ds_read_b128 v[220:223], v150 offset:7168
	global_load_lds_dwordx4 v[204:205], off
	v_lshl_add_u64 v[204:205], s[30:31], 0, v[142:143]
	s_add_i32 m0, s6, 0xe000
	s_nop 0
	global_load_lds_dwordx4 v[204:205], off
	s_waitcnt vmcnt(8)
	s_waitcnt lgkmcnt(0)
	s_barrier
	s_setprio 1
	s_waitcnt lgkmcnt(0)
	v_mfma_f32_16x16x32_bf16 v[126:129], v[154:157], v[186:189], v[126:129]
	v_mfma_f32_16x16x32_bf16 v[122:125], v[162:165], v[186:189], v[122:125]
	v_mfma_f32_16x16x32_bf16 v[118:121], v[154:157], v[194:197], v[118:121]
	v_mfma_f32_16x16x32_bf16 v[114:117], v[162:165], v[194:197], v[114:117]
	v_mfma_f32_16x16x32_bf16 v[102:105], v[154:157], v[208:211], v[102:105]
	v_mfma_f32_16x16x32_bf16 v[98:101], v[162:165], v[208:211], v[98:101]
	v_mfma_f32_16x16x32_bf16 v[86:89], v[154:157], v[216:219], v[86:89]
	v_mfma_f32_16x16x32_bf16 v[82:85], v[162:165], v[216:219], v[82:85]
	v_mfma_f32_16x16x32_bf16 v[126:129], v[158:161], v[190:193], v[126:129]
	v_mfma_f32_16x16x32_bf16 v[122:125], v[166:169], v[190:193], v[122:125]
	v_mfma_f32_16x16x32_bf16 v[118:121], v[158:161], v[200:203], v[118:121]
	v_mfma_f32_16x16x32_bf16 v[114:117], v[166:169], v[200:203], v[114:117]
	v_mfma_f32_16x16x32_bf16 v[102:105], v[158:161], v[212:215], v[102:105]
	v_mfma_f32_16x16x32_bf16 v[98:101], v[166:169], v[212:215], v[98:101]
	v_mfma_f32_16x16x32_bf16 v[86:89], v[158:161], v[220:223], v[86:89]
	v_mfma_f32_16x16x32_bf16 v[82:85], v[166:169], v[220:223], v[82:85]
	s_setprio 0
	s_setprio 1
	v_mfma_f32_16x16x32_bf16 v[110:113], v[170:173], v[186:189], v[110:113]
	v_mfma_f32_16x16x32_bf16 v[106:109], v[178:181], v[186:189], v[106:109]
	v_mfma_f32_16x16x32_bf16 v[94:97], v[170:173], v[194:197], v[94:97]
	v_mfma_f32_16x16x32_bf16 v[90:93], v[178:181], v[194:197], v[90:93]
	v_mfma_f32_16x16x32_bf16 v[78:81], v[170:173], v[208:211], v[78:81]
	v_mfma_f32_16x16x32_bf16 v[74:77], v[178:181], v[208:211], v[74:77]
	v_mfma_f32_16x16x32_bf16 v[70:73], v[170:173], v[216:219], v[70:73]
	v_mfma_f32_16x16x32_bf16 v[66:69], v[178:181], v[216:219], v[66:69]
	v_mfma_f32_16x16x32_bf16 v[110:113], v[174:177], v[190:193], v[110:113]
	v_mfma_f32_16x16x32_bf16 v[106:109], v[182:185], v[190:193], v[106:109]
	v_mfma_f32_16x16x32_bf16 v[94:97], v[174:177], v[200:203], v[94:97]
	v_mfma_f32_16x16x32_bf16 v[90:93], v[182:185], v[200:203], v[90:93]
	v_mfma_f32_16x16x32_bf16 v[78:81], v[174:177], v[212:215], v[78:81]
	v_mfma_f32_16x16x32_bf16 v[74:77], v[182:185], v[212:215], v[74:77]
	v_mfma_f32_16x16x32_bf16 v[70:73], v[174:177], v[220:223], v[70:73]
	v_mfma_f32_16x16x32_bf16 v[66:69], v[182:185], v[220:223], v[66:69]
	s_setprio 0
	s_barrier
	s_add_i32 s48, s33, s2
	v_lshl_add_u64 v[204:205], s[34:35], 0, v[136:137]
	s_mov_b32 m0, s48
	ds_read_b128 v[186:189], v150 offset:16384
	ds_read_b128 v[190:193], v150 offset:17408
	ds_read_b128 v[194:197], v150 offset:18432
	ds_read_b128 v[200:203], v150 offset:19456
	ds_read_b128 v[208:211], v150 offset:20480
	ds_read_b128 v[212:215], v150 offset:21504
	ds_read_b128 v[216:219], v150 offset:22528
	ds_read_b128 v[220:223], v150 offset:23552
	global_load_lds_dwordx4 v[204:205], off
	s_add_i32 m0, s48, 0x2000
	s_add_u32 s48, s34, 0x40000
	v_lshl_add_u64 v[224:225], s[34:35], 0, v[132:133]
	s_addc_u32 s49, s35, 0
	s_add_i32 s50, s38, s2
	global_load_lds_dwordx4 v[224:225], off
	v_lshl_add_u64 v[226:227], s[48:49], 0, v[136:137]
	s_mov_b32 m0, s50
	v_lshl_add_u64 v[228:229], s[36:37], 0, v[134:135]
	global_load_lds_dwordx4 v[226:227], off
	v_lshl_add_u64 v[226:227], s[48:49], 0, v[132:133]
	s_add_i32 m0, s50, 0x2000
	s_nop 0
	global_load_lds_dwordx4 v[226:227], off
	v_lshl_add_u64 v[226:227], s[36:37], 0, v[138:139]
	s_mov_b32 m0, s6
	s_nop 0
	global_load_lds_dwordx4 v[226:227], off
	s_mov_b32 m0, s7
	s_nop 0
	global_load_lds_dwordx4 v[228:229], off
	s_waitcnt vmcnt(8)
	s_waitcnt lgkmcnt(0)
	s_barrier
; #define PG8_STAGE(bufoff, gbase, voff) do { _Pragma("unroll") for (int _i = 0; _i < 2; ++_i) \
;         __builtin_amdgcn_global_load_lds((const unsigned*)((const char*)(gbase) + (voff)[_i]), (PG8_LAS unsigned*)(lds + (bufoff) + ldsw + _i * 8192), 16, 0, 0); } while (0)
; #define PG8_LDA(dst, b, h) do { _Pragma("unroll") for (int m = 0; m < 4; ++m) _Pragma("unroll") for (int k = 0; k < 2; ++k) dst[m][k] = *(const PG8_LAS bf16x8*)(lds + PG8_SA(b, h) + aoff + m * 2048 + k * 1024); } while (0)
; #define PG8_LDB(dst, b, h) do { _Pragma("unroll") for (int n = 0; n < 2; ++n) _Pragma("unroll") for (int k = 0; k < 2; ++k) dst[n][k] = *(const PG8_LAS bf16x8*)(lds + PG8_SB(b, h) + boff + n * 2048 + k * 1024); } while (0)
; #define PG8_MMA(ai, bj, At, Bt) do { __builtin_amdgcn_s_setprio(1); _Pragma("unroll") for (int m = 0; m < 4; ++m) _Pragma("unroll") for (int n = 0; n < 2; ++n) _Pragma("unroll") for (int k = 0; k < 2; ++k) \
;         acc[ai][bj][m][n] = __builtin_amdgcn_mfma_f32_16x16x32_bf16(Bt[n][k], At[m][k], acc[ai][bj][m][n], 0, 0, 0); __builtin_amdgcn_s_setprio(0); } while (0)
; #define PG8_WAIT_V(n) asm volatile("s_waitcnt vmcnt(" #n ")" ::: "memory")
; #define PG8_WAIT_L(n) asm volatile("s_waitcnt lgkmcnt(" #n ")" ::: "memory")
; #define PG8_BAR __builtin_amdgcn_s_barrier()
; #define PG8_SCHED __builtin_amdgcn_sched_barrier(0)
; template <class Epi, class Sched, bool ALIGN_EPI = false, bool SP2 = false>
; __device__ __forceinline__ void gemm_phase(PG8_LAS unsigned char* lds, const Gemm g, const Sched& S, const Epi& E) {
;     ...
;             PG8_WAIT_V(8); PG8_WAIT_L(0); PG8_BAR; PG8_MMA(1, 0, At, B0); PG8_MMA(1, 1, At, B1); PG8_BAR; PG8_SCHED;
;             PG8_LDB(B0, 1, 0); PG8_LDB(B1, 1, 1); PG8_SCHED; PG8_LDA(At, 1, 0); PG8_STAGE(PG8_SA(0, 1), a2 + hstep, voffA);
;             PG8_WAIT_V(8); PG8_WAIT_L(0); PG8_BAR; PG8_MMA(0, 0, At, B0); PG8_MMA(0, 1, At, B1); PG8_BAR; PG8_SCHED;
	s_setprio 1
	s_waitcnt lgkmcnt(0)
	v_mfma_f32_16x16x32_bf16 v[62:65], v[154:157], v[186:189], v[62:65]
	v_mfma_f32_16x16x32_bf16 v[58:61], v[162:165], v[186:189], v[58:61]
	v_mfma_f32_16x16x32_bf16 v[54:57], v[154:157], v[194:197], v[54:57]
	v_mfma_f32_16x16x32_bf16 v[50:53], v[162:165], v[194:197], v[50:53]
	v_mfma_f32_16x16x32_bf16 v[38:41], v[154:157], v[208:211], v[38:41]
	v_mfma_f32_16x16x32_bf16 v[34:37], v[162:165], v[208:211], v[34:37]
	v_mfma_f32_16x16x32_bf16 v[22:25], v[154:157], v[216:219], v[22:25]
	v_mfma_f32_16x16x32_bf16 v[18:21], v[162:165], v[216:219], v[18:21]
	v_mfma_f32_16x16x32_bf16 v[62:65], v[158:161], v[190:193], v[62:65]
	v_mfma_f32_16x16x32_bf16 v[58:61], v[166:169], v[190:193], v[58:61]
	v_mfma_f32_16x16x32_bf16 v[54:57], v[158:161], v[200:203], v[54:57]
	v_mfma_f32_16x16x32_bf16 v[50:53], v[166:169], v[200:203], v[50:53]
	v_mfma_f32_16x16x32_bf16 v[38:41], v[158:161], v[212:215], v[38:41]
	v_mfma_f32_16x16x32_bf16 v[34:37], v[166:169], v[212:215], v[34:37]
	v_mfma_f32_16x16x32_bf16 v[22:25], v[158:161], v[220:223], v[22:25]
	v_mfma_f32_16x16x32_bf16 v[18:21], v[166:169], v[220:223], v[18:21]
	s_setprio 0
	s_setprio 1
	v_mfma_f32_16x16x32_bf16 v[46:49], v[170:173], v[186:189], v[46:49]
	v_mfma_f32_16x16x32_bf16 v[42:45], v[178:181], v[186:189], v[42:45]
	v_mfma_f32_16x16x32_bf16 v[30:33], v[170:173], v[194:197], v[30:33]
	v_mfma_f32_16x16x32_bf16 v[26:29], v[178:181], v[194:197], v[26:29]
	v_mfma_f32_16x16x32_bf16 v[14:17], v[170:173], v[208:211], v[14:17]
	v_mfma_f32_16x16x32_bf16 v[10:13], v[178:181], v[208:211], v[10:13]
	v_mfma_f32_16x16x32_bf16 v[6:9], v[170:173], v[216:219], v[6:9]
	v_mfma_f32_16x16x32_bf16 v[2:5], v[178:181], v[216:219], v[2:5]
	v_mfma_f32_16x16x32_bf16 v[46:49], v[174:177], v[190:193], v[46:49]
	v_mfma_f32_16x16x32_bf16 v[42:45], v[182:185], v[190:193], v[42:45]
	v_mfma_f32_16x16x32_bf16 v[30:33], v[174:177], v[200:203], v[30:33]
	v_mfma_f32_16x16x32_bf16 v[26:29], v[182:185], v[200:203], v[26:29]
	v_mfma_f32_16x16x32_bf16 v[14:17], v[174:177], v[212:215], v[14:17]
	v_mfma_f32_16x16x32_bf16 v[10:13], v[182:185], v[212:215], v[10:13]
	v_mfma_f32_16x16x32_bf16 v[6:9], v[174:177], v[220:223], v[6:9]
	v_mfma_f32_16x16x32_bf16 v[2:5], v[182:185], v[220:223], v[2:5]
	s_setprio 0
	s_barrier
	ds_read_b128 v[154:157], v151
	ds_read_b128 v[158:161], v151 offset:1024
	ds_read_b128 v[162:165], v151 offset:2048
	ds_read_b128 v[166:169], v151 offset:3072
	ds_read_b128 v[170:173], v152
	ds_read_b128 v[174:177], v152 offset:1024
	ds_read_b128 v[178:181], v152 offset:2048
	ds_read_b128 v[182:185], v152 offset:3072
	s_add_u32 s36, s36, 0x40000
	s_addc_u32 s37, s37, 0
	s_mov_b32 m0, s10
	v_lshl_add_u64 v[230:231], s[36:37], 0, v[138:139]
	ds_read_b128 v[186:189], v150 offset:32768
	ds_read_b128 v[190:193], v150 offset:33792
	ds_read_b128 v[194:197], v150 offset:34816
	ds_read_b128 v[200:203], v150 offset:35840
	ds_read_b128 v[208:211], v150 offset:36864
	ds_read_b128 v[212:215], v150 offset:37888
	ds_read_b128 v[216:219], v150 offset:38912
	ds_read_b128 v[220:223], v150 offset:39936
	global_load_lds_dwordx4 v[230:231], off
	v_lshl_add_u64 v[230:231], s[36:37], 0, v[134:135]
	s_mov_b32 m0, s11
	s_nop 0
	global_load_lds_dwordx4 v[230:231], off
	s_waitcnt vmcnt(8)
	s_waitcnt lgkmcnt(0)
	s_barrier
	s_setprio 1
	s_waitcnt lgkmcnt(0)
	v_mfma_f32_16x16x32_bf16 v[126:129], v[154:157], v[186:189], v[126:129]
	v_mfma_f32_16x16x32_bf16 v[122:125], v[162:165], v[186:189], v[122:125]
	v_mfma_f32_16x16x32_bf16 v[118:121], v[154:157], v[194:197], v[118:121]
	v_mfma_f32_16x16x32_bf16 v[114:117], v[162:165], v[194:197], v[114:117]
	v_mfma_f32_16x16x32_bf16 v[102:105], v[154:157], v[208:211], v[102:105]
	v_mfma_f32_16x16x32_bf16 v[98:101], v[162:165], v[208:211], v[98:101]
	v_mfma_f32_16x16x32_bf16 v[86:89], v[154:157], v[216:219], v[86:89]
	v_mfma_f32_16x16x32_bf16 v[82:85], v[162:165], v[216:219], v[82:85]
	v_mfma_f32_16x16x32_bf16 v[126:129], v[158:161], v[190:193], v[126:129]
	v_mfma_f32_16x16x32_bf16 v[122:125], v[166:169], v[190:193], v[122:125]
	v_mfma_f32_16x16x32_bf16 v[118:121], v[158:161], v[200:203], v[118:121]
	v_mfma_f32_16x16x32_bf16 v[114:117], v[166:169], v[200:203], v[114:117]
	v_mfma_f32_16x16x32_bf16 v[102:105], v[158:161], v[212:215], v[102:105]
	v_mfma_f32_16x16x32_bf16 v[98:101], v[166:169], v[212:215], v[98:101]
	v_mfma_f32_16x16x32_bf16 v[86:89], v[158:161], v[220:223], v[86:89]
	v_mfma_f32_16x16x32_bf16 v[82:85], v[166:169], v[220:223], v[82:85]
	s_setprio 0
	s_setprio 1
	v_mfma_f32_16x16x32_bf16 v[110:113], v[170:173], v[186:189], v[110:113]
	v_mfma_f32_16x16x32_bf16 v[106:109], v[178:181], v[186:189], v[106:109]
	v_mfma_f32_16x16x32_bf16 v[94:97], v[170:173], v[194:197], v[94:97]
	v_mfma_f32_16x16x32_bf16 v[90:93], v[178:181], v[194:197], v[90:93]
	v_mfma_f32_16x16x32_bf16 v[78:81], v[170:173], v[208:211], v[78:81]
	v_mfma_f32_16x16x32_bf16 v[74:77], v[178:181], v[208:211], v[74:77]
	v_mfma_f32_16x16x32_bf16 v[70:73], v[170:173], v[216:219], v[70:73]
	v_mfma_f32_16x16x32_bf16 v[66:69], v[178:181], v[216:219], v[66:69]
	v_mfma_f32_16x16x32_bf16 v[110:113], v[174:177], v[190:193], v[110:113]
	v_mfma_f32_16x16x32_bf16 v[106:109], v[182:185], v[190:193], v[106:109]
	v_mfma_f32_16x16x32_bf16 v[94:97], v[174:177], v[200:203], v[94:97]
	v_mfma_f32_16x16x32_bf16 v[90:93], v[182:185], v[200:203], v[90:93]
	v_mfma_f32_16x16x32_bf16 v[78:81], v[174:177], v[212:215], v[78:81]
	v_mfma_f32_16x16x32_bf16 v[74:77], v[182:185], v[212:215], v[74:77]
	v_mfma_f32_16x16x32_bf16 v[70:73], v[174:177], v[220:223], v[70:73]
	v_mfma_f32_16x16x32_bf16 v[66:69], v[182:185], v[220:223], v[66:69]
	s_setprio 0
	s_barrier
; #define PG8_STAGE(bufoff, gbase, voff) do { _Pragma("unroll") for (int _i = 0; _i < 2; ++_i) \
;         __builtin_amdgcn_global_load_lds((const unsigned*)((const char*)(gbase) + (voff)[_i]), (PG8_LAS unsigned*)(lds + (bufoff) + ldsw + _i * 8192), 16, 0, 0); } while (0)
; #define PG8_LDA(dst, b, h) do { _Pragma("unroll") for (int m = 0; m < 4; ++m) _Pragma("unroll") for (int k = 0; k < 2; ++k) dst[m][k] = *(const PG8_LAS bf16x8*)(lds + PG8_SA(b, h) + aoff + m * 2048 + k * 1024); } while (0)
; #define PG8_MMA(ai, bj, At, Bt) do { __builtin_amdgcn_s_setprio(1); _Pragma("unroll") for (int m = 0; m < 4; ++m) _Pragma("unroll") for (int n = 0; n < 2; ++n) _Pragma("unroll") for (int k = 0; k < 2; ++k) \
;         acc[ai][bj][m][n] = __builtin_amdgcn_mfma_f32_16x16x32_bf16(Bt[n][k], At[m][k], acc[ai][bj][m][n], 0, 0, 0); __builtin_amdgcn_s_setprio(0); } while (0)
; #define PG8_WAIT_V(n) asm volatile("s_waitcnt vmcnt(" #n ")" ::: "memory")
; #define PG8_WAIT_L(n) asm volatile("s_waitcnt lgkmcnt(" #n ")" ::: "memory")
; #define PG8_BAR __builtin_amdgcn_s_barrier()
; #define PG8_SCHED __builtin_amdgcn_sched_barrier(0)
; template <class Epi, class Sched, bool ALIGN_EPI = false, bool SP2 = false>
; __device__ __forceinline__ void gemm_phase(PG8_LAS unsigned char* lds, const Gemm g, const Sched& S, const Epi& E) {
;     ...
;         for (int t = 0; t < nt; t += 2) {
;     ...
;             PG8_LDA(At, 1, 1); PG8_STAGE(PG8_SB(1, 0), b3, voffB); PG8_STAGE(PG8_SB(1, 1), b3 + hstep, voffB); PG8_STAGE(PG8_SA(1, 0), a3, voffA);
;             PG8_WAIT_V(8); PG8_WAIT_L(0); PG8_BAR; PG8_MMA(1, 0, At, B0); PG8_MMA(1, 1, At, B1); PG8_BAR; PG8_SCHED;
;     ...
;         if constexpr (ALIGN_EPI) { if (wr == 0) PG8_BAR; }
	s_add_i32 s36, s40, s2
	v_lshl_add_u64 v[204:205], v[204:205], 0, s[16:17]
	s_mov_b32 m0, s36
	ds_read_b128 v[186:189], v150 offset:49152
	ds_read_b128 v[190:193], v150 offset:50176
	ds_read_b128 v[194:197], v150 offset:51200
	ds_read_b128 v[200:203], v150 offset:52224
	ds_read_b128 v[208:211], v150 offset:53248
	ds_read_b128 v[212:215], v150 offset:54272
	ds_read_b128 v[216:219], v150 offset:55296
	ds_read_b128 v[220:223], v150 offset:56320
	global_load_lds_dwordx4 v[204:205], off
	s_add_i32 m0, s36, 0x2000
	s_add_u32 s34, s34, 0x40080
	v_lshl_add_u64 v[204:205], v[224:225], 0, s[16:17]
	s_addc_u32 s35, s35, 0
	s_add_i32 s36, s41, s2
	global_load_lds_dwordx4 v[204:205], off
	v_lshl_add_u64 v[204:205], s[34:35], 0, v[136:137]
	s_mov_b32 m0, s36
	s_nop 0
	global_load_lds_dwordx4 v[204:205], off
	v_lshl_add_u64 v[204:205], s[34:35], 0, v[132:133]
	s_add_i32 m0, s36, 0x2000
	s_nop 0
	global_load_lds_dwordx4 v[204:205], off
	v_lshl_add_u64 v[204:205], v[226:227], 0, s[16:17]
	s_mov_b32 m0, s15
	s_nop 0
	global_load_lds_dwordx4 v[204:205], off
	v_lshl_add_u64 v[204:205], v[228:229], 0, s[16:17]
	s_mov_b32 m0, s21
	s_nop 0
	global_load_lds_dwordx4 v[204:205], off
	s_waitcnt vmcnt(8)
	s_waitcnt lgkmcnt(0)
	s_barrier
	s_setprio 1
	s_waitcnt lgkmcnt(0)
	v_mfma_f32_16x16x32_bf16 v[62:65], v[154:157], v[186:189], v[62:65]
	v_mfma_f32_16x16x32_bf16 v[58:61], v[162:165], v[186:189], v[58:61]
	v_mfma_f32_16x16x32_bf16 v[54:57], v[154:157], v[194:197], v[54:57]
	v_mfma_f32_16x16x32_bf16 v[50:53], v[162:165], v[194:197], v[50:53]
	v_mfma_f32_16x16x32_bf16 v[38:41], v[154:157], v[208:211], v[38:41]
	v_mfma_f32_16x16x32_bf16 v[34:37], v[162:165], v[208:211], v[34:37]
	v_mfma_f32_16x16x32_bf16 v[22:25], v[154:157], v[216:219], v[22:25]
	v_mfma_f32_16x16x32_bf16 v[18:21], v[162:165], v[216:219], v[18:21]
	v_mfma_f32_16x16x32_bf16 v[62:65], v[158:161], v[190:193], v[62:65]
	v_mfma_f32_16x16x32_bf16 v[58:61], v[166:169], v[190:193], v[58:61]
	v_mfma_f32_16x16x32_bf16 v[54:57], v[158:161], v[200:203], v[54:57]
	v_mfma_f32_16x16x32_bf16 v[50:53], v[166:169], v[200:203], v[50:53]
	v_mfma_f32_16x16x32_bf16 v[38:41], v[158:161], v[212:215], v[38:41]
	v_mfma_f32_16x16x32_bf16 v[34:37], v[166:169], v[212:215], v[34:37]
	v_mfma_f32_16x16x32_bf16 v[22:25], v[158:161], v[220:223], v[22:25]
	v_mfma_f32_16x16x32_bf16 v[18:21], v[166:169], v[220:223], v[18:21]
	s_setprio 0
	s_setprio 1
	v_mfma_f32_16x16x32_bf16 v[46:49], v[170:173], v[186:189], v[46:49]
	v_mfma_f32_16x16x32_bf16 v[42:45], v[178:181], v[186:189], v[42:45]
	v_mfma_f32_16x16x32_bf16 v[30:33], v[170:173], v[194:197], v[30:33]
	v_mfma_f32_16x16x32_bf16 v[26:29], v[178:181], v[194:197], v[26:29]
	v_mfma_f32_16x16x32_bf16 v[14:17], v[170:173], v[208:211], v[14:17]
	v_mfma_f32_16x16x32_bf16 v[10:13], v[178:181], v[208:211], v[10:13]
	v_mfma_f32_16x16x32_bf16 v[6:9], v[170:173], v[216:219], v[6:9]
	v_mfma_f32_16x16x32_bf16 v[2:5], v[178:181], v[216:219], v[2:5]
	v_mfma_f32_16x16x32_bf16 v[46:49], v[174:177], v[190:193], v[46:49]
	v_mfma_f32_16x16x32_bf16 v[42:45], v[182:185], v[190:193], v[42:45]
	v_mfma_f32_16x16x32_bf16 v[30:33], v[174:177], v[200:203], v[30:33]
	v_mfma_f32_16x16x32_bf16 v[26:29], v[182:185], v[200:203], v[26:29]
	v_mfma_f32_16x16x32_bf16 v[14:17], v[174:177], v[212:215], v[14:17]
	v_mfma_f32_16x16x32_bf16 v[10:13], v[182:185], v[212:215], v[10:13]
	v_mfma_f32_16x16x32_bf16 v[6:9], v[174:177], v[220:223], v[6:9]
	v_mfma_f32_16x16x32_bf16 v[2:5], v[182:185], v[220:223], v[2:5]
	s_setprio 0
	s_barrier
	s_add_i32 s47, s47, 2
	s_add_u32 s30, s30, 0x100
	s_addc_u32 s31, s31, 0
	s_add_u32 s45, s45, 0x100
	s_addc_u32 s46, s46, 0
	s_cmp_gt_u32 s47, 13
	s_cbranch_scc0 .LBB0_190
	s_and_b64 vcc, exec, s[18:19]
	s_cbranch_vccz .LBB0_193
	s_barrier

; #define PG8_STAGE(bufoff, gbase, voff) do { _Pragma("unroll") for (int _i = 0; _i < 2; ++_i) \
;         __builtin_amdgcn_global_load_lds((const unsigned*)((const char*)(gbase) + (voff)[_i]), (PG8_LAS unsigned*)(lds + (bufoff) + ldsw + _i * 8192), 16, 0, 0); } while (0)
; #define PG8_WAIT_V(n) asm volatile("s_waitcnt vmcnt(" #n ")" ::: "memory")
; #define PG8_BAR __builtin_amdgcn_s_barrier()
; template <class Epi, class Sched, bool ALIGN_EPI = false, bool SP2 = false>
; __device__ __forceinline__ void gemm_phase(PG8_LAS unsigned char* lds, const Gemm g, const Sched& S, const Epi& E) {
;     ...
;     for (int i = 0; i < 2; ++i) { int R, C; stage_rc(tid * 16 + i * 8192, R, C); const int Rb = Epi::PERM ? ((R & ~31) + perm32(R & 31)) : R;
;         voffA[i] = (unsigned)(R * LD + C) * 2u; voffB[i] = (unsigned)(Rb * LD + C) * 2u; }
;     const size_t kstep = (size_t)(BK * 2);
;     const size_t hstep = (size_t)HALF * LD * 2;
;     const size_t tstep = 2 * hstep;
;     const unsigned ldsw = (unsigned)wid * 1024u;
;     const int aoff = lds_byte(wr * 64 + fr, fq * 8), boff = lds_byte(wc * 32 + fr, fq * 8);
;     ...
;         PG8_WAIT_V(2); PG8_BAR;
;         PG8_STAGE(PG8_SB(1, 0), cB + kstep, voffB); PG8_STAGE(PG8_SA(1, 0), cA + kstep, voffA); PG8_STAGE(PG8_SB(1, 1), cB + hstep + kstep, voffB);
;         PG8_WAIT_V(6); PG8_BAR;
.LBB0_364:
	s_mov_b64 s[18:19], 0x80
	s_lshl_b32 s4, s4, 5
	s_add_i32 m0, s3, 0x18000
	v_lshl_add_u64 v[8:9], v[8:9], 0, s[18:19]
	s_lshl_b32 s20, s1, 13
	s_and_b32 s4, s4, 0x60
	s_waitcnt vmcnt(2)
	s_barrier
	global_load_lds_dwordx4 v[8:9], off
	v_lshl_add_u64 v[4:5], v[4:5], 0, s[18:19]
	s_add_i32 m0, s3, 0x1a000
	s_add_i32 s14, s3, 0x8000
	s_add_i32 s15, s3, 0xa000
	global_load_lds_dwordx4 v[4:5], off
	v_lshl_add_u64 v[2:3], v[2:3], 0, s[18:19]
	s_mov_b32 m0, s14
	s_add_u32 s16, s28, 0x30080
	global_load_lds_dwordx4 v[2:3], off
	v_lshl_add_u64 v[2:3], v[6:7], 0, s[18:19]
	s_mov_b32 m0, s15
	s_addc_u32 s17, s29, 0
	global_load_lds_dwordx4 v[2:3], off
	s_add_i32 m0, s3, 0x1c000
	v_lshl_add_u64 v[2:3], s[16:17], 0, v[134:135]
	global_load_lds_dwordx4 v[2:3], off
	v_lshl_add_u64 v[2:3], s[16:17], 0, v[130:131]
	s_add_i32 m0, s3, 0x1e000
	s_cmpk_lt_u32 s0, 0x100
	global_load_lds_dwordx4 v[2:3], off
	v_lshlrev_b32_e32 v3, 2, v204
	v_lshl_or_b32 v2, v204, 6, v147
	v_and_b32_e32 v3, 32, v3
	s_mov_b32 s0, 0x10000
	s_sext_i32_i8 s41, s5
	v_lshl_or_b32 v153, s1, 6, v204
	v_bitop3_b32 v2, v2, s20, v3 bitop3:0xde
	s_mov_b32 s1, 0x18000
	s_mov_b32 s5, 0x1c000
	s_waitcnt vmcnt(6)
	s_cselect_b64 s[20:21], -1, 0
	v_add_u16_e32 v4, v10, v205
	s_add_i32 s16, s0, 0x100
	s_mov_b32 s0, 0x14000
	v_lshl_or_b32 v3, s4, 7, v146
	v_lshrrev_b16_e32 v4, 1, v4
	s_add_i32 s17, s0, 0x100
	s_add_i32 s36, s1, 0x100
	s_add_i32 s37, s5, 0x100
	v_or_b32_e32 v154, s4, v1
	v_add_lshl_u32 v138, v12, v4, 1
	v_mov_b32_e32 v139, v135
	v_add_lshl_u32 v140, v11, v4, 1
	v_mov_b32_e32 v141, v135
	v_mov_b64_e32 v[142:143], 0x198
	v_mov_b64_e32 v[144:145], 0x197
	v_add_u32_e32 v155, s16, v3
	v_add_u32_e32 v156, s17, v3
	v_add_u32_e32 v157, 0x100, v2
	s_movk_i32 s33, 0x600
	s_add_i32 s34, s3, 0xc000
	s_add_i32 s35, s3, 0xe000
	v_add_u32_e32 v158, s36, v3
	v_add_u32_e32 v159, s37, v3
	s_barrier
	s_branch .LBB0_367

;     __device__ __forceinline__ bool next(int i, Unit& u) const { const int L = i * G + c; if (L >= nunits) return false; const int t = L / S, ks = L % S; u.pm = pm0 + t / nN; u.pn = t % nN; u.ko = ks * Ksub; return true; }
; #define PG8_STAGE(bufoff, gbase, voff) do { _Pragma("unroll") for (int _i = 0; _i < 2; ++_i) \
;         __builtin_amdgcn_global_load_lds((const unsigned*)((const char*)(gbase) + (voff)[_i]), (PG8_LAS unsigned*)(lds + (bufoff) + ldsw + _i * 8192), 16, 0, 0); } while (0)
; #define PG8_LDA(dst, b, h) do { _Pragma("unroll") for (int m = 0; m < 4; ++m) _Pragma("unroll") for (int k = 0; k < 2; ++k) dst[m][k] = *(const PG8_LAS bf16x8*)(lds + PG8_SA(b, h) + aoff + m * 2048 + k * 1024); } while (0)
; #define PG8_LDB(dst, b, h) do { _Pragma("unroll") for (int n = 0; n < 2; ++n) _Pragma("unroll") for (int k = 0; k < 2; ++k) dst[n][k] = *(const PG8_LAS bf16x8*)(lds + PG8_SB(b, h) + boff + n * 2048 + k * 1024); } while (0)
; template <class Epi, class Sched, bool ALIGN_EPI = false, bool SP2 = false>
; __device__ __forceinline__ void gemm_phase(PG8_LAS unsigned char* lds, const Gemm g, const Sched& S, const Epi& E) {
;     ...
;         const bool has_next = S.next(ui + 1, nxt);
;         const char* nA = has_next ? (const char*)g.A + (size_t)nxt.pm * tstep + (size_t)nxt.ko * 2 : cA; const char* nB = has_next ? (const char*)g.Bt + (size_t)nxt.pn * tstep + (size_t)nxt.ko * 2 : cB;
;         for (int t = 0; t < nt; t += 2) {
;             const bool last = (t == nt - 2);
;             const char* a1 = cA + (size_t)(t + 1) * kstep;
;             const char* a2 = last ? nA : cA + (size_t)(t + 2) * kstep; const char* b2 = last ? nB : cB + (size_t)(t + 2) * kstep;
;             const char* a3 = a2 + kstep; const char* b3 = b2 + kstep;
;             if (last && has_next) S.a_ready(nxt);
;             if constexpr (SP2) {
;             PG8_LDB(B0, 0, 0); PG8_LDB(B1, 0, 1); PG8_SCHED; PG8_LDA(At, 0, 0); PG8_STAGE(PG8_SA(1, 1), a1 + hstep, voffA);
;             PG8_WAIT_V(8); PG8_WAIT_L(0); PG8_BAR; PG8_MMA(0, 0, At, B0); PG8_MMA(0, 1, At, B1); PG8_BAR; PG8_SCHED;
;             PG8_LDA(At, 0, 1); PG8_STAGE(PG8_SB(0, 0), b2, voffB); PG8_STAGE(PG8_SB(0, 1), b2 + hstep, voffB); PG8_STAGE(PG8_SA(0, 0), a2, voffA);
;             PG8_WAIT_V(8); PG8_WAIT_L(0); PG8_BAR; PG8_MMA(1, 0, At, B0); PG8_MMA(1, 1, At, B1); PG8_BAR; PG8_SCHED;
.LBB0_374:
	ds_read_b128 v[160:163], v155
	ds_read_b128 v[164:167], v155 offset:1024
	ds_read_b128 v[168:171], v155 offset:2048
	ds_read_b128 v[172:175], v155 offset:3072
	ds_read_b128 v[176:179], v156
	ds_read_b128 v[180:183], v156 offset:1024
	ds_read_b128 v[184:187], v156 offset:2048
	ds_read_b128 v[188:191], v156 offset:3072
	s_add_u32 s28, s24, 0xfffd0080
	s_addc_u32 s29, s25, -1
	s_cmp_eq_u32 s44, 8
	s_cselect_b32 s31, s1, s29
	s_cselect_b32 s30, s0, s28
	s_cselect_b32 s29, s23, s43
	s_cselect_b32 s28, s22, s42
	s_mov_b32 m0, s34
	v_lshl_add_u64 v[196:197], s[24:25], 0, v[138:139]
	ds_read_b128 v[192:195], v157
	ds_read_b128 v[208:211], v157 offset:1024
	ds_read_b128 v[212:215], v157 offset:2048
	ds_read_b128 v[216:219], v157 offset:3072
	ds_read_b128 v[220:223], v157 offset:4096
	ds_read_b128 v[224:227], v157 offset:5120
	ds_read_b128 v[236:239], v157 offset:6144
	ds_read_b128 v[240:243], v157 offset:7168
	global_load_lds_dwordx4 v[196:197], off
	v_lshl_add_u64 v[196:197], s[24:25], 0, v[140:141]
	s_mov_b32 m0, s35
	s_nop 0
	global_load_lds_dwordx4 v[196:197], off
	s_waitcnt vmcnt(8)
	s_waitcnt lgkmcnt(0)
	s_barrier
	s_setprio 1
	s_waitcnt lgkmcnt(0)
	v_mfma_f32_16x16x32_bf16 v[126:129], v[160:163], v[192:195], v[126:129]
	v_mfma_f32_16x16x32_bf16 v[122:125], v[168:171], v[192:195], v[122:125]
	v_mfma_f32_16x16x32_bf16 v[118:121], v[160:163], v[212:215], v[118:121]
	v_mfma_f32_16x16x32_bf16 v[114:117], v[168:171], v[212:215], v[114:117]
	v_mfma_f32_16x16x32_bf16 v[102:105], v[160:163], v[220:223], v[102:105]
	v_mfma_f32_16x16x32_bf16 v[98:101], v[168:171], v[220:223], v[98:101]
	v_mfma_f32_16x16x32_bf16 v[86:89], v[160:163], v[236:239], v[86:89]
	v_mfma_f32_16x16x32_bf16 v[82:85], v[168:171], v[236:239], v[82:85]
	v_mfma_f32_16x16x32_bf16 v[126:129], v[164:167], v[208:211], v[126:129]
	v_mfma_f32_16x16x32_bf16 v[122:125], v[172:175], v[208:211], v[122:125]
	v_mfma_f32_16x16x32_bf16 v[118:121], v[164:167], v[216:219], v[118:121]
	v_mfma_f32_16x16x32_bf16 v[114:117], v[172:175], v[216:219], v[114:117]
	v_mfma_f32_16x16x32_bf16 v[102:105], v[164:167], v[224:227], v[102:105]
	v_mfma_f32_16x16x32_bf16 v[98:101], v[172:175], v[224:227], v[98:101]
	v_mfma_f32_16x16x32_bf16 v[86:89], v[164:167], v[240:243], v[86:89]
	v_mfma_f32_16x16x32_bf16 v[82:85], v[172:175], v[240:243], v[82:85]
	s_setprio 0
	s_setprio 1
	v_mfma_f32_16x16x32_bf16 v[110:113], v[176:179], v[192:195], v[110:113]
	v_mfma_f32_16x16x32_bf16 v[106:109], v[184:187], v[192:195], v[106:109]
	v_mfma_f32_16x16x32_bf16 v[94:97], v[176:179], v[212:215], v[94:97]
	v_mfma_f32_16x16x32_bf16 v[90:93], v[184:187], v[212:215], v[90:93]
	v_mfma_f32_16x16x32_bf16 v[78:81], v[176:179], v[220:223], v[78:81]
	v_mfma_f32_16x16x32_bf16 v[74:77], v[184:187], v[220:223], v[74:77]
	v_mfma_f32_16x16x32_bf16 v[70:73], v[176:179], v[236:239], v[70:73]
	v_mfma_f32_16x16x32_bf16 v[66:69], v[184:187], v[236:239], v[66:69]
	v_mfma_f32_16x16x32_bf16 v[110:113], v[180:183], v[208:211], v[110:113]
	v_mfma_f32_16x16x32_bf16 v[106:109], v[188:191], v[208:211], v[106:109]
	v_mfma_f32_16x16x32_bf16 v[94:97], v[180:183], v[216:219], v[94:97]
	v_mfma_f32_16x16x32_bf16 v[90:93], v[188:191], v[216:219], v[90:93]
	v_mfma_f32_16x16x32_bf16 v[78:81], v[180:183], v[224:227], v[78:81]
	v_mfma_f32_16x16x32_bf16 v[74:77], v[188:191], v[224:227], v[74:77]
	v_mfma_f32_16x16x32_bf16 v[70:73], v[180:183], v[240:243], v[70:73]
	v_mfma_f32_16x16x32_bf16 v[66:69], v[188:191], v[240:243], v[66:69]
	s_setprio 0
	s_barrier
	s_add_i32 s45, s16, s2
	v_lshl_add_u64 v[196:197], s[28:29], 0, v[134:135]
	s_mov_b32 m0, s45
	ds_read_b128 v[192:195], v157 offset:16384
	ds_read_b128 v[208:211], v157 offset:17408
	ds_read_b128 v[212:215], v157 offset:18432
	ds_read_b128 v[216:219], v157 offset:19456
	ds_read_b128 v[220:223], v157 offset:20480
	ds_read_b128 v[224:227], v157 offset:21504
	ds_read_b128 v[236:239], v157 offset:22528
	ds_read_b128 v[240:243], v157 offset:23552
	global_load_lds_dwordx4 v[196:197], off
	s_add_i32 m0, s45, 0x2000
	s_add_u32 s46, s28, 0x30000
	v_lshl_add_u64 v[228:229], s[28:29], 0, v[130:131]
	s_addc_u32 s47, s29, 0
	s_add_i32 s45, s17, s2
	global_load_lds_dwordx4 v[228:229], off
	v_lshl_add_u64 v[244:245], s[46:47], 0, v[134:135]
	s_mov_b32 m0, s45
	v_lshl_add_u64 v[246:247], s[30:31], 0, v[132:133]
	global_load_lds_dwordx4 v[244:245], off
	v_lshl_add_u64 v[244:245], s[46:47], 0, v[130:131]
	s_add_i32 m0, s45, 0x2000
	s_nop 0
	global_load_lds_dwordx4 v[244:245], off
	v_lshl_add_u64 v[244:245], s[30:31], 0, v[136:137]
	s_mov_b32 m0, s3
	s_nop 0
	global_load_lds_dwordx4 v[244:245], off
	s_mov_b32 m0, s8
	s_nop 0
	global_load_lds_dwordx4 v[246:247], off
	s_waitcnt vmcnt(8)
	s_waitcnt lgkmcnt(0)
	s_barrier
; #define PG8_STAGE(bufoff, gbase, voff) do { _Pragma("unroll") for (int _i = 0; _i < 2; ++_i) \
;         __builtin_amdgcn_global_load_lds((const unsigned*)((const char*)(gbase) + (voff)[_i]), (PG8_LAS unsigned*)(lds + (bufoff) + ldsw + _i * 8192), 16, 0, 0); } while (0)
; #define PG8_LDA(dst, b, h) do { _Pragma("unroll") for (int m = 0; m < 4; ++m) _Pragma("unroll") for (int k = 0; k < 2; ++k) dst[m][k] = *(const PG8_LAS bf16x8*)(lds + PG8_SA(b, h) + aoff + m * 2048 + k * 1024); } while (0)
; #define PG8_LDB(dst, b, h) do { _Pragma("unroll") for (int n = 0; n < 2; ++n) _Pragma("unroll") for (int k = 0; k < 2; ++k) dst[n][k] = *(const PG8_LAS bf16x8*)(lds + PG8_SB(b, h) + boff + n * 2048 + k * 1024); } while (0)
; #define PG8_MMA(ai, bj, At, Bt) do { __builtin_amdgcn_s_setprio(1); _Pragma("unroll") for (int m = 0; m < 4; ++m) _Pragma("unroll") for (int n = 0; n < 2; ++n) _Pragma("unroll") for (int k = 0; k < 2; ++k) \
;         acc[ai][bj][m][n] = __builtin_amdgcn_mfma_f32_16x16x32_bf16(Bt[n][k], At[m][k], acc[ai][bj][m][n], 0, 0, 0); __builtin_amdgcn_s_setprio(0); } while (0)
; #define PG8_WAIT_V(n) asm volatile("s_waitcnt vmcnt(" #n ")" ::: "memory")
; #define PG8_WAIT_L(n) asm volatile("s_waitcnt lgkmcnt(" #n ")" ::: "memory")
; #define PG8_BAR __builtin_amdgcn_s_barrier()
; #define PG8_SCHED __builtin_amdgcn_sched_barrier(0)
; template <class Epi, class Sched, bool ALIGN_EPI = false, bool SP2 = false>
; __device__ __forceinline__ void gemm_phase(PG8_LAS unsigned char* lds, const Gemm g, const Sched& S, const Epi& E) {
;     ...
;             PG8_WAIT_V(8); PG8_WAIT_L(0); PG8_BAR; PG8_MMA(1, 0, At, B0); PG8_MMA(1, 1, At, B1); PG8_BAR; PG8_SCHED;
;             PG8_LDB(B0, 1, 0); PG8_LDB(B1, 1, 1); PG8_SCHED; PG8_LDA(At, 1, 0); PG8_STAGE(PG8_SA(0, 1), a2 + hstep, voffA);
;             PG8_WAIT_V(8); PG8_WAIT_L(0); PG8_BAR; PG8_MMA(0, 0, At, B0); PG8_MMA(0, 1, At, B1); PG8_BAR; PG8_SCHED;
	s_setprio 1
	s_waitcnt lgkmcnt(0)
	v_mfma_f32_16x16x32_bf16 v[62:65], v[160:163], v[192:195], v[62:65]
	v_mfma_f32_16x16x32_bf16 v[58:61], v[168:171], v[192:195], v[58:61]
	v_mfma_f32_16x16x32_bf16 v[54:57], v[160:163], v[212:215], v[54:57]
	v_mfma_f32_16x16x32_bf16 v[50:53], v[168:171], v[212:215], v[50:53]
	v_mfma_f32_16x16x32_bf16 v[38:41], v[160:163], v[220:223], v[38:41]
	v_mfma_f32_16x16x32_bf16 v[34:37], v[168:171], v[220:223], v[34:37]
	v_mfma_f32_16x16x32_bf16 v[22:25], v[160:163], v[236:239], v[22:25]
	v_mfma_f32_16x16x32_bf16 v[18:21], v[168:171], v[236:239], v[18:21]
	v_mfma_f32_16x16x32_bf16 v[62:65], v[164:167], v[208:211], v[62:65]
	v_mfma_f32_16x16x32_bf16 v[58:61], v[172:175], v[208:211], v[58:61]
	v_mfma_f32_16x16x32_bf16 v[54:57], v[164:167], v[216:219], v[54:57]
	v_mfma_f32_16x16x32_bf16 v[50:53], v[172:175], v[216:219], v[50:53]
	v_mfma_f32_16x16x32_bf16 v[38:41], v[164:167], v[224:227], v[38:41]
	v_mfma_f32_16x16x32_bf16 v[34:37], v[172:175], v[224:227], v[34:37]
	v_mfma_f32_16x16x32_bf16 v[22:25], v[164:167], v[240:243], v[22:25]
	v_mfma_f32_16x16x32_bf16 v[18:21], v[172:175], v[240:243], v[18:21]
	s_setprio 0
	s_setprio 1
	v_mfma_f32_16x16x32_bf16 v[46:49], v[176:179], v[192:195], v[46:49]
	v_mfma_f32_16x16x32_bf16 v[42:45], v[184:187], v[192:195], v[42:45]
	v_mfma_f32_16x16x32_bf16 v[30:33], v[176:179], v[212:215], v[30:33]
	v_mfma_f32_16x16x32_bf16 v[26:29], v[184:187], v[212:215], v[26:29]
	v_mfma_f32_16x16x32_bf16 v[14:17], v[176:179], v[220:223], v[14:17]
	v_mfma_f32_16x16x32_bf16 v[10:13], v[184:187], v[220:223], v[10:13]
	v_mfma_f32_16x16x32_bf16 v[6:9], v[176:179], v[236:239], v[6:9]
	v_mfma_f32_16x16x32_bf16 v[2:5], v[184:187], v[236:239], v[2:5]
	v_mfma_f32_16x16x32_bf16 v[46:49], v[180:183], v[208:211], v[46:49]
	v_mfma_f32_16x16x32_bf16 v[42:45], v[188:191], v[208:211], v[42:45]
	v_mfma_f32_16x16x32_bf16 v[30:33], v[180:183], v[216:219], v[30:33]
	v_mfma_f32_16x16x32_bf16 v[26:29], v[188:191], v[216:219], v[26:29]
	v_mfma_f32_16x16x32_bf16 v[14:17], v[180:183], v[224:227], v[14:17]
	v_mfma_f32_16x16x32_bf16 v[10:13], v[188:191], v[224:227], v[10:13]
	v_mfma_f32_16x16x32_bf16 v[6:9], v[180:183], v[240:243], v[6:9]
	v_mfma_f32_16x16x32_bf16 v[2:5], v[188:191], v[240:243], v[2:5]
	s_setprio 0
	s_barrier
	ds_read_b128 v[160:163], v158
	ds_read_b128 v[164:167], v158 offset:1024
	ds_read_b128 v[168:171], v158 offset:2048
	ds_read_b128 v[172:175], v158 offset:3072
	ds_read_b128 v[176:179], v159
	ds_read_b128 v[180:183], v159 offset:1024
	ds_read_b128 v[184:187], v159 offset:2048
	ds_read_b128 v[188:191], v159 offset:3072
	s_add_u32 s30, s30, 0x30000
	s_addc_u32 s31, s31, 0
	s_mov_b32 m0, s9
	v_lshl_add_u64 v[248:249], s[30:31], 0, v[136:137]
	ds_read_b128 v[192:195], v157 offset:32768
	ds_read_b128 v[208:211], v157 offset:33792
	ds_read_b128 v[212:215], v157 offset:34816
	ds_read_b128 v[216:219], v157 offset:35840
	ds_read_b128 v[220:223], v157 offset:36864
	ds_read_b128 v[224:227], v157 offset:37888
	ds_read_b128 v[236:239], v157 offset:38912
	ds_read_b128 v[240:243], v157 offset:39936
	global_load_lds_dwordx4 v[248:249], off
	v_lshl_add_u64 v[248:249], s[30:31], 0, v[132:133]
	s_mov_b32 m0, s12
	s_nop 0
	global_load_lds_dwordx4 v[248:249], off
	s_waitcnt vmcnt(8)
	s_waitcnt lgkmcnt(0)
	s_barrier
	s_setprio 1
	s_waitcnt lgkmcnt(0)
	v_mfma_f32_16x16x32_bf16 v[126:129], v[160:163], v[192:195], v[126:129]
	v_mfma_f32_16x16x32_bf16 v[122:125], v[168:171], v[192:195], v[122:125]
	v_mfma_f32_16x16x32_bf16 v[118:121], v[160:163], v[212:215], v[118:121]
	v_mfma_f32_16x16x32_bf16 v[114:117], v[168:171], v[212:215], v[114:117]
	v_mfma_f32_16x16x32_bf16 v[102:105], v[160:163], v[220:223], v[102:105]
	v_mfma_f32_16x16x32_bf16 v[98:101], v[168:171], v[220:223], v[98:101]
	v_mfma_f32_16x16x32_bf16 v[86:89], v[160:163], v[236:239], v[86:89]
	v_mfma_f32_16x16x32_bf16 v[82:85], v[168:171], v[236:239], v[82:85]
	v_mfma_f32_16x16x32_bf16 v[126:129], v[164:167], v[208:211], v[126:129]
	v_mfma_f32_16x16x32_bf16 v[122:125], v[172:175], v[208:211], v[122:125]
	v_mfma_f32_16x16x32_bf16 v[118:121], v[164:167], v[216:219], v[118:121]
	v_mfma_f32_16x16x32_bf16 v[114:117], v[172:175], v[216:219], v[114:117]
	v_mfma_f32_16x16x32_bf16 v[102:105], v[164:167], v[224:227], v[102:105]
	v_mfma_f32_16x16x32_bf16 v[98:101], v[172:175], v[224:227], v[98:101]
	v_mfma_f32_16x16x32_bf16 v[86:89], v[164:167], v[240:243], v[86:89]
	v_mfma_f32_16x16x32_bf16 v[82:85], v[172:175], v[240:243], v[82:85]
	s_setprio 0
	s_setprio 1
	v_mfma_f32_16x16x32_bf16 v[110:113], v[176:179], v[192:195], v[110:113]
	v_mfma_f32_16x16x32_bf16 v[106:109], v[184:187], v[192:195], v[106:109]
	v_mfma_f32_16x16x32_bf16 v[94:97], v[176:179], v[212:215], v[94:97]
	v_mfma_f32_16x16x32_bf16 v[90:93], v[184:187], v[212:215], v[90:93]
	v_mfma_f32_16x16x32_bf16 v[78:81], v[176:179], v[220:223], v[78:81]
	v_mfma_f32_16x16x32_bf16 v[74:77], v[184:187], v[220:223], v[74:77]
	v_mfma_f32_16x16x32_bf16 v[70:73], v[176:179], v[236:239], v[70:73]
	v_mfma_f32_16x16x32_bf16 v[66:69], v[184:187], v[236:239], v[66:69]
	v_mfma_f32_16x16x32_bf16 v[110:113], v[180:183], v[208:211], v[110:113]
	v_mfma_f32_16x16x32_bf16 v[106:109], v[188:191], v[208:211], v[106:109]
	v_mfma_f32_16x16x32_bf16 v[94:97], v[180:183], v[216:219], v[94:97]
	v_mfma_f32_16x16x32_bf16 v[90:93], v[188:191], v[216:219], v[90:93]
	v_mfma_f32_16x16x32_bf16 v[78:81], v[180:183], v[224:227], v[78:81]
	v_mfma_f32_16x16x32_bf16 v[74:77], v[188:191], v[224:227], v[74:77]
	v_mfma_f32_16x16x32_bf16 v[70:73], v[180:183], v[240:243], v[70:73]
	v_mfma_f32_16x16x32_bf16 v[66:69], v[188:191], v[240:243], v[66:69]
	s_setprio 0
	s_barrier
; #define PG8_STAGE(bufoff, gbase, voff) do { _Pragma("unroll") for (int _i = 0; _i < 2; ++_i) \
;         __builtin_amdgcn_global_load_lds((const unsigned*)((const char*)(gbase) + (voff)[_i]), (PG8_LAS unsigned*)(lds + (bufoff) + ldsw + _i * 8192), 16, 0, 0); } while (0)
; #define PG8_LDA(dst, b, h) do { _Pragma("unroll") for (int m = 0; m < 4; ++m) _Pragma("unroll") for (int k = 0; k < 2; ++k) dst[m][k] = *(const PG8_LAS bf16x8*)(lds + PG8_SA(b, h) + aoff + m * 2048 + k * 1024); } while (0)
; #define PG8_MMA(ai, bj, At, Bt) do { __builtin_amdgcn_s_setprio(1); _Pragma("unroll") for (int m = 0; m < 4; ++m) _Pragma("unroll") for (int n = 0; n < 2; ++n) _Pragma("unroll") for (int k = 0; k < 2; ++k) \
;         acc[ai][bj][m][n] = __builtin_amdgcn_mfma_f32_16x16x32_bf16(Bt[n][k], At[m][k], acc[ai][bj][m][n], 0, 0, 0); __builtin_amdgcn_s_setprio(0); } while (0)
; #define PG8_WAIT_V(n) asm volatile("s_waitcnt vmcnt(" #n ")" ::: "memory")
; #define PG8_WAIT_L(n) asm volatile("s_waitcnt lgkmcnt(" #n ")" ::: "memory")
; #define PG8_BAR __builtin_amdgcn_s_barrier()
; #define PG8_SCHED __builtin_amdgcn_sched_barrier(0)
; template <class Epi, class Sched, bool ALIGN_EPI = false, bool SP2 = false>
; __device__ __forceinline__ void gemm_phase(PG8_LAS unsigned char* lds, const Gemm g, const Sched& S, const Epi& E) {
;     ...
;         for (int t = 0; t < nt; t += 2) {
;     ...
;             PG8_LDA(At, 1, 1); PG8_STAGE(PG8_SB(1, 0), b3, voffB); PG8_STAGE(PG8_SB(1, 1), b3 + hstep, voffB); PG8_STAGE(PG8_SA(1, 0), a3, voffA);
;             PG8_WAIT_V(8); PG8_WAIT_L(0); PG8_BAR; PG8_MMA(1, 0, At, B0); PG8_MMA(1, 1, At, B1); PG8_BAR; PG8_SCHED;
;     ...
;         if constexpr (ALIGN_EPI) { if (wr == 0) PG8_BAR; }
	s_add_i32 s30, s36, s2
	v_lshl_add_u64 v[196:197], v[196:197], 0, s[18:19]
	s_mov_b32 m0, s30
	ds_read_b128 v[192:195], v157 offset:49152
	ds_read_b128 v[208:211], v157 offset:50176
	ds_read_b128 v[212:215], v157 offset:51200
	ds_read_b128 v[216:219], v157 offset:52224
	ds_read_b128 v[220:223], v157 offset:53248
	ds_read_b128 v[224:227], v157 offset:54272
	ds_read_b128 v[236:239], v157 offset:55296
	ds_read_b128 v[240:243], v157 offset:56320
	global_load_lds_dwordx4 v[196:197], off
	s_add_i32 m0, s30, 0x2000
	s_add_u32 s28, s28, 0x30080
	v_lshl_add_u64 v[196:197], v[228:229], 0, s[18:19]
	s_addc_u32 s29, s29, 0
	s_add_i32 s30, s37, s2
	global_load_lds_dwordx4 v[196:197], off
	v_lshl_add_u64 v[196:197], s[28:29], 0, v[134:135]
	s_mov_b32 m0, s30
	s_nop 0
	global_load_lds_dwordx4 v[196:197], off
	v_lshl_add_u64 v[196:197], s[28:29], 0, v[130:131]
	s_add_i32 m0, s30, 0x2000
	s_nop 0
	global_load_lds_dwordx4 v[196:197], off
	v_lshl_add_u64 v[196:197], v[244:245], 0, s[18:19]
	s_mov_b32 m0, s14
	s_nop 0
	global_load_lds_dwordx4 v[196:197], off
	v_lshl_add_u64 v[196:197], v[246:247], 0, s[18:19]
	s_mov_b32 m0, s15
	s_nop 0
	global_load_lds_dwordx4 v[196:197], off
	s_waitcnt vmcnt(8)
	s_waitcnt lgkmcnt(0)
	s_barrier
	s_setprio 1
	s_waitcnt lgkmcnt(0)
	v_mfma_f32_16x16x32_bf16 v[62:65], v[160:163], v[192:195], v[62:65]
	v_mfma_f32_16x16x32_bf16 v[58:61], v[168:171], v[192:195], v[58:61]
	v_mfma_f32_16x16x32_bf16 v[54:57], v[160:163], v[212:215], v[54:57]
	v_mfma_f32_16x16x32_bf16 v[50:53], v[168:171], v[212:215], v[50:53]
	v_mfma_f32_16x16x32_bf16 v[38:41], v[160:163], v[220:223], v[38:41]
	v_mfma_f32_16x16x32_bf16 v[34:37], v[168:171], v[220:223], v[34:37]
	v_mfma_f32_16x16x32_bf16 v[22:25], v[160:163], v[236:239], v[22:25]
	v_mfma_f32_16x16x32_bf16 v[18:21], v[168:171], v[236:239], v[18:21]
	v_mfma_f32_16x16x32_bf16 v[62:65], v[164:167], v[208:211], v[62:65]
	v_mfma_f32_16x16x32_bf16 v[58:61], v[172:175], v[208:211], v[58:61]
	v_mfma_f32_16x16x32_bf16 v[54:57], v[164:167], v[216:219], v[54:57]
	v_mfma_f32_16x16x32_bf16 v[50:53], v[172:175], v[216:219], v[50:53]
	v_mfma_f32_16x16x32_bf16 v[38:41], v[164:167], v[224:227], v[38:41]
	v_mfma_f32_16x16x32_bf16 v[34:37], v[172:175], v[224:227], v[34:37]
	v_mfma_f32_16x16x32_bf16 v[22:25], v[164:167], v[240:243], v[22:25]
	v_mfma_f32_16x16x32_bf16 v[18:21], v[172:175], v[240:243], v[18:21]
	s_setprio 0
	s_setprio 1
	v_mfma_f32_16x16x32_bf16 v[46:49], v[176:179], v[192:195], v[46:49]
	v_mfma_f32_16x16x32_bf16 v[42:45], v[184:187], v[192:195], v[42:45]
	v_mfma_f32_16x16x32_bf16 v[30:33], v[176:179], v[212:215], v[30:33]
	v_mfma_f32_16x16x32_bf16 v[26:29], v[184:187], v[212:215], v[26:29]
	v_mfma_f32_16x16x32_bf16 v[14:17], v[176:179], v[220:223], v[14:17]
	v_mfma_f32_16x16x32_bf16 v[10:13], v[184:187], v[220:223], v[10:13]
	v_mfma_f32_16x16x32_bf16 v[6:9], v[176:179], v[236:239], v[6:9]
	v_mfma_f32_16x16x32_bf16 v[2:5], v[184:187], v[236:239], v[2:5]
	v_mfma_f32_16x16x32_bf16 v[46:49], v[180:183], v[208:211], v[46:49]
	v_mfma_f32_16x16x32_bf16 v[42:45], v[188:191], v[208:211], v[42:45]
	v_mfma_f32_16x16x32_bf16 v[30:33], v[180:183], v[216:219], v[30:33]
	v_mfma_f32_16x16x32_bf16 v[26:29], v[188:191], v[216:219], v[26:29]
	v_mfma_f32_16x16x32_bf16 v[14:17], v[180:183], v[224:227], v[14:17]
	v_mfma_f32_16x16x32_bf16 v[10:13], v[188:191], v[224:227], v[10:13]
	v_mfma_f32_16x16x32_bf16 v[6:9], v[180:183], v[240:243], v[6:9]
	v_mfma_f32_16x16x32_bf16 v[2:5], v[188:191], v[240:243], v[2:5]
	s_setprio 0
	s_barrier
	s_add_i32 s44, s44, 2
	s_add_u32 s24, s24, 0x100
	s_addc_u32 s25, s25, 0
	s_add_u32 s42, s42, 0x100
	s_addc_u32 s43, s43, 0
	s_cmp_gt_u32 s44, 9
	s_cbranch_scc0 .LBB0_374
	s_and_b64 vcc, exec, s[20:21]
	s_cbranch_vccz .LBB0_377
	s_barrier

; #define PG8_STAGE(bufoff, gbase, voff) do { _Pragma("unroll") for (int _i = 0; _i < 2; ++_i) \
;         __builtin_amdgcn_global_load_lds((const unsigned*)((const char*)(gbase) + (voff)[_i]), (PG8_LAS unsigned*)(lds + (bufoff) + ldsw + _i * 8192), 16, 0, 0); } while (0)
; #define PG8_WAIT_V(n) asm volatile("s_waitcnt vmcnt(" #n ")" ::: "memory")
; #define PG8_BAR __builtin_amdgcn_s_barrier()
; template <class Epi, class Sched, bool ALIGN_EPI = false, bool SP2 = false>
; __device__ __forceinline__ void gemm_phase(PG8_LAS unsigned char* lds, const Gemm g, const Sched& S, const Epi& E) {
;     ...
;     for (int i = 0; i < 2; ++i) { int R, C; stage_rc(tid * 16 + i * 8192, R, C); const int Rb = Epi::PERM ? ((R & ~31) + perm32(R & 31)) : R;
;         voffA[i] = (unsigned)(R * LD + C) * 2u; voffB[i] = (unsigned)(Rb * LD + C) * 2u; }
;     const size_t kstep = (size_t)(BK * 2);
;     const size_t hstep = (size_t)HALF * LD * 2;
;     const size_t tstep = 2 * hstep;
;     const unsigned ldsw = (unsigned)wid * 1024u;
;     const int aoff = lds_byte(wr * 64 + fr, fq * 8), boff = lds_byte(wc * 32 + fr, fq * 8);
;     ...
;         PG8_WAIT_V(2); PG8_BAR;
;         PG8_STAGE(PG8_SB(1, 0), cB + kstep, voffB); PG8_STAGE(PG8_SA(1, 0), cA + kstep, voffA); PG8_STAGE(PG8_SB(1, 1), cB + hstep + kstep, voffB);
;         PG8_WAIT_V(6); PG8_BAR;
.LBB0_384:
	v_lshlrev_b32_e32 v11, 2, v204
	s_sext_i32_i8 s55, s4
	v_lshl_or_b32 v10, v204, 6, v147
	s_lshl_b32 s4, s11, 13
	v_and_b32_e32 v11, 32, v11
	v_lshl_or_b32 v142, s11, 6, v204
	v_bitop3_b32 v10, v10, s4, v11 bitop3:0xde
	s_lshl_b32 s4, s10, 5
	s_mov_b64 s[10:11], 0x80
	s_add_i32 m0, s14, 0x18000
	v_lshl_add_u64 v[8:9], v[8:9], 0, s[10:11]
	s_and_b32 s4, s4, 0x60
	s_waitcnt vmcnt(2)
	s_barrier
	global_load_lds_dwordx4 v[8:9], off
	v_lshl_add_u64 v[4:5], v[4:5], 0, s[10:11]
	s_add_i32 m0, s14, 0x1a000
	s_add_i32 s33, s14, 0x8000
	s_add_i32 s50, s14, 0xa000
	global_load_lds_dwordx4 v[4:5], off
	v_lshl_add_u64 v[2:3], v[2:3], 0, s[10:11]
	s_mov_b32 m0, s33
	s_add_u32 s12, s20, 0x10080
	global_load_lds_dwordx4 v[2:3], off
	v_lshl_add_u64 v[2:3], v[6:7], 0, s[10:11]
	s_mov_b32 m0, s50
	s_addc_u32 s13, s21, 0
	global_load_lds_dwordx4 v[2:3], off
	s_add_i32 m0, s14, 0x1c000
	v_lshl_add_u64 v[2:3], s[12:13], 0, v[134:135]
	global_load_lds_dwordx4 v[2:3], off
	v_lshl_add_u64 v[2:3], s[12:13], 0, v[130:131]
	s_add_i32 m0, s14, 0x1e000
	v_lshl_or_b32 v11, s4, 7, v146
	global_load_lds_dwordx4 v[2:3], off
	s_cmpk_lt_u32 s5, 0x100
	v_or_b32_e32 v1, s4, v1
	s_mov_b32 s4, 0x10000
	s_mov_b32 s22, 0x18000
	s_mov_b32 s23, 0x1c000
	s_waitcnt vmcnt(6)
	s_cselect_b64 s[12:13], -1, 0
	s_add_i32 s51, s4, 0x100
	s_mov_b32 s4, 0x14000
	s_add_i32 s52, s4, 0x100
	s_add_i32 s53, s22, 0x100
	s_add_i32 s54, s23, 0x100
	v_mov_b64_e32 v[138:139], 0x420
	v_mov_b64_e32 v[140:141], 0x41f
	v_add_u32_e32 v143, s51, v11
	v_add_u32_e32 v144, s52, v11
	v_add_u32_e32 v145, 0x100, v10
	v_add_u32_e32 v146, s53, v11
	v_add_u32_e32 v147, s54, v11
	s_barrier
	s_branch .LBB0_387

;     __device__ __forceinline__ bool next(int i, Unit& u) const { const int L = i * G + c; if (L >= nunits) return false; const int t = L / S, ks = L % S; u.pm = pm0 + t / nN; u.pn = t % nN; u.ko = ks * Ksub; return true; }
; #define PG8_STAGE(bufoff, gbase, voff) do { _Pragma("unroll") for (int _i = 0; _i < 2; ++_i) \
;         __builtin_amdgcn_global_load_lds((const unsigned*)((const char*)(gbase) + (voff)[_i]), (PG8_LAS unsigned*)(lds + (bufoff) + ldsw + _i * 8192), 16, 0, 0); } while (0)
; #define PG8_LDA(dst, b, h) do { _Pragma("unroll") for (int m = 0; m < 4; ++m) _Pragma("unroll") for (int k = 0; k < 2; ++k) dst[m][k] = *(const PG8_LAS bf16x8*)(lds + PG8_SA(b, h) + aoff + m * 2048 + k * 1024); } while (0)
; #define PG8_LDB(dst, b, h) do { _Pragma("unroll") for (int n = 0; n < 2; ++n) _Pragma("unroll") for (int k = 0; k < 2; ++k) dst[n][k] = *(const PG8_LAS bf16x8*)(lds + PG8_SB(b, h) + boff + n * 2048 + k * 1024); } while (0)
; template <class Epi, class Sched, bool ALIGN_EPI = false, bool SP2 = false>
; __device__ __forceinline__ void gemm_phase(PG8_LAS unsigned char* lds, const Gemm g, const Sched& S, const Epi& E) {
;     ...
;         const bool has_next = S.next(ui + 1, nxt);
;         const char* nA = has_next ? (const char*)g.A + (size_t)nxt.pm * tstep + (size_t)nxt.ko * 2 : cA; const char* nB = has_next ? (const char*)g.Bt + (size_t)nxt.pn * tstep + (size_t)nxt.ko * 2 : cB;
;         for (int t = 0; t < nt; t += 2) {
;             const bool last = (t == nt - 2);
;             const char* a1 = cA + (size_t)(t + 1) * kstep;
;             const char* a2 = last ? nA : cA + (size_t)(t + 2) * kstep; const char* b2 = last ? nB : cB + (size_t)(t + 2) * kstep;
;             const char* a3 = a2 + kstep; const char* b3 = b2 + kstep;
;             if (last && has_next) S.a_ready(nxt);
;             if constexpr (SP2) {
;             PG8_LDB(B0, 0, 0); PG8_LDB(B1, 0, 1); PG8_SCHED; PG8_LDA(At, 0, 0); PG8_STAGE(PG8_SA(1, 1), a1 + hstep, voffA);
;             PG8_WAIT_V(8); PG8_WAIT_L(0); PG8_BAR; PG8_MMA(0, 0, At, B0); PG8_MMA(0, 1, At, B1); PG8_BAR; PG8_SCHED;
;             PG8_LDA(At, 0, 1); PG8_STAGE(PG8_SB(0, 0), b2, voffB); PG8_STAGE(PG8_SB(0, 1), b2 + hstep, voffB); PG8_STAGE(PG8_SA(0, 0), a2, voffA);
;             PG8_WAIT_V(8); PG8_WAIT_L(0); PG8_BAR; PG8_MMA(1, 0, At, B0); PG8_MMA(1, 1, At, B1); PG8_BAR; PG8_SCHED;
.LBB0_390:
	s_add_u32 s41, s28, s40
	s_addc_u32 s46, s29, 0
	s_add_u32 s44, s41, 0x100
	s_addc_u32 s45, s46, 0
	s_and_b64 s[42:43], s[38:39], exec
	s_cselect_b32 s43, s25, s45
	s_cselect_b32 s42, s56, s44
	s_add_u32 s40, s20, s40
	s_addc_u32 s44, s21, 0
	s_add_u32 s40, s40, 0x100
	s_addc_u32 s44, s44, 0
	s_and_b64 s[38:39], s[38:39], exec
	s_cselect_b32 s45, s23, s44
	s_cselect_b32 s44, s57, s40
	s_add_u32 s48, s41, 0x10080
	ds_read_b128 v[148:151], v143
	ds_read_b128 v[152:155], v143 offset:1024
	ds_read_b128 v[156:159], v143 offset:2048
	ds_read_b128 v[160:163], v143 offset:3072
	ds_read_b128 v[164:167], v144
	ds_read_b128 v[168:171], v144 offset:1024
	ds_read_b128 v[172:175], v144 offset:2048
	ds_read_b128 v[176:179], v144 offset:3072
	s_addc_u32 s49, s46, 0
	s_add_i32 s65, s51, s3
	s_add_i32 m0, s14, 0xc000
	s_add_i32 s66, s14, 0xe000
	s_add_i32 s62, s65, 0x2000
	s_add_u32 s46, s44, 0x10000
	s_addc_u32 s47, s45, 0
	s_add_i32 s64, s52, s3
	s_add_i32 s63, s64, 0x2000
	s_add_u32 s40, s42, 0x10000
	s_addc_u32 s41, s43, 0
	s_add_i32 s61, s53, s3
	s_add_i32 s59, s61, 0x2000
	s_add_u32 s38, s44, 0x10080
	s_addc_u32 s39, s45, 0
	s_add_i32 s60, s54, s3
	s_add_i32 s58, s60, 0x2000
	v_lshl_add_u64 v[196:197], s[48:49], 0, v[136:137]
	ds_read_b128 v[180:183], v145
	ds_read_b128 v[184:187], v145 offset:1024
	ds_read_b128 v[188:191], v145 offset:2048
	ds_read_b128 v[192:195], v145 offset:3072
	ds_read_b128 v[208:211], v145 offset:4096
	ds_read_b128 v[212:215], v145 offset:5120
	ds_read_b128 v[216:219], v145 offset:6144
	ds_read_b128 v[220:223], v145 offset:7168
	global_load_lds_dwordx4 v[196:197], off
	v_lshl_add_u64 v[196:197], s[48:49], 0, v[132:133]
	s_mov_b32 m0, s66
	s_nop 0
	global_load_lds_dwordx4 v[196:197], off
	s_waitcnt vmcnt(8)
	s_waitcnt lgkmcnt(0)
	s_barrier
	s_setprio 1
	s_waitcnt lgkmcnt(0)
	v_mfma_f32_16x16x32_bf16 v[126:129], v[148:151], v[180:183], v[126:129]
	v_mfma_f32_16x16x32_bf16 v[122:125], v[156:159], v[180:183], v[122:125]
	v_mfma_f32_16x16x32_bf16 v[118:121], v[148:151], v[188:191], v[118:121]
	v_mfma_f32_16x16x32_bf16 v[114:117], v[156:159], v[188:191], v[114:117]
	v_mfma_f32_16x16x32_bf16 v[102:105], v[148:151], v[208:211], v[102:105]
	v_mfma_f32_16x16x32_bf16 v[98:101], v[156:159], v[208:211], v[98:101]
	v_mfma_f32_16x16x32_bf16 v[86:89], v[148:151], v[216:219], v[86:89]
	v_mfma_f32_16x16x32_bf16 v[82:85], v[156:159], v[216:219], v[82:85]
	v_mfma_f32_16x16x32_bf16 v[126:129], v[152:155], v[184:187], v[126:129]
	v_mfma_f32_16x16x32_bf16 v[122:125], v[160:163], v[184:187], v[122:125]
	v_mfma_f32_16x16x32_bf16 v[118:121], v[152:155], v[192:195], v[118:121]
	v_mfma_f32_16x16x32_bf16 v[114:117], v[160:163], v[192:195], v[114:117]
	v_mfma_f32_16x16x32_bf16 v[102:105], v[152:155], v[212:215], v[102:105]
	v_mfma_f32_16x16x32_bf16 v[98:101], v[160:163], v[212:215], v[98:101]
	v_mfma_f32_16x16x32_bf16 v[86:89], v[152:155], v[220:223], v[86:89]
	v_mfma_f32_16x16x32_bf16 v[82:85], v[160:163], v[220:223], v[82:85]
	s_setprio 0
	s_setprio 1
	v_mfma_f32_16x16x32_bf16 v[110:113], v[164:167], v[180:183], v[110:113]
	v_mfma_f32_16x16x32_bf16 v[106:109], v[172:175], v[180:183], v[106:109]
	v_mfma_f32_16x16x32_bf16 v[94:97], v[164:167], v[188:191], v[94:97]
	v_mfma_f32_16x16x32_bf16 v[90:93], v[172:175], v[188:191], v[90:93]
	v_mfma_f32_16x16x32_bf16 v[78:81], v[164:167], v[208:211], v[78:81]
	v_mfma_f32_16x16x32_bf16 v[74:77], v[172:175], v[208:211], v[74:77]
	v_mfma_f32_16x16x32_bf16 v[70:73], v[164:167], v[216:219], v[70:73]
	v_mfma_f32_16x16x32_bf16 v[66:69], v[172:175], v[216:219], v[66:69]
	v_mfma_f32_16x16x32_bf16 v[110:113], v[168:171], v[184:187], v[110:113]
	v_mfma_f32_16x16x32_bf16 v[106:109], v[176:179], v[184:187], v[106:109]
	v_mfma_f32_16x16x32_bf16 v[94:97], v[168:171], v[192:195], v[94:97]
	v_mfma_f32_16x16x32_bf16 v[90:93], v[176:179], v[192:195], v[90:93]
	v_mfma_f32_16x16x32_bf16 v[78:81], v[168:171], v[212:215], v[78:81]
	v_mfma_f32_16x16x32_bf16 v[74:77], v[176:179], v[212:215], v[74:77]
	v_mfma_f32_16x16x32_bf16 v[70:73], v[168:171], v[220:223], v[70:73]
	v_mfma_f32_16x16x32_bf16 v[66:69], v[176:179], v[220:223], v[66:69]
	s_setprio 0
	s_barrier
	s_mov_b32 m0, s65
	v_lshl_add_u64 v[196:197], s[44:45], 0, v[134:135]
	ds_read_b128 v[180:183], v145 offset:16384
	ds_read_b128 v[184:187], v145 offset:17408
	ds_read_b128 v[188:191], v145 offset:18432
	ds_read_b128 v[192:195], v145 offset:19456
	ds_read_b128 v[208:211], v145 offset:20480
	ds_read_b128 v[212:215], v145 offset:21504
	ds_read_b128 v[216:219], v145 offset:22528
	ds_read_b128 v[220:223], v145 offset:23552
	global_load_lds_dwordx4 v[196:197], off
	v_lshl_add_u64 v[224:225], s[44:45], 0, v[130:131]
	s_mov_b32 m0, s62
	v_lshl_add_u64 v[226:227], s[46:47], 0, v[134:135]
	global_load_lds_dwordx4 v[224:225], off
	s_mov_b32 m0, s64
	v_lshl_add_u64 v[228:229], s[42:43], 0, v[132:133]
	global_load_lds_dwordx4 v[226:227], off
	v_lshl_add_u64 v[226:227], s[46:47], 0, v[130:131]
	s_mov_b32 m0, s63
	s_nop 0
	global_load_lds_dwordx4 v[226:227], off
	v_lshl_add_u64 v[226:227], s[42:43], 0, v[136:137]
	s_mov_b32 m0, s14
	s_nop 0
	global_load_lds_dwordx4 v[226:227], off
	s_mov_b32 m0, s15
	s_nop 0
	global_load_lds_dwordx4 v[228:229], off
	s_waitcnt vmcnt(8)
	s_waitcnt lgkmcnt(0)
	s_barrier
; #define PG8_STAGE(bufoff, gbase, voff) do { _Pragma("unroll") for (int _i = 0; _i < 2; ++_i) \
;         __builtin_amdgcn_global_load_lds((const unsigned*)((const char*)(gbase) + (voff)[_i]), (PG8_LAS unsigned*)(lds + (bufoff) + ldsw + _i * 8192), 16, 0, 0); } while (0)
; #define PG8_LDA(dst, b, h) do { _Pragma("unroll") for (int m = 0; m < 4; ++m) _Pragma("unroll") for (int k = 0; k < 2; ++k) dst[m][k] = *(const PG8_LAS bf16x8*)(lds + PG8_SA(b, h) + aoff + m * 2048 + k * 1024); } while (0)
; #define PG8_LDB(dst, b, h) do { _Pragma("unroll") for (int n = 0; n < 2; ++n) _Pragma("unroll") for (int k = 0; k < 2; ++k) dst[n][k] = *(const PG8_LAS bf16x8*)(lds + PG8_SB(b, h) + boff + n * 2048 + k * 1024); } while (0)
; #define PG8_MMA(ai, bj, At, Bt) do { __builtin_amdgcn_s_setprio(1); _Pragma("unroll") for (int m = 0; m < 4; ++m) _Pragma("unroll") for (int n = 0; n < 2; ++n) _Pragma("unroll") for (int k = 0; k < 2; ++k) \
;         acc[ai][bj][m][n] = __builtin_amdgcn_mfma_f32_16x16x32_bf16(Bt[n][k], At[m][k], acc[ai][bj][m][n], 0, 0, 0); __builtin_amdgcn_s_setprio(0); } while (0)
; #define PG8_WAIT_V(n) asm volatile("s_waitcnt vmcnt(" #n ")" ::: "memory")
; #define PG8_WAIT_L(n) asm volatile("s_waitcnt lgkmcnt(" #n ")" ::: "memory")
; #define PG8_BAR __builtin_amdgcn_s_barrier()
; #define PG8_SCHED __builtin_amdgcn_sched_barrier(0)
; template <class Epi, class Sched, bool ALIGN_EPI = false, bool SP2 = false>
; __device__ __forceinline__ void gemm_phase(PG8_LAS unsigned char* lds, const Gemm g, const Sched& S, const Epi& E) {
;     ...
;             PG8_WAIT_V(8); PG8_WAIT_L(0); PG8_BAR; PG8_MMA(1, 0, At, B0); PG8_MMA(1, 1, At, B1); PG8_BAR; PG8_SCHED;
;             PG8_LDB(B0, 1, 0); PG8_LDB(B1, 1, 1); PG8_SCHED; PG8_LDA(At, 1, 0); PG8_STAGE(PG8_SA(0, 1), a2 + hstep, voffA);
;             PG8_WAIT_V(8); PG8_WAIT_L(0); PG8_BAR; PG8_MMA(0, 0, At, B0); PG8_MMA(0, 1, At, B1); PG8_BAR; PG8_SCHED;
	s_setprio 1
	s_waitcnt lgkmcnt(0)
	v_mfma_f32_16x16x32_bf16 v[62:65], v[148:151], v[180:183], v[62:65]
	v_mfma_f32_16x16x32_bf16 v[58:61], v[156:159], v[180:183], v[58:61]
	v_mfma_f32_16x16x32_bf16 v[54:57], v[148:151], v[188:191], v[54:57]
	v_mfma_f32_16x16x32_bf16 v[50:53], v[156:159], v[188:191], v[50:53]
	v_mfma_f32_16x16x32_bf16 v[38:41], v[148:151], v[208:211], v[38:41]
	v_mfma_f32_16x16x32_bf16 v[34:37], v[156:159], v[208:211], v[34:37]
	v_mfma_f32_16x16x32_bf16 v[22:25], v[148:151], v[216:219], v[22:25]
	v_mfma_f32_16x16x32_bf16 v[18:21], v[156:159], v[216:219], v[18:21]
	v_mfma_f32_16x16x32_bf16 v[62:65], v[152:155], v[184:187], v[62:65]
	v_mfma_f32_16x16x32_bf16 v[58:61], v[160:163], v[184:187], v[58:61]
	v_mfma_f32_16x16x32_bf16 v[54:57], v[152:155], v[192:195], v[54:57]
	v_mfma_f32_16x16x32_bf16 v[50:53], v[160:163], v[192:195], v[50:53]
	v_mfma_f32_16x16x32_bf16 v[38:41], v[152:155], v[212:215], v[38:41]
	v_mfma_f32_16x16x32_bf16 v[34:37], v[160:163], v[212:215], v[34:37]
	v_mfma_f32_16x16x32_bf16 v[22:25], v[152:155], v[220:223], v[22:25]
	v_mfma_f32_16x16x32_bf16 v[18:21], v[160:163], v[220:223], v[18:21]
	s_setprio 0
	s_setprio 1
	v_mfma_f32_16x16x32_bf16 v[46:49], v[164:167], v[180:183], v[46:49]
	v_mfma_f32_16x16x32_bf16 v[42:45], v[172:175], v[180:183], v[42:45]
	v_mfma_f32_16x16x32_bf16 v[30:33], v[164:167], v[188:191], v[30:33]
	v_mfma_f32_16x16x32_bf16 v[26:29], v[172:175], v[188:191], v[26:29]
	v_mfma_f32_16x16x32_bf16 v[14:17], v[164:167], v[208:211], v[14:17]
	v_mfma_f32_16x16x32_bf16 v[10:13], v[172:175], v[208:211], v[10:13]
	v_mfma_f32_16x16x32_bf16 v[6:9], v[164:167], v[216:219], v[6:9]
	v_mfma_f32_16x16x32_bf16 v[2:5], v[172:175], v[216:219], v[2:5]
	v_mfma_f32_16x16x32_bf16 v[46:49], v[168:171], v[184:187], v[46:49]
	v_mfma_f32_16x16x32_bf16 v[42:45], v[176:179], v[184:187], v[42:45]
	v_mfma_f32_16x16x32_bf16 v[30:33], v[168:171], v[192:195], v[30:33]
	v_mfma_f32_16x16x32_bf16 v[26:29], v[176:179], v[192:195], v[26:29]
	v_mfma_f32_16x16x32_bf16 v[14:17], v[168:171], v[212:215], v[14:17]
	v_mfma_f32_16x16x32_bf16 v[10:13], v[176:179], v[212:215], v[10:13]
	v_mfma_f32_16x16x32_bf16 v[6:9], v[168:171], v[220:223], v[6:9]
	v_mfma_f32_16x16x32_bf16 v[2:5], v[176:179], v[220:223], v[2:5]
	s_setprio 0
	s_barrier
	ds_read_b128 v[148:151], v146
	ds_read_b128 v[152:155], v146 offset:1024
	ds_read_b128 v[156:159], v146 offset:2048
	ds_read_b128 v[160:163], v146 offset:3072
	ds_read_b128 v[164:167], v147
	ds_read_b128 v[168:171], v147 offset:1024
	ds_read_b128 v[172:175], v147 offset:2048
	ds_read_b128 v[176:179], v147 offset:3072
	s_mov_b32 m0, s16
	v_lshl_add_u64 v[236:237], s[40:41], 0, v[136:137]
	ds_read_b128 v[180:183], v145 offset:32768
	ds_read_b128 v[184:187], v145 offset:33792
	ds_read_b128 v[188:191], v145 offset:34816
	ds_read_b128 v[192:195], v145 offset:35840
	ds_read_b128 v[208:211], v145 offset:36864
	ds_read_b128 v[212:215], v145 offset:37888
	ds_read_b128 v[216:219], v145 offset:38912
	ds_read_b128 v[220:223], v145 offset:39936
	global_load_lds_dwordx4 v[236:237], off
	v_lshl_add_u64 v[236:237], s[40:41], 0, v[132:133]
	s_mov_b32 m0, s17
	s_nop 0
	global_load_lds_dwordx4 v[236:237], off
	s_waitcnt vmcnt(8)
	s_waitcnt lgkmcnt(0)
	s_barrier
	s_setprio 1
	s_waitcnt lgkmcnt(0)
	v_mfma_f32_16x16x32_bf16 v[126:129], v[148:151], v[180:183], v[126:129]
	v_mfma_f32_16x16x32_bf16 v[122:125], v[156:159], v[180:183], v[122:125]
	v_mfma_f32_16x16x32_bf16 v[118:121], v[148:151], v[188:191], v[118:121]
	v_mfma_f32_16x16x32_bf16 v[114:117], v[156:159], v[188:191], v[114:117]
	v_mfma_f32_16x16x32_bf16 v[102:105], v[148:151], v[208:211], v[102:105]
	v_mfma_f32_16x16x32_bf16 v[98:101], v[156:159], v[208:211], v[98:101]
	v_mfma_f32_16x16x32_bf16 v[86:89], v[148:151], v[216:219], v[86:89]
	v_mfma_f32_16x16x32_bf16 v[82:85], v[156:159], v[216:219], v[82:85]
	v_mfma_f32_16x16x32_bf16 v[126:129], v[152:155], v[184:187], v[126:129]
	v_mfma_f32_16x16x32_bf16 v[122:125], v[160:163], v[184:187], v[122:125]
	v_mfma_f32_16x16x32_bf16 v[118:121], v[152:155], v[192:195], v[118:121]
	v_mfma_f32_16x16x32_bf16 v[114:117], v[160:163], v[192:195], v[114:117]
	v_mfma_f32_16x16x32_bf16 v[102:105], v[152:155], v[212:215], v[102:105]
	v_mfma_f32_16x16x32_bf16 v[98:101], v[160:163], v[212:215], v[98:101]
	v_mfma_f32_16x16x32_bf16 v[86:89], v[152:155], v[220:223], v[86:89]
	v_mfma_f32_16x16x32_bf16 v[82:85], v[160:163], v[220:223], v[82:85]
	s_setprio 0
	s_setprio 1
	v_mfma_f32_16x16x32_bf16 v[110:113], v[164:167], v[180:183], v[110:113]
	v_mfma_f32_16x16x32_bf16 v[106:109], v[172:175], v[180:183], v[106:109]
	v_mfma_f32_16x16x32_bf16 v[94:97], v[164:167], v[188:191], v[94:97]
	v_mfma_f32_16x16x32_bf16 v[90:93], v[172:175], v[188:191], v[90:93]
	v_mfma_f32_16x16x32_bf16 v[78:81], v[164:167], v[208:211], v[78:81]
	v_mfma_f32_16x16x32_bf16 v[74:77], v[172:175], v[208:211], v[74:77]
	v_mfma_f32_16x16x32_bf16 v[70:73], v[164:167], v[216:219], v[70:73]
	v_mfma_f32_16x16x32_bf16 v[66:69], v[172:175], v[216:219], v[66:69]
	v_mfma_f32_16x16x32_bf16 v[110:113], v[168:171], v[184:187], v[110:113]
	v_mfma_f32_16x16x32_bf16 v[106:109], v[176:179], v[184:187], v[106:109]
	v_mfma_f32_16x16x32_bf16 v[94:97], v[168:171], v[192:195], v[94:97]
	v_mfma_f32_16x16x32_bf16 v[90:93], v[176:179], v[192:195], v[90:93]
	v_mfma_f32_16x16x32_bf16 v[78:81], v[168:171], v[212:215], v[78:81]
	v_mfma_f32_16x16x32_bf16 v[74:77], v[176:179], v[212:215], v[74:77]
	v_mfma_f32_16x16x32_bf16 v[70:73], v[168:171], v[220:223], v[70:73]
	v_mfma_f32_16x16x32_bf16 v[66:69], v[176:179], v[220:223], v[66:69]
	s_setprio 0
	s_barrier
; #define PG8_STAGE(bufoff, gbase, voff) do { _Pragma("unroll") for (int _i = 0; _i < 2; ++_i) \
;         __builtin_amdgcn_global_load_lds((const unsigned*)((const char*)(gbase) + (voff)[_i]), (PG8_LAS unsigned*)(lds + (bufoff) + ldsw + _i * 8192), 16, 0, 0); } while (0)
; #define PG8_LDA(dst, b, h) do { _Pragma("unroll") for (int m = 0; m < 4; ++m) _Pragma("unroll") for (int k = 0; k < 2; ++k) dst[m][k] = *(const PG8_LAS bf16x8*)(lds + PG8_SA(b, h) + aoff + m * 2048 + k * 1024); } while (0)
; #define PG8_MMA(ai, bj, At, Bt) do { __builtin_amdgcn_s_setprio(1); _Pragma("unroll") for (int m = 0; m < 4; ++m) _Pragma("unroll") for (int n = 0; n < 2; ++n) _Pragma("unroll") for (int k = 0; k < 2; ++k) \
;         acc[ai][bj][m][n] = __builtin_amdgcn_mfma_f32_16x16x32_bf16(Bt[n][k], At[m][k], acc[ai][bj][m][n], 0, 0, 0); __builtin_amdgcn_s_setprio(0); } while (0)
; #define PG8_WAIT_V(n) asm volatile("s_waitcnt vmcnt(" #n ")" ::: "memory")
; #define PG8_WAIT_L(n) asm volatile("s_waitcnt lgkmcnt(" #n ")" ::: "memory")
; #define PG8_BAR __builtin_amdgcn_s_barrier()
; #define PG8_SCHED __builtin_amdgcn_sched_barrier(0)
; template <class Epi, class Sched, bool ALIGN_EPI = false, bool SP2 = false>
; __device__ __forceinline__ void gemm_phase(PG8_LAS unsigned char* lds, const Gemm g, const Sched& S, const Epi& E) {
;     ...
;         for (int t = 0; t < nt; t += 2) {
;     ...
;             PG8_LDA(At, 1, 1); PG8_STAGE(PG8_SB(1, 0), b3, voffB); PG8_STAGE(PG8_SB(1, 1), b3 + hstep, voffB); PG8_STAGE(PG8_SA(1, 0), a3, voffA);
;             PG8_WAIT_V(8); PG8_WAIT_L(0); PG8_BAR; PG8_MMA(1, 0, At, B0); PG8_MMA(1, 1, At, B1); PG8_BAR; PG8_SCHED;
;     ...
;         if constexpr (ALIGN_EPI) { if (wr == 0) PG8_BAR; }
	s_mov_b32 m0, s61
	v_lshl_add_u64 v[196:197], v[196:197], 0, s[10:11]
	ds_read_b128 v[180:183], v145 offset:49152
	ds_read_b128 v[184:187], v145 offset:50176
	ds_read_b128 v[188:191], v145 offset:51200
	ds_read_b128 v[192:195], v145 offset:52224
	ds_read_b128 v[208:211], v145 offset:53248
	ds_read_b128 v[212:215], v145 offset:54272
	ds_read_b128 v[216:219], v145 offset:55296
	ds_read_b128 v[220:223], v145 offset:56320
	global_load_lds_dwordx4 v[196:197], off
	v_lshl_add_u64 v[196:197], v[224:225], 0, s[10:11]
	s_mov_b32 m0, s59
	s_nop 0
	global_load_lds_dwordx4 v[196:197], off
	v_lshl_add_u64 v[196:197], s[38:39], 0, v[134:135]
	s_mov_b32 m0, s60
	s_nop 0
	global_load_lds_dwordx4 v[196:197], off
	v_lshl_add_u64 v[196:197], s[38:39], 0, v[130:131]
	s_mov_b32 m0, s58
	s_nop 0
	global_load_lds_dwordx4 v[196:197], off
	v_lshl_add_u64 v[196:197], v[226:227], 0, s[10:11]
	s_mov_b32 m0, s33
	s_nop 0
	global_load_lds_dwordx4 v[196:197], off
	v_lshl_add_u64 v[196:197], v[228:229], 0, s[10:11]
	s_mov_b32 m0, s50
	s_nop 0
	global_load_lds_dwordx4 v[196:197], off
	s_waitcnt vmcnt(8)
	s_waitcnt lgkmcnt(0)
	s_barrier
	s_setprio 1
	s_waitcnt lgkmcnt(0)
	v_mfma_f32_16x16x32_bf16 v[62:65], v[148:151], v[180:183], v[62:65]
	v_mfma_f32_16x16x32_bf16 v[58:61], v[156:159], v[180:183], v[58:61]
	v_mfma_f32_16x16x32_bf16 v[54:57], v[148:151], v[188:191], v[54:57]
	v_mfma_f32_16x16x32_bf16 v[50:53], v[156:159], v[188:191], v[50:53]
	v_mfma_f32_16x16x32_bf16 v[38:41], v[148:151], v[208:211], v[38:41]
	v_mfma_f32_16x16x32_bf16 v[34:37], v[156:159], v[208:211], v[34:37]
	v_mfma_f32_16x16x32_bf16 v[22:25], v[148:151], v[216:219], v[22:25]
	v_mfma_f32_16x16x32_bf16 v[18:21], v[156:159], v[216:219], v[18:21]
	v_mfma_f32_16x16x32_bf16 v[62:65], v[152:155], v[184:187], v[62:65]
	v_mfma_f32_16x16x32_bf16 v[58:61], v[160:163], v[184:187], v[58:61]
	v_mfma_f32_16x16x32_bf16 v[54:57], v[152:155], v[192:195], v[54:57]
	v_mfma_f32_16x16x32_bf16 v[50:53], v[160:163], v[192:195], v[50:53]
	v_mfma_f32_16x16x32_bf16 v[38:41], v[152:155], v[212:215], v[38:41]
	v_mfma_f32_16x16x32_bf16 v[34:37], v[160:163], v[212:215], v[34:37]
	v_mfma_f32_16x16x32_bf16 v[22:25], v[152:155], v[220:223], v[22:25]
	v_mfma_f32_16x16x32_bf16 v[18:21], v[160:163], v[220:223], v[18:21]
	s_setprio 0
	s_setprio 1
	v_mfma_f32_16x16x32_bf16 v[46:49], v[164:167], v[180:183], v[46:49]
	v_mfma_f32_16x16x32_bf16 v[42:45], v[172:175], v[180:183], v[42:45]
	v_mfma_f32_16x16x32_bf16 v[30:33], v[164:167], v[188:191], v[30:33]
	v_mfma_f32_16x16x32_bf16 v[26:29], v[172:175], v[188:191], v[26:29]
	v_mfma_f32_16x16x32_bf16 v[14:17], v[164:167], v[208:211], v[14:17]
	v_mfma_f32_16x16x32_bf16 v[10:13], v[172:175], v[208:211], v[10:13]
	v_mfma_f32_16x16x32_bf16 v[6:9], v[164:167], v[216:219], v[6:9]
	v_mfma_f32_16x16x32_bf16 v[2:5], v[172:175], v[216:219], v[2:5]
	v_mfma_f32_16x16x32_bf16 v[46:49], v[168:171], v[184:187], v[46:49]
	v_mfma_f32_16x16x32_bf16 v[42:45], v[176:179], v[184:187], v[42:45]
	v_mfma_f32_16x16x32_bf16 v[30:33], v[168:171], v[192:195], v[30:33]
	v_mfma_f32_16x16x32_bf16 v[26:29], v[176:179], v[192:195], v[26:29]
	v_mfma_f32_16x16x32_bf16 v[14:17], v[168:171], v[212:215], v[14:17]
	v_mfma_f32_16x16x32_bf16 v[10:13], v[176:179], v[212:215], v[10:13]
	v_mfma_f32_16x16x32_bf16 v[6:9], v[168:171], v[220:223], v[6:9]
	v_mfma_f32_16x16x32_bf16 v[2:5], v[176:179], v[220:223], v[2:5]
	s_setprio 0
	s_barrier
	s_movk_i32 s40, 0x100
	s_andn2_b64 vcc, exec, s[36:37]
	s_mov_b64 s[38:39], -1
	s_mov_b64 s[36:37], 0
	s_cbranch_vccz .LBB0_390
	s_and_b64 vcc, exec, s[12:13]
	s_cbranch_vccz .LBB0_393
	s_barrier

; #define LAS __attribute__((address_space(3)))
; #define MFMA32(a, b, c) __builtin_amdgcn_mfma_f32_32x32x16_bf16((a), (b), (c), 0, 0, 0)
;     constexpr int NS = MODE == 0 ? 6 : 4, KSTR = MODE == 0 ? 208 : 144;
;     const LAS unsigned char* kb = buf + r * KSTR + hi * 16;
; #pragma unroll
;     for (int s = 0; s < NS; ++s) { const bf16x8 a0 = *(const LAS bf16x8*)(kb + 32 * s), a1 = *(const LAS bf16x8*)(kb + 32 * KSTR + 32 * s);
;         if (s == 0) { s0 = MFMA32(a0, qf[0], negm); s1 = MFMA32(a1, qf[0], negm); }
;         else { s0 = MFMA32(a0, qf[s], s0); s1 = MFMA32(a1, qf[s], s1); } }
; __device__ __forceinline__ void st_vread(const LAS unsigned char* buf, int vlane, bf16x8 (&vf)[8]) {
;     const LAS unsigned char* vb = buf + KB_MAX + vlane;
; #pragma unroll
;     for (int ks = 0; ks < 4; ++ks) {
; #pragma unroll
;         for (int db = 0; db < 2; ++db) {
;             const v4i16_t lo = __builtin_amdgcn_ds_read_tr16_b64_v4i16((LAS v4i16_t*)(vb + (16 * ks) * VSTR + db * 64));
;             const v4i16_t hh = __builtin_amdgcn_ds_read_tr16_b64_v4i16((LAS v4i16_t*)(vb + (16 * ks + 8) * VSTR + db * 64));
;             vf[2 * ks + db] = (bf16x8){lo[0], lo[1], lo[2], lo[3], hh[0], hh[1], hh[2], hh[3]}; } }
.LBB0_666:
	s_add_i32 s0, s11, 1
	s_min_i32 s6, s0, s3
	s_waitcnt vmcnt(2)
	v_mad_i64_i32 v[4:5], s[0:1], v170, s6, v[180:181]
	s_waitcnt vmcnt(1)
	v_mad_i64_i32 v[8:9], s[0:1], v172, s6, v[178:179]
	s_waitcnt vmcnt(0)
	v_mad_i64_i32 v[12:13], s[0:1], v174, s6, v[176:177]
	global_load_dwordx4 v[4:7], v[4:5], off
	s_add_i32 s13, s11, -1
	global_load_dwordx4 v[8:11], v[8:9], off
	s_cmp_le_i32 s13, s10
	global_load_dwordx4 v[12:15], v[12:13], off
	s_cselect_b64 s[0:1], -1, 0
	s_and_b64 s[0:1], s[8:9], s[0:1]
	s_andn2_b64 vcc, exec, s[0:1]
	s_cbranch_vccnz .LBB0_674
	v_add_u32_e32 v2, v171, v168
	s_xor_b64 s[0:1], s[4:5], -1
	s_and_b64 vcc, exec, s[0:1]
	ds_read_b128 v[66:69], v2
	ds_read_b128 v[134:137], v2 offset:6656
	ds_read_b128 v[138:141], v2 offset:32
	ds_read_b128 v[142:145], v2 offset:6688
	ds_read_b128 v[146:149], v2 offset:64
	ds_read_b128 v[150:153], v2 offset:6720
	ds_read_b128 v[154:157], v2 offset:96
	ds_read_b128 v[158:161], v2 offset:6752
	ds_read_b128 v[162:165], v2 offset:128
	s_waitcnt lgkmcnt(8)
	v_mfma_f32_32x32x16_bf16 v[82:97], v[66:69], v[110:113], v[50:65]
	s_waitcnt lgkmcnt(7)
	v_mfma_f32_32x32x16_bf16 v[66:81], v[134:137], v[110:113], v[50:65]
	ds_read_b128 v[134:137], v2 offset:6784
	s_waitcnt lgkmcnt(7)
	v_mfma_f32_32x32x16_bf16 v[82:97], v[138:141], v[106:109], v[82:97]
	ds_read_b128 v[138:141], v2 offset:160
	s_waitcnt lgkmcnt(7)
	v_mfma_f32_32x32x16_bf16 v[66:81], v[142:145], v[106:109], v[66:81]
	ds_read_b128 v[142:145], v2 offset:6816
	v_add_u32_e32 v2, 0x100, v183
	s_waitcnt lgkmcnt(7)
	v_mfma_f32_32x32x16_bf16 v[82:97], v[146:149], v[102:105], v[82:97]
	s_waitcnt lgkmcnt(6)
	v_mfma_f32_32x32x16_bf16 v[66:81], v[150:153], v[102:105], v[66:81]
	s_waitcnt lgkmcnt(5)
	v_mfma_f32_32x32x16_bf16 v[82:97], v[154:157], v[98:101], v[82:97]
	s_waitcnt lgkmcnt(4)
	v_mfma_f32_32x32x16_bf16 v[66:81], v[158:161], v[98:101], v[66:81]
	s_waitcnt lgkmcnt(3)
	v_mfma_f32_32x32x16_bf16 v[82:97], v[162:165], v[118:121], v[82:97]
	s_waitcnt lgkmcnt(2)
	v_mfma_f32_32x32x16_bf16 v[66:81], v[134:137], v[118:121], v[66:81]
	s_waitcnt lgkmcnt(1)
	v_mfma_f32_32x32x16_bf16 v[82:97], v[138:141], v[114:117], v[82:97]
	s_waitcnt lgkmcnt(0)
	v_mfma_f32_32x32x16_bf16 v[66:81], v[142:145], v[114:117], v[66:81]
	ds_read_b64_tr_b16 v[162:163], v2 offset:13312
	ds_read_b64_tr_b16 v[164:165], v2 offset:14848
	ds_read_b64_tr_b16 v[158:159], v2 offset:13376
	ds_read_b64_tr_b16 v[160:161], v2 offset:14912
	ds_read_b64_tr_b16 v[150:151], v2 offset:16384
	ds_read_b64_tr_b16 v[152:153], v2 offset:17920
	ds_read_b64_tr_b16 v[154:155], v2 offset:16448
	ds_read_b64_tr_b16 v[156:157], v2 offset:17984
	ds_read_b64_tr_b16 v[146:147], v2 offset:19456
	ds_read_b64_tr_b16 v[148:149], v2 offset:20992
	ds_read_b64_tr_b16 v[142:143], v2 offset:19520
	ds_read_b64_tr_b16 v[144:145], v2 offset:21056
	ds_read_b64_tr_b16 v[138:139], v2 offset:22528
	ds_read_b64_tr_b16 v[140:141], v2 offset:24064
	ds_read_b64_tr_b16 v[134:135], v2 offset:22592
	ds_read_b64_tr_b16 v[136:137], v2 offset:24128
	v_max_f32_e32 v2, v83, v83
	v_max_f32_e32 v16, v82, v82
	v_max_f32_e32 v2, v16, v2
	v_max3_f32 v16, v84, v85, v67
	v_max3_f32 v2, v2, v66, v68
	v_max3_f32 v2, v2, v69, v86
	v_max3_f32 v16, v16, v88, v89
	v_max3_f32 v2, v2, v87, v70
	v_max3_f32 v16, v16, v72, v73
	v_max3_f32 v2, v2, v71, v90
	v_max3_f32 v16, v16, v92, v93
	v_max3_f32 v2, v2, v91, v74
	v_max3_f32 v16, v16, v76, v77
	v_max3_f32 v2, v2, v75, v94
	v_max3_f32 v16, v16, v96, v97
	v_max3_f32 v2, v2, v95, v78
	v_max3_f32 v16, v16, v80, v81
	v_max3_f32 v2, v2, v79, v16
	v_mov_b32_e32 v16, v2
	s_nop 1
	v_permlane32_swap_b32_e32 v2, v16
	v_max_f32_e32 v16, v16, v16
	v_max_f32_e32 v2, v2, v2
	v_max_f32_e32 v2, v2, v16
	s_cbranch_vccz .LBB0_669
	v_cmp_lt_f32_e32 vcc, s58, v2
	s_cmp_lg_u64 vcc, 0
	s_cselect_b64 s[0:1], -1, 0
	s_cbranch_execz .LBB0_670
	s_branch .LBB0_671

; __device__ __forceinline__ unsigned pk2(float lo, float hi) { f32x2_t v = {lo, hi}; bf16x2_t b = __builtin_convertvector(v, bf16x2_t); return __builtin_bit_cast(unsigned, b); }
; #define MFMA32(a, b, c) __builtin_amdgcn_mfma_f32_32x32x16_bf16((a), (b), (c), 0, 0, 0)
; template <int MODE> __device__ __forceinline__ void st_sm(int T, int tq, int qpos, int hi, const LAS float* biasl, f32x16& s0, f32x16& s1, f32x16& o0, f32x16& o1, f32x16& negm, float& lrun, bool& fresh) {
;     ...
;     float sum = 0.f;
; #pragma unroll
;     for (int i = 0; i < 16; ++i) { s0[i] = __builtin_amdgcn_exp2f(s0[i]); s1[i] = __builtin_amdgcn_exp2f(s1[i]); sum += s0[i] + s1[i]; }
;     lrun += sum;
; __device__ __forceinline__ void st_pv(const bf16x8 (&vf)[8], const f32x16& s0, const f32x16& s1, f32x16& o0, f32x16& o1) {
;     bf16x8 pf[4];
; #pragma unroll
;     for (int s = 0; s < 2; ++s) {
;         v4u a, b;
;         a.x = pk2(s0[8 * s], s0[8 * s + 1]); a.y = pk2(s0[8 * s + 2], s0[8 * s + 3]); a.z = pk2(s0[8 * s + 4], s0[8 * s + 5]); a.w = pk2(s0[8 * s + 6], s0[8 * s + 7]);
;         b.x = pk2(s1[8 * s], s1[8 * s + 1]); b.y = pk2(s1[8 * s + 2], s1[8 * s + 3]); b.z = pk2(s1[8 * s + 4], s1[8 * s + 5]); b.w = pk2(s1[8 * s + 6], s1[8 * s + 7]);
;         pf[s] = __builtin_bit_cast(bf16x8, a); pf[2 + s] = __builtin_bit_cast(bf16x8, b); }
; #pragma unroll
;     for (int ks = 0; ks < 4; ++ks) { o0 = MFMA32(vf[2 * ks], pf[ks], o0); o1 = MFMA32(vf[2 * ks + 1], pf[ks], o1); }
.LBB0_673:
	s_mov_b64 s[4:5], 0
	v_exp_f32_e32 v82, v82
	v_exp_f32_e32 v83, v83
	v_exp_f32_e32 v84, v84
	v_exp_f32_e32 v85, v85
	v_exp_f32_e32 v86, v86
	v_exp_f32_e32 v87, v87
	v_exp_f32_e32 v88, v88
	v_exp_f32_e32 v89, v89
	v_cvt_pk_bf16_f32 v188, v82, v83
	v_cvt_pk_bf16_f32 v189, v84, v85
	v_cvt_pk_bf16_f32 v190, v86, v87
	v_cvt_pk_bf16_f32 v191, v88, v89
	v_exp_f32_e32 v90, v90
	v_exp_f32_e32 v91, v91
	s_waitcnt lgkmcnt(14)
	v_mfma_f32_32x32x16_bf16 v[34:49], v[162:165], v[188:191], v[34:49]
	v_exp_f32_e32 v92, v92
	v_exp_f32_e32 v93, v93
	s_waitcnt lgkmcnt(12)
	v_mfma_f32_32x32x16_bf16 v[18:33], v[158:161], v[188:191], v[18:33]
	v_exp_f32_e32 v94, v94
	v_exp_f32_e32 v95, v95
	v_exp_f32_e32 v96, v96
	v_exp_f32_e32 v97, v97
	v_add_f32_e32 v2, v82, v83
	v_add_f32_e32 v16, v84, v85
	v_add_f32_e32 v17, v86, v87
	v_add_f32_e32 v184, v88, v89
	v_cvt_pk_bf16_f32 v192, v90, v91
	v_cvt_pk_bf16_f32 v193, v92, v93
	v_cvt_pk_bf16_f32 v194, v94, v95
	v_cvt_pk_bf16_f32 v195, v96, v97
	v_add_f32_e32 v2, v2, v16
	v_add_f32_e32 v17, v17, v184
	s_waitcnt lgkmcnt(10)
	v_mfma_f32_32x32x16_bf16 v[34:49], v[150:153], v[192:195], v[34:49]
	v_add_f32_e32 v2, v2, v17
	v_exp_f32_e32 v66, v66
	s_waitcnt lgkmcnt(8)
	v_mfma_f32_32x32x16_bf16 v[18:33], v[154:157], v[192:195], v[18:33]
	v_exp_f32_e32 v67, v67
	v_exp_f32_e32 v68, v68
	v_exp_f32_e32 v69, v69
	v_exp_f32_e32 v70, v70
	v_exp_f32_e32 v71, v71
	v_exp_f32_e32 v72, v72
	v_exp_f32_e32 v73, v73
	v_add_f32_e32 v185, v90, v91
	v_add_f32_e32 v186, v92, v93
	v_add_f32_e32 v196, v94, v95
	v_add_f32_e32 v197, v96, v97
	v_cvt_pk_bf16_f32 v188, v66, v67
	v_cvt_pk_bf16_f32 v189, v68, v69
	v_cvt_pk_bf16_f32 v190, v70, v71
	v_cvt_pk_bf16_f32 v191, v72, v73
	v_add_f32_e32 v185, v185, v186
	v_add_f32_e32 v196, v196, v197
	s_waitcnt lgkmcnt(6)
	v_mfma_f32_32x32x16_bf16 v[34:49], v[146:149], v[188:191], v[34:49]
	v_add_f32_e32 v185, v185, v196
	v_exp_f32_e32 v74, v74
	s_waitcnt lgkmcnt(4)
	v_mfma_f32_32x32x16_bf16 v[18:33], v[142:145], v[188:191], v[18:33]
	v_exp_f32_e32 v75, v75
	v_exp_f32_e32 v76, v76
	v_exp_f32_e32 v77, v77
	v_exp_f32_e32 v78, v78
	v_exp_f32_e32 v79, v79
	v_exp_f32_e32 v80, v80
	v_exp_f32_e32 v81, v81
	v_add_f32_e32 v2, v2, v185
	v_add_f32_e32 v185, v66, v67
	v_add_f32_e32 v186, v68, v69
	v_add_f32_e32 v196, v70, v71
	v_add_f32_e32 v197, v72, v73
	v_cvt_pk_bf16_f32 v192, v74, v75
	v_cvt_pk_bf16_f32 v193, v76, v77
	v_cvt_pk_bf16_f32 v194, v78, v79
	v_cvt_pk_bf16_f32 v195, v80, v81
	v_add_f32_e32 v185, v185, v186
	v_add_f32_e32 v196, v196, v197
	s_waitcnt lgkmcnt(2)
	v_mfma_f32_32x32x16_bf16 v[34:49], v[138:141], v[192:195], v[34:49]
	v_add_f32_e32 v185, v185, v196
	v_add_f32_e32 v2, v2, v185
	s_waitcnt lgkmcnt(0)
	v_mfma_f32_32x32x16_bf16 v[18:33], v[134:137], v[192:195], v[18:33]
	v_add_f32_e32 v185, v74, v75
	v_add_f32_e32 v186, v76, v77
	v_add_f32_e32 v196, v78, v79
	v_add_f32_e32 v197, v80, v81
	v_add_f32_e32 v185, v185, v186
	v_add_f32_e32 v196, v196, v197
	v_add_f32_e32 v185, v185, v196
	v_add_f32_e32 v2, v2, v185
	v_add_f32_e32 v167, v167, v2

; #define LAS __attribute__((address_space(3)))
; #define MFMA32(a, b, c) __builtin_amdgcn_mfma_f32_32x32x16_bf16((a), (b), (c), 0, 0, 0)
;     constexpr int NS = MODE == 0 ? 6 : 4, KSTR = MODE == 0 ? 208 : 144;
;     const LAS unsigned char* kb = buf + r * KSTR + hi * 16;
; #pragma unroll
;     for (int s = 0; s < NS; ++s) { const bf16x8 a0 = *(const LAS bf16x8*)(kb + 32 * s), a1 = *(const LAS bf16x8*)(kb + 32 * KSTR + 32 * s);
;         if (s == 0) { s0 = MFMA32(a0, qf[0], negm); s1 = MFMA32(a1, qf[0], negm); }
;         else { s0 = MFMA32(a0, qf[s], s0); s1 = MFMA32(a1, qf[s], s1); } }
; __device__ __forceinline__ void st_vread(const LAS unsigned char* buf, int vlane, bf16x8 (&vf)[8]) {
;     const LAS unsigned char* vb = buf + KB_MAX + vlane;
; #pragma unroll
;     for (int ks = 0; ks < 4; ++ks) {
; #pragma unroll
;         for (int db = 0; db < 2; ++db) {
;             const v4i16_t lo = __builtin_amdgcn_ds_read_tr16_b64_v4i16((LAS v4i16_t*)(vb + (16 * ks) * VSTR + db * 64));
;             const v4i16_t hh = __builtin_amdgcn_ds_read_tr16_b64_v4i16((LAS v4i16_t*)(vb + (16 * ks + 8) * VSTR + db * 64));
;             vf[2 * ks + db] = (bf16x8){lo[0], lo[1], lo[2], lo[3], hh[0], hh[1], hh[2], hh[3]}; } }
.LBB0_676:
	s_waitcnt lgkmcnt(0)
	s_barrier
	s_andn2_b64 vcc, exec, s[0:1]
	s_mov_b64 s[0:1], -1
	s_cbranch_vccnz .LBB0_680
	s_add_i32 s12, s11, 2
	s_min_i32 s6, s12, s3
	v_mad_i64_i32 v[16:17], s[0:1], v170, s6, v[180:181]
	global_load_dwordx4 v[122:125], v[16:17], off
	v_mad_i64_i32 v[16:17], s[0:1], v172, s6, v[178:179]
	global_load_dwordx4 v[126:129], v[16:17], off
	v_mad_i64_i32 v[16:17], s[0:1], v174, s6, v[176:177]
	global_load_dwordx4 v[130:133], v[16:17], off
	s_cmp_lt_i32 s13, s10
	s_cselect_b64 s[0:1], -1, 0
	s_and_b64 s[0:1], s[8:9], s[0:1]
	s_andn2_b64 vcc, exec, s[0:1]
	s_cbranch_vccnz .LBB0_686
	v_add_u32_e32 v2, v171, v168
	s_xor_b64 s[0:1], s[4:5], -1
	s_and_b64 vcc, exec, s[0:1]
	ds_read_b128 v[66:69], v2 offset:25600
	ds_read_b128 v[134:137], v2 offset:32256
	ds_read_b128 v[138:141], v2 offset:25632
	ds_read_b128 v[142:145], v2 offset:32288
	ds_read_b128 v[146:149], v2 offset:25664
	ds_read_b128 v[150:153], v2 offset:32320
	ds_read_b128 v[154:157], v2 offset:25696
	ds_read_b128 v[158:161], v2 offset:32352
	ds_read_b128 v[162:165], v2 offset:25728
	s_waitcnt lgkmcnt(8)
	v_mfma_f32_32x32x16_bf16 v[82:97], v[66:69], v[110:113], v[50:65]
	s_waitcnt lgkmcnt(7)
	v_mfma_f32_32x32x16_bf16 v[66:81], v[134:137], v[110:113], v[50:65]
	ds_read_b128 v[134:137], v2 offset:32384
	s_waitcnt lgkmcnt(7)
	v_mfma_f32_32x32x16_bf16 v[82:97], v[138:141], v[106:109], v[82:97]
	ds_read_b128 v[138:141], v2 offset:25760
	s_waitcnt lgkmcnt(7)
	v_mfma_f32_32x32x16_bf16 v[66:81], v[142:145], v[106:109], v[66:81]
	ds_read_b128 v[142:145], v2 offset:32416
	v_add_u32_e32 v2, 0x100, v183
	s_waitcnt lgkmcnt(7)
	v_mfma_f32_32x32x16_bf16 v[82:97], v[146:149], v[102:105], v[82:97]
	s_waitcnt lgkmcnt(6)
	v_mfma_f32_32x32x16_bf16 v[66:81], v[150:153], v[102:105], v[66:81]
	s_waitcnt lgkmcnt(5)
	v_mfma_f32_32x32x16_bf16 v[82:97], v[154:157], v[98:101], v[82:97]
	s_waitcnt lgkmcnt(4)
	v_mfma_f32_32x32x16_bf16 v[66:81], v[158:161], v[98:101], v[66:81]
	s_waitcnt lgkmcnt(3)
	v_mfma_f32_32x32x16_bf16 v[82:97], v[162:165], v[118:121], v[82:97]
	s_waitcnt lgkmcnt(2)
	v_mfma_f32_32x32x16_bf16 v[66:81], v[134:137], v[118:121], v[66:81]
	s_waitcnt lgkmcnt(1)
	v_mfma_f32_32x32x16_bf16 v[82:97], v[138:141], v[114:117], v[82:97]
	s_waitcnt lgkmcnt(0)
	v_mfma_f32_32x32x16_bf16 v[66:81], v[142:145], v[114:117], v[66:81]
	ds_read_b64_tr_b16 v[162:163], v2 offset:38912
	ds_read_b64_tr_b16 v[164:165], v2 offset:40448
	ds_read_b64_tr_b16 v[158:159], v2 offset:38976
	ds_read_b64_tr_b16 v[160:161], v2 offset:40512
	ds_read_b64_tr_b16 v[150:151], v2 offset:41984
	ds_read_b64_tr_b16 v[152:153], v2 offset:43520
	ds_read_b64_tr_b16 v[154:155], v2 offset:42048
	ds_read_b64_tr_b16 v[156:157], v2 offset:43584
	ds_read_b64_tr_b16 v[146:147], v2 offset:45056
	ds_read_b64_tr_b16 v[148:149], v2 offset:46592
	ds_read_b64_tr_b16 v[142:143], v2 offset:45120
	ds_read_b64_tr_b16 v[144:145], v2 offset:46656
	ds_read_b64_tr_b16 v[138:139], v2 offset:48128
	ds_read_b64_tr_b16 v[140:141], v2 offset:49664
	ds_read_b64_tr_b16 v[134:135], v2 offset:48192
	ds_read_b64_tr_b16 v[136:137], v2 offset:49728
	v_max_f32_e32 v2, v83, v83
	v_max_f32_e32 v16, v82, v82
	v_max_f32_e32 v2, v16, v2
	v_max3_f32 v16, v84, v85, v67
	v_max3_f32 v2, v2, v66, v68
	v_max3_f32 v2, v2, v69, v86
	v_max3_f32 v16, v16, v88, v89
	v_max3_f32 v2, v2, v87, v70
	v_max3_f32 v16, v16, v72, v73
	v_max3_f32 v2, v2, v71, v90
	v_max3_f32 v16, v16, v92, v93
	v_max3_f32 v2, v2, v91, v74
	v_max3_f32 v16, v16, v76, v77
	v_max3_f32 v2, v2, v75, v94
	v_max3_f32 v16, v16, v96, v97
	v_max3_f32 v2, v2, v95, v78
	v_max3_f32 v16, v16, v80, v81
	v_max3_f32 v2, v2, v79, v16
	v_mov_b32_e32 v16, v2
	s_nop 1
	v_permlane32_swap_b32_e32 v2, v16
	v_max_f32_e32 v16, v16, v16
	v_max_f32_e32 v2, v2, v2
	v_max_f32_e32 v2, v2, v16
	s_cbranch_vccz .LBB0_681
	v_cmp_lt_f32_e32 vcc, s58, v2
	s_cmp_lg_u64 vcc, 0
	s_cselect_b64 s[0:1], -1, 0
	s_cbranch_execz .LBB0_682
	s_branch .LBB0_683

; #define PG8_STAGE(bufoff, gbase, voff) do { _Pragma("unroll") for (int _i = 0; _i < 2; ++_i) \
;         __builtin_amdgcn_global_load_lds((const unsigned*)((const char*)(gbase) + (voff)[_i]), (PG8_LAS unsigned*)(lds + (bufoff) + ldsw + _i * 8192), 16, 0, 0); } while (0)
; #define PG8_WAIT_V(n) asm volatile("s_waitcnt vmcnt(" #n ")" ::: "memory")
; #define PG8_BAR __builtin_amdgcn_s_barrier()
; template <class Epi, class Sched, bool ALIGN_EPI = false, bool SP2 = false>
; __device__ __forceinline__ void gemm_phase(PG8_LAS unsigned char* lds, const Gemm g, const Sched& S, const Epi& E) {
;     ...
;     for (int i = 0; i < 2; ++i) { int R, C; stage_rc(tid * 16 + i * 8192, R, C); const int Rb = Epi::PERM ? ((R & ~31) + perm32(R & 31)) : R;
;         voffA[i] = (unsigned)(R * LD + C) * 2u; voffB[i] = (unsigned)(Rb * LD + C) * 2u; }
;     const size_t kstep = (size_t)(BK * 2);
;     const size_t hstep = (size_t)HALF * LD * 2;
;     const size_t tstep = 2 * hstep;
;     const unsigned ldsw = (unsigned)wid * 1024u;
;     const int aoff = lds_byte(wr * 64 + fr, fq * 8), boff = lds_byte(wc * 32 + fr, fq * 8);
;     ...
;         PG8_WAIT_V(2); PG8_BAR;
;         PG8_STAGE(PG8_SB(1, 0), cB + kstep, voffB); PG8_STAGE(PG8_SA(1, 0), cA + kstep, voffA); PG8_STAGE(PG8_SB(1, 1), cB + hstep + kstep, voffB);
;         PG8_WAIT_V(6); PG8_BAR;
.LBB0_817:
	s_lshl_b32 s8, s8, 5
	s_and_b32 s12, s8, 0x60
	s_mov_b64 s[8:9], 0x80
	s_add_i32 m0, s3, 0x18000
	v_lshl_add_u64 v[8:9], v[8:9], 0, s[8:9]
	s_lshl_b32 s11, s5, 13
	s_lshl_b32 s16, s12, 7
	s_waitcnt vmcnt(2)
	s_barrier
	global_load_lds_dwordx4 v[8:9], off
	v_lshl_add_u64 v[4:5], v[4:5], 0, s[8:9]
	s_add_i32 m0, s3, 0x1a000
	s_add_i32 s33, s3, 0x8000
	s_add_i32 s34, s3, 0xa000
	global_load_lds_dwordx4 v[4:5], off
	v_lshl_add_u64 v[2:3], v[2:3], 0, s[8:9]
	s_mov_b32 m0, s33
	s_add_u32 s14, s24, 0x40080
	global_load_lds_dwordx4 v[2:3], off
	v_lshl_add_u64 v[2:3], v[6:7], 0, s[8:9]
	s_mov_b32 m0, s34
	s_addc_u32 s15, s25, 0
	global_load_lds_dwordx4 v[2:3], off
	s_add_i32 m0, s3, 0x1c000
	v_lshl_add_u64 v[2:3], s[14:15], 0, v[134:135]
	global_load_lds_dwordx4 v[2:3], off
	v_lshl_add_u64 v[2:3], s[14:15], 0, v[136:137]
	s_add_i32 m0, s3, 0x1e000
	v_lshlrev_b32_e32 v5, 2, v204
	global_load_lds_dwordx4 v[2:3], off
	v_lshrrev_b32_e32 v2, 1, v198
	v_and_b32_e32 v2, 24, v2
	v_lshlrev_b32_e32 v3, 1, v2
	v_lshl_or_b32 v4, v204, 6, v3
	v_and_b32_e32 v5, 32, v5
	v_or_b32_e32 v154, s12, v2
	v_lshlrev_b32_e32 v2, 8, v198
	v_bitop3_b32 v4, v4, s11, v5 bitop3:0xde
	v_and_b32_e32 v2, 0x38000, v2
	v_lshlrev_b32_e32 v5, 11, v230
	v_or3_b32 v2, v10, v2, v5
	s_cmpk_lt_u32 s10, 0x100
	v_add_u32_e32 v138, v2, v205
	v_lshlrev_b32_e32 v2, 4, v11
	s_mov_b32 s12, 0x10000
	s_sext_i32_i8 s21, s4
	v_lshl_or_b32 v153, s5, 6, v204
	v_or_b32_e32 v3, v3, v1
	s_mov_b32 s4, 0x18000
	s_mov_b32 s5, 0x1c000
	s_waitcnt vmcnt(6)
	s_cselect_b64 s[10:11], -1, 0
	v_and_b32_e32 v2, 0x78000, v2
	s_add_i32 s36, s12, 0x100
	s_mov_b32 s12, 0x14000
	v_bitop3_b32 v3, s16, v3, v152 bitop3:0xf6
	v_or3_b32 v2, v10, v2, v5
	s_add_i32 s37, s12, 0x100
	s_add_i32 s38, s4, 0x100
	s_add_i32 s39, s5, 0x100
	v_mov_b32_e32 v139, v135
	v_add_u32_e32 v140, v2, v205
	v_mov_b32_e32 v141, v135
	s_mov_b32 s35, 0
	v_mov_b64_e32 v[142:143], 0x200
	v_mov_b64_e32 v[144:145], 0x1ff
	v_add_u32_e32 v155, s36, v3
	v_add_u32_e32 v156, s37, v3
	v_add_u32_e32 v157, 0x100, v4
	s_mov_b32 s12, 0x3fb504f3
	v_add_u32_e32 v158, s38, v3
	v_add_u32_e32 v159, s39, v3
	s_barrier
	s_branch .LBB0_820

;     __device__ __forceinline__ bool next(int i, Unit& u) const { const int L = i * G + c; if (L >= nunits) return false; const int t = L / S, ks = L % S; u.pm = pm0 + t / nN; u.pn = t % nN; u.ko = ks * Ksub; return true; }
; #define PG8_STAGE(bufoff, gbase, voff) do { _Pragma("unroll") for (int _i = 0; _i < 2; ++_i) \
;         __builtin_amdgcn_global_load_lds((const unsigned*)((const char*)(gbase) + (voff)[_i]), (PG8_LAS unsigned*)(lds + (bufoff) + ldsw + _i * 8192), 16, 0, 0); } while (0)
; #define PG8_LDA(dst, b, h) do { _Pragma("unroll") for (int m = 0; m < 4; ++m) _Pragma("unroll") for (int k = 0; k < 2; ++k) dst[m][k] = *(const PG8_LAS bf16x8*)(lds + PG8_SA(b, h) + aoff + m * 2048 + k * 1024); } while (0)
; #define PG8_LDB(dst, b, h) do { _Pragma("unroll") for (int n = 0; n < 2; ++n) _Pragma("unroll") for (int k = 0; k < 2; ++k) dst[n][k] = *(const PG8_LAS bf16x8*)(lds + PG8_SB(b, h) + boff + n * 2048 + k * 1024); } while (0)
; template <class Epi, class Sched, bool ALIGN_EPI = false, bool SP2 = false>
; __device__ __forceinline__ void gemm_phase(PG8_LAS unsigned char* lds, const Gemm g, const Sched& S, const Epi& E) {
;     ...
;         const bool has_next = S.next(ui + 1, nxt);
;         const char* nA = has_next ? (const char*)g.A + (size_t)nxt.pm * tstep + (size_t)nxt.ko * 2 : cA; const char* nB = has_next ? (const char*)g.Bt + (size_t)nxt.pn * tstep + (size_t)nxt.ko * 2 : cB;
;         for (int t = 0; t < nt; t += 2) {
;             const bool last = (t == nt - 2);
;             const char* a1 = cA + (size_t)(t + 1) * kstep;
;             const char* a2 = last ? nA : cA + (size_t)(t + 2) * kstep; const char* b2 = last ? nB : cB + (size_t)(t + 2) * kstep;
;             const char* a3 = a2 + kstep; const char* b3 = b2 + kstep;
;             if (last && has_next) S.a_ready(nxt);
;             if constexpr (SP2) {
;             PG8_LDB(B0, 0, 0); PG8_LDB(B1, 0, 1); PG8_SCHED; PG8_LDA(At, 0, 0); PG8_STAGE(PG8_SA(1, 1), a1 + hstep, voffA);
;             PG8_WAIT_V(8); PG8_WAIT_L(0); PG8_BAR; PG8_MMA(0, 0, At, B0); PG8_MMA(0, 1, At, B1); PG8_BAR; PG8_SCHED;
;             PG8_LDA(At, 0, 1); PG8_STAGE(PG8_SB(0, 0), b2, voffB); PG8_STAGE(PG8_SB(0, 1), b2 + hstep, voffB); PG8_STAGE(PG8_SA(0, 0), a2, voffA);
;             PG8_WAIT_V(8); PG8_WAIT_L(0); PG8_BAR; PG8_MMA(1, 0, At, B0); PG8_MMA(1, 1, At, B1); PG8_BAR; PG8_SCHED;
.LBB0_827:
	ds_read_b128 v[146:149], v155
	ds_read_b128 v[160:163], v155 offset:1024
	ds_read_b128 v[164:167], v155 offset:2048
	ds_read_b128 v[168:171], v155 offset:3072
	ds_read_b128 v[172:175], v156
	ds_read_b128 v[176:179], v156 offset:1024
	ds_read_b128 v[180:183], v156 offset:2048
	ds_read_b128 v[184:187], v156 offset:3072
	s_add_u32 s24, s22, 0xfffc0080
	s_addc_u32 s25, s23, -1
	s_cmp_eq_u32 s44, 12
	s_cselect_b32 s29, s17, s25
	s_cselect_b32 s28, s40, s24
	s_cselect_b32 s25, s15, s43
	s_cselect_b32 s24, s41, s42
	v_lshl_add_u64 v[150:151], s[22:23], 0, v[138:139]
	s_add_i32 m0, s3, 0xc000
	ds_read_b128 v[188:191], v157
	ds_read_b128 v[192:195], v157 offset:1024
	ds_read_b128 v[208:211], v157 offset:2048
	ds_read_b128 v[212:215], v157 offset:3072
	ds_read_b128 v[216:219], v157 offset:4096
	ds_read_b128 v[220:223], v157 offset:5120
	ds_read_b128 v[224:227], v157 offset:6144
	ds_read_b128 v[236:239], v157 offset:7168
	global_load_lds_dwordx4 v[150:151], off
	v_lshl_add_u64 v[150:151], s[22:23], 0, v[140:141]
	s_add_i32 m0, s3, 0xe000
	s_nop 0
	global_load_lds_dwordx4 v[150:151], off
	s_waitcnt vmcnt(8)
	s_waitcnt lgkmcnt(0)
	s_barrier
	s_setprio 1
	s_waitcnt lgkmcnt(0)
	v_mfma_f32_16x16x32_bf16 v[126:129], v[146:149], v[188:191], v[126:129]
	v_mfma_f32_16x16x32_bf16 v[122:125], v[164:167], v[188:191], v[122:125]
	v_mfma_f32_16x16x32_bf16 v[110:113], v[146:149], v[208:211], v[110:113]
	v_mfma_f32_16x16x32_bf16 v[106:109], v[164:167], v[208:211], v[106:109]
	v_mfma_f32_16x16x32_bf16 v[94:97], v[146:149], v[216:219], v[94:97]
	v_mfma_f32_16x16x32_bf16 v[90:93], v[164:167], v[216:219], v[90:93]
	v_mfma_f32_16x16x32_bf16 v[78:81], v[146:149], v[224:227], v[78:81]
	v_mfma_f32_16x16x32_bf16 v[74:77], v[164:167], v[224:227], v[74:77]
	v_mfma_f32_16x16x32_bf16 v[126:129], v[160:163], v[192:195], v[126:129]
	v_mfma_f32_16x16x32_bf16 v[122:125], v[168:171], v[192:195], v[122:125]
	v_mfma_f32_16x16x32_bf16 v[110:113], v[160:163], v[212:215], v[110:113]
	v_mfma_f32_16x16x32_bf16 v[106:109], v[168:171], v[212:215], v[106:109]
	v_mfma_f32_16x16x32_bf16 v[94:97], v[160:163], v[220:223], v[94:97]
	v_mfma_f32_16x16x32_bf16 v[90:93], v[168:171], v[220:223], v[90:93]
	v_mfma_f32_16x16x32_bf16 v[78:81], v[160:163], v[236:239], v[78:81]
	v_mfma_f32_16x16x32_bf16 v[74:77], v[168:171], v[236:239], v[74:77]
	s_setprio 0
	s_setprio 1
	v_mfma_f32_16x16x32_bf16 v[118:121], v[172:175], v[188:191], v[118:121]
	v_mfma_f32_16x16x32_bf16 v[114:117], v[180:183], v[188:191], v[114:117]
	v_mfma_f32_16x16x32_bf16 v[102:105], v[172:175], v[208:211], v[102:105]
	v_mfma_f32_16x16x32_bf16 v[98:101], v[180:183], v[208:211], v[98:101]
	v_mfma_f32_16x16x32_bf16 v[86:89], v[172:175], v[216:219], v[86:89]
	v_mfma_f32_16x16x32_bf16 v[82:85], v[180:183], v[216:219], v[82:85]
	v_mfma_f32_16x16x32_bf16 v[70:73], v[172:175], v[224:227], v[70:73]
	v_mfma_f32_16x16x32_bf16 v[66:69], v[180:183], v[224:227], v[66:69]
	v_mfma_f32_16x16x32_bf16 v[118:121], v[176:179], v[192:195], v[118:121]
	v_mfma_f32_16x16x32_bf16 v[114:117], v[184:187], v[192:195], v[114:117]
	v_mfma_f32_16x16x32_bf16 v[102:105], v[176:179], v[212:215], v[102:105]
	v_mfma_f32_16x16x32_bf16 v[98:101], v[184:187], v[212:215], v[98:101]
	v_mfma_f32_16x16x32_bf16 v[86:89], v[176:179], v[220:223], v[86:89]
	v_mfma_f32_16x16x32_bf16 v[82:85], v[184:187], v[220:223], v[82:85]
	v_mfma_f32_16x16x32_bf16 v[70:73], v[176:179], v[236:239], v[70:73]
	v_mfma_f32_16x16x32_bf16 v[66:69], v[184:187], v[236:239], v[66:69]
	s_setprio 0
	s_barrier
	s_add_i32 s45, s36, s2
	v_lshl_add_u64 v[150:151], s[24:25], 0, v[134:135]
	s_mov_b32 m0, s45
	ds_read_b128 v[188:191], v157 offset:16384
	ds_read_b128 v[192:195], v157 offset:17408
	ds_read_b128 v[208:211], v157 offset:18432
	ds_read_b128 v[212:215], v157 offset:19456
	ds_read_b128 v[216:219], v157 offset:20480
	ds_read_b128 v[220:223], v157 offset:21504
	ds_read_b128 v[224:227], v157 offset:22528
	ds_read_b128 v[236:239], v157 offset:23552
	global_load_lds_dwordx4 v[150:151], off
	s_add_i32 m0, s45, 0x2000
	s_add_u32 s46, s24, 0x40000
	v_lshl_add_u64 v[196:197], s[24:25], 0, v[136:137]
	s_addc_u32 s47, s25, 0
	s_add_i32 s45, s37, s2
	global_load_lds_dwordx4 v[196:197], off
	v_lshl_add_u64 v[228:229], s[46:47], 0, v[134:135]
	s_mov_b32 m0, s45
	v_lshl_add_u64 v[240:241], s[28:29], 0, v[132:133]
	global_load_lds_dwordx4 v[228:229], off
	v_lshl_add_u64 v[228:229], s[46:47], 0, v[136:137]
	s_add_i32 m0, s45, 0x2000
	s_nop 0
	global_load_lds_dwordx4 v[228:229], off
	v_lshl_add_u64 v[228:229], s[28:29], 0, v[130:131]
	s_mov_b32 m0, s3
	s_nop 0
	global_load_lds_dwordx4 v[228:229], off
	s_mov_b32 m0, s13
	s_nop 0
	global_load_lds_dwordx4 v[240:241], off
	s_waitcnt vmcnt(8)
	s_waitcnt lgkmcnt(0)
	s_barrier
; #define PG8_STAGE(bufoff, gbase, voff) do { _Pragma("unroll") for (int _i = 0; _i < 2; ++_i) \
;         __builtin_amdgcn_global_load_lds((const unsigned*)((const char*)(gbase) + (voff)[_i]), (PG8_LAS unsigned*)(lds + (bufoff) + ldsw + _i * 8192), 16, 0, 0); } while (0)
; #define PG8_LDA(dst, b, h) do { _Pragma("unroll") for (int m = 0; m < 4; ++m) _Pragma("unroll") for (int k = 0; k < 2; ++k) dst[m][k] = *(const PG8_LAS bf16x8*)(lds + PG8_SA(b, h) + aoff + m * 2048 + k * 1024); } while (0)
; #define PG8_LDB(dst, b, h) do { _Pragma("unroll") for (int n = 0; n < 2; ++n) _Pragma("unroll") for (int k = 0; k < 2; ++k) dst[n][k] = *(const PG8_LAS bf16x8*)(lds + PG8_SB(b, h) + boff + n * 2048 + k * 1024); } while (0)
; #define PG8_MMA(ai, bj, At, Bt) do { __builtin_amdgcn_s_setprio(1); _Pragma("unroll") for (int m = 0; m < 4; ++m) _Pragma("unroll") for (int n = 0; n < 2; ++n) _Pragma("unroll") for (int k = 0; k < 2; ++k) \
;         acc[ai][bj][m][n] = __builtin_amdgcn_mfma_f32_16x16x32_bf16(Bt[n][k], At[m][k], acc[ai][bj][m][n], 0, 0, 0); __builtin_amdgcn_s_setprio(0); } while (0)
; #define PG8_WAIT_V(n) asm volatile("s_waitcnt vmcnt(" #n ")" ::: "memory")
; #define PG8_WAIT_L(n) asm volatile("s_waitcnt lgkmcnt(" #n ")" ::: "memory")
; #define PG8_BAR __builtin_amdgcn_s_barrier()
; #define PG8_SCHED __builtin_amdgcn_sched_barrier(0)
; template <class Epi, class Sched, bool ALIGN_EPI = false, bool SP2 = false>
; __device__ __forceinline__ void gemm_phase(PG8_LAS unsigned char* lds, const Gemm g, const Sched& S, const Epi& E) {
;     ...
;             PG8_WAIT_V(8); PG8_WAIT_L(0); PG8_BAR; PG8_MMA(1, 0, At, B0); PG8_MMA(1, 1, At, B1); PG8_BAR; PG8_SCHED;
;             PG8_LDB(B0, 1, 0); PG8_LDB(B1, 1, 1); PG8_SCHED; PG8_LDA(At, 1, 0); PG8_STAGE(PG8_SA(0, 1), a2 + hstep, voffA);
;             PG8_WAIT_V(8); PG8_WAIT_L(0); PG8_BAR; PG8_MMA(0, 0, At, B0); PG8_MMA(0, 1, At, B1); PG8_BAR; PG8_SCHED;
	s_setprio 1
	s_waitcnt lgkmcnt(0)
	v_mfma_f32_16x16x32_bf16 v[62:65], v[146:149], v[188:191], v[62:65]
	v_mfma_f32_16x16x32_bf16 v[58:61], v[164:167], v[188:191], v[58:61]
	v_mfma_f32_16x16x32_bf16 v[46:49], v[146:149], v[208:211], v[46:49]
	v_mfma_f32_16x16x32_bf16 v[42:45], v[164:167], v[208:211], v[42:45]
	v_mfma_f32_16x16x32_bf16 v[30:33], v[146:149], v[216:219], v[30:33]
	v_mfma_f32_16x16x32_bf16 v[26:29], v[164:167], v[216:219], v[26:29]
	v_mfma_f32_16x16x32_bf16 v[14:17], v[146:149], v[224:227], v[14:17]
	v_mfma_f32_16x16x32_bf16 v[10:13], v[164:167], v[224:227], v[10:13]
	v_mfma_f32_16x16x32_bf16 v[62:65], v[160:163], v[192:195], v[62:65]
	v_mfma_f32_16x16x32_bf16 v[58:61], v[168:171], v[192:195], v[58:61]
	v_mfma_f32_16x16x32_bf16 v[46:49], v[160:163], v[212:215], v[46:49]
	v_mfma_f32_16x16x32_bf16 v[42:45], v[168:171], v[212:215], v[42:45]
	v_mfma_f32_16x16x32_bf16 v[30:33], v[160:163], v[220:223], v[30:33]
	v_mfma_f32_16x16x32_bf16 v[26:29], v[168:171], v[220:223], v[26:29]
	v_mfma_f32_16x16x32_bf16 v[14:17], v[160:163], v[236:239], v[14:17]
	v_mfma_f32_16x16x32_bf16 v[10:13], v[168:171], v[236:239], v[10:13]
	s_setprio 0
	s_setprio 1
	v_mfma_f32_16x16x32_bf16 v[54:57], v[172:175], v[188:191], v[54:57]
	v_mfma_f32_16x16x32_bf16 v[50:53], v[180:183], v[188:191], v[50:53]
	v_mfma_f32_16x16x32_bf16 v[38:41], v[172:175], v[208:211], v[38:41]
	v_mfma_f32_16x16x32_bf16 v[34:37], v[180:183], v[208:211], v[34:37]
	v_mfma_f32_16x16x32_bf16 v[22:25], v[172:175], v[216:219], v[22:25]
	v_mfma_f32_16x16x32_bf16 v[18:21], v[180:183], v[216:219], v[18:21]
	v_mfma_f32_16x16x32_bf16 v[6:9], v[172:175], v[224:227], v[6:9]
	v_mfma_f32_16x16x32_bf16 v[2:5], v[180:183], v[224:227], v[2:5]
	v_mfma_f32_16x16x32_bf16 v[54:57], v[176:179], v[192:195], v[54:57]
	v_mfma_f32_16x16x32_bf16 v[50:53], v[184:187], v[192:195], v[50:53]
	v_mfma_f32_16x16x32_bf16 v[38:41], v[176:179], v[212:215], v[38:41]
	v_mfma_f32_16x16x32_bf16 v[34:37], v[184:187], v[212:215], v[34:37]
	v_mfma_f32_16x16x32_bf16 v[22:25], v[176:179], v[220:223], v[22:25]
	v_mfma_f32_16x16x32_bf16 v[18:21], v[184:187], v[220:223], v[18:21]
	v_mfma_f32_16x16x32_bf16 v[6:9], v[176:179], v[236:239], v[6:9]
	v_mfma_f32_16x16x32_bf16 v[2:5], v[184:187], v[236:239], v[2:5]
	s_setprio 0
	s_barrier
	ds_read_b128 v[146:149], v158
	ds_read_b128 v[160:163], v158 offset:1024
	ds_read_b128 v[164:167], v158 offset:2048
	ds_read_b128 v[168:171], v158 offset:3072
	ds_read_b128 v[172:175], v159
	ds_read_b128 v[176:179], v159 offset:1024
	ds_read_b128 v[180:183], v159 offset:2048
	ds_read_b128 v[184:187], v159 offset:3072
	s_add_u32 s28, s28, 0x40000
	s_addc_u32 s29, s29, 0
	s_mov_b32 m0, s30
	v_lshl_add_u64 v[242:243], s[28:29], 0, v[130:131]
	ds_read_b128 v[188:191], v157 offset:32768
	ds_read_b128 v[192:195], v157 offset:33792
	ds_read_b128 v[208:211], v157 offset:34816
	ds_read_b128 v[212:215], v157 offset:35840
	ds_read_b128 v[216:219], v157 offset:36864
	ds_read_b128 v[220:223], v157 offset:37888
	ds_read_b128 v[224:227], v157 offset:38912
	ds_read_b128 v[236:239], v157 offset:39936
	global_load_lds_dwordx4 v[242:243], off
	v_lshl_add_u64 v[242:243], s[28:29], 0, v[132:133]
	s_mov_b32 m0, s31
	s_nop 0
	global_load_lds_dwordx4 v[242:243], off
	s_waitcnt vmcnt(8)
	s_waitcnt lgkmcnt(0)
	s_barrier
	s_setprio 1
	s_waitcnt lgkmcnt(0)
	v_mfma_f32_16x16x32_bf16 v[126:129], v[146:149], v[188:191], v[126:129]
	v_mfma_f32_16x16x32_bf16 v[122:125], v[164:167], v[188:191], v[122:125]
	v_mfma_f32_16x16x32_bf16 v[110:113], v[146:149], v[208:211], v[110:113]
	v_mfma_f32_16x16x32_bf16 v[106:109], v[164:167], v[208:211], v[106:109]
	v_mfma_f32_16x16x32_bf16 v[94:97], v[146:149], v[216:219], v[94:97]
	v_mfma_f32_16x16x32_bf16 v[90:93], v[164:167], v[216:219], v[90:93]
	v_mfma_f32_16x16x32_bf16 v[78:81], v[146:149], v[224:227], v[78:81]
	v_mfma_f32_16x16x32_bf16 v[74:77], v[164:167], v[224:227], v[74:77]
	v_mfma_f32_16x16x32_bf16 v[126:129], v[160:163], v[192:195], v[126:129]
	v_mfma_f32_16x16x32_bf16 v[122:125], v[168:171], v[192:195], v[122:125]
	v_mfma_f32_16x16x32_bf16 v[110:113], v[160:163], v[212:215], v[110:113]
	v_mfma_f32_16x16x32_bf16 v[106:109], v[168:171], v[212:215], v[106:109]
	v_mfma_f32_16x16x32_bf16 v[94:97], v[160:163], v[220:223], v[94:97]
	v_mfma_f32_16x16x32_bf16 v[90:93], v[168:171], v[220:223], v[90:93]
	v_mfma_f32_16x16x32_bf16 v[78:81], v[160:163], v[236:239], v[78:81]
	v_mfma_f32_16x16x32_bf16 v[74:77], v[168:171], v[236:239], v[74:77]
	s_setprio 0
	s_setprio 1
	v_mfma_f32_16x16x32_bf16 v[118:121], v[172:175], v[188:191], v[118:121]
	v_mfma_f32_16x16x32_bf16 v[114:117], v[180:183], v[188:191], v[114:117]
	v_mfma_f32_16x16x32_bf16 v[102:105], v[172:175], v[208:211], v[102:105]
	v_mfma_f32_16x16x32_bf16 v[98:101], v[180:183], v[208:211], v[98:101]
	v_mfma_f32_16x16x32_bf16 v[86:89], v[172:175], v[216:219], v[86:89]
	v_mfma_f32_16x16x32_bf16 v[82:85], v[180:183], v[216:219], v[82:85]
	v_mfma_f32_16x16x32_bf16 v[70:73], v[172:175], v[224:227], v[70:73]
	v_mfma_f32_16x16x32_bf16 v[66:69], v[180:183], v[224:227], v[66:69]
	v_mfma_f32_16x16x32_bf16 v[118:121], v[176:179], v[192:195], v[118:121]
	v_mfma_f32_16x16x32_bf16 v[114:117], v[184:187], v[192:195], v[114:117]
	v_mfma_f32_16x16x32_bf16 v[102:105], v[176:179], v[212:215], v[102:105]
	v_mfma_f32_16x16x32_bf16 v[98:101], v[184:187], v[212:215], v[98:101]
	v_mfma_f32_16x16x32_bf16 v[86:89], v[176:179], v[220:223], v[86:89]
	v_mfma_f32_16x16x32_bf16 v[82:85], v[184:187], v[220:223], v[82:85]
	v_mfma_f32_16x16x32_bf16 v[70:73], v[176:179], v[236:239], v[70:73]
	v_mfma_f32_16x16x32_bf16 v[66:69], v[184:187], v[236:239], v[66:69]
	s_setprio 0
	s_barrier
; #define PG8_STAGE(bufoff, gbase, voff) do { _Pragma("unroll") for (int _i = 0; _i < 2; ++_i) \
;         __builtin_amdgcn_global_load_lds((const unsigned*)((const char*)(gbase) + (voff)[_i]), (PG8_LAS unsigned*)(lds + (bufoff) + ldsw + _i * 8192), 16, 0, 0); } while (0)
; #define PG8_LDA(dst, b, h) do { _Pragma("unroll") for (int m = 0; m < 4; ++m) _Pragma("unroll") for (int k = 0; k < 2; ++k) dst[m][k] = *(const PG8_LAS bf16x8*)(lds + PG8_SA(b, h) + aoff + m * 2048 + k * 1024); } while (0)
; #define PG8_MMA(ai, bj, At, Bt) do { __builtin_amdgcn_s_setprio(1); _Pragma("unroll") for (int m = 0; m < 4; ++m) _Pragma("unroll") for (int n = 0; n < 2; ++n) _Pragma("unroll") for (int k = 0; k < 2; ++k) \
;         acc[ai][bj][m][n] = __builtin_amdgcn_mfma_f32_16x16x32_bf16(Bt[n][k], At[m][k], acc[ai][bj][m][n], 0, 0, 0); __builtin_amdgcn_s_setprio(0); } while (0)
; #define PG8_WAIT_V(n) asm volatile("s_waitcnt vmcnt(" #n ")" ::: "memory")
; #define PG8_WAIT_L(n) asm volatile("s_waitcnt lgkmcnt(" #n ")" ::: "memory")
; #define PG8_BAR __builtin_amdgcn_s_barrier()
; #define PG8_SCHED __builtin_amdgcn_sched_barrier(0)
; template <class Epi, class Sched, bool ALIGN_EPI = false, bool SP2 = false>
; __device__ __forceinline__ void gemm_phase(PG8_LAS unsigned char* lds, const Gemm g, const Sched& S, const Epi& E) {
;     ...
;         for (int t = 0; t < nt; t += 2) {
;     ...
;             PG8_LDA(At, 1, 1); PG8_STAGE(PG8_SB(1, 0), b3, voffB); PG8_STAGE(PG8_SB(1, 1), b3 + hstep, voffB); PG8_STAGE(PG8_SA(1, 0), a3, voffA);
;             PG8_WAIT_V(8); PG8_WAIT_L(0); PG8_BAR; PG8_MMA(1, 0, At, B0); PG8_MMA(1, 1, At, B1); PG8_BAR; PG8_SCHED;
;     ...
;         if constexpr (ALIGN_EPI) { if (wr == 0) PG8_BAR; }
	s_add_i32 s28, s38, s2
	v_lshl_add_u64 v[150:151], v[150:151], 0, s[8:9]
	s_mov_b32 m0, s28
	ds_read_b128 v[188:191], v157 offset:49152
	ds_read_b128 v[192:195], v157 offset:50176
	ds_read_b128 v[208:211], v157 offset:51200
	ds_read_b128 v[212:215], v157 offset:52224
	ds_read_b128 v[216:219], v157 offset:53248
	ds_read_b128 v[220:223], v157 offset:54272
	ds_read_b128 v[224:227], v157 offset:55296
	ds_read_b128 v[236:239], v157 offset:56320
	global_load_lds_dwordx4 v[150:151], off
	s_add_i32 m0, s28, 0x2000
	s_add_u32 s24, s24, 0x40080
	v_lshl_add_u64 v[150:151], v[196:197], 0, s[8:9]
	s_addc_u32 s25, s25, 0
	s_add_i32 s28, s39, s2
	global_load_lds_dwordx4 v[150:151], off
	v_lshl_add_u64 v[150:151], s[24:25], 0, v[134:135]
	s_mov_b32 m0, s28
	s_nop 0
	global_load_lds_dwordx4 v[150:151], off
	v_lshl_add_u64 v[150:151], s[24:25], 0, v[136:137]
	s_add_i32 m0, s28, 0x2000
	s_nop 0
	global_load_lds_dwordx4 v[150:151], off
	v_lshl_add_u64 v[150:151], v[228:229], 0, s[8:9]
	s_mov_b32 m0, s33
	s_nop 0
	global_load_lds_dwordx4 v[150:151], off
	v_lshl_add_u64 v[150:151], v[240:241], 0, s[8:9]
	s_mov_b32 m0, s34
	s_nop 0
	global_load_lds_dwordx4 v[150:151], off
	s_waitcnt vmcnt(8)
	s_waitcnt lgkmcnt(0)
	s_barrier
	s_setprio 1
	s_waitcnt lgkmcnt(0)
	v_mfma_f32_16x16x32_bf16 v[62:65], v[146:149], v[188:191], v[62:65]
	v_mfma_f32_16x16x32_bf16 v[58:61], v[164:167], v[188:191], v[58:61]
	v_mfma_f32_16x16x32_bf16 v[46:49], v[146:149], v[208:211], v[46:49]
	v_mfma_f32_16x16x32_bf16 v[42:45], v[164:167], v[208:211], v[42:45]
	v_mfma_f32_16x16x32_bf16 v[30:33], v[146:149], v[216:219], v[30:33]
	v_mfma_f32_16x16x32_bf16 v[26:29], v[164:167], v[216:219], v[26:29]
	v_mfma_f32_16x16x32_bf16 v[14:17], v[146:149], v[224:227], v[14:17]
	v_mfma_f32_16x16x32_bf16 v[10:13], v[164:167], v[224:227], v[10:13]
	v_mfma_f32_16x16x32_bf16 v[62:65], v[160:163], v[192:195], v[62:65]
	v_mfma_f32_16x16x32_bf16 v[58:61], v[168:171], v[192:195], v[58:61]
	v_mfma_f32_16x16x32_bf16 v[46:49], v[160:163], v[212:215], v[46:49]
	v_mfma_f32_16x16x32_bf16 v[42:45], v[168:171], v[212:215], v[42:45]
	v_mfma_f32_16x16x32_bf16 v[30:33], v[160:163], v[220:223], v[30:33]
	v_mfma_f32_16x16x32_bf16 v[26:29], v[168:171], v[220:223], v[26:29]
	v_mfma_f32_16x16x32_bf16 v[14:17], v[160:163], v[236:239], v[14:17]
	v_mfma_f32_16x16x32_bf16 v[10:13], v[168:171], v[236:239], v[10:13]
	s_setprio 0
	s_setprio 1
	v_mfma_f32_16x16x32_bf16 v[54:57], v[172:175], v[188:191], v[54:57]
	v_mfma_f32_16x16x32_bf16 v[50:53], v[180:183], v[188:191], v[50:53]
	v_mfma_f32_16x16x32_bf16 v[38:41], v[172:175], v[208:211], v[38:41]
	v_mfma_f32_16x16x32_bf16 v[34:37], v[180:183], v[208:211], v[34:37]
	v_mfma_f32_16x16x32_bf16 v[22:25], v[172:175], v[216:219], v[22:25]
	v_mfma_f32_16x16x32_bf16 v[18:21], v[180:183], v[216:219], v[18:21]
	v_mfma_f32_16x16x32_bf16 v[6:9], v[172:175], v[224:227], v[6:9]
	v_mfma_f32_16x16x32_bf16 v[2:5], v[180:183], v[224:227], v[2:5]
	v_mfma_f32_16x16x32_bf16 v[54:57], v[176:179], v[192:195], v[54:57]
	v_mfma_f32_16x16x32_bf16 v[50:53], v[184:187], v[192:195], v[50:53]
	v_mfma_f32_16x16x32_bf16 v[38:41], v[176:179], v[212:215], v[38:41]
	v_mfma_f32_16x16x32_bf16 v[34:37], v[184:187], v[212:215], v[34:37]
	v_mfma_f32_16x16x32_bf16 v[22:25], v[176:179], v[220:223], v[22:25]
	v_mfma_f32_16x16x32_bf16 v[18:21], v[184:187], v[220:223], v[18:21]
	v_mfma_f32_16x16x32_bf16 v[6:9], v[176:179], v[236:239], v[6:9]
	v_mfma_f32_16x16x32_bf16 v[2:5], v[184:187], v[236:239], v[2:5]
	s_setprio 0
	s_barrier
	s_add_i32 s44, s44, 2
	s_add_u32 s22, s22, 0x100
	s_addc_u32 s23, s23, 0
	s_add_u32 s42, s42, 0x100
	s_addc_u32 s43, s43, 0
	s_cmp_gt_u32 s44, 13
	s_cbranch_scc0 .LBB0_827
	s_and_b64 vcc, exec, s[10:11]
	s_cbranch_vccz .LBB0_830
	s_barrier

; #define PG8_STAGE(bufoff, gbase, voff) do { _Pragma("unroll") for (int _i = 0; _i < 2; ++_i) \
;         __builtin_amdgcn_global_load_lds((const unsigned*)((const char*)(gbase) + (voff)[_i]), (PG8_LAS unsigned*)(lds + (bufoff) + ldsw + _i * 8192), 16, 0, 0); } while (0)
; #define PG8_WAIT_V(n) asm volatile("s_waitcnt vmcnt(" #n ")" ::: "memory")
; #define PG8_BAR __builtin_amdgcn_s_barrier()
; template <class Epi, class Sched, bool ALIGN_EPI = false, bool SP2 = false>
; __device__ __forceinline__ void gemm_phase(PG8_LAS unsigned char* lds, const Gemm g, const Sched& S, const Epi& E) {
;     ...
;     for (int i = 0; i < 2; ++i) { int R, C; stage_rc(tid * 16 + i * 8192, R, C); const int Rb = Epi::PERM ? ((R & ~31) + perm32(R & 31)) : R;
;         voffA[i] = (unsigned)(R * LD + C) * 2u; voffB[i] = (unsigned)(Rb * LD + C) * 2u; }
;     const size_t kstep = (size_t)(BK * 2);
;     const size_t hstep = (size_t)HALF * LD * 2;
;     const size_t tstep = 2 * hstep;
;     const unsigned ldsw = (unsigned)wid * 1024u;
;     const int aoff = lds_byte(wr * 64 + fr, fq * 8), boff = lds_byte(wc * 32 + fr, fq * 8);
;     ...
;         PG8_WAIT_V(2); PG8_BAR;
;         PG8_STAGE(PG8_SB(1, 0), cB + kstep, voffB); PG8_STAGE(PG8_SA(1, 0), cA + kstep, voffA); PG8_STAGE(PG8_SB(1, 1), cB + hstep + kstep, voffB);
;         PG8_WAIT_V(6); PG8_BAR;
.LBB0_837:
	s_lshl_b32 s14, s14, 5
	s_and_b32 s23, s14, 0x60
	s_mov_b64 s[14:15], 0x80
	s_add_i32 m0, s3, 0x18000
	v_lshl_add_u64 v[8:9], v[8:9], 0, s[14:15]
	s_lshl_b32 s22, s5, 13
	s_lshl_b32 s24, s23, 7
	s_waitcnt vmcnt(2)
	s_barrier
	global_load_lds_dwordx4 v[8:9], off
	v_lshl_add_u64 v[6:7], v[6:7], 0, s[14:15]
	s_add_i32 m0, s3, 0x1a000
	s_add_i32 s48, s3, 0x8000
	s_add_i32 s49, s3, 0xa000
	global_load_lds_dwordx4 v[6:7], off
	v_lshl_add_u64 v[2:3], v[2:3], 0, s[14:15]
	s_mov_b32 m0, s48
	s_add_u32 s18, s16, 0x40080
	global_load_lds_dwordx4 v[2:3], off
	v_lshl_add_u64 v[2:3], v[4:5], 0, s[14:15]
	s_mov_b32 m0, s49
	s_addc_u32 s19, s17, 0
	global_load_lds_dwordx4 v[2:3], off
	s_add_i32 m0, s3, 0x1c000
	v_lshl_add_u64 v[2:3], s[18:19], 0, v[130:131]
	global_load_lds_dwordx4 v[2:3], off
	v_lshl_add_u64 v[2:3], s[18:19], 0, v[132:133]
	s_add_i32 m0, s3, 0x1e000
	v_bfe_u32 v18, v198, 4, 2
	global_load_lds_dwordx4 v[2:3], off
	v_lshlrev_b32_e32 v3, 4, v18
	v_lshlrev_b32_e32 v5, 2, v204
	v_lshl_or_b32 v4, v204, 6, v3
	v_and_b32_e32 v5, 32, v5
	v_or_b32_e32 v1, v3, v1
	s_cmpk_lt_u32 s4, 0x100
	s_mov_b32 s4, 0x10000
	v_lshl_or_b32 v2, s5, 6, v204
	v_bitop3_b32 v19, v4, s22, v5 bitop3:0xde
	v_bitop3_b32 v20, s24, v1, v152 bitop3:0xf6
	s_mov_b32 s5, 0x18000
	s_mov_b32 s22, 0x1c000
	s_waitcnt vmcnt(6)
	s_cselect_b64 s[18:19], -1, 0
	s_add_i32 s53, s4, 0x100
	s_add_i32 s55, s7, 0x100
	v_mov_b32_e32 v3, v131
	v_or_b32_e32 v4, 16, v2
	v_mov_b32_e32 v5, v131
	v_or_b32_e32 v6, 32, v2
	v_mov_b32_e32 v7, v131
	v_or_b32_e32 v8, 48, v2
	v_mov_b32_e32 v9, v131
	v_add_u32_e32 v10, 0x80, v2
	v_mov_b32_e32 v11, v131
	v_add_u32_e32 v12, 0x90, v2
	v_mov_b32_e32 v13, v131
	v_add_u32_e32 v14, 0xa0, v2
	v_mov_b32_e32 v15, v131
	v_add_u32_e32 v16, 0xb0, v2
	v_mov_b32_e32 v17, v131
	v_add_u32_e32 v150, s53, v20
	v_add_u32_e32 v151, s55, v20
	s_add_i32 s53, s53, s2
	s_add_i32 s55, s55, s2
	s_add_i32 s57, s5, 0x100
	s_add_i32 s58, s22, 0x100
	v_lshlrev_b64 v[134:135], 12, v[2:3]
	v_lshlrev_b64 v[136:137], 12, v[4:5]
	v_lshlrev_b64 v[138:139], 12, v[6:7]
	v_lshlrev_b64 v[140:141], 12, v[8:9]
	v_lshlrev_b64 v[142:143], 12, v[10:11]
	v_lshlrev_b64 v[144:145], 12, v[12:13]
	v_lshlrev_b64 v[146:147], 12, v[14:15]
	v_lshlrev_b64 v[148:149], 12, v[16:17]
	v_lshl_or_b32 v1, v18, 2, s23
	s_mov_b32 s50, 0
	v_add_u32_e32 v152, 0x100, v19
	s_add_i32 s51, s3, 0xc000
	s_add_i32 s52, s3, 0xe000
	s_add_i32 s54, s53, 0x2000
	s_add_i32 s56, s55, 0x2000
	v_add_u32_e32 v153, s57, v20
	v_add_u32_e32 v154, s58, v20
	s_barrier
	s_branch .LBB0_840

;     __device__ __forceinline__ bool next(int i, Unit& u) const { const int L = i * G + c; if (L >= nunits) return false; const int t = L / S, ks = L % S; u.pm = pm0 + t / nN; u.pn = t % nN; u.ko = ks * Ksub; return true; }
; #define PG8_STAGE(bufoff, gbase, voff) do { _Pragma("unroll") for (int _i = 0; _i < 2; ++_i) \
;         __builtin_amdgcn_global_load_lds((const unsigned*)((const char*)(gbase) + (voff)[_i]), (PG8_LAS unsigned*)(lds + (bufoff) + ldsw + _i * 8192), 16, 0, 0); } while (0)
; #define PG8_LDA(dst, b, h) do { _Pragma("unroll") for (int m = 0; m < 4; ++m) _Pragma("unroll") for (int k = 0; k < 2; ++k) dst[m][k] = *(const PG8_LAS bf16x8*)(lds + PG8_SA(b, h) + aoff + m * 2048 + k * 1024); } while (0)
; #define PG8_LDB(dst, b, h) do { _Pragma("unroll") for (int n = 0; n < 2; ++n) _Pragma("unroll") for (int k = 0; k < 2; ++k) dst[n][k] = *(const PG8_LAS bf16x8*)(lds + PG8_SB(b, h) + boff + n * 2048 + k * 1024); } while (0)
; template <class Epi, class Sched, bool ALIGN_EPI = false, bool SP2 = false>
; __device__ __forceinline__ void gemm_phase(PG8_LAS unsigned char* lds, const Gemm g, const Sched& S, const Epi& E) {
;     ...
;         const bool has_next = S.next(ui + 1, nxt);
;         const char* nA = has_next ? (const char*)g.A + (size_t)nxt.pm * tstep + (size_t)nxt.ko * 2 : cA; const char* nB = has_next ? (const char*)g.Bt + (size_t)nxt.pn * tstep + (size_t)nxt.ko * 2 : cB;
;         for (int t = 0; t < nt; t += 2) {
;             const bool last = (t == nt - 2);
;             const char* a1 = cA + (size_t)(t + 1) * kstep;
;             const char* a2 = last ? nA : cA + (size_t)(t + 2) * kstep; const char* b2 = last ? nB : cB + (size_t)(t + 2) * kstep;
;             const char* a3 = a2 + kstep; const char* b3 = b2 + kstep;
;             if (last && has_next) S.a_ready(nxt);
;             if constexpr (SP2) {
;             PG8_LDB(B0, 0, 0); PG8_LDB(B1, 0, 1); PG8_SCHED; PG8_LDA(At, 0, 0); PG8_STAGE(PG8_SA(1, 1), a1 + hstep, voffA);
;             PG8_WAIT_V(8); PG8_WAIT_L(0); PG8_BAR; PG8_MMA(0, 0, At, B0); PG8_MMA(0, 1, At, B1); PG8_BAR; PG8_SCHED;
;             PG8_LDA(At, 0, 1); PG8_STAGE(PG8_SB(0, 0), b2, voffB); PG8_STAGE(PG8_SB(0, 1), b2 + hstep, voffB); PG8_STAGE(PG8_SA(0, 0), a2, voffA);
;             PG8_WAIT_V(8); PG8_WAIT_L(0); PG8_BAR; PG8_MMA(1, 0, At, B0); PG8_MMA(1, 1, At, B1); PG8_BAR; PG8_SCHED;
.LBB0_847:
	s_add_u32 s23, s20, s7
	s_addc_u32 s25, s21, 0
	s_add_u32 s27, s23, 0x100
	s_addc_u32 s40, s25, 0
	s_and_b64 s[38:39], s[36:37], exec
	s_cselect_b32 s41, s29, s40
	s_cselect_b32 s40, s28, s27
	s_add_u32 s7, s16, s7
	s_addc_u32 s27, s17, 0
	s_add_u32 s7, s7, 0x100
	s_addc_u32 s27, s27, 0
	s_and_b64 s[36:37], s[36:37], exec
	ds_read_b128 v[156:159], v150
	ds_read_b128 v[160:163], v150 offset:1024
	ds_read_b128 v[164:167], v150 offset:2048
	ds_read_b128 v[168:171], v150 offset:3072
	ds_read_b128 v[172:175], v151
	ds_read_b128 v[176:179], v151 offset:1024
	ds_read_b128 v[180:183], v151 offset:2048
	ds_read_b128 v[184:187], v151 offset:3072
	s_cselect_b32 s43, s31, s27
	s_cselect_b32 s42, s30, s7
	s_add_u32 s46, s23, 0x40080
	s_addc_u32 s47, s25, 0
	s_add_u32 s44, s42, 0x40000
	s_addc_u32 s45, s43, 0
	s_add_u32 s38, s40, 0x40000
	s_addc_u32 s39, s41, 0
	s_add_i32 s27, s57, s2
	s_add_i32 s23, s27, 0x2000
	s_add_u32 s36, s42, 0x40080
	s_addc_u32 s37, s43, 0
	s_add_i32 s25, s58, s2
	s_add_i32 s7, s25, 0x2000
	s_mov_b32 m0, s51
	v_lshl_add_u64 v[196:197], s[46:47], 0, v[130:131]
	ds_read_b128 v[188:191], v152
	ds_read_b128 v[192:195], v152 offset:1024
	ds_read_b128 v[208:211], v152 offset:2048
	ds_read_b128 v[212:215], v152 offset:3072
	ds_read_b128 v[216:219], v152 offset:4096
	ds_read_b128 v[220:223], v152 offset:5120
	ds_read_b128 v[224:227], v152 offset:6144
	ds_read_b128 v[236:239], v152 offset:7168
	global_load_lds_dwordx4 v[196:197], off
	v_lshl_add_u64 v[196:197], s[46:47], 0, v[132:133]
	s_mov_b32 m0, s52
	s_nop 0
	global_load_lds_dwordx4 v[196:197], off
	s_waitcnt vmcnt(8)
	s_waitcnt lgkmcnt(0)
	s_barrier
	s_setprio 1
	s_waitcnt lgkmcnt(0)
	v_mfma_f32_16x16x32_bf16 v[126:129], v[156:159], v[188:191], v[126:129]
	v_mfma_f32_16x16x32_bf16 v[122:125], v[164:167], v[188:191], v[122:125]
	v_mfma_f32_16x16x32_bf16 v[118:121], v[156:159], v[208:211], v[118:121]
	v_mfma_f32_16x16x32_bf16 v[114:117], v[164:167], v[208:211], v[114:117]
	v_mfma_f32_16x16x32_bf16 v[110:113], v[156:159], v[216:219], v[110:113]
	v_mfma_f32_16x16x32_bf16 v[106:109], v[164:167], v[216:219], v[106:109]
	v_mfma_f32_16x16x32_bf16 v[98:101], v[156:159], v[224:227], v[98:101]
	v_mfma_f32_16x16x32_bf16 v[90:93], v[164:167], v[224:227], v[90:93]
	v_mfma_f32_16x16x32_bf16 v[126:129], v[160:163], v[192:195], v[126:129]
	v_mfma_f32_16x16x32_bf16 v[122:125], v[168:171], v[192:195], v[122:125]
	v_mfma_f32_16x16x32_bf16 v[118:121], v[160:163], v[212:215], v[118:121]
	v_mfma_f32_16x16x32_bf16 v[114:117], v[168:171], v[212:215], v[114:117]
	v_mfma_f32_16x16x32_bf16 v[110:113], v[160:163], v[220:223], v[110:113]
	v_mfma_f32_16x16x32_bf16 v[106:109], v[168:171], v[220:223], v[106:109]
	v_mfma_f32_16x16x32_bf16 v[98:101], v[160:163], v[236:239], v[98:101]
	v_mfma_f32_16x16x32_bf16 v[90:93], v[168:171], v[236:239], v[90:93]
	s_setprio 0
	s_setprio 1
	v_mfma_f32_16x16x32_bf16 v[102:105], v[172:175], v[188:191], v[102:105]
	v_mfma_f32_16x16x32_bf16 v[94:97], v[180:183], v[188:191], v[94:97]
	v_mfma_f32_16x16x32_bf16 v[86:89], v[172:175], v[208:211], v[86:89]
	v_mfma_f32_16x16x32_bf16 v[82:85], v[180:183], v[208:211], v[82:85]
	v_mfma_f32_16x16x32_bf16 v[78:81], v[172:175], v[216:219], v[78:81]
	v_mfma_f32_16x16x32_bf16 v[74:77], v[180:183], v[216:219], v[74:77]
	v_mfma_f32_16x16x32_bf16 v[70:73], v[172:175], v[224:227], v[70:73]
	v_mfma_f32_16x16x32_bf16 v[66:69], v[180:183], v[224:227], v[66:69]
	v_mfma_f32_16x16x32_bf16 v[102:105], v[176:179], v[192:195], v[102:105]
	v_mfma_f32_16x16x32_bf16 v[94:97], v[184:187], v[192:195], v[94:97]
	v_mfma_f32_16x16x32_bf16 v[86:89], v[176:179], v[212:215], v[86:89]
	v_mfma_f32_16x16x32_bf16 v[82:85], v[184:187], v[212:215], v[82:85]
	v_mfma_f32_16x16x32_bf16 v[78:81], v[176:179], v[220:223], v[78:81]
	v_mfma_f32_16x16x32_bf16 v[74:77], v[184:187], v[220:223], v[74:77]
	v_mfma_f32_16x16x32_bf16 v[70:73], v[176:179], v[236:239], v[70:73]
	v_mfma_f32_16x16x32_bf16 v[66:69], v[184:187], v[236:239], v[66:69]
	s_setprio 0
	s_barrier
	s_mov_b32 m0, s53
	v_lshl_add_u64 v[196:197], s[42:43], 0, v[130:131]
	ds_read_b128 v[188:191], v152 offset:16384
	ds_read_b128 v[192:195], v152 offset:17408
	ds_read_b128 v[208:211], v152 offset:18432
	ds_read_b128 v[212:215], v152 offset:19456
	ds_read_b128 v[216:219], v152 offset:20480
	ds_read_b128 v[220:223], v152 offset:21504
	ds_read_b128 v[224:227], v152 offset:22528
	ds_read_b128 v[236:239], v152 offset:23552
	global_load_lds_dwordx4 v[196:197], off
	v_lshl_add_u64 v[228:229], s[42:43], 0, v[132:133]
	s_mov_b32 m0, s54
	v_lshl_add_u64 v[240:241], s[44:45], 0, v[130:131]
	global_load_lds_dwordx4 v[228:229], off
	s_mov_b32 m0, s55
	v_lshl_add_u64 v[242:243], s[40:41], 0, v[132:133]
	global_load_lds_dwordx4 v[240:241], off
	v_lshl_add_u64 v[240:241], s[44:45], 0, v[132:133]
	s_mov_b32 m0, s56
	s_nop 0
	global_load_lds_dwordx4 v[240:241], off
	v_lshl_add_u64 v[240:241], s[40:41], 0, v[130:131]
	s_mov_b32 m0, s3
	s_nop 0
	global_load_lds_dwordx4 v[240:241], off
	s_mov_b32 m0, s11
	s_nop 0
	global_load_lds_dwordx4 v[242:243], off
	s_waitcnt vmcnt(8)
	s_waitcnt lgkmcnt(0)
	s_barrier
; #define PG8_STAGE(bufoff, gbase, voff) do { _Pragma("unroll") for (int _i = 0; _i < 2; ++_i) \
;         __builtin_amdgcn_global_load_lds((const unsigned*)((const char*)(gbase) + (voff)[_i]), (PG8_LAS unsigned*)(lds + (bufoff) + ldsw + _i * 8192), 16, 0, 0); } while (0)
; #define PG8_LDA(dst, b, h) do { _Pragma("unroll") for (int m = 0; m < 4; ++m) _Pragma("unroll") for (int k = 0; k < 2; ++k) dst[m][k] = *(const PG8_LAS bf16x8*)(lds + PG8_SA(b, h) + aoff + m * 2048 + k * 1024); } while (0)
; #define PG8_LDB(dst, b, h) do { _Pragma("unroll") for (int n = 0; n < 2; ++n) _Pragma("unroll") for (int k = 0; k < 2; ++k) dst[n][k] = *(const PG8_LAS bf16x8*)(lds + PG8_SB(b, h) + boff + n * 2048 + k * 1024); } while (0)
; #define PG8_MMA(ai, bj, At, Bt) do { __builtin_amdgcn_s_setprio(1); _Pragma("unroll") for (int m = 0; m < 4; ++m) _Pragma("unroll") for (int n = 0; n < 2; ++n) _Pragma("unroll") for (int k = 0; k < 2; ++k) \
;         acc[ai][bj][m][n] = __builtin_amdgcn_mfma_f32_16x16x32_bf16(Bt[n][k], At[m][k], acc[ai][bj][m][n], 0, 0, 0); __builtin_amdgcn_s_setprio(0); } while (0)
; #define PG8_WAIT_V(n) asm volatile("s_waitcnt vmcnt(" #n ")" ::: "memory")
; #define PG8_WAIT_L(n) asm volatile("s_waitcnt lgkmcnt(" #n ")" ::: "memory")
; #define PG8_BAR __builtin_amdgcn_s_barrier()
; #define PG8_SCHED __builtin_amdgcn_sched_barrier(0)
; template <class Epi, class Sched, bool ALIGN_EPI = false, bool SP2 = false>
; __device__ __forceinline__ void gemm_phase(PG8_LAS unsigned char* lds, const Gemm g, const Sched& S, const Epi& E) {
;     ...
;             PG8_WAIT_V(8); PG8_WAIT_L(0); PG8_BAR; PG8_MMA(1, 0, At, B0); PG8_MMA(1, 1, At, B1); PG8_BAR; PG8_SCHED;
;             PG8_LDB(B0, 1, 0); PG8_LDB(B1, 1, 1); PG8_SCHED; PG8_LDA(At, 1, 0); PG8_STAGE(PG8_SA(0, 1), a2 + hstep, voffA);
;             PG8_WAIT_V(8); PG8_WAIT_L(0); PG8_BAR; PG8_MMA(0, 0, At, B0); PG8_MMA(0, 1, At, B1); PG8_BAR; PG8_SCHED;
	s_setprio 1
	s_waitcnt lgkmcnt(0)
	v_mfma_f32_16x16x32_bf16 v[62:65], v[156:159], v[188:191], v[62:65]
	v_mfma_f32_16x16x32_bf16 v[58:61], v[164:167], v[188:191], v[58:61]
	v_mfma_f32_16x16x32_bf16 v[54:57], v[156:159], v[208:211], v[54:57]
	v_mfma_f32_16x16x32_bf16 v[50:53], v[164:167], v[208:211], v[50:53]
	v_mfma_f32_16x16x32_bf16 v[46:49], v[156:159], v[216:219], v[46:49]
	v_mfma_f32_16x16x32_bf16 v[42:45], v[164:167], v[216:219], v[42:45]
	v_mfma_f32_16x16x32_bf16 v[34:37], v[156:159], v[224:227], v[34:37]
	v_mfma_f32_16x16x32_bf16 v[26:29], v[164:167], v[224:227], v[26:29]
	v_mfma_f32_16x16x32_bf16 v[62:65], v[160:163], v[192:195], v[62:65]
	v_mfma_f32_16x16x32_bf16 v[58:61], v[168:171], v[192:195], v[58:61]
	v_mfma_f32_16x16x32_bf16 v[54:57], v[160:163], v[212:215], v[54:57]
	v_mfma_f32_16x16x32_bf16 v[50:53], v[168:171], v[212:215], v[50:53]
	v_mfma_f32_16x16x32_bf16 v[46:49], v[160:163], v[220:223], v[46:49]
	v_mfma_f32_16x16x32_bf16 v[42:45], v[168:171], v[220:223], v[42:45]
	v_mfma_f32_16x16x32_bf16 v[34:37], v[160:163], v[236:239], v[34:37]
	v_mfma_f32_16x16x32_bf16 v[26:29], v[168:171], v[236:239], v[26:29]
	s_setprio 0
	s_setprio 1
	v_mfma_f32_16x16x32_bf16 v[38:41], v[172:175], v[188:191], v[38:41]
	v_mfma_f32_16x16x32_bf16 v[30:33], v[180:183], v[188:191], v[30:33]
	v_mfma_f32_16x16x32_bf16 v[22:25], v[172:175], v[208:211], v[22:25]
	v_mfma_f32_16x16x32_bf16 v[18:21], v[180:183], v[208:211], v[18:21]
	v_mfma_f32_16x16x32_bf16 v[14:17], v[172:175], v[216:219], v[14:17]
	v_mfma_f32_16x16x32_bf16 v[10:13], v[180:183], v[216:219], v[10:13]
	v_mfma_f32_16x16x32_bf16 v[6:9], v[172:175], v[224:227], v[6:9]
	v_mfma_f32_16x16x32_bf16 v[2:5], v[180:183], v[224:227], v[2:5]
	v_mfma_f32_16x16x32_bf16 v[38:41], v[176:179], v[192:195], v[38:41]
	v_mfma_f32_16x16x32_bf16 v[30:33], v[184:187], v[192:195], v[30:33]
	v_mfma_f32_16x16x32_bf16 v[22:25], v[176:179], v[212:215], v[22:25]
	v_mfma_f32_16x16x32_bf16 v[18:21], v[184:187], v[212:215], v[18:21]
	v_mfma_f32_16x16x32_bf16 v[14:17], v[176:179], v[220:223], v[14:17]
	v_mfma_f32_16x16x32_bf16 v[10:13], v[184:187], v[220:223], v[10:13]
	v_mfma_f32_16x16x32_bf16 v[6:9], v[176:179], v[236:239], v[6:9]
	v_mfma_f32_16x16x32_bf16 v[2:5], v[184:187], v[236:239], v[2:5]
	s_setprio 0
	s_barrier
	ds_read_b128 v[156:159], v153
	ds_read_b128 v[160:163], v153 offset:1024
	ds_read_b128 v[164:167], v153 offset:2048
	ds_read_b128 v[168:171], v153 offset:3072
	ds_read_b128 v[172:175], v154
	ds_read_b128 v[176:179], v154 offset:1024
	ds_read_b128 v[180:183], v154 offset:2048
	ds_read_b128 v[184:187], v154 offset:3072
	s_mov_b32 m0, s13
	v_lshl_add_u64 v[244:245], s[38:39], 0, v[130:131]
	ds_read_b128 v[188:191], v152 offset:32768
	ds_read_b128 v[192:195], v152 offset:33792
	ds_read_b128 v[208:211], v152 offset:34816
	ds_read_b128 v[212:215], v152 offset:35840
	ds_read_b128 v[216:219], v152 offset:36864
	ds_read_b128 v[220:223], v152 offset:37888
	ds_read_b128 v[224:227], v152 offset:38912
	ds_read_b128 v[236:239], v152 offset:39936
	global_load_lds_dwordx4 v[244:245], off
	v_lshl_add_u64 v[244:245], s[38:39], 0, v[132:133]
	s_mov_b32 m0, s33
	s_nop 0
	global_load_lds_dwordx4 v[244:245], off
	s_waitcnt vmcnt(8)
	s_waitcnt lgkmcnt(0)
	s_barrier
	s_setprio 1
	s_waitcnt lgkmcnt(0)
	v_mfma_f32_16x16x32_bf16 v[126:129], v[156:159], v[188:191], v[126:129]
	v_mfma_f32_16x16x32_bf16 v[122:125], v[164:167], v[188:191], v[122:125]
	v_mfma_f32_16x16x32_bf16 v[118:121], v[156:159], v[208:211], v[118:121]
	v_mfma_f32_16x16x32_bf16 v[114:117], v[164:167], v[208:211], v[114:117]
	v_mfma_f32_16x16x32_bf16 v[110:113], v[156:159], v[216:219], v[110:113]
	v_mfma_f32_16x16x32_bf16 v[106:109], v[164:167], v[216:219], v[106:109]
	v_mfma_f32_16x16x32_bf16 v[98:101], v[156:159], v[224:227], v[98:101]
	v_mfma_f32_16x16x32_bf16 v[90:93], v[164:167], v[224:227], v[90:93]
	v_mfma_f32_16x16x32_bf16 v[126:129], v[160:163], v[192:195], v[126:129]
	v_mfma_f32_16x16x32_bf16 v[122:125], v[168:171], v[192:195], v[122:125]
	v_mfma_f32_16x16x32_bf16 v[118:121], v[160:163], v[212:215], v[118:121]
	v_mfma_f32_16x16x32_bf16 v[114:117], v[168:171], v[212:215], v[114:117]
	v_mfma_f32_16x16x32_bf16 v[110:113], v[160:163], v[220:223], v[110:113]
	v_mfma_f32_16x16x32_bf16 v[106:109], v[168:171], v[220:223], v[106:109]
	v_mfma_f32_16x16x32_bf16 v[98:101], v[160:163], v[236:239], v[98:101]
	v_mfma_f32_16x16x32_bf16 v[90:93], v[168:171], v[236:239], v[90:93]
	s_setprio 0
	s_setprio 1
	v_mfma_f32_16x16x32_bf16 v[102:105], v[172:175], v[188:191], v[102:105]
	v_mfma_f32_16x16x32_bf16 v[94:97], v[180:183], v[188:191], v[94:97]
	v_mfma_f32_16x16x32_bf16 v[86:89], v[172:175], v[208:211], v[86:89]
	v_mfma_f32_16x16x32_bf16 v[82:85], v[180:183], v[208:211], v[82:85]
	v_mfma_f32_16x16x32_bf16 v[78:81], v[172:175], v[216:219], v[78:81]
	v_mfma_f32_16x16x32_bf16 v[74:77], v[180:183], v[216:219], v[74:77]
	v_mfma_f32_16x16x32_bf16 v[70:73], v[172:175], v[224:227], v[70:73]
	v_mfma_f32_16x16x32_bf16 v[66:69], v[180:183], v[224:227], v[66:69]
	v_mfma_f32_16x16x32_bf16 v[102:105], v[176:179], v[192:195], v[102:105]
	v_mfma_f32_16x16x32_bf16 v[94:97], v[184:187], v[192:195], v[94:97]
	v_mfma_f32_16x16x32_bf16 v[86:89], v[176:179], v[212:215], v[86:89]
	v_mfma_f32_16x16x32_bf16 v[82:85], v[184:187], v[212:215], v[82:85]
	v_mfma_f32_16x16x32_bf16 v[78:81], v[176:179], v[220:223], v[78:81]
	v_mfma_f32_16x16x32_bf16 v[74:77], v[184:187], v[220:223], v[74:77]
	v_mfma_f32_16x16x32_bf16 v[70:73], v[176:179], v[236:239], v[70:73]
	v_mfma_f32_16x16x32_bf16 v[66:69], v[184:187], v[236:239], v[66:69]
	s_setprio 0
	s_barrier
; #define PG8_STAGE(bufoff, gbase, voff) do { _Pragma("unroll") for (int _i = 0; _i < 2; ++_i) \
;         __builtin_amdgcn_global_load_lds((const unsigned*)((const char*)(gbase) + (voff)[_i]), (PG8_LAS unsigned*)(lds + (bufoff) + ldsw + _i * 8192), 16, 0, 0); } while (0)
; #define PG8_LDA(dst, b, h) do { _Pragma("unroll") for (int m = 0; m < 4; ++m) _Pragma("unroll") for (int k = 0; k < 2; ++k) dst[m][k] = *(const PG8_LAS bf16x8*)(lds + PG8_SA(b, h) + aoff + m * 2048 + k * 1024); } while (0)
; #define PG8_MMA(ai, bj, At, Bt) do { __builtin_amdgcn_s_setprio(1); _Pragma("unroll") for (int m = 0; m < 4; ++m) _Pragma("unroll") for (int n = 0; n < 2; ++n) _Pragma("unroll") for (int k = 0; k < 2; ++k) \
;         acc[ai][bj][m][n] = __builtin_amdgcn_mfma_f32_16x16x32_bf16(Bt[n][k], At[m][k], acc[ai][bj][m][n], 0, 0, 0); __builtin_amdgcn_s_setprio(0); } while (0)
; #define PG8_WAIT_V(n) asm volatile("s_waitcnt vmcnt(" #n ")" ::: "memory")
; #define PG8_WAIT_L(n) asm volatile("s_waitcnt lgkmcnt(" #n ")" ::: "memory")
; #define PG8_BAR __builtin_amdgcn_s_barrier()
; #define PG8_SCHED __builtin_amdgcn_sched_barrier(0)
; template <class Epi, class Sched, bool ALIGN_EPI = false, bool SP2 = false>
; __device__ __forceinline__ void gemm_phase(PG8_LAS unsigned char* lds, const Gemm g, const Sched& S, const Epi& E) {
;     ...
;         for (int t = 0; t < nt; t += 2) {
;     ...
;             PG8_LDA(At, 1, 1); PG8_STAGE(PG8_SB(1, 0), b3, voffB); PG8_STAGE(PG8_SB(1, 1), b3 + hstep, voffB); PG8_STAGE(PG8_SA(1, 0), a3, voffA);
;             PG8_WAIT_V(8); PG8_WAIT_L(0); PG8_BAR; PG8_MMA(1, 0, At, B0); PG8_MMA(1, 1, At, B1); PG8_BAR; PG8_SCHED;
;     ...
;         if constexpr (ALIGN_EPI) { if (wr == 0) PG8_BAR; }
	s_mov_b32 m0, s27
	v_lshl_add_u64 v[196:197], v[196:197], 0, s[14:15]
	ds_read_b128 v[188:191], v152 offset:49152
	ds_read_b128 v[192:195], v152 offset:50176
	ds_read_b128 v[208:211], v152 offset:51200
	ds_read_b128 v[212:215], v152 offset:52224
	ds_read_b128 v[216:219], v152 offset:53248
	ds_read_b128 v[220:223], v152 offset:54272
	ds_read_b128 v[224:227], v152 offset:55296
	ds_read_b128 v[236:239], v152 offset:56320
	global_load_lds_dwordx4 v[196:197], off
	v_lshl_add_u64 v[196:197], v[228:229], 0, s[14:15]
	s_mov_b32 m0, s23
	s_nop 0
	global_load_lds_dwordx4 v[196:197], off
	v_lshl_add_u64 v[196:197], s[36:37], 0, v[130:131]
	s_mov_b32 m0, s25
	s_nop 0
	global_load_lds_dwordx4 v[196:197], off
	v_lshl_add_u64 v[196:197], s[36:37], 0, v[132:133]
	s_mov_b32 m0, s7
	s_nop 0
	global_load_lds_dwordx4 v[196:197], off
	v_lshl_add_u64 v[196:197], v[240:241], 0, s[14:15]
	s_mov_b32 m0, s48
	s_nop 0
	global_load_lds_dwordx4 v[196:197], off
	v_lshl_add_u64 v[196:197], v[242:243], 0, s[14:15]
	s_mov_b32 m0, s49
	s_nop 0
	global_load_lds_dwordx4 v[196:197], off
	s_waitcnt vmcnt(8)
	s_waitcnt lgkmcnt(0)
	s_barrier
	s_setprio 1
	s_waitcnt lgkmcnt(0)
	v_mfma_f32_16x16x32_bf16 v[62:65], v[156:159], v[188:191], v[62:65]
	v_mfma_f32_16x16x32_bf16 v[58:61], v[164:167], v[188:191], v[58:61]
	v_mfma_f32_16x16x32_bf16 v[54:57], v[156:159], v[208:211], v[54:57]
	v_mfma_f32_16x16x32_bf16 v[50:53], v[164:167], v[208:211], v[50:53]
	v_mfma_f32_16x16x32_bf16 v[46:49], v[156:159], v[216:219], v[46:49]
	v_mfma_f32_16x16x32_bf16 v[42:45], v[164:167], v[216:219], v[42:45]
	v_mfma_f32_16x16x32_bf16 v[34:37], v[156:159], v[224:227], v[34:37]
	v_mfma_f32_16x16x32_bf16 v[26:29], v[164:167], v[224:227], v[26:29]
	v_mfma_f32_16x16x32_bf16 v[62:65], v[160:163], v[192:195], v[62:65]
	v_mfma_f32_16x16x32_bf16 v[58:61], v[168:171], v[192:195], v[58:61]
	v_mfma_f32_16x16x32_bf16 v[54:57], v[160:163], v[212:215], v[54:57]
	v_mfma_f32_16x16x32_bf16 v[50:53], v[168:171], v[212:215], v[50:53]
	v_mfma_f32_16x16x32_bf16 v[46:49], v[160:163], v[220:223], v[46:49]
	v_mfma_f32_16x16x32_bf16 v[42:45], v[168:171], v[220:223], v[42:45]
	v_mfma_f32_16x16x32_bf16 v[34:37], v[160:163], v[236:239], v[34:37]
	v_mfma_f32_16x16x32_bf16 v[26:29], v[168:171], v[236:239], v[26:29]
	s_setprio 0
	s_setprio 1
	v_mfma_f32_16x16x32_bf16 v[38:41], v[172:175], v[188:191], v[38:41]
	v_mfma_f32_16x16x32_bf16 v[30:33], v[180:183], v[188:191], v[30:33]
	v_mfma_f32_16x16x32_bf16 v[22:25], v[172:175], v[208:211], v[22:25]
	v_mfma_f32_16x16x32_bf16 v[18:21], v[180:183], v[208:211], v[18:21]
	v_mfma_f32_16x16x32_bf16 v[14:17], v[172:175], v[216:219], v[14:17]
	v_mfma_f32_16x16x32_bf16 v[10:13], v[180:183], v[216:219], v[10:13]
	v_mfma_f32_16x16x32_bf16 v[6:9], v[172:175], v[224:227], v[6:9]
	v_mfma_f32_16x16x32_bf16 v[2:5], v[180:183], v[224:227], v[2:5]
	v_mfma_f32_16x16x32_bf16 v[38:41], v[176:179], v[192:195], v[38:41]
	v_mfma_f32_16x16x32_bf16 v[30:33], v[184:187], v[192:195], v[30:33]
	v_mfma_f32_16x16x32_bf16 v[22:25], v[176:179], v[212:215], v[22:25]
	v_mfma_f32_16x16x32_bf16 v[18:21], v[184:187], v[212:215], v[18:21]
	v_mfma_f32_16x16x32_bf16 v[14:17], v[176:179], v[220:223], v[14:17]
	v_mfma_f32_16x16x32_bf16 v[10:13], v[184:187], v[220:223], v[10:13]
	v_mfma_f32_16x16x32_bf16 v[6:9], v[176:179], v[236:239], v[6:9]
	v_mfma_f32_16x16x32_bf16 v[2:5], v[184:187], v[236:239], v[2:5]
	s_setprio 0
	s_barrier
	s_movk_i32 s7, 0x100
	s_andn2_b64 vcc, exec, s[34:35]
	s_mov_b64 s[36:37], -1
	s_mov_b64 s[34:35], 0
	s_cbranch_vccz .LBB0_847
	s_and_b64 vcc, exec, s[18:19]
	s_cbranch_vccz .LBB0_850
	s_barrier

; #define PG8_STAGE(bufoff, gbase, voff) do { _Pragma("unroll") for (int _i = 0; _i < 2; ++_i) \
;         __builtin_amdgcn_global_load_lds((const unsigned*)((const char*)(gbase) + (voff)[_i]), (PG8_LAS unsigned*)(lds + (bufoff) + ldsw + _i * 8192), 16, 0, 0); } while (0)
; #define PG8_WAIT_V(n) asm volatile("s_waitcnt vmcnt(" #n ")" ::: "memory")
; #define PG8_BAR __builtin_amdgcn_s_barrier()
; template <class Epi, class Sched, bool ALIGN_EPI = false, bool SP2 = false>
; __device__ __forceinline__ void gemm_phase(PG8_LAS unsigned char* lds, const Gemm g, const Sched& S, const Epi& E) {
;     ...
;     for (int i = 0; i < 2; ++i) { int R, C; stage_rc(tid * 16 + i * 8192, R, C); const int Rb = Epi::PERM ? ((R & ~31) + perm32(R & 31)) : R;
;         voffA[i] = (unsigned)(R * LD + C) * 2u; voffB[i] = (unsigned)(Rb * LD + C) * 2u; }
;     const size_t kstep = (size_t)(BK * 2);
;     const size_t hstep = (size_t)HALF * LD * 2;
;     const size_t tstep = 2 * hstep;
;     const unsigned ldsw = (unsigned)wid * 1024u;
;     const int aoff = lds_byte(wr * 64 + fr, fq * 8), boff = lds_byte(wc * 32 + fr, fq * 8);
;     ...
;         PG8_WAIT_V(2); PG8_BAR;
;         PG8_STAGE(PG8_SB(1, 0), cB + kstep, voffB); PG8_STAGE(PG8_SA(1, 0), cA + kstep, voffA); PG8_STAGE(PG8_SB(1, 1), cB + hstep + kstep, voffB);
;         PG8_WAIT_V(6); PG8_BAR;
.LBB0_1013:
	s_lshl_b32 s8, s8, 5
	s_and_b32 s14, s8, 0x60
	s_mov_b64 s[8:9], 0x80
	s_add_i32 m0, s21, 0x18000
	v_lshl_add_u64 v[8:9], v[8:9], 0, s[8:9]
	s_lshl_b32 s11, s10, 13
	s_lshl_b32 s15, s14, 7
	s_waitcnt vmcnt(2)
	s_barrier
	global_load_lds_dwordx4 v[8:9], off
	v_lshl_add_u64 v[4:5], v[4:5], 0, s[8:9]
	s_add_i32 m0, s21, 0x1a000
	s_add_i32 s33, s21, 0x8000
	s_add_i32 s34, s21, 0xa000
	global_load_lds_dwordx4 v[4:5], off
	v_lshl_add_u64 v[2:3], v[2:3], 0, s[8:9]
	s_mov_b32 m0, s33
	s_add_u32 s12, s24, 0x40080
	global_load_lds_dwordx4 v[2:3], off
	v_lshl_add_u64 v[2:3], v[6:7], 0, s[8:9]
	s_mov_b32 m0, s34
	s_addc_u32 s13, s25, 0
	global_load_lds_dwordx4 v[2:3], off
	s_add_i32 m0, s21, 0x1c000
	v_lshl_add_u64 v[2:3], s[12:13], 0, v[134:135]
	global_load_lds_dwordx4 v[2:3], off
	v_lshl_add_u64 v[2:3], s[12:13], 0, v[130:131]
	s_add_i32 m0, s21, 0x1e000
	s_sext_i32_i8 s39, s4
	global_load_lds_dwordx4 v[2:3], off
	v_lshlrev_b32_e32 v2, 1, v12
	s_movk_i32 s4, 0x3c0
	v_lshl_or_b32 v3, v204, 6, v2
	v_and_b32_e32 v4, 32, v232
	v_and_or_b32 v2, v234, s4, v2
	v_bitop3_b32 v3, v3, s11, v4 bitop3:0xde
	v_bitop3_b32 v2, s15, v2, v4 bitop3:0xf6
	v_lshlrev_b32_e32 v4, 8, v198
	v_and_b32_e32 v4, 0x38000, v4
	v_lshlrev_b32_e32 v5, 11, v230
	v_or3_b32 v4, v11, v4, v5
	s_cmpk_lt_u32 s5, 0x100
	v_add_u32_e32 v138, v4, v205
	v_lshlrev_b32_e32 v4, 4, v10
	s_mov_b32 s5, 0x10000
	v_lshl_or_b32 v1, s10, 6, v204
	s_mov_b32 s4, 0x18000
	s_mov_b32 s12, 0x1c000
	s_waitcnt vmcnt(6)
	s_cselect_b64 s[10:11], -1, 0
	v_and_b32_e32 v4, 0x78000, v4
	s_add_i32 s35, s5, 0x100
	s_mov_b32 s5, 0x14000
	v_or3_b32 v4, v11, v4, v5
	s_add_i32 s36, s5, 0x100
	s_add_i32 s37, s4, 0x100
	s_add_i32 s38, s12, 0x100
	v_or_b32_e32 v148, s14, v12
	v_mov_b32_e32 v139, v135
	v_add_u32_e32 v140, v4, v205
	v_mov_b32_e32 v141, v135
	v_mov_b64_e32 v[142:143], 0x880
	v_mov_b64_e32 v[144:145], 0x87f
	v_add_u32_e32 v149, s35, v2
	v_add_u32_e32 v150, s36, v2
	v_add_u32_e32 v151, 0x100, v3
	v_add_u32_e32 v152, s37, v2
	v_add_u32_e32 v153, s38, v2
	s_barrier
	s_branch .LBB0_1016

;     __device__ __forceinline__ bool next(int i, Unit& u) const { const int L = i * G + c; if (L >= nunits) return false; const int t = L / S, ks = L % S; u.pm = pm0 + t / nN; u.pn = t % nN; u.ko = ks * Ksub; return true; }
; #define PG8_STAGE(bufoff, gbase, voff) do { _Pragma("unroll") for (int _i = 0; _i < 2; ++_i) \
;         __builtin_amdgcn_global_load_lds((const unsigned*)((const char*)(gbase) + (voff)[_i]), (PG8_LAS unsigned*)(lds + (bufoff) + ldsw + _i * 8192), 16, 0, 0); } while (0)
; #define PG8_LDA(dst, b, h) do { _Pragma("unroll") for (int m = 0; m < 4; ++m) _Pragma("unroll") for (int k = 0; k < 2; ++k) dst[m][k] = *(const PG8_LAS bf16x8*)(lds + PG8_SA(b, h) + aoff + m * 2048 + k * 1024); } while (0)
; #define PG8_LDB(dst, b, h) do { _Pragma("unroll") for (int n = 0; n < 2; ++n) _Pragma("unroll") for (int k = 0; k < 2; ++k) dst[n][k] = *(const PG8_LAS bf16x8*)(lds + PG8_SB(b, h) + boff + n * 2048 + k * 1024); } while (0)
; template <class Epi, class Sched, bool ALIGN_EPI = false, bool SP2 = false>
; __device__ __forceinline__ void gemm_phase(PG8_LAS unsigned char* lds, const Gemm g, const Sched& S, const Epi& E) {
;     ...
;         const bool has_next = S.next(ui + 1, nxt);
;         const char* nA = has_next ? (const char*)g.A + (size_t)nxt.pm * tstep + (size_t)nxt.ko * 2 : cA; const char* nB = has_next ? (const char*)g.Bt + (size_t)nxt.pn * tstep + (size_t)nxt.ko * 2 : cB;
;         for (int t = 0; t < nt; t += 2) {
;             const bool last = (t == nt - 2);
;             const char* a1 = cA + (size_t)(t + 1) * kstep;
;             const char* a2 = last ? nA : cA + (size_t)(t + 2) * kstep; const char* b2 = last ? nB : cB + (size_t)(t + 2) * kstep;
;             const char* a3 = a2 + kstep; const char* b3 = b2 + kstep;
;             if (last && has_next) S.a_ready(nxt);
;             if constexpr (SP2) {
;             PG8_LDB(B0, 0, 0); PG8_LDB(B1, 0, 1); PG8_SCHED; PG8_LDA(At, 0, 0); PG8_STAGE(PG8_SA(1, 1), a1 + hstep, voffA);
;             PG8_WAIT_V(8); PG8_WAIT_L(0); PG8_BAR; PG8_MMA(0, 0, At, B0); PG8_MMA(0, 1, At, B1); PG8_BAR; PG8_SCHED;
;             PG8_LDA(At, 0, 1); PG8_STAGE(PG8_SB(0, 0), b2, voffB); PG8_STAGE(PG8_SB(0, 1), b2 + hstep, voffB); PG8_STAGE(PG8_SA(0, 0), a2, voffA);
;             PG8_WAIT_V(8); PG8_WAIT_L(0); PG8_BAR; PG8_MMA(1, 0, At, B0); PG8_MMA(1, 1, At, B1); PG8_BAR; PG8_SCHED;
.LBB0_1019:
	ds_read_b128 v[154:157], v149
	ds_read_b128 v[158:161], v149 offset:1024
	ds_read_b128 v[162:165], v149 offset:2048
	ds_read_b128 v[166:169], v149 offset:3072
	ds_read_b128 v[170:173], v150
	ds_read_b128 v[174:177], v150 offset:1024
	ds_read_b128 v[178:181], v150 offset:2048
	ds_read_b128 v[182:185], v150 offset:3072
	s_add_u32 s24, s22, 0xfffc0080
	s_addc_u32 s25, s23, -1
	s_cmp_eq_u32 s44, 12
	s_cselect_b32 s27, s15, s25
	s_cselect_b32 s26, s40, s24
	s_cselect_b32 s25, s13, s43
	s_cselect_b32 s24, s41, s42
	v_lshl_add_u64 v[146:147], s[22:23], 0, v[138:139]
	s_add_i32 m0, s21, 0xc000
	ds_read_b128 v[186:189], v151
	ds_read_b128 v[190:193], v151 offset:1024
	ds_read_b128 v[194:197], v151 offset:2048
	ds_read_b128 v[208:211], v151 offset:3072
	ds_read_b128 v[212:215], v151 offset:4096
	ds_read_b128 v[216:219], v151 offset:5120
	ds_read_b128 v[220:223], v151 offset:6144
	ds_read_b128 v[224:227], v151 offset:7168
	global_load_lds_dwordx4 v[146:147], off
	v_lshl_add_u64 v[146:147], s[22:23], 0, v[140:141]
	s_add_i32 m0, s21, 0xe000
	s_nop 0
	global_load_lds_dwordx4 v[146:147], off
	s_waitcnt vmcnt(8)
	s_waitcnt lgkmcnt(0)
	s_barrier
	s_setprio 1
	s_waitcnt lgkmcnt(0)
	v_mfma_f32_16x16x32_bf16 v[126:129], v[154:157], v[186:189], v[126:129]
	v_mfma_f32_16x16x32_bf16 v[122:125], v[162:165], v[186:189], v[122:125]
	v_mfma_f32_16x16x32_bf16 v[110:113], v[154:157], v[194:197], v[110:113]
	v_mfma_f32_16x16x32_bf16 v[106:109], v[162:165], v[194:197], v[106:109]
	v_mfma_f32_16x16x32_bf16 v[94:97], v[154:157], v[212:215], v[94:97]
	v_mfma_f32_16x16x32_bf16 v[90:93], v[162:165], v[212:215], v[90:93]
	v_mfma_f32_16x16x32_bf16 v[78:81], v[154:157], v[220:223], v[78:81]
	v_mfma_f32_16x16x32_bf16 v[74:77], v[162:165], v[220:223], v[74:77]
	v_mfma_f32_16x16x32_bf16 v[126:129], v[158:161], v[190:193], v[126:129]
	v_mfma_f32_16x16x32_bf16 v[122:125], v[166:169], v[190:193], v[122:125]
	v_mfma_f32_16x16x32_bf16 v[110:113], v[158:161], v[208:211], v[110:113]
	v_mfma_f32_16x16x32_bf16 v[106:109], v[166:169], v[208:211], v[106:109]
	v_mfma_f32_16x16x32_bf16 v[94:97], v[158:161], v[216:219], v[94:97]
	v_mfma_f32_16x16x32_bf16 v[90:93], v[166:169], v[216:219], v[90:93]
	v_mfma_f32_16x16x32_bf16 v[78:81], v[158:161], v[224:227], v[78:81]
	v_mfma_f32_16x16x32_bf16 v[74:77], v[166:169], v[224:227], v[74:77]
	s_setprio 0
	s_setprio 1
	v_mfma_f32_16x16x32_bf16 v[118:121], v[170:173], v[186:189], v[118:121]
	v_mfma_f32_16x16x32_bf16 v[114:117], v[178:181], v[186:189], v[114:117]
	v_mfma_f32_16x16x32_bf16 v[102:105], v[170:173], v[194:197], v[102:105]
	v_mfma_f32_16x16x32_bf16 v[98:101], v[178:181], v[194:197], v[98:101]
	v_mfma_f32_16x16x32_bf16 v[86:89], v[170:173], v[212:215], v[86:89]
	v_mfma_f32_16x16x32_bf16 v[82:85], v[178:181], v[212:215], v[82:85]
	v_mfma_f32_16x16x32_bf16 v[70:73], v[170:173], v[220:223], v[70:73]
	v_mfma_f32_16x16x32_bf16 v[66:69], v[178:181], v[220:223], v[66:69]
	v_mfma_f32_16x16x32_bf16 v[118:121], v[174:177], v[190:193], v[118:121]
	v_mfma_f32_16x16x32_bf16 v[114:117], v[182:185], v[190:193], v[114:117]
	v_mfma_f32_16x16x32_bf16 v[102:105], v[174:177], v[208:211], v[102:105]
	v_mfma_f32_16x16x32_bf16 v[98:101], v[182:185], v[208:211], v[98:101]
	v_mfma_f32_16x16x32_bf16 v[86:89], v[174:177], v[216:219], v[86:89]
	v_mfma_f32_16x16x32_bf16 v[82:85], v[182:185], v[216:219], v[82:85]
	v_mfma_f32_16x16x32_bf16 v[70:73], v[174:177], v[224:227], v[70:73]
	v_mfma_f32_16x16x32_bf16 v[66:69], v[182:185], v[224:227], v[66:69]
	s_setprio 0
	s_barrier
	s_add_i32 s45, s35, s2
	v_lshl_add_u64 v[146:147], s[24:25], 0, v[134:135]
	s_mov_b32 m0, s45
	ds_read_b128 v[186:189], v151 offset:16384
	ds_read_b128 v[190:193], v151 offset:17408
	ds_read_b128 v[194:197], v151 offset:18432
	ds_read_b128 v[208:211], v151 offset:19456
	ds_read_b128 v[212:215], v151 offset:20480
	ds_read_b128 v[216:219], v151 offset:21504
	ds_read_b128 v[220:223], v151 offset:22528
	ds_read_b128 v[224:227], v151 offset:23552
	global_load_lds_dwordx4 v[146:147], off
	s_add_i32 m0, s45, 0x2000
	s_add_u32 s46, s24, 0x40000
	v_lshl_add_u64 v[228:229], s[24:25], 0, v[130:131]
	s_addc_u32 s47, s25, 0
	s_add_i32 s45, s36, s2
	global_load_lds_dwordx4 v[228:229], off
	v_lshl_add_u64 v[236:237], s[46:47], 0, v[134:135]
	s_mov_b32 m0, s45
	v_lshl_add_u64 v[238:239], s[26:27], 0, v[132:133]
	global_load_lds_dwordx4 v[236:237], off
	v_lshl_add_u64 v[236:237], s[46:47], 0, v[130:131]
	s_add_i32 m0, s45, 0x2000
	s_nop 0
	global_load_lds_dwordx4 v[236:237], off
	v_lshl_add_u64 v[236:237], s[26:27], 0, v[136:137]
	s_mov_b32 m0, s21
	s_nop 0
	global_load_lds_dwordx4 v[236:237], off
	s_mov_b32 m0, s28
	s_nop 0
	global_load_lds_dwordx4 v[238:239], off
	s_waitcnt vmcnt(8)
	s_waitcnt lgkmcnt(0)
	s_barrier
; #define PG8_STAGE(bufoff, gbase, voff) do { _Pragma("unroll") for (int _i = 0; _i < 2; ++_i) \
;         __builtin_amdgcn_global_load_lds((const unsigned*)((const char*)(gbase) + (voff)[_i]), (PG8_LAS unsigned*)(lds + (bufoff) + ldsw + _i * 8192), 16, 0, 0); } while (0)
; #define PG8_LDA(dst, b, h) do { _Pragma("unroll") for (int m = 0; m < 4; ++m) _Pragma("unroll") for (int k = 0; k < 2; ++k) dst[m][k] = *(const PG8_LAS bf16x8*)(lds + PG8_SA(b, h) + aoff + m * 2048 + k * 1024); } while (0)
; #define PG8_LDB(dst, b, h) do { _Pragma("unroll") for (int n = 0; n < 2; ++n) _Pragma("unroll") for (int k = 0; k < 2; ++k) dst[n][k] = *(const PG8_LAS bf16x8*)(lds + PG8_SB(b, h) + boff + n * 2048 + k * 1024); } while (0)
; #define PG8_MMA(ai, bj, At, Bt) do { __builtin_amdgcn_s_setprio(1); _Pragma("unroll") for (int m = 0; m < 4; ++m) _Pragma("unroll") for (int n = 0; n < 2; ++n) _Pragma("unroll") for (int k = 0; k < 2; ++k) \
;         acc[ai][bj][m][n] = __builtin_amdgcn_mfma_f32_16x16x32_bf16(Bt[n][k], At[m][k], acc[ai][bj][m][n], 0, 0, 0); __builtin_amdgcn_s_setprio(0); } while (0)
; #define PG8_WAIT_V(n) asm volatile("s_waitcnt vmcnt(" #n ")" ::: "memory")
; #define PG8_WAIT_L(n) asm volatile("s_waitcnt lgkmcnt(" #n ")" ::: "memory")
; #define PG8_BAR __builtin_amdgcn_s_barrier()
; #define PG8_SCHED __builtin_amdgcn_sched_barrier(0)
; template <class Epi, class Sched, bool ALIGN_EPI = false, bool SP2 = false>
; __device__ __forceinline__ void gemm_phase(PG8_LAS unsigned char* lds, const Gemm g, const Sched& S, const Epi& E) {
;     ...
;             PG8_WAIT_V(8); PG8_WAIT_L(0); PG8_BAR; PG8_MMA(1, 0, At, B0); PG8_MMA(1, 1, At, B1); PG8_BAR; PG8_SCHED;
;             PG8_LDB(B0, 1, 0); PG8_LDB(B1, 1, 1); PG8_SCHED; PG8_LDA(At, 1, 0); PG8_STAGE(PG8_SA(0, 1), a2 + hstep, voffA);
;             PG8_WAIT_V(8); PG8_WAIT_L(0); PG8_BAR; PG8_MMA(0, 0, At, B0); PG8_MMA(0, 1, At, B1); PG8_BAR; PG8_SCHED;
	s_setprio 1
	s_waitcnt lgkmcnt(0)
	v_mfma_f32_16x16x32_bf16 v[62:65], v[154:157], v[186:189], v[62:65]
	v_mfma_f32_16x16x32_bf16 v[58:61], v[162:165], v[186:189], v[58:61]
	v_mfma_f32_16x16x32_bf16 v[46:49], v[154:157], v[194:197], v[46:49]
	v_mfma_f32_16x16x32_bf16 v[42:45], v[162:165], v[194:197], v[42:45]
	v_mfma_f32_16x16x32_bf16 v[30:33], v[154:157], v[212:215], v[30:33]
	v_mfma_f32_16x16x32_bf16 v[26:29], v[162:165], v[212:215], v[26:29]
	v_mfma_f32_16x16x32_bf16 v[14:17], v[154:157], v[220:223], v[14:17]
	v_mfma_f32_16x16x32_bf16 v[10:13], v[162:165], v[220:223], v[10:13]
	v_mfma_f32_16x16x32_bf16 v[62:65], v[158:161], v[190:193], v[62:65]
	v_mfma_f32_16x16x32_bf16 v[58:61], v[166:169], v[190:193], v[58:61]
	v_mfma_f32_16x16x32_bf16 v[46:49], v[158:161], v[208:211], v[46:49]
	v_mfma_f32_16x16x32_bf16 v[42:45], v[166:169], v[208:211], v[42:45]
	v_mfma_f32_16x16x32_bf16 v[30:33], v[158:161], v[216:219], v[30:33]
	v_mfma_f32_16x16x32_bf16 v[26:29], v[166:169], v[216:219], v[26:29]
	v_mfma_f32_16x16x32_bf16 v[14:17], v[158:161], v[224:227], v[14:17]
	v_mfma_f32_16x16x32_bf16 v[10:13], v[166:169], v[224:227], v[10:13]
	s_setprio 0
	s_setprio 1
	v_mfma_f32_16x16x32_bf16 v[54:57], v[170:173], v[186:189], v[54:57]
	v_mfma_f32_16x16x32_bf16 v[50:53], v[178:181], v[186:189], v[50:53]
	v_mfma_f32_16x16x32_bf16 v[38:41], v[170:173], v[194:197], v[38:41]
	v_mfma_f32_16x16x32_bf16 v[34:37], v[178:181], v[194:197], v[34:37]
	v_mfma_f32_16x16x32_bf16 v[22:25], v[170:173], v[212:215], v[22:25]
	v_mfma_f32_16x16x32_bf16 v[18:21], v[178:181], v[212:215], v[18:21]
	v_mfma_f32_16x16x32_bf16 v[6:9], v[170:173], v[220:223], v[6:9]
	v_mfma_f32_16x16x32_bf16 v[2:5], v[178:181], v[220:223], v[2:5]
	v_mfma_f32_16x16x32_bf16 v[54:57], v[174:177], v[190:193], v[54:57]
	v_mfma_f32_16x16x32_bf16 v[50:53], v[182:185], v[190:193], v[50:53]
	v_mfma_f32_16x16x32_bf16 v[38:41], v[174:177], v[208:211], v[38:41]
	v_mfma_f32_16x16x32_bf16 v[34:37], v[182:185], v[208:211], v[34:37]
	v_mfma_f32_16x16x32_bf16 v[22:25], v[174:177], v[216:219], v[22:25]
	v_mfma_f32_16x16x32_bf16 v[18:21], v[182:185], v[216:219], v[18:21]
	v_mfma_f32_16x16x32_bf16 v[6:9], v[174:177], v[224:227], v[6:9]
	v_mfma_f32_16x16x32_bf16 v[2:5], v[182:185], v[224:227], v[2:5]
	s_setprio 0
	s_barrier
	ds_read_b128 v[154:157], v152
	ds_read_b128 v[158:161], v152 offset:1024
	ds_read_b128 v[162:165], v152 offset:2048
	ds_read_b128 v[166:169], v152 offset:3072
	ds_read_b128 v[170:173], v153
	ds_read_b128 v[174:177], v153 offset:1024
	ds_read_b128 v[178:181], v153 offset:2048
	ds_read_b128 v[182:185], v153 offset:3072
	s_add_u32 s26, s26, 0x40000
	s_addc_u32 s27, s27, 0
	s_mov_b32 m0, s29
	v_lshl_add_u64 v[240:241], s[26:27], 0, v[136:137]
	ds_read_b128 v[186:189], v151 offset:32768
	ds_read_b128 v[190:193], v151 offset:33792
	ds_read_b128 v[194:197], v151 offset:34816
	ds_read_b128 v[208:211], v151 offset:35840
	ds_read_b128 v[212:215], v151 offset:36864
	ds_read_b128 v[216:219], v151 offset:37888
	ds_read_b128 v[220:223], v151 offset:38912
	ds_read_b128 v[224:227], v151 offset:39936
	global_load_lds_dwordx4 v[240:241], off
	v_lshl_add_u64 v[240:241], s[26:27], 0, v[132:133]
	s_mov_b32 m0, s30
	s_nop 0
	global_load_lds_dwordx4 v[240:241], off
	s_waitcnt vmcnt(8)
	s_waitcnt lgkmcnt(0)
	s_barrier
	s_setprio 1
	s_waitcnt lgkmcnt(0)
	v_mfma_f32_16x16x32_bf16 v[126:129], v[154:157], v[186:189], v[126:129]
	v_mfma_f32_16x16x32_bf16 v[122:125], v[162:165], v[186:189], v[122:125]
	v_mfma_f32_16x16x32_bf16 v[110:113], v[154:157], v[194:197], v[110:113]
	v_mfma_f32_16x16x32_bf16 v[106:109], v[162:165], v[194:197], v[106:109]
	v_mfma_f32_16x16x32_bf16 v[94:97], v[154:157], v[212:215], v[94:97]
	v_mfma_f32_16x16x32_bf16 v[90:93], v[162:165], v[212:215], v[90:93]
	v_mfma_f32_16x16x32_bf16 v[78:81], v[154:157], v[220:223], v[78:81]
	v_mfma_f32_16x16x32_bf16 v[74:77], v[162:165], v[220:223], v[74:77]
	v_mfma_f32_16x16x32_bf16 v[126:129], v[158:161], v[190:193], v[126:129]
	v_mfma_f32_16x16x32_bf16 v[122:125], v[166:169], v[190:193], v[122:125]
	v_mfma_f32_16x16x32_bf16 v[110:113], v[158:161], v[208:211], v[110:113]
	v_mfma_f32_16x16x32_bf16 v[106:109], v[166:169], v[208:211], v[106:109]
	v_mfma_f32_16x16x32_bf16 v[94:97], v[158:161], v[216:219], v[94:97]
	v_mfma_f32_16x16x32_bf16 v[90:93], v[166:169], v[216:219], v[90:93]
	v_mfma_f32_16x16x32_bf16 v[78:81], v[158:161], v[224:227], v[78:81]
	v_mfma_f32_16x16x32_bf16 v[74:77], v[166:169], v[224:227], v[74:77]
	s_setprio 0
	s_setprio 1
	v_mfma_f32_16x16x32_bf16 v[118:121], v[170:173], v[186:189], v[118:121]
	v_mfma_f32_16x16x32_bf16 v[114:117], v[178:181], v[186:189], v[114:117]
	v_mfma_f32_16x16x32_bf16 v[102:105], v[170:173], v[194:197], v[102:105]
	v_mfma_f32_16x16x32_bf16 v[98:101], v[178:181], v[194:197], v[98:101]
	v_mfma_f32_16x16x32_bf16 v[86:89], v[170:173], v[212:215], v[86:89]
	v_mfma_f32_16x16x32_bf16 v[82:85], v[178:181], v[212:215], v[82:85]
	v_mfma_f32_16x16x32_bf16 v[70:73], v[170:173], v[220:223], v[70:73]
	v_mfma_f32_16x16x32_bf16 v[66:69], v[178:181], v[220:223], v[66:69]
	v_mfma_f32_16x16x32_bf16 v[118:121], v[174:177], v[190:193], v[118:121]
	v_mfma_f32_16x16x32_bf16 v[114:117], v[182:185], v[190:193], v[114:117]
	v_mfma_f32_16x16x32_bf16 v[102:105], v[174:177], v[208:211], v[102:105]
	v_mfma_f32_16x16x32_bf16 v[98:101], v[182:185], v[208:211], v[98:101]
	v_mfma_f32_16x16x32_bf16 v[86:89], v[174:177], v[216:219], v[86:89]
	v_mfma_f32_16x16x32_bf16 v[82:85], v[182:185], v[216:219], v[82:85]
	v_mfma_f32_16x16x32_bf16 v[70:73], v[174:177], v[224:227], v[70:73]
	v_mfma_f32_16x16x32_bf16 v[66:69], v[182:185], v[224:227], v[66:69]
	s_setprio 0
	s_barrier
; #define PG8_STAGE(bufoff, gbase, voff) do { _Pragma("unroll") for (int _i = 0; _i < 2; ++_i) \
;         __builtin_amdgcn_global_load_lds((const unsigned*)((const char*)(gbase) + (voff)[_i]), (PG8_LAS unsigned*)(lds + (bufoff) + ldsw + _i * 8192), 16, 0, 0); } while (0)
; #define PG8_LDA(dst, b, h) do { _Pragma("unroll") for (int m = 0; m < 4; ++m) _Pragma("unroll") for (int k = 0; k < 2; ++k) dst[m][k] = *(const PG8_LAS bf16x8*)(lds + PG8_SA(b, h) + aoff + m * 2048 + k * 1024); } while (0)
; #define PG8_MMA(ai, bj, At, Bt) do { __builtin_amdgcn_s_setprio(1); _Pragma("unroll") for (int m = 0; m < 4; ++m) _Pragma("unroll") for (int n = 0; n < 2; ++n) _Pragma("unroll") for (int k = 0; k < 2; ++k) \
;         acc[ai][bj][m][n] = __builtin_amdgcn_mfma_f32_16x16x32_bf16(Bt[n][k], At[m][k], acc[ai][bj][m][n], 0, 0, 0); __builtin_amdgcn_s_setprio(0); } while (0)
; #define PG8_WAIT_V(n) asm volatile("s_waitcnt vmcnt(" #n ")" ::: "memory")
; #define PG8_WAIT_L(n) asm volatile("s_waitcnt lgkmcnt(" #n ")" ::: "memory")
; #define PG8_BAR __builtin_amdgcn_s_barrier()
; #define PG8_SCHED __builtin_amdgcn_sched_barrier(0)
; template <class Epi, class Sched, bool ALIGN_EPI = false, bool SP2 = false>
; __device__ __forceinline__ void gemm_phase(PG8_LAS unsigned char* lds, const Gemm g, const Sched& S, const Epi& E) {
;     ...
;         for (int t = 0; t < nt; t += 2) {
;     ...
;             PG8_LDA(At, 1, 1); PG8_STAGE(PG8_SB(1, 0), b3, voffB); PG8_STAGE(PG8_SB(1, 1), b3 + hstep, voffB); PG8_STAGE(PG8_SA(1, 0), a3, voffA);
;             PG8_WAIT_V(8); PG8_WAIT_L(0); PG8_BAR; PG8_MMA(1, 0, At, B0); PG8_MMA(1, 1, At, B1); PG8_BAR; PG8_SCHED;
;     ...
;         if constexpr (ALIGN_EPI) { if (wr == 0) PG8_BAR; }
	s_add_i32 s26, s37, s2
	v_lshl_add_u64 v[146:147], v[146:147], 0, s[8:9]
	s_mov_b32 m0, s26
	ds_read_b128 v[186:189], v151 offset:49152
	ds_read_b128 v[190:193], v151 offset:50176
	ds_read_b128 v[194:197], v151 offset:51200
	ds_read_b128 v[208:211], v151 offset:52224
	ds_read_b128 v[212:215], v151 offset:53248
	ds_read_b128 v[216:219], v151 offset:54272
	ds_read_b128 v[220:223], v151 offset:55296
	ds_read_b128 v[224:227], v151 offset:56320
	global_load_lds_dwordx4 v[146:147], off
	s_add_i32 m0, s26, 0x2000
	s_add_u32 s24, s24, 0x40080
	v_lshl_add_u64 v[146:147], v[228:229], 0, s[8:9]
	s_addc_u32 s25, s25, 0
	s_add_i32 s26, s38, s2
	global_load_lds_dwordx4 v[146:147], off
	v_lshl_add_u64 v[146:147], s[24:25], 0, v[134:135]
	s_mov_b32 m0, s26
	s_nop 0
	global_load_lds_dwordx4 v[146:147], off
	v_lshl_add_u64 v[146:147], s[24:25], 0, v[130:131]
	s_add_i32 m0, s26, 0x2000
	s_nop 0
	global_load_lds_dwordx4 v[146:147], off
	v_lshl_add_u64 v[146:147], v[236:237], 0, s[8:9]
	s_mov_b32 m0, s33
	s_nop 0
	global_load_lds_dwordx4 v[146:147], off
	v_lshl_add_u64 v[146:147], v[238:239], 0, s[8:9]
	s_mov_b32 m0, s34
	s_nop 0
	global_load_lds_dwordx4 v[146:147], off
	s_waitcnt vmcnt(8)
	s_waitcnt lgkmcnt(0)
	s_barrier
	s_setprio 1
	s_waitcnt lgkmcnt(0)
	v_mfma_f32_16x16x32_bf16 v[62:65], v[154:157], v[186:189], v[62:65]
	v_mfma_f32_16x16x32_bf16 v[58:61], v[162:165], v[186:189], v[58:61]
	v_mfma_f32_16x16x32_bf16 v[46:49], v[154:157], v[194:197], v[46:49]
	v_mfma_f32_16x16x32_bf16 v[42:45], v[162:165], v[194:197], v[42:45]
	v_mfma_f32_16x16x32_bf16 v[30:33], v[154:157], v[212:215], v[30:33]
	v_mfma_f32_16x16x32_bf16 v[26:29], v[162:165], v[212:215], v[26:29]
	v_mfma_f32_16x16x32_bf16 v[14:17], v[154:157], v[220:223], v[14:17]
	v_mfma_f32_16x16x32_bf16 v[10:13], v[162:165], v[220:223], v[10:13]
	v_mfma_f32_16x16x32_bf16 v[62:65], v[158:161], v[190:193], v[62:65]
	v_mfma_f32_16x16x32_bf16 v[58:61], v[166:169], v[190:193], v[58:61]
	v_mfma_f32_16x16x32_bf16 v[46:49], v[158:161], v[208:211], v[46:49]
	v_mfma_f32_16x16x32_bf16 v[42:45], v[166:169], v[208:211], v[42:45]
	v_mfma_f32_16x16x32_bf16 v[30:33], v[158:161], v[216:219], v[30:33]
	v_mfma_f32_16x16x32_bf16 v[26:29], v[166:169], v[216:219], v[26:29]
	v_mfma_f32_16x16x32_bf16 v[14:17], v[158:161], v[224:227], v[14:17]
	v_mfma_f32_16x16x32_bf16 v[10:13], v[166:169], v[224:227], v[10:13]
	s_setprio 0
	s_setprio 1
	v_mfma_f32_16x16x32_bf16 v[54:57], v[170:173], v[186:189], v[54:57]
	v_mfma_f32_16x16x32_bf16 v[50:53], v[178:181], v[186:189], v[50:53]
	v_mfma_f32_16x16x32_bf16 v[38:41], v[170:173], v[194:197], v[38:41]
	v_mfma_f32_16x16x32_bf16 v[34:37], v[178:181], v[194:197], v[34:37]
	v_mfma_f32_16x16x32_bf16 v[22:25], v[170:173], v[212:215], v[22:25]
	v_mfma_f32_16x16x32_bf16 v[18:21], v[178:181], v[212:215], v[18:21]
	v_mfma_f32_16x16x32_bf16 v[6:9], v[170:173], v[220:223], v[6:9]
	v_mfma_f32_16x16x32_bf16 v[2:5], v[178:181], v[220:223], v[2:5]
	v_mfma_f32_16x16x32_bf16 v[54:57], v[174:177], v[190:193], v[54:57]
	v_mfma_f32_16x16x32_bf16 v[50:53], v[182:185], v[190:193], v[50:53]
	v_mfma_f32_16x16x32_bf16 v[38:41], v[174:177], v[208:211], v[38:41]
	v_mfma_f32_16x16x32_bf16 v[34:37], v[182:185], v[208:211], v[34:37]
	v_mfma_f32_16x16x32_bf16 v[22:25], v[174:177], v[216:219], v[22:25]
	v_mfma_f32_16x16x32_bf16 v[18:21], v[182:185], v[216:219], v[18:21]
	v_mfma_f32_16x16x32_bf16 v[6:9], v[174:177], v[224:227], v[6:9]
	v_mfma_f32_16x16x32_bf16 v[2:5], v[182:185], v[224:227], v[2:5]
	s_setprio 0
	s_barrier
	s_add_i32 s44, s44, 2
	s_add_u32 s22, s22, 0x100
	s_addc_u32 s23, s23, 0
	s_add_u32 s42, s42, 0x100
	s_addc_u32 s43, s43, 0
	s_cmp_gt_u32 s44, 13
	s_cbranch_scc0 .LBB0_1019
	s_and_b64 vcc, exec, s[10:11]
	s_cbranch_vccz .LBB0_1022
	s_barrier

; #define PG8_STAGE(bufoff, gbase, voff) do { _Pragma("unroll") for (int _i = 0; _i < 2; ++_i) \
;         __builtin_amdgcn_global_load_lds((const unsigned*)((const char*)(gbase) + (voff)[_i]), (PG8_LAS unsigned*)(lds + (bufoff) + ldsw + _i * 8192), 16, 0, 0); } while (0)
; #define PG8_WAIT_V(n) asm volatile("s_waitcnt vmcnt(" #n ")" ::: "memory")
; #define PG8_BAR __builtin_amdgcn_s_barrier()
; template <class Epi, class Sched, bool ALIGN_EPI = false, bool SP2 = false>
; __device__ __forceinline__ void gemm_phase(PG8_LAS unsigned char* lds, const Gemm g, const Sched& S, const Epi& E) {
;     ...
;     for (int i = 0; i < 2; ++i) { int R, C; stage_rc(tid * 16 + i * 8192, R, C); const int Rb = Epi::PERM ? ((R & ~31) + perm32(R & 31)) : R;
;         voffA[i] = (unsigned)(R * LD + C) * 2u; voffB[i] = (unsigned)(Rb * LD + C) * 2u; }
;     const size_t kstep = (size_t)(BK * 2);
;     const size_t hstep = (size_t)HALF * LD * 2;
;     const size_t tstep = 2 * hstep;
;     const unsigned ldsw = (unsigned)wid * 1024u;
;     const int aoff = lds_byte(wr * 64 + fr, fq * 8), boff = lds_byte(wc * 32 + fr, fq * 8);
;     ...
;         PG8_WAIT_V(2); PG8_BAR;
;         PG8_STAGE(PG8_SB(1, 0), cB + kstep, voffB); PG8_STAGE(PG8_SA(1, 0), cA + kstep, voffA); PG8_STAGE(PG8_SB(1, 1), cB + hstep + kstep, voffB);
;         PG8_WAIT_V(6); PG8_BAR;
.LBB0_1088:
	s_lshl_b32 s8, s8, 5
	s_and_b32 s15, s8, 0x60
	s_mov_b64 s[8:9], 0x80
	s_add_i32 m0, s3, 0x18000
	v_lshl_add_u64 v[8:9], v[8:9], 0, s[8:9]
	s_lshl_b32 s11, s5, 13
	s_lshl_b32 s18, s15, 7
	s_waitcnt vmcnt(2)
	s_barrier
	global_load_lds_dwordx4 v[8:9], off
	v_lshl_add_u64 v[4:5], v[4:5], 0, s[8:9]
	s_add_i32 m0, s3, 0x1a000
	s_add_i32 s31, s3, 0x8000
	s_add_i32 s33, s3, 0xa000
	global_load_lds_dwordx4 v[4:5], off
	v_lshl_add_u64 v[2:3], v[2:3], 0, s[8:9]
	s_mov_b32 m0, s31
	s_add_u32 s16, s26, 0x100080
	global_load_lds_dwordx4 v[2:3], off
	v_lshl_add_u64 v[2:3], v[6:7], 0, s[8:9]
	s_mov_b32 m0, s33
	s_addc_u32 s17, s27, 0
	global_load_lds_dwordx4 v[2:3], off
	s_add_i32 m0, s3, 0x1c000
	v_lshl_add_u64 v[2:3], s[16:17], 0, v[134:135]
	global_load_lds_dwordx4 v[2:3], off
	v_lshl_add_u64 v[2:3], s[16:17], 0, v[136:137]
	s_add_i32 m0, s3, 0x1e000
	v_lshlrev_b32_e32 v5, 2, v204
	global_load_lds_dwordx4 v[2:3], off
	v_lshrrev_b32_e32 v2, 1, v198
	v_and_b32_e32 v2, 24, v2
	v_lshlrev_b32_e32 v3, 1, v2
	v_lshl_or_b32 v4, v204, 6, v3
	v_and_b32_e32 v5, 32, v5
	v_or_b32_e32 v156, s15, v2
	v_lshlrev_b32_e32 v2, 10, v198
	v_bitop3_b32 v4, v4, s11, v5 bitop3:0xde
	v_and_b32_e32 v2, 0xe0000, v2
	v_lshlrev_b32_e32 v5, 13, v230
	v_or3_b32 v2, v1, v2, v5
	v_add_u32_e32 v138, v2, v205
	v_lshlrev_b32_e32 v2, 6, v152
	s_sext_i32_i8 s39, s4
	v_lshl_or_b32 v155, s5, 6, v204
	v_or_b32_e32 v3, v3, v153
	s_mov_b32 s4, 0x18000
	s_mov_b32 s5, 0x1c000
	s_waitcnt vmcnt(6)
	s_cmpk_lt_u32 s10, 0x100
	v_and_b32_e32 v2, 0x1e0000, v2
	v_bitop3_b32 v3, s18, v3, v154 bitop3:0xf6
	s_cselect_b64 s[10:11], -1, 0
	v_or3_b32 v2, v1, v2, v5
	s_add_i32 s35, s12, 0x100
	s_add_i32 s36, s14, 0x100
	s_add_i32 s37, s4, 0x100
	s_add_i32 s38, s5, 0x100
	v_mov_b32_e32 v139, v135
	v_add_u32_e32 v140, v2, v205
	v_mov_b32_e32 v141, v135
	s_mov_b32 s34, 0
	v_mov_b64_e32 v[142:143], 0x200
	v_mov_b64_e32 v[144:145], 0x1ff
	v_add_u32_e32 v157, s35, v3
	v_add_u32_e32 v158, s36, v3
	v_add_u32_e32 v159, 0x100, v4
	s_mov_b32 s12, 0x3fb504f3
	v_add_u32_e32 v160, s37, v3
	v_add_u32_e32 v161, s38, v3
	s_barrier
	s_branch .LBB0_1091

;     __device__ __forceinline__ bool next(int i, Unit& u) const { const int L = i * G + c; if (L >= nunits) return false; const int t = L / S, ks = L % S; u.pm = pm0 + t / nN; u.pn = t % nN; u.ko = ks * Ksub; return true; }
; #define PG8_STAGE(bufoff, gbase, voff) do { _Pragma("unroll") for (int _i = 0; _i < 2; ++_i) \
;         __builtin_amdgcn_global_load_lds((const unsigned*)((const char*)(gbase) + (voff)[_i]), (PG8_LAS unsigned*)(lds + (bufoff) + ldsw + _i * 8192), 16, 0, 0); } while (0)
; #define PG8_LDA(dst, b, h) do { _Pragma("unroll") for (int m = 0; m < 4; ++m) _Pragma("unroll") for (int k = 0; k < 2; ++k) dst[m][k] = *(const PG8_LAS bf16x8*)(lds + PG8_SA(b, h) + aoff + m * 2048 + k * 1024); } while (0)
; #define PG8_LDB(dst, b, h) do { _Pragma("unroll") for (int n = 0; n < 2; ++n) _Pragma("unroll") for (int k = 0; k < 2; ++k) dst[n][k] = *(const PG8_LAS bf16x8*)(lds + PG8_SB(b, h) + boff + n * 2048 + k * 1024); } while (0)
; template <class Epi, class Sched, bool ALIGN_EPI = false, bool SP2 = false>
; __device__ __forceinline__ void gemm_phase(PG8_LAS unsigned char* lds, const Gemm g, const Sched& S, const Epi& E) {
;     ...
;         const bool has_next = S.next(ui + 1, nxt);
;         const char* nA = has_next ? (const char*)g.A + (size_t)nxt.pm * tstep + (size_t)nxt.ko * 2 : cA; const char* nB = has_next ? (const char*)g.Bt + (size_t)nxt.pn * tstep + (size_t)nxt.ko * 2 : cB;
;         for (int t = 0; t < nt; t += 2) {
;             const bool last = (t == nt - 2);
;             const char* a1 = cA + (size_t)(t + 1) * kstep;
;             const char* a2 = last ? nA : cA + (size_t)(t + 2) * kstep; const char* b2 = last ? nB : cB + (size_t)(t + 2) * kstep;
;             const char* a3 = a2 + kstep; const char* b3 = b2 + kstep;
;             if (last && has_next) S.a_ready(nxt);
;             if constexpr (SP2) {
;             PG8_LDB(B0, 0, 0); PG8_LDB(B1, 0, 1); PG8_SCHED; PG8_LDA(At, 0, 0); PG8_STAGE(PG8_SA(1, 1), a1 + hstep, voffA);
;             PG8_WAIT_V(8); PG8_WAIT_L(0); PG8_BAR; PG8_MMA(0, 0, At, B0); PG8_MMA(0, 1, At, B1); PG8_BAR; PG8_SCHED;
;             PG8_LDA(At, 0, 1); PG8_STAGE(PG8_SB(0, 0), b2, voffB); PG8_STAGE(PG8_SB(0, 1), b2 + hstep, voffB); PG8_STAGE(PG8_SA(0, 0), a2, voffA);
;             PG8_WAIT_V(8); PG8_WAIT_L(0); PG8_BAR; PG8_MMA(1, 0, At, B0); PG8_MMA(1, 1, At, B1); PG8_BAR; PG8_SCHED;
.LBB0_1098:
	ds_read_b128 v[146:149], v157
	ds_read_b128 v[162:165], v157 offset:1024
	ds_read_b128 v[166:169], v157 offset:2048
	ds_read_b128 v[170:173], v157 offset:3072
	ds_read_b128 v[174:177], v158
	ds_read_b128 v[178:181], v158 offset:1024
	ds_read_b128 v[182:185], v158 offset:2048
	ds_read_b128 v[186:189], v158 offset:3072
	s_add_u32 s26, s24, 0xfff00080
	s_addc_u32 s27, s25, -1
	s_cmp_eq_u32 s44, 60
	s_cselect_b32 s29, s17, s27
	s_cselect_b32 s28, s40, s26
	s_cselect_b32 s27, s15, s43
	s_cselect_b32 s26, s41, s42
	v_lshl_add_u64 v[150:151], s[24:25], 0, v[138:139]
	s_add_i32 m0, s3, 0xc000
	ds_read_b128 v[190:193], v159
	ds_read_b128 v[194:197], v159 offset:1024
	ds_read_b128 v[208:211], v159 offset:2048
	ds_read_b128 v[212:215], v159 offset:3072
	ds_read_b128 v[216:219], v159 offset:4096
	ds_read_b128 v[220:223], v159 offset:5120
	ds_read_b128 v[224:227], v159 offset:6144
	ds_read_b128 v[236:239], v159 offset:7168
	global_load_lds_dwordx4 v[150:151], off
	v_lshl_add_u64 v[150:151], s[24:25], 0, v[140:141]
	s_add_i32 m0, s3, 0xe000
	s_nop 0
	global_load_lds_dwordx4 v[150:151], off
	s_waitcnt vmcnt(8)
	s_waitcnt lgkmcnt(0)
	s_barrier
	s_setprio 1
	s_waitcnt lgkmcnt(0)
	v_mfma_f32_16x16x32_bf16 v[126:129], v[146:149], v[190:193], v[126:129]
	v_mfma_f32_16x16x32_bf16 v[122:125], v[166:169], v[190:193], v[122:125]
	v_mfma_f32_16x16x32_bf16 v[110:113], v[146:149], v[208:211], v[110:113]
	v_mfma_f32_16x16x32_bf16 v[106:109], v[166:169], v[208:211], v[106:109]
	v_mfma_f32_16x16x32_bf16 v[94:97], v[146:149], v[216:219], v[94:97]
	v_mfma_f32_16x16x32_bf16 v[90:93], v[166:169], v[216:219], v[90:93]
	v_mfma_f32_16x16x32_bf16 v[78:81], v[146:149], v[224:227], v[78:81]
	v_mfma_f32_16x16x32_bf16 v[74:77], v[166:169], v[224:227], v[74:77]
	v_mfma_f32_16x16x32_bf16 v[126:129], v[162:165], v[194:197], v[126:129]
	v_mfma_f32_16x16x32_bf16 v[122:125], v[170:173], v[194:197], v[122:125]
	v_mfma_f32_16x16x32_bf16 v[110:113], v[162:165], v[212:215], v[110:113]
	v_mfma_f32_16x16x32_bf16 v[106:109], v[170:173], v[212:215], v[106:109]
	v_mfma_f32_16x16x32_bf16 v[94:97], v[162:165], v[220:223], v[94:97]
	v_mfma_f32_16x16x32_bf16 v[90:93], v[170:173], v[220:223], v[90:93]
	v_mfma_f32_16x16x32_bf16 v[78:81], v[162:165], v[236:239], v[78:81]
	v_mfma_f32_16x16x32_bf16 v[74:77], v[170:173], v[236:239], v[74:77]
	s_setprio 0
	s_setprio 1
	v_mfma_f32_16x16x32_bf16 v[118:121], v[174:177], v[190:193], v[118:121]
	v_mfma_f32_16x16x32_bf16 v[114:117], v[182:185], v[190:193], v[114:117]
	v_mfma_f32_16x16x32_bf16 v[102:105], v[174:177], v[208:211], v[102:105]
	v_mfma_f32_16x16x32_bf16 v[98:101], v[182:185], v[208:211], v[98:101]
	v_mfma_f32_16x16x32_bf16 v[86:89], v[174:177], v[216:219], v[86:89]
	v_mfma_f32_16x16x32_bf16 v[82:85], v[182:185], v[216:219], v[82:85]
	v_mfma_f32_16x16x32_bf16 v[70:73], v[174:177], v[224:227], v[70:73]
	v_mfma_f32_16x16x32_bf16 v[66:69], v[182:185], v[224:227], v[66:69]
	v_mfma_f32_16x16x32_bf16 v[118:121], v[178:181], v[194:197], v[118:121]
	v_mfma_f32_16x16x32_bf16 v[114:117], v[186:189], v[194:197], v[114:117]
	v_mfma_f32_16x16x32_bf16 v[102:105], v[178:181], v[212:215], v[102:105]
	v_mfma_f32_16x16x32_bf16 v[98:101], v[186:189], v[212:215], v[98:101]
	v_mfma_f32_16x16x32_bf16 v[86:89], v[178:181], v[220:223], v[86:89]
	v_mfma_f32_16x16x32_bf16 v[82:85], v[186:189], v[220:223], v[82:85]
	v_mfma_f32_16x16x32_bf16 v[70:73], v[178:181], v[236:239], v[70:73]
	v_mfma_f32_16x16x32_bf16 v[66:69], v[186:189], v[236:239], v[66:69]
	s_setprio 0
	s_barrier
	s_add_i32 s45, s35, s2
	v_lshl_add_u64 v[150:151], s[26:27], 0, v[134:135]
	s_mov_b32 m0, s45
	ds_read_b128 v[190:193], v159 offset:16384
	ds_read_b128 v[194:197], v159 offset:17408
	ds_read_b128 v[208:211], v159 offset:18432
	ds_read_b128 v[212:215], v159 offset:19456
	ds_read_b128 v[216:219], v159 offset:20480
	ds_read_b128 v[220:223], v159 offset:21504
	ds_read_b128 v[224:227], v159 offset:22528
	ds_read_b128 v[236:239], v159 offset:23552
	global_load_lds_dwordx4 v[150:151], off
	s_add_i32 m0, s45, 0x2000
	s_add_u32 s46, s26, 0x100000
	v_lshl_add_u64 v[228:229], s[26:27], 0, v[136:137]
	s_addc_u32 s47, s27, 0
	s_add_i32 s45, s36, s2
	global_load_lds_dwordx4 v[228:229], off
	v_lshl_add_u64 v[240:241], s[46:47], 0, v[134:135]
	s_mov_b32 m0, s45
	v_lshl_add_u64 v[242:243], s[28:29], 0, v[132:133]
	global_load_lds_dwordx4 v[240:241], off
	v_lshl_add_u64 v[240:241], s[46:47], 0, v[136:137]
	s_add_i32 m0, s45, 0x2000
	s_nop 0
	global_load_lds_dwordx4 v[240:241], off
	v_lshl_add_u64 v[240:241], s[28:29], 0, v[130:131]
	s_mov_b32 m0, s3
	s_nop 0
	global_load_lds_dwordx4 v[240:241], off
	s_mov_b32 m0, s13
	s_nop 0
	global_load_lds_dwordx4 v[242:243], off
	s_waitcnt vmcnt(8)
	s_waitcnt lgkmcnt(0)
	s_barrier
; #define PG8_STAGE(bufoff, gbase, voff) do { _Pragma("unroll") for (int _i = 0; _i < 2; ++_i) \
;         __builtin_amdgcn_global_load_lds((const unsigned*)((const char*)(gbase) + (voff)[_i]), (PG8_LAS unsigned*)(lds + (bufoff) + ldsw + _i * 8192), 16, 0, 0); } while (0)
; #define PG8_LDA(dst, b, h) do { _Pragma("unroll") for (int m = 0; m < 4; ++m) _Pragma("unroll") for (int k = 0; k < 2; ++k) dst[m][k] = *(const PG8_LAS bf16x8*)(lds + PG8_SA(b, h) + aoff + m * 2048 + k * 1024); } while (0)
; #define PG8_LDB(dst, b, h) do { _Pragma("unroll") for (int n = 0; n < 2; ++n) _Pragma("unroll") for (int k = 0; k < 2; ++k) dst[n][k] = *(const PG8_LAS bf16x8*)(lds + PG8_SB(b, h) + boff + n * 2048 + k * 1024); } while (0)
; #define PG8_MMA(ai, bj, At, Bt) do { __builtin_amdgcn_s_setprio(1); _Pragma("unroll") for (int m = 0; m < 4; ++m) _Pragma("unroll") for (int n = 0; n < 2; ++n) _Pragma("unroll") for (int k = 0; k < 2; ++k) \
;         acc[ai][bj][m][n] = __builtin_amdgcn_mfma_f32_16x16x32_bf16(Bt[n][k], At[m][k], acc[ai][bj][m][n], 0, 0, 0); __builtin_amdgcn_s_setprio(0); } while (0)
; #define PG8_WAIT_V(n) asm volatile("s_waitcnt vmcnt(" #n ")" ::: "memory")
; #define PG8_WAIT_L(n) asm volatile("s_waitcnt lgkmcnt(" #n ")" ::: "memory")
; #define PG8_BAR __builtin_amdgcn_s_barrier()
; #define PG8_SCHED __builtin_amdgcn_sched_barrier(0)
; template <class Epi, class Sched, bool ALIGN_EPI = false, bool SP2 = false>
; __device__ __forceinline__ void gemm_phase(PG8_LAS unsigned char* lds, const Gemm g, const Sched& S, const Epi& E) {
;     ...
;             PG8_LDA(At, 0, 1); PG8_STAGE(PG8_SB(0, 0), b2, voffB); PG8_STAGE(PG8_SB(0, 1), b2 + hstep, voffB); PG8_STAGE(PG8_SA(0, 0), a2, voffA);
;             PG8_WAIT_V(8); PG8_WAIT_L(0); PG8_BAR; PG8_MMA(1, 0, At, B0); PG8_MMA(1, 1, At, B1); PG8_BAR; PG8_SCHED;
;             PG8_LDB(B0, 1, 0); PG8_LDB(B1, 1, 1); PG8_SCHED; PG8_LDA(At, 1, 0); PG8_STAGE(PG8_SA(0, 1), a2 + hstep, voffA);
;             PG8_WAIT_V(8); PG8_WAIT_L(0); PG8_BAR; PG8_MMA(0, 0, At, B0); PG8_MMA(0, 1, At, B1); PG8_BAR; PG8_SCHED;
	s_setprio 1
	s_waitcnt lgkmcnt(0)
	v_mfma_f32_16x16x32_bf16 v[62:65], v[146:149], v[190:193], v[62:65]
	v_mfma_f32_16x16x32_bf16 v[58:61], v[166:169], v[190:193], v[58:61]
	v_mfma_f32_16x16x32_bf16 v[46:49], v[146:149], v[208:211], v[46:49]
	v_mfma_f32_16x16x32_bf16 v[42:45], v[166:169], v[208:211], v[42:45]
	v_mfma_f32_16x16x32_bf16 v[30:33], v[146:149], v[216:219], v[30:33]
	v_mfma_f32_16x16x32_bf16 v[26:29], v[166:169], v[216:219], v[26:29]
	v_mfma_f32_16x16x32_bf16 v[14:17], v[146:149], v[224:227], v[14:17]
	v_mfma_f32_16x16x32_bf16 v[10:13], v[166:169], v[224:227], v[10:13]
	v_mfma_f32_16x16x32_bf16 v[62:65], v[162:165], v[194:197], v[62:65]
	v_mfma_f32_16x16x32_bf16 v[58:61], v[170:173], v[194:197], v[58:61]
	v_mfma_f32_16x16x32_bf16 v[46:49], v[162:165], v[212:215], v[46:49]
	v_mfma_f32_16x16x32_bf16 v[42:45], v[170:173], v[212:215], v[42:45]
	v_mfma_f32_16x16x32_bf16 v[30:33], v[162:165], v[220:223], v[30:33]
	v_mfma_f32_16x16x32_bf16 v[26:29], v[170:173], v[220:223], v[26:29]
	v_mfma_f32_16x16x32_bf16 v[14:17], v[162:165], v[236:239], v[14:17]
	v_mfma_f32_16x16x32_bf16 v[10:13], v[170:173], v[236:239], v[10:13]
	s_setprio 0
	s_setprio 1
	v_mfma_f32_16x16x32_bf16 v[54:57], v[174:177], v[190:193], v[54:57]
	v_mfma_f32_16x16x32_bf16 v[50:53], v[182:185], v[190:193], v[50:53]
	v_mfma_f32_16x16x32_bf16 v[38:41], v[174:177], v[208:211], v[38:41]
	v_mfma_f32_16x16x32_bf16 v[34:37], v[182:185], v[208:211], v[34:37]
	v_mfma_f32_16x16x32_bf16 v[22:25], v[174:177], v[216:219], v[22:25]
	v_mfma_f32_16x16x32_bf16 v[18:21], v[182:185], v[216:219], v[18:21]
	v_mfma_f32_16x16x32_bf16 v[6:9], v[174:177], v[224:227], v[6:9]
	v_mfma_f32_16x16x32_bf16 v[2:5], v[182:185], v[224:227], v[2:5]
	v_mfma_f32_16x16x32_bf16 v[54:57], v[178:181], v[194:197], v[54:57]
	v_mfma_f32_16x16x32_bf16 v[50:53], v[186:189], v[194:197], v[50:53]
	v_mfma_f32_16x16x32_bf16 v[38:41], v[178:181], v[212:215], v[38:41]
	v_mfma_f32_16x16x32_bf16 v[34:37], v[186:189], v[212:215], v[34:37]
	v_mfma_f32_16x16x32_bf16 v[22:25], v[178:181], v[220:223], v[22:25]
	v_mfma_f32_16x16x32_bf16 v[18:21], v[186:189], v[220:223], v[18:21]
	v_mfma_f32_16x16x32_bf16 v[6:9], v[178:181], v[236:239], v[6:9]
	v_mfma_f32_16x16x32_bf16 v[2:5], v[186:189], v[236:239], v[2:5]
	s_setprio 0
	s_barrier
	ds_read_b128 v[146:149], v160
	ds_read_b128 v[162:165], v160 offset:1024
	ds_read_b128 v[166:169], v160 offset:2048
	ds_read_b128 v[170:173], v160 offset:3072
	ds_read_b128 v[174:177], v161
	ds_read_b128 v[178:181], v161 offset:1024
	ds_read_b128 v[182:185], v161 offset:2048
	ds_read_b128 v[186:189], v161 offset:3072
	s_add_u32 s28, s28, 0x100000
	s_addc_u32 s29, s29, 0
	s_mov_b32 m0, s21
	v_lshl_add_u64 v[244:245], s[28:29], 0, v[130:131]
	ds_read_b128 v[190:193], v159 offset:32768
	ds_read_b128 v[194:197], v159 offset:33792
	ds_read_b128 v[208:211], v159 offset:34816
	ds_read_b128 v[212:215], v159 offset:35840
	ds_read_b128 v[216:219], v159 offset:36864
	ds_read_b128 v[220:223], v159 offset:37888
	ds_read_b128 v[224:227], v159 offset:38912
	ds_read_b128 v[236:239], v159 offset:39936
	global_load_lds_dwordx4 v[244:245], off
	v_lshl_add_u64 v[244:245], s[28:29], 0, v[132:133]
	s_mov_b32 m0, s30
	s_nop 0
	global_load_lds_dwordx4 v[244:245], off
	s_waitcnt vmcnt(8)
	s_waitcnt lgkmcnt(0)
	s_barrier
	s_setprio 1
	s_waitcnt lgkmcnt(0)
	v_mfma_f32_16x16x32_bf16 v[126:129], v[146:149], v[190:193], v[126:129]
	v_mfma_f32_16x16x32_bf16 v[122:125], v[166:169], v[190:193], v[122:125]
	v_mfma_f32_16x16x32_bf16 v[110:113], v[146:149], v[208:211], v[110:113]
	v_mfma_f32_16x16x32_bf16 v[106:109], v[166:169], v[208:211], v[106:109]
	v_mfma_f32_16x16x32_bf16 v[94:97], v[146:149], v[216:219], v[94:97]
	v_mfma_f32_16x16x32_bf16 v[90:93], v[166:169], v[216:219], v[90:93]
	v_mfma_f32_16x16x32_bf16 v[78:81], v[146:149], v[224:227], v[78:81]
	v_mfma_f32_16x16x32_bf16 v[74:77], v[166:169], v[224:227], v[74:77]
	v_mfma_f32_16x16x32_bf16 v[126:129], v[162:165], v[194:197], v[126:129]
	v_mfma_f32_16x16x32_bf16 v[122:125], v[170:173], v[194:197], v[122:125]
	v_mfma_f32_16x16x32_bf16 v[110:113], v[162:165], v[212:215], v[110:113]
	v_mfma_f32_16x16x32_bf16 v[106:109], v[170:173], v[212:215], v[106:109]
	v_mfma_f32_16x16x32_bf16 v[94:97], v[162:165], v[220:223], v[94:97]
	v_mfma_f32_16x16x32_bf16 v[90:93], v[170:173], v[220:223], v[90:93]
	v_mfma_f32_16x16x32_bf16 v[78:81], v[162:165], v[236:239], v[78:81]
	v_mfma_f32_16x16x32_bf16 v[74:77], v[170:173], v[236:239], v[74:77]
	s_setprio 0
	s_setprio 1
	v_mfma_f32_16x16x32_bf16 v[118:121], v[174:177], v[190:193], v[118:121]
	v_mfma_f32_16x16x32_bf16 v[114:117], v[182:185], v[190:193], v[114:117]
	v_mfma_f32_16x16x32_bf16 v[102:105], v[174:177], v[208:211], v[102:105]
	v_mfma_f32_16x16x32_bf16 v[98:101], v[182:185], v[208:211], v[98:101]
	v_mfma_f32_16x16x32_bf16 v[86:89], v[174:177], v[216:219], v[86:89]
	v_mfma_f32_16x16x32_bf16 v[82:85], v[182:185], v[216:219], v[82:85]
	v_mfma_f32_16x16x32_bf16 v[70:73], v[174:177], v[224:227], v[70:73]
	v_mfma_f32_16x16x32_bf16 v[66:69], v[182:185], v[224:227], v[66:69]
	v_mfma_f32_16x16x32_bf16 v[118:121], v[178:181], v[194:197], v[118:121]
	v_mfma_f32_16x16x32_bf16 v[114:117], v[186:189], v[194:197], v[114:117]
	v_mfma_f32_16x16x32_bf16 v[102:105], v[178:181], v[212:215], v[102:105]
	v_mfma_f32_16x16x32_bf16 v[98:101], v[186:189], v[212:215], v[98:101]
	v_mfma_f32_16x16x32_bf16 v[86:89], v[178:181], v[220:223], v[86:89]
	v_mfma_f32_16x16x32_bf16 v[82:85], v[186:189], v[220:223], v[82:85]
	v_mfma_f32_16x16x32_bf16 v[70:73], v[178:181], v[236:239], v[70:73]
	v_mfma_f32_16x16x32_bf16 v[66:69], v[186:189], v[236:239], v[66:69]
	s_setprio 0
	s_barrier
; #define PG8_STAGE(bufoff, gbase, voff) do { _Pragma("unroll") for (int _i = 0; _i < 2; ++_i) \
;         __builtin_amdgcn_global_load_lds((const unsigned*)((const char*)(gbase) + (voff)[_i]), (PG8_LAS unsigned*)(lds + (bufoff) + ldsw + _i * 8192), 16, 0, 0); } while (0)
; #define PG8_LDA(dst, b, h) do { _Pragma("unroll") for (int m = 0; m < 4; ++m) _Pragma("unroll") for (int k = 0; k < 2; ++k) dst[m][k] = *(const PG8_LAS bf16x8*)(lds + PG8_SA(b, h) + aoff + m * 2048 + k * 1024); } while (0)
; #define PG8_MMA(ai, bj, At, Bt) do { __builtin_amdgcn_s_setprio(1); _Pragma("unroll") for (int m = 0; m < 4; ++m) _Pragma("unroll") for (int n = 0; n < 2; ++n) _Pragma("unroll") for (int k = 0; k < 2; ++k) \
;         acc[ai][bj][m][n] = __builtin_amdgcn_mfma_f32_16x16x32_bf16(Bt[n][k], At[m][k], acc[ai][bj][m][n], 0, 0, 0); __builtin_amdgcn_s_setprio(0); } while (0)
; #define PG8_WAIT_V(n) asm volatile("s_waitcnt vmcnt(" #n ")" ::: "memory")
; #define PG8_WAIT_L(n) asm volatile("s_waitcnt lgkmcnt(" #n ")" ::: "memory")
; #define PG8_BAR __builtin_amdgcn_s_barrier()
; #define PG8_SCHED __builtin_amdgcn_sched_barrier(0)
; template <class Epi, class Sched, bool ALIGN_EPI = false, bool SP2 = false>
; __device__ __forceinline__ void gemm_phase(PG8_LAS unsigned char* lds, const Gemm g, const Sched& S, const Epi& E) {
;     ...
;         for (int t = 0; t < nt; t += 2) {
;     ...
;             PG8_LDA(At, 1, 1); PG8_STAGE(PG8_SB(1, 0), b3, voffB); PG8_STAGE(PG8_SB(1, 1), b3 + hstep, voffB); PG8_STAGE(PG8_SA(1, 0), a3, voffA);
;             PG8_WAIT_V(8); PG8_WAIT_L(0); PG8_BAR; PG8_MMA(1, 0, At, B0); PG8_MMA(1, 1, At, B1); PG8_BAR; PG8_SCHED;
	s_add_i32 s28, s37, s2
	v_lshl_add_u64 v[150:151], v[150:151], 0, s[8:9]
	s_mov_b32 m0, s28
	ds_read_b128 v[190:193], v159 offset:49152
	ds_read_b128 v[194:197], v159 offset:50176
	ds_read_b128 v[208:211], v159 offset:51200
	ds_read_b128 v[212:215], v159 offset:52224
	ds_read_b128 v[216:219], v159 offset:53248
	ds_read_b128 v[220:223], v159 offset:54272
	ds_read_b128 v[224:227], v159 offset:55296
	ds_read_b128 v[236:239], v159 offset:56320
	global_load_lds_dwordx4 v[150:151], off
	s_add_i32 m0, s28, 0x2000
	s_add_u32 s26, s26, 0x100080
	v_lshl_add_u64 v[150:151], v[228:229], 0, s[8:9]
	s_addc_u32 s27, s27, 0
	s_add_i32 s28, s38, s2
	global_load_lds_dwordx4 v[150:151], off
	v_lshl_add_u64 v[150:151], s[26:27], 0, v[134:135]
	s_mov_b32 m0, s28
	s_nop 0
	global_load_lds_dwordx4 v[150:151], off
	v_lshl_add_u64 v[150:151], s[26:27], 0, v[136:137]
	s_add_i32 m0, s28, 0x2000
	s_nop 0
	global_load_lds_dwordx4 v[150:151], off
	v_lshl_add_u64 v[150:151], v[240:241], 0, s[8:9]
	s_mov_b32 m0, s31
	s_nop 0
	global_load_lds_dwordx4 v[150:151], off
	v_lshl_add_u64 v[150:151], v[242:243], 0, s[8:9]
	s_mov_b32 m0, s33
	s_nop 0
	global_load_lds_dwordx4 v[150:151], off
	s_waitcnt vmcnt(8)
	s_waitcnt lgkmcnt(0)
	s_barrier
	s_setprio 1
	s_waitcnt lgkmcnt(0)
	v_mfma_f32_16x16x32_bf16 v[62:65], v[146:149], v[190:193], v[62:65]
	v_mfma_f32_16x16x32_bf16 v[58:61], v[166:169], v[190:193], v[58:61]
	v_mfma_f32_16x16x32_bf16 v[46:49], v[146:149], v[208:211], v[46:49]
	v_mfma_f32_16x16x32_bf16 v[42:45], v[166:169], v[208:211], v[42:45]
	v_mfma_f32_16x16x32_bf16 v[30:33], v[146:149], v[216:219], v[30:33]
	v_mfma_f32_16x16x32_bf16 v[26:29], v[166:169], v[216:219], v[26:29]
	v_mfma_f32_16x16x32_bf16 v[14:17], v[146:149], v[224:227], v[14:17]
	v_mfma_f32_16x16x32_bf16 v[10:13], v[166:169], v[224:227], v[10:13]
	v_mfma_f32_16x16x32_bf16 v[62:65], v[162:165], v[194:197], v[62:65]
	v_mfma_f32_16x16x32_bf16 v[58:61], v[170:173], v[194:197], v[58:61]
	v_mfma_f32_16x16x32_bf16 v[46:49], v[162:165], v[212:215], v[46:49]
	v_mfma_f32_16x16x32_bf16 v[42:45], v[170:173], v[212:215], v[42:45]
	v_mfma_f32_16x16x32_bf16 v[30:33], v[162:165], v[220:223], v[30:33]
	v_mfma_f32_16x16x32_bf16 v[26:29], v[170:173], v[220:223], v[26:29]
	v_mfma_f32_16x16x32_bf16 v[14:17], v[162:165], v[236:239], v[14:17]
	v_mfma_f32_16x16x32_bf16 v[10:13], v[170:173], v[236:239], v[10:13]
	s_setprio 0
	s_setprio 1
	v_mfma_f32_16x16x32_bf16 v[54:57], v[174:177], v[190:193], v[54:57]
	v_mfma_f32_16x16x32_bf16 v[50:53], v[182:185], v[190:193], v[50:53]
	v_mfma_f32_16x16x32_bf16 v[38:41], v[174:177], v[208:211], v[38:41]
	v_mfma_f32_16x16x32_bf16 v[34:37], v[182:185], v[208:211], v[34:37]
	v_mfma_f32_16x16x32_bf16 v[22:25], v[174:177], v[216:219], v[22:25]
	v_mfma_f32_16x16x32_bf16 v[18:21], v[182:185], v[216:219], v[18:21]
	v_mfma_f32_16x16x32_bf16 v[6:9], v[174:177], v[224:227], v[6:9]
	v_mfma_f32_16x16x32_bf16 v[2:5], v[182:185], v[224:227], v[2:5]
	v_mfma_f32_16x16x32_bf16 v[54:57], v[178:181], v[194:197], v[54:57]
	v_mfma_f32_16x16x32_bf16 v[50:53], v[186:189], v[194:197], v[50:53]
	v_mfma_f32_16x16x32_bf16 v[38:41], v[178:181], v[212:215], v[38:41]
	v_mfma_f32_16x16x32_bf16 v[34:37], v[186:189], v[212:215], v[34:37]
	v_mfma_f32_16x16x32_bf16 v[22:25], v[178:181], v[220:223], v[22:25]
	v_mfma_f32_16x16x32_bf16 v[18:21], v[186:189], v[220:223], v[18:21]
	v_mfma_f32_16x16x32_bf16 v[6:9], v[178:181], v[236:239], v[6:9]
	v_mfma_f32_16x16x32_bf16 v[2:5], v[186:189], v[236:239], v[2:5]
	s_setprio 0
	s_barrier
	s_add_i32 s44, s44, 2
	s_add_u32 s24, s24, 0x100
	s_addc_u32 s25, s25, 0
	s_add_u32 s42, s42, 0x100
	s_addc_u32 s43, s43, 0
	s_cmp_gt_u32 s44, 61
	s_cbranch_scc0 .LBB0_1098
	s_and_b64 vcc, exec, s[10:11]
	s_cbranch_vccz .LBB0_1101
	s_barrier

; #define PG8_STAGE(bufoff, gbase, voff) do { _Pragma("unroll") for (int _i = 0; _i < 2; ++_i) \
;         __builtin_amdgcn_global_load_lds((const unsigned*)((const char*)(gbase) + (voff)[_i]), (PG8_LAS unsigned*)(lds + (bufoff) + ldsw + _i * 8192), 16, 0, 0); } while (0)
; #define PG8_WAIT_V(n) asm volatile("s_waitcnt vmcnt(" #n ")" ::: "memory")
; #define PG8_BAR __builtin_amdgcn_s_barrier()
; template <class Epi, class Sched, bool ALIGN_EPI = false, bool SP2 = false>
; __device__ __forceinline__ void gemm_phase(PG8_LAS unsigned char* lds, const Gemm g, const Sched& S, const Epi& E) {
;     ...
;     const int K = g.K, LD = g.ld, nt = K / BK;
;     unsigned voffA[2], voffB[2];
; #pragma unroll
;     for (int i = 0; i < 2; ++i) { int R, C; stage_rc(tid * 16 + i * 8192, R, C); const int Rb = Epi::PERM ? ((R & ~31) + perm32(R & 31)) : R;
;         voffA[i] = (unsigned)(R * LD + C) * 2u; voffB[i] = (unsigned)(Rb * LD + C) * 2u; }
;     const size_t kstep = (size_t)(BK * 2);
;     const size_t hstep = (size_t)HALF * LD * 2;
;     const size_t tstep = 2 * hstep;
;     const unsigned ldsw = (unsigned)wid * 1024u;
;     const int aoff = lds_byte(wr * 64 + fr, fq * 8), boff = lds_byte(wc * 32 + fr, fq * 8);
;     ...
;         PG8_STAGE(PG8_SB(0, 0), cB, voffB); PG8_STAGE(PG8_SB(0, 1), cB + hstep, voffB); PG8_STAGE(PG8_SA(0, 0), cA, voffA); PG8_STAGE(PG8_SA(0, 1), cA + hstep, voffA);
;         if (wr == 1) PG8_BAR;
;         PG8_WAIT_V(2); PG8_BAR;
;         PG8_STAGE(PG8_SB(1, 0), cB + kstep, voffB); PG8_STAGE(PG8_SA(1, 0), cA + kstep, voffA); PG8_STAGE(PG8_SB(1, 1), cB + hstep + kstep, voffB);
;         PG8_WAIT_V(6); PG8_BAR;
.LBB0_1108:
	s_lshl_b32 s14, s14, 5
	s_and_b32 s20, s14, 0x60
	s_mov_b64 s[14:15], 0x80
	s_add_i32 m0, s3, 0x18000
	v_lshl_add_u64 v[8:9], v[8:9], 0, s[14:15]
	s_lshl_b32 s19, s5, 13
	s_lshl_b32 s21, s20, 7
	s_waitcnt vmcnt(2)
	s_barrier
	global_load_lds_dwordx4 v[8:9], off
	v_lshl_add_u64 v[6:7], v[6:7], 0, s[14:15]
	s_add_i32 m0, s3, 0x1a000
	s_add_i32 s36, s3, 0x8000
	s_add_i32 s37, s3, 0xa000
	global_load_lds_dwordx4 v[6:7], off
	v_lshl_add_u64 v[2:3], v[2:3], 0, s[14:15]
	s_mov_b32 m0, s36
	s_add_u32 s16, s30, 0x100080
	global_load_lds_dwordx4 v[2:3], off
	v_lshl_add_u64 v[2:3], v[4:5], 0, s[14:15]
	s_mov_b32 m0, s37
	s_addc_u32 s17, s31, 0
	global_load_lds_dwordx4 v[2:3], off
	s_add_i32 m0, s3, 0x1c000
	v_lshl_add_u64 v[2:3], s[16:17], 0, v[130:131]
	global_load_lds_dwordx4 v[2:3], off
	v_lshl_add_u64 v[2:3], s[16:17], 0, v[132:133]
	s_add_i32 m0, s3, 0x1e000
	v_bfe_u32 v18, v198, 4, 2
	global_load_lds_dwordx4 v[2:3], off
	v_lshlrev_b32_e32 v3, 4, v18
	v_lshl_or_b32 v4, v204, 6, v3
	v_lshlrev_b32_e32 v5, 2, v204
	v_or_b32_e32 v3, v3, v153
	v_lshl_or_b32 v2, s5, 6, v204
	v_and_b32_e32 v5, 32, v5
	v_bitop3_b32 v20, s21, v3, v154 bitop3:0xf6
	v_mov_b32_e32 v3, v131
	v_bitop3_b32 v19, v4, s19, v5 bitop3:0xde
	v_or_b32_e32 v4, 16, v2
	v_or_b32_e32 v6, 32, v2
	v_or_b32_e32 v8, 48, v2
	v_add_u32_e32 v10, 0x80, v2
	v_add_u32_e32 v12, 0x90, v2
	v_add_u32_e32 v14, 0xa0, v2
	v_add_u32_e32 v16, 0xb0, v2
	v_lshlrev_b64 v[134:135], 12, v[2:3]
	v_lshlrev_b32_e32 v2, 10, v198
	v_and_b32_e32 v2, 0xe0000, v2
	v_lshlrev_b32_e32 v3, 13, v230
	v_or3_b32 v2, v1, v2, v3
	v_add_u32_e32 v150, v2, v205
	v_lshlrev_b32_e32 v2, 6, v152
	s_cmpk_lt_u32 s4, 0x100
	v_and_b32_e32 v2, 0x1e0000, v2
	s_mov_b32 s5, 0x18000
	s_mov_b32 s19, 0x1c000
	s_waitcnt vmcnt(6)
	s_cselect_b64 s[16:17], -1, 0
	v_or3_b32 v1, v1, v2, v3
	s_add_i32 s42, s7, 0x100
	v_mov_b32_e32 v5, v131
	v_mov_b32_e32 v7, v131
	v_mov_b32_e32 v9, v131
	v_mov_b32_e32 v11, v131
	v_mov_b32_e32 v13, v131
	v_mov_b32_e32 v15, v131
	v_mov_b32_e32 v17, v131
	v_add_u32_e32 v152, v1, v205
	v_add_u32_e32 v1, s42, v20
	s_add_i32 s39, s18, 0x100
	s_add_i32 s42, s42, s2
	s_add_i32 s44, s5, 0x100
	s_add_i32 s45, s19, 0x100
	v_lshlrev_b64 v[136:137], 12, v[4:5]
	v_lshlrev_b64 v[138:139], 12, v[6:7]
	v_lshlrev_b64 v[140:141], 12, v[8:9]
	v_lshlrev_b64 v[142:143], 12, v[10:11]
	v_lshlrev_b64 v[144:145], 12, v[12:13]
	v_lshlrev_b64 v[146:147], 12, v[14:15]
	v_lshlrev_b64 v[148:149], 12, v[16:17]
	v_lshl_or_b32 v154, v18, 2, s20
	v_mov_b32_e32 v151, v131
	v_mov_b32_e32 v153, v131
	s_mov_b32 s38, 0
	v_add_u32_e32 v155, s39, v20
	v_add_u32_e32 v156, 0x100, v19
	s_add_i32 s40, s3, 0xc000
	s_add_i32 s41, s3, 0xe000
	s_add_i32 s43, s42, 0x2000
	v_add_u32_e32 v157, s44, v20
	v_add_u32_e32 v158, s45, v20
	s_barrier
	s_branch .LBB0_1111

; #define PG8_STAGE(bufoff, gbase, voff) do { _Pragma("unroll") for (int _i = 0; _i < 2; ++_i) \
;         __builtin_amdgcn_global_load_lds((const unsigned*)((const char*)(gbase) + (voff)[_i]), (PG8_LAS unsigned*)(lds + (bufoff) + ldsw + _i * 8192), 16, 0, 0); } while (0)
; #define PG8_LDA(dst, b, h) do { _Pragma("unroll") for (int m = 0; m < 4; ++m) _Pragma("unroll") for (int k = 0; k < 2; ++k) dst[m][k] = *(const PG8_LAS bf16x8*)(lds + PG8_SA(b, h) + aoff + m * 2048 + k * 1024); } while (0)
; #define PG8_LDB(dst, b, h) do { _Pragma("unroll") for (int n = 0; n < 2; ++n) _Pragma("unroll") for (int k = 0; k < 2; ++k) dst[n][k] = *(const PG8_LAS bf16x8*)(lds + PG8_SB(b, h) + boff + n * 2048 + k * 1024); } while (0)
; #define PG8_MMA(ai, bj, At, Bt) do { __builtin_amdgcn_s_setprio(1); _Pragma("unroll") for (int m = 0; m < 4; ++m) _Pragma("unroll") for (int n = 0; n < 2; ++n) _Pragma("unroll") for (int k = 0; k < 2; ++k) \
;         acc[ai][bj][m][n] = __builtin_amdgcn_mfma_f32_16x16x32_bf16(Bt[n][k], At[m][k], acc[ai][bj][m][n], 0, 0, 0); __builtin_amdgcn_s_setprio(0); } while (0)
; #define PG8_WAIT_V(n) asm volatile("s_waitcnt vmcnt(" #n ")" ::: "memory")
; #define PG8_WAIT_L(n) asm volatile("s_waitcnt lgkmcnt(" #n ")" ::: "memory")
; template <class Epi, class Sched, bool ALIGN_EPI = false, bool SP2 = false>
; __device__ __forceinline__ void gemm_phase(PG8_LAS unsigned char* lds, const Gemm g, const Sched& S, const Epi& E) {
;     ...
;             const bool last = (t == nt - 2);
;             const char* a1 = cA + (size_t)(t + 1) * kstep;
;             const char* a2 = last ? nA : cA + (size_t)(t + 2) * kstep; const char* b2 = last ? nB : cB + (size_t)(t + 2) * kstep;
;             const char* a3 = a2 + kstep; const char* b3 = b2 + kstep;
;             if (last && has_next) S.a_ready(nxt);
;             if constexpr (SP2) {
;             PG8_LDB(B0, 0, 0); PG8_LDB(B1, 0, 1); PG8_SCHED; PG8_LDA(At, 0, 0); PG8_STAGE(PG8_SA(1, 1), a1 + hstep, voffA);
;             PG8_WAIT_V(8); PG8_WAIT_L(0); PG8_BAR; PG8_MMA(0, 0, At, B0); PG8_MMA(0, 1, At, B1); PG8_BAR; PG8_SCHED;
;             PG8_LDA(At, 0, 1); PG8_STAGE(PG8_SB(0, 0), b2, voffB); PG8_STAGE(PG8_SB(0, 1), b2 + hstep, voffB); PG8_STAGE(PG8_SA(0, 0), a2, voffA);
;             PG8_WAIT_V(8); PG8_WAIT_L(0); PG8_BAR; PG8_MMA(1, 0, At, B0); PG8_MMA(1, 1, At, B1); PG8_BAR; PG8_SCHED;
.LBB0_1118:
	ds_read_b128 v[160:163], v1
	ds_read_b128 v[164:167], v1 offset:1024
	ds_read_b128 v[168:171], v1 offset:2048
	ds_read_b128 v[172:175], v1 offset:3072
	ds_read_b128 v[176:179], v155
	ds_read_b128 v[180:183], v155 offset:1024
	ds_read_b128 v[184:187], v155 offset:2048
	ds_read_b128 v[188:191], v155 offset:3072
	s_add_u32 s23, s28, 0xfff00080
	s_addc_u32 s30, s29, -1
	s_cmp_eq_u32 s21, 4
	s_cselect_b32 s35, s25, s30
	s_cselect_b32 s34, s24, s23
	s_cselect_b32 s31, s27, s19
	s_cselect_b32 s30, s26, s7
	s_mov_b32 m0, s40
	v_lshl_add_u64 v[196:197], s[28:29], 0, v[150:151]
	ds_read_b128 v[192:195], v156
	ds_read_b128 v[208:211], v156 offset:1024
	ds_read_b128 v[212:215], v156 offset:2048
	ds_read_b128 v[216:219], v156 offset:3072
	ds_read_b128 v[220:223], v156 offset:4096
	ds_read_b128 v[224:227], v156 offset:5120
	ds_read_b128 v[236:239], v156 offset:6144
	ds_read_b128 v[240:243], v156 offset:7168
	global_load_lds_dwordx4 v[196:197], off
	v_lshl_add_u64 v[196:197], s[28:29], 0, v[152:153]
	s_mov_b32 m0, s41
	s_nop 0
	global_load_lds_dwordx4 v[196:197], off
	s_waitcnt vmcnt(8)
	s_waitcnt lgkmcnt(0)
	s_barrier
	s_setprio 1
	s_waitcnt lgkmcnt(0)
	v_mfma_f32_16x16x32_bf16 v[126:129], v[160:163], v[192:195], v[126:129]
	v_mfma_f32_16x16x32_bf16 v[122:125], v[168:171], v[192:195], v[122:125]
	v_mfma_f32_16x16x32_bf16 v[118:121], v[160:163], v[212:215], v[118:121]
	v_mfma_f32_16x16x32_bf16 v[114:117], v[168:171], v[212:215], v[114:117]
	v_mfma_f32_16x16x32_bf16 v[110:113], v[160:163], v[220:223], v[110:113]
	v_mfma_f32_16x16x32_bf16 v[106:109], v[168:171], v[220:223], v[106:109]
	v_mfma_f32_16x16x32_bf16 v[98:101], v[160:163], v[236:239], v[98:101]
	v_mfma_f32_16x16x32_bf16 v[90:93], v[168:171], v[236:239], v[90:93]
	v_mfma_f32_16x16x32_bf16 v[126:129], v[164:167], v[208:211], v[126:129]
	v_mfma_f32_16x16x32_bf16 v[122:125], v[172:175], v[208:211], v[122:125]
	v_mfma_f32_16x16x32_bf16 v[118:121], v[164:167], v[216:219], v[118:121]
	v_mfma_f32_16x16x32_bf16 v[114:117], v[172:175], v[216:219], v[114:117]
	v_mfma_f32_16x16x32_bf16 v[110:113], v[164:167], v[224:227], v[110:113]
	v_mfma_f32_16x16x32_bf16 v[106:109], v[172:175], v[224:227], v[106:109]
	v_mfma_f32_16x16x32_bf16 v[98:101], v[164:167], v[240:243], v[98:101]
	v_mfma_f32_16x16x32_bf16 v[90:93], v[172:175], v[240:243], v[90:93]
	s_setprio 0
	s_setprio 1
	v_mfma_f32_16x16x32_bf16 v[102:105], v[176:179], v[192:195], v[102:105]
	v_mfma_f32_16x16x32_bf16 v[94:97], v[184:187], v[192:195], v[94:97]
	v_mfma_f32_16x16x32_bf16 v[86:89], v[176:179], v[212:215], v[86:89]
	v_mfma_f32_16x16x32_bf16 v[82:85], v[184:187], v[212:215], v[82:85]
	v_mfma_f32_16x16x32_bf16 v[78:81], v[176:179], v[220:223], v[78:81]
	v_mfma_f32_16x16x32_bf16 v[74:77], v[184:187], v[220:223], v[74:77]
	v_mfma_f32_16x16x32_bf16 v[70:73], v[176:179], v[236:239], v[70:73]
	v_mfma_f32_16x16x32_bf16 v[66:69], v[184:187], v[236:239], v[66:69]
	v_mfma_f32_16x16x32_bf16 v[102:105], v[180:183], v[208:211], v[102:105]
	v_mfma_f32_16x16x32_bf16 v[94:97], v[188:191], v[208:211], v[94:97]
	v_mfma_f32_16x16x32_bf16 v[86:89], v[180:183], v[216:219], v[86:89]
	v_mfma_f32_16x16x32_bf16 v[82:85], v[188:191], v[216:219], v[82:85]
	v_mfma_f32_16x16x32_bf16 v[78:81], v[180:183], v[224:227], v[78:81]
	v_mfma_f32_16x16x32_bf16 v[74:77], v[188:191], v[224:227], v[74:77]
	v_mfma_f32_16x16x32_bf16 v[70:73], v[180:183], v[240:243], v[70:73]
	v_mfma_f32_16x16x32_bf16 v[66:69], v[188:191], v[240:243], v[66:69]
	s_setprio 0
	s_barrier
	s_mov_b32 m0, s42
	v_lshl_add_u64 v[196:197], s[30:31], 0, v[130:131]
	s_add_u32 s46, s30, 0x100000
	ds_read_b128 v[192:195], v156 offset:16384
	ds_read_b128 v[208:211], v156 offset:17408
	ds_read_b128 v[212:215], v156 offset:18432
	ds_read_b128 v[216:219], v156 offset:19456
	ds_read_b128 v[220:223], v156 offset:20480
	ds_read_b128 v[224:227], v156 offset:21504
	ds_read_b128 v[236:239], v156 offset:22528
	ds_read_b128 v[240:243], v156 offset:23552
	global_load_lds_dwordx4 v[196:197], off
	v_lshl_add_u64 v[228:229], s[30:31], 0, v[132:133]
	s_mov_b32 m0, s43
	s_addc_u32 s47, s31, 0
	s_add_i32 s23, s39, s2
	global_load_lds_dwordx4 v[228:229], off
	v_lshl_add_u64 v[244:245], s[46:47], 0, v[130:131]
	s_mov_b32 m0, s23
	v_lshl_add_u64 v[246:247], s[34:35], 0, v[132:133]
	global_load_lds_dwordx4 v[244:245], off
	v_lshl_add_u64 v[244:245], s[46:47], 0, v[132:133]
	s_add_i32 m0, s23, 0x2000
	s_nop 0
	global_load_lds_dwordx4 v[244:245], off
	v_lshl_add_u64 v[244:245], s[34:35], 0, v[130:131]
	s_mov_b32 m0, s3
	s_nop 0
	global_load_lds_dwordx4 v[244:245], off
	s_mov_b32 m0, s11
	s_nop 0
	global_load_lds_dwordx4 v[246:247], off
	s_waitcnt vmcnt(8)
	s_waitcnt lgkmcnt(0)
	s_barrier
; #define PG8_STAGE(bufoff, gbase, voff) do { _Pragma("unroll") for (int _i = 0; _i < 2; ++_i) \
;         __builtin_amdgcn_global_load_lds((const unsigned*)((const char*)(gbase) + (voff)[_i]), (PG8_LAS unsigned*)(lds + (bufoff) + ldsw + _i * 8192), 16, 0, 0); } while (0)
; #define PG8_LDA(dst, b, h) do { _Pragma("unroll") for (int m = 0; m < 4; ++m) _Pragma("unroll") for (int k = 0; k < 2; ++k) dst[m][k] = *(const PG8_LAS bf16x8*)(lds + PG8_SA(b, h) + aoff + m * 2048 + k * 1024); } while (0)
; #define PG8_LDB(dst, b, h) do { _Pragma("unroll") for (int n = 0; n < 2; ++n) _Pragma("unroll") for (int k = 0; k < 2; ++k) dst[n][k] = *(const PG8_LAS bf16x8*)(lds + PG8_SB(b, h) + boff + n * 2048 + k * 1024); } while (0)
; #define PG8_MMA(ai, bj, At, Bt) do { __builtin_amdgcn_s_setprio(1); _Pragma("unroll") for (int m = 0; m < 4; ++m) _Pragma("unroll") for (int n = 0; n < 2; ++n) _Pragma("unroll") for (int k = 0; k < 2; ++k) \
;         acc[ai][bj][m][n] = __builtin_amdgcn_mfma_f32_16x16x32_bf16(Bt[n][k], At[m][k], acc[ai][bj][m][n], 0, 0, 0); __builtin_amdgcn_s_setprio(0); } while (0)
; #define PG8_WAIT_V(n) asm volatile("s_waitcnt vmcnt(" #n ")" ::: "memory")
; #define PG8_WAIT_L(n) asm volatile("s_waitcnt lgkmcnt(" #n ")" ::: "memory")
; #define PG8_BAR __builtin_amdgcn_s_barrier()
; #define PG8_SCHED __builtin_amdgcn_sched_barrier(0)
; template <class Epi, class Sched, bool ALIGN_EPI = false, bool SP2 = false>
; __device__ __forceinline__ void gemm_phase(PG8_LAS unsigned char* lds, const Gemm g, const Sched& S, const Epi& E) {
;     ...
;             PG8_WAIT_V(8); PG8_WAIT_L(0); PG8_BAR; PG8_MMA(1, 0, At, B0); PG8_MMA(1, 1, At, B1); PG8_BAR; PG8_SCHED;
;             PG8_LDB(B0, 1, 0); PG8_LDB(B1, 1, 1); PG8_SCHED; PG8_LDA(At, 1, 0); PG8_STAGE(PG8_SA(0, 1), a2 + hstep, voffA);
;             PG8_WAIT_V(8); PG8_WAIT_L(0); PG8_BAR; PG8_MMA(0, 0, At, B0); PG8_MMA(0, 1, At, B1); PG8_BAR; PG8_SCHED;
	s_setprio 1
	s_waitcnt lgkmcnt(0)
	v_mfma_f32_16x16x32_bf16 v[62:65], v[160:163], v[192:195], v[62:65]
	v_mfma_f32_16x16x32_bf16 v[58:61], v[168:171], v[192:195], v[58:61]
	v_mfma_f32_16x16x32_bf16 v[54:57], v[160:163], v[212:215], v[54:57]
	v_mfma_f32_16x16x32_bf16 v[50:53], v[168:171], v[212:215], v[50:53]
	v_mfma_f32_16x16x32_bf16 v[46:49], v[160:163], v[220:223], v[46:49]
	v_mfma_f32_16x16x32_bf16 v[42:45], v[168:171], v[220:223], v[42:45]
	v_mfma_f32_16x16x32_bf16 v[34:37], v[160:163], v[236:239], v[34:37]
	v_mfma_f32_16x16x32_bf16 v[26:29], v[168:171], v[236:239], v[26:29]
	v_mfma_f32_16x16x32_bf16 v[62:65], v[164:167], v[208:211], v[62:65]
	v_mfma_f32_16x16x32_bf16 v[58:61], v[172:175], v[208:211], v[58:61]
	v_mfma_f32_16x16x32_bf16 v[54:57], v[164:167], v[216:219], v[54:57]
	v_mfma_f32_16x16x32_bf16 v[50:53], v[172:175], v[216:219], v[50:53]
	v_mfma_f32_16x16x32_bf16 v[46:49], v[164:167], v[224:227], v[46:49]
	v_mfma_f32_16x16x32_bf16 v[42:45], v[172:175], v[224:227], v[42:45]
	v_mfma_f32_16x16x32_bf16 v[34:37], v[164:167], v[240:243], v[34:37]
	v_mfma_f32_16x16x32_bf16 v[26:29], v[172:175], v[240:243], v[26:29]
	s_setprio 0
	s_setprio 1
	v_mfma_f32_16x16x32_bf16 v[38:41], v[176:179], v[192:195], v[38:41]
	v_mfma_f32_16x16x32_bf16 v[30:33], v[184:187], v[192:195], v[30:33]
	v_mfma_f32_16x16x32_bf16 v[22:25], v[176:179], v[212:215], v[22:25]
	v_mfma_f32_16x16x32_bf16 v[18:21], v[184:187], v[212:215], v[18:21]
	v_mfma_f32_16x16x32_bf16 v[14:17], v[176:179], v[220:223], v[14:17]
	v_mfma_f32_16x16x32_bf16 v[10:13], v[184:187], v[220:223], v[10:13]
	v_mfma_f32_16x16x32_bf16 v[6:9], v[176:179], v[236:239], v[6:9]
	v_mfma_f32_16x16x32_bf16 v[2:5], v[184:187], v[236:239], v[2:5]
	v_mfma_f32_16x16x32_bf16 v[38:41], v[180:183], v[208:211], v[38:41]
	v_mfma_f32_16x16x32_bf16 v[30:33], v[188:191], v[208:211], v[30:33]
	v_mfma_f32_16x16x32_bf16 v[22:25], v[180:183], v[216:219], v[22:25]
	v_mfma_f32_16x16x32_bf16 v[18:21], v[188:191], v[216:219], v[18:21]
	v_mfma_f32_16x16x32_bf16 v[14:17], v[180:183], v[224:227], v[14:17]
	v_mfma_f32_16x16x32_bf16 v[10:13], v[188:191], v[224:227], v[10:13]
	v_mfma_f32_16x16x32_bf16 v[6:9], v[180:183], v[240:243], v[6:9]
	v_mfma_f32_16x16x32_bf16 v[2:5], v[188:191], v[240:243], v[2:5]
	s_setprio 0
	s_barrier
	ds_read_b128 v[160:163], v157
	ds_read_b128 v[164:167], v157 offset:1024
	ds_read_b128 v[168:171], v157 offset:2048
	ds_read_b128 v[172:175], v157 offset:3072
	ds_read_b128 v[176:179], v158
	ds_read_b128 v[180:183], v158 offset:1024
	ds_read_b128 v[184:187], v158 offset:2048
	ds_read_b128 v[188:191], v158 offset:3072
	s_add_u32 s34, s34, 0x100000
	s_addc_u32 s35, s35, 0
	s_mov_b32 m0, s13
	v_lshl_add_u64 v[248:249], s[34:35], 0, v[130:131]
	ds_read_b128 v[192:195], v156 offset:32768
	ds_read_b128 v[208:211], v156 offset:33792
	ds_read_b128 v[212:215], v156 offset:34816
	ds_read_b128 v[216:219], v156 offset:35840
	ds_read_b128 v[220:223], v156 offset:36864
	ds_read_b128 v[224:227], v156 offset:37888
	ds_read_b128 v[236:239], v156 offset:38912
	ds_read_b128 v[240:243], v156 offset:39936
	global_load_lds_dwordx4 v[248:249], off
	v_lshl_add_u64 v[248:249], s[34:35], 0, v[132:133]
	s_mov_b32 m0, s33
	s_nop 0
	global_load_lds_dwordx4 v[248:249], off
	s_waitcnt vmcnt(8)
	s_waitcnt lgkmcnt(0)
	s_barrier
	s_setprio 1
	s_waitcnt lgkmcnt(0)
	v_mfma_f32_16x16x32_bf16 v[126:129], v[160:163], v[192:195], v[126:129]
	v_mfma_f32_16x16x32_bf16 v[122:125], v[168:171], v[192:195], v[122:125]
	v_mfma_f32_16x16x32_bf16 v[118:121], v[160:163], v[212:215], v[118:121]
	v_mfma_f32_16x16x32_bf16 v[114:117], v[168:171], v[212:215], v[114:117]
	v_mfma_f32_16x16x32_bf16 v[110:113], v[160:163], v[220:223], v[110:113]
	v_mfma_f32_16x16x32_bf16 v[106:109], v[168:171], v[220:223], v[106:109]
	v_mfma_f32_16x16x32_bf16 v[98:101], v[160:163], v[236:239], v[98:101]
	v_mfma_f32_16x16x32_bf16 v[90:93], v[168:171], v[236:239], v[90:93]
	v_mfma_f32_16x16x32_bf16 v[126:129], v[164:167], v[208:211], v[126:129]
	v_mfma_f32_16x16x32_bf16 v[122:125], v[172:175], v[208:211], v[122:125]
	v_mfma_f32_16x16x32_bf16 v[118:121], v[164:167], v[216:219], v[118:121]
	v_mfma_f32_16x16x32_bf16 v[114:117], v[172:175], v[216:219], v[114:117]
	v_mfma_f32_16x16x32_bf16 v[110:113], v[164:167], v[224:227], v[110:113]
	v_mfma_f32_16x16x32_bf16 v[106:109], v[172:175], v[224:227], v[106:109]
	v_mfma_f32_16x16x32_bf16 v[98:101], v[164:167], v[240:243], v[98:101]
	v_mfma_f32_16x16x32_bf16 v[90:93], v[172:175], v[240:243], v[90:93]
	s_setprio 0
	s_setprio 1
	v_mfma_f32_16x16x32_bf16 v[102:105], v[176:179], v[192:195], v[102:105]
	v_mfma_f32_16x16x32_bf16 v[94:97], v[184:187], v[192:195], v[94:97]
	v_mfma_f32_16x16x32_bf16 v[86:89], v[176:179], v[212:215], v[86:89]
	v_mfma_f32_16x16x32_bf16 v[82:85], v[184:187], v[212:215], v[82:85]
	v_mfma_f32_16x16x32_bf16 v[78:81], v[176:179], v[220:223], v[78:81]
	v_mfma_f32_16x16x32_bf16 v[74:77], v[184:187], v[220:223], v[74:77]
	v_mfma_f32_16x16x32_bf16 v[70:73], v[176:179], v[236:239], v[70:73]
	v_mfma_f32_16x16x32_bf16 v[66:69], v[184:187], v[236:239], v[66:69]
	v_mfma_f32_16x16x32_bf16 v[102:105], v[180:183], v[208:211], v[102:105]
	v_mfma_f32_16x16x32_bf16 v[94:97], v[188:191], v[208:211], v[94:97]
	v_mfma_f32_16x16x32_bf16 v[86:89], v[180:183], v[216:219], v[86:89]
	v_mfma_f32_16x16x32_bf16 v[82:85], v[188:191], v[216:219], v[82:85]
	v_mfma_f32_16x16x32_bf16 v[78:81], v[180:183], v[224:227], v[78:81]
	v_mfma_f32_16x16x32_bf16 v[74:77], v[188:191], v[224:227], v[74:77]
	v_mfma_f32_16x16x32_bf16 v[70:73], v[180:183], v[240:243], v[70:73]
	v_mfma_f32_16x16x32_bf16 v[66:69], v[188:191], v[240:243], v[66:69]
	s_setprio 0
	s_barrier
; #define PG8_STAGE(bufoff, gbase, voff) do { _Pragma("unroll") for (int _i = 0; _i < 2; ++_i) \
;         __builtin_amdgcn_global_load_lds((const unsigned*)((const char*)(gbase) + (voff)[_i]), (PG8_LAS unsigned*)(lds + (bufoff) + ldsw + _i * 8192), 16, 0, 0); } while (0)
; #define PG8_LDA(dst, b, h) do { _Pragma("unroll") for (int m = 0; m < 4; ++m) _Pragma("unroll") for (int k = 0; k < 2; ++k) dst[m][k] = *(const PG8_LAS bf16x8*)(lds + PG8_SA(b, h) + aoff + m * 2048 + k * 1024); } while (0)
; #define PG8_MMA(ai, bj, At, Bt) do { __builtin_amdgcn_s_setprio(1); _Pragma("unroll") for (int m = 0; m < 4; ++m) _Pragma("unroll") for (int n = 0; n < 2; ++n) _Pragma("unroll") for (int k = 0; k < 2; ++k) \
;         acc[ai][bj][m][n] = __builtin_amdgcn_mfma_f32_16x16x32_bf16(Bt[n][k], At[m][k], acc[ai][bj][m][n], 0, 0, 0); __builtin_amdgcn_s_setprio(0); } while (0)
; #define PG8_WAIT_V(n) asm volatile("s_waitcnt vmcnt(" #n ")" ::: "memory")
; #define PG8_WAIT_L(n) asm volatile("s_waitcnt lgkmcnt(" #n ")" ::: "memory")
; #define PG8_BAR __builtin_amdgcn_s_barrier()
; #define PG8_SCHED __builtin_amdgcn_sched_barrier(0)
; template <class Epi, class Sched, bool ALIGN_EPI = false, bool SP2 = false>
; __device__ __forceinline__ void gemm_phase(PG8_LAS unsigned char* lds, const Gemm g, const Sched& S, const Epi& E) {
;     ...
;         for (int t = 0; t < nt; t += 2) {
;     ...
;             PG8_LDA(At, 1, 1); PG8_STAGE(PG8_SB(1, 0), b3, voffB); PG8_STAGE(PG8_SB(1, 1), b3 + hstep, voffB); PG8_STAGE(PG8_SA(1, 0), a3, voffA);
;             PG8_WAIT_V(8); PG8_WAIT_L(0); PG8_BAR; PG8_MMA(1, 0, At, B0); PG8_MMA(1, 1, At, B1); PG8_BAR; PG8_SCHED;
	s_add_i32 s23, s44, s2
	v_lshl_add_u64 v[196:197], v[196:197], 0, s[14:15]
	s_mov_b32 m0, s23
	ds_read_b128 v[192:195], v156 offset:49152
	ds_read_b128 v[208:211], v156 offset:50176
	ds_read_b128 v[212:215], v156 offset:51200
	ds_read_b128 v[216:219], v156 offset:52224
	ds_read_b128 v[220:223], v156 offset:53248
	ds_read_b128 v[224:227], v156 offset:54272
	ds_read_b128 v[236:239], v156 offset:55296
	ds_read_b128 v[240:243], v156 offset:56320
	global_load_lds_dwordx4 v[196:197], off
	s_add_i32 m0, s23, 0x2000
	s_add_u32 s30, s30, 0x100080
	v_lshl_add_u64 v[196:197], v[228:229], 0, s[14:15]
	s_addc_u32 s31, s31, 0
	s_add_i32 s23, s45, s2
	global_load_lds_dwordx4 v[196:197], off
	v_lshl_add_u64 v[196:197], s[30:31], 0, v[130:131]
	s_mov_b32 m0, s23
	s_nop 0
	global_load_lds_dwordx4 v[196:197], off
	v_lshl_add_u64 v[196:197], s[30:31], 0, v[132:133]
	s_add_i32 m0, s23, 0x2000
	s_nop 0
	global_load_lds_dwordx4 v[196:197], off
	v_lshl_add_u64 v[196:197], v[244:245], 0, s[14:15]
	s_mov_b32 m0, s36
	s_nop 0
	global_load_lds_dwordx4 v[196:197], off
	v_lshl_add_u64 v[196:197], v[246:247], 0, s[14:15]
	s_mov_b32 m0, s37
	s_nop 0
	global_load_lds_dwordx4 v[196:197], off
	s_waitcnt vmcnt(8)
	s_waitcnt lgkmcnt(0)
	s_barrier
	s_setprio 1
	s_waitcnt lgkmcnt(0)
	v_mfma_f32_16x16x32_bf16 v[62:65], v[160:163], v[192:195], v[62:65]
	v_mfma_f32_16x16x32_bf16 v[58:61], v[168:171], v[192:195], v[58:61]
	v_mfma_f32_16x16x32_bf16 v[54:57], v[160:163], v[212:215], v[54:57]
	v_mfma_f32_16x16x32_bf16 v[50:53], v[168:171], v[212:215], v[50:53]
	v_mfma_f32_16x16x32_bf16 v[46:49], v[160:163], v[220:223], v[46:49]
	v_mfma_f32_16x16x32_bf16 v[42:45], v[168:171], v[220:223], v[42:45]
	v_mfma_f32_16x16x32_bf16 v[34:37], v[160:163], v[236:239], v[34:37]
	v_mfma_f32_16x16x32_bf16 v[26:29], v[168:171], v[236:239], v[26:29]
	v_mfma_f32_16x16x32_bf16 v[62:65], v[164:167], v[208:211], v[62:65]
	v_mfma_f32_16x16x32_bf16 v[58:61], v[172:175], v[208:211], v[58:61]
	v_mfma_f32_16x16x32_bf16 v[54:57], v[164:167], v[216:219], v[54:57]
	v_mfma_f32_16x16x32_bf16 v[50:53], v[172:175], v[216:219], v[50:53]
	v_mfma_f32_16x16x32_bf16 v[46:49], v[164:167], v[224:227], v[46:49]
	v_mfma_f32_16x16x32_bf16 v[42:45], v[172:175], v[224:227], v[42:45]
	v_mfma_f32_16x16x32_bf16 v[34:37], v[164:167], v[240:243], v[34:37]
	v_mfma_f32_16x16x32_bf16 v[26:29], v[172:175], v[240:243], v[26:29]
	s_setprio 0
	s_setprio 1
	v_mfma_f32_16x16x32_bf16 v[38:41], v[176:179], v[192:195], v[38:41]
	v_mfma_f32_16x16x32_bf16 v[30:33], v[184:187], v[192:195], v[30:33]
	v_mfma_f32_16x16x32_bf16 v[22:25], v[176:179], v[212:215], v[22:25]
	v_mfma_f32_16x16x32_bf16 v[18:21], v[184:187], v[212:215], v[18:21]
	v_mfma_f32_16x16x32_bf16 v[14:17], v[176:179], v[220:223], v[14:17]
	v_mfma_f32_16x16x32_bf16 v[10:13], v[184:187], v[220:223], v[10:13]
	v_mfma_f32_16x16x32_bf16 v[6:9], v[176:179], v[236:239], v[6:9]
	v_mfma_f32_16x16x32_bf16 v[2:5], v[184:187], v[236:239], v[2:5]
	v_mfma_f32_16x16x32_bf16 v[38:41], v[180:183], v[208:211], v[38:41]
	v_mfma_f32_16x16x32_bf16 v[30:33], v[188:191], v[208:211], v[30:33]
	v_mfma_f32_16x16x32_bf16 v[22:25], v[180:183], v[216:219], v[22:25]
	v_mfma_f32_16x16x32_bf16 v[18:21], v[188:191], v[216:219], v[18:21]
	v_mfma_f32_16x16x32_bf16 v[14:17], v[180:183], v[224:227], v[14:17]
	v_mfma_f32_16x16x32_bf16 v[10:13], v[188:191], v[224:227], v[10:13]
	v_mfma_f32_16x16x32_bf16 v[6:9], v[180:183], v[240:243], v[6:9]
	v_mfma_f32_16x16x32_bf16 v[2:5], v[188:191], v[240:243], v[2:5]
	s_setprio 0
	s_barrier
	s_add_i32 s21, s21, 2
	s_add_u32 s28, s28, 0x100
	s_addc_u32 s29, s29, 0
	s_add_u32 s7, s7, 0x100
	s_addc_u32 s19, s19, 0
	s_cmp_gt_u32 s21, 5
	s_cbranch_scc0 .LBB0_1118
	s_and_b64 vcc, exec, s[16:17]
	s_cbranch_vccz .LBB0_1121
	s_barrier

; #define PG8_STAGE(bufoff, gbase, voff) do { _Pragma("unroll") for (int _i = 0; _i < 2; ++_i) \
;         __builtin_amdgcn_global_load_lds((const unsigned*)((const char*)(gbase) + (voff)[_i]), (PG8_LAS unsigned*)(lds + (bufoff) + ldsw + _i * 8192), 16, 0, 0); } while (0)
; #define PG8_WAIT_V(n) asm volatile("s_waitcnt vmcnt(" #n ")" ::: "memory")
; #define PG8_BAR __builtin_amdgcn_s_barrier()
; template <class Epi, class Sched, bool ALIGN_EPI = false, bool SP2 = false>
; __device__ __forceinline__ void gemm_phase(PG8_LAS unsigned char* lds, const Gemm g, const Sched& S, const Epi& E) {
;     ...
;     const int K = g.K, LD = g.ld, nt = K / BK;
;     unsigned voffA[2], voffB[2];
; #pragma unroll
;     for (int i = 0; i < 2; ++i) { int R, C; stage_rc(tid * 16 + i * 8192, R, C); const int Rb = Epi::PERM ? ((R & ~31) + perm32(R & 31)) : R;
;         voffA[i] = (unsigned)(R * LD + C) * 2u; voffB[i] = (unsigned)(Rb * LD + C) * 2u; }
;     const size_t kstep = (size_t)(BK * 2);
;     const size_t hstep = (size_t)HALF * LD * 2;
;     const size_t tstep = 2 * hstep;
;     const unsigned ldsw = (unsigned)wid * 1024u;
;     const int aoff = lds_byte(wr * 64 + fr, fq * 8), boff = lds_byte(wc * 32 + fr, fq * 8);
;     ...
;         PG8_STAGE(PG8_SB(0, 0), cB, voffB); PG8_STAGE(PG8_SB(0, 1), cB + hstep, voffB); PG8_STAGE(PG8_SA(0, 0), cA, voffA); PG8_STAGE(PG8_SA(0, 1), cA + hstep, voffA);
;         if (wr == 1) PG8_BAR;
;         PG8_WAIT_V(2); PG8_BAR;
;         PG8_STAGE(PG8_SB(1, 0), cB + kstep, voffB); PG8_STAGE(PG8_SA(1, 0), cA + kstep, voffA); PG8_STAGE(PG8_SB(1, 1), cB + hstep + kstep, voffB);
;         PG8_WAIT_V(6); PG8_BAR;
.LBB0_1268:
	s_lshl_b32 s8, s8, 5
	s_and_b32 s13, s8, 0x60
	s_mov_b64 s[8:9], 0x80
	s_add_i32 m0, s21, 0x18000
	v_lshl_add_u64 v[8:9], v[8:9], 0, s[8:9]
	s_lshl_b32 s11, s10, 13
	s_lshl_b32 s16, s13, 7
	s_waitcnt vmcnt(2)
	s_barrier
	global_load_lds_dwordx4 v[8:9], off
	v_lshl_add_u64 v[4:5], v[4:5], 0, s[8:9]
	s_add_i32 m0, s21, 0x1a000
	s_add_i32 s34, s21, 0x8000
	s_add_i32 s35, s21, 0xa000
	global_load_lds_dwordx4 v[4:5], off
	v_lshl_add_u64 v[2:3], v[2:3], 0, s[8:9]
	s_mov_b32 m0, s34
	s_add_u32 s14, s24, 0x40080
	global_load_lds_dwordx4 v[2:3], off
	v_lshl_add_u64 v[2:3], v[6:7], 0, s[8:9]
	s_mov_b32 m0, s35
	s_addc_u32 s15, s25, 0
	global_load_lds_dwordx4 v[2:3], off
	s_add_i32 m0, s21, 0x1c000
	v_lshl_add_u64 v[2:3], s[14:15], 0, v[134:135]
	global_load_lds_dwordx4 v[2:3], off
	v_lshl_add_u64 v[2:3], s[14:15], 0, v[130:131]
	s_add_i32 m0, s21, 0x1e000
	s_sext_i32_i8 s41, s4
	global_load_lds_dwordx4 v[2:3], off
	v_lshlrev_b32_e32 v2, 1, v12
	s_movk_i32 s4, 0x3c0
	v_lshl_or_b32 v3, v204, 6, v2
	v_and_b32_e32 v4, 32, v232
	v_and_or_b32 v2, v234, s4, v2
	v_bitop3_b32 v148, s16, v2, v4 bitop3:0xf6
	v_lshlrev_b32_e32 v2, 8, v198
	v_bitop3_b32 v3, v3, s11, v4 bitop3:0xde
	v_and_b32_e32 v2, 0x38000, v2
	v_lshlrev_b32_e32 v4, 11, v230
	v_or3_b32 v2, v11, v2, v4
	v_add_u32_e32 v138, v2, v205
	v_lshlrev_b32_e32 v2, 4, v10
	s_mov_b32 s4, 0x1c000
	s_waitcnt vmcnt(6)
	s_cmpk_lt_u32 s5, 0x100
	v_and_b32_e32 v2, 0x78000, v2
	v_lshl_or_b32 v1, s10, 6, v204
	s_cselect_b64 s[10:11], -1, 0
	v_or3_b32 v2, v11, v2, v4
	s_add_i32 s37, s33, 0x100
	s_add_i32 s38, s12, 0x100
	s_add_i32 s40, s4, 0x100
	s_mov_b32 s36, 0x18000
	v_or_b32_e32 v149, s13, v12
	v_mov_b32_e32 v139, v135
	v_add_u32_e32 v140, v2, v205
	v_mov_b32_e32 v141, v135
	v_mov_b64_e32 v[142:143], 0x660
	v_mov_b64_e32 v[144:145], 0x65f
	v_add_u32_e32 v150, s37, v148
	v_add_u32_e32 v151, s38, v148
	v_add_u32_e32 v152, 0x100, v3
	s_mov_b32 s39, 0x30000
	v_add_u32_e32 v153, s40, v148
	s_barrier
	s_branch .LBB0_1271

; #define PG8_STAGE(bufoff, gbase, voff) do { _Pragma("unroll") for (int _i = 0; _i < 2; ++_i) \
;         __builtin_amdgcn_global_load_lds((const unsigned*)((const char*)(gbase) + (voff)[_i]), (PG8_LAS unsigned*)(lds + (bufoff) + ldsw + _i * 8192), 16, 0, 0); } while (0)
; #define PG8_LDA(dst, b, h) do { _Pragma("unroll") for (int m = 0; m < 4; ++m) _Pragma("unroll") for (int k = 0; k < 2; ++k) dst[m][k] = *(const PG8_LAS bf16x8*)(lds + PG8_SA(b, h) + aoff + m * 2048 + k * 1024); } while (0)
; #define PG8_LDB(dst, b, h) do { _Pragma("unroll") for (int n = 0; n < 2; ++n) _Pragma("unroll") for (int k = 0; k < 2; ++k) dst[n][k] = *(const PG8_LAS bf16x8*)(lds + PG8_SB(b, h) + boff + n * 2048 + k * 1024); } while (0)
; #define PG8_MMA(ai, bj, At, Bt) do { __builtin_amdgcn_s_setprio(1); _Pragma("unroll") for (int m = 0; m < 4; ++m) _Pragma("unroll") for (int n = 0; n < 2; ++n) _Pragma("unroll") for (int k = 0; k < 2; ++k) \
;         acc[ai][bj][m][n] = __builtin_amdgcn_mfma_f32_16x16x32_bf16(Bt[n][k], At[m][k], acc[ai][bj][m][n], 0, 0, 0); __builtin_amdgcn_s_setprio(0); } while (0)
; #define PG8_WAIT_V(n) asm volatile("s_waitcnt vmcnt(" #n ")" ::: "memory")
; #define PG8_WAIT_L(n) asm volatile("s_waitcnt lgkmcnt(" #n ")" ::: "memory")
; template <class Epi, class Sched, bool ALIGN_EPI = false, bool SP2 = false>
; __device__ __forceinline__ void gemm_phase(PG8_LAS unsigned char* lds, const Gemm g, const Sched& S, const Epi& E) {
;     ...
;             const bool last = (t == nt - 2);
;             const char* a1 = cA + (size_t)(t + 1) * kstep;
;             const char* a2 = last ? nA : cA + (size_t)(t + 2) * kstep; const char* b2 = last ? nB : cB + (size_t)(t + 2) * kstep;
;             const char* a3 = a2 + kstep; const char* b3 = b2 + kstep;
;             if (last && has_next) S.a_ready(nxt);
;             if constexpr (SP2) {
;             PG8_LDB(B0, 0, 0); PG8_LDB(B1, 0, 1); PG8_SCHED; PG8_LDA(At, 0, 0); PG8_STAGE(PG8_SA(1, 1), a1 + hstep, voffA);
;             PG8_WAIT_V(8); PG8_WAIT_L(0); PG8_BAR; PG8_MMA(0, 0, At, B0); PG8_MMA(0, 1, At, B1); PG8_BAR; PG8_SCHED;
;             PG8_LDA(At, 0, 1); PG8_STAGE(PG8_SB(0, 0), b2, voffB); PG8_STAGE(PG8_SB(0, 1), b2 + hstep, voffB); PG8_STAGE(PG8_SA(0, 0), a2, voffA);
;             PG8_WAIT_V(8); PG8_WAIT_L(0); PG8_BAR; PG8_MMA(1, 0, At, B0); PG8_MMA(1, 1, At, B1); PG8_BAR; PG8_SCHED;
.LBB0_1274:
	ds_read_b128 v[154:157], v150
	ds_read_b128 v[158:161], v150 offset:1024
	ds_read_b128 v[162:165], v150 offset:2048
	ds_read_b128 v[166:169], v150 offset:3072
	ds_read_b128 v[170:173], v151
	ds_read_b128 v[174:177], v151 offset:1024
	ds_read_b128 v[178:181], v151 offset:2048
	ds_read_b128 v[182:185], v151 offset:3072
	s_add_u32 s24, s22, 0xfffc0080
	s_addc_u32 s25, s23, -1
	s_cmp_eq_u32 s46, 12
	s_cselect_b32 s27, s15, s25
	s_cselect_b32 s26, s42, s24
	s_cselect_b32 s25, s13, s45
	s_cselect_b32 s24, s43, s44
	v_lshl_add_u64 v[146:147], s[22:23], 0, v[138:139]
	s_add_i32 m0, s21, 0xc000
	ds_read_b128 v[186:189], v152
	ds_read_b128 v[190:193], v152 offset:1024
	ds_read_b128 v[194:197], v152 offset:2048
	ds_read_b128 v[208:211], v152 offset:3072
	ds_read_b128 v[212:215], v152 offset:4096
	ds_read_b128 v[216:219], v152 offset:5120
	ds_read_b128 v[220:223], v152 offset:6144
	ds_read_b128 v[224:227], v152 offset:7168
	global_load_lds_dwordx4 v[146:147], off
	v_lshl_add_u64 v[146:147], s[22:23], 0, v[140:141]
	s_add_i32 m0, s21, 0xe000
	s_nop 0
	global_load_lds_dwordx4 v[146:147], off
	s_waitcnt vmcnt(8)
	s_waitcnt lgkmcnt(0)
	s_barrier
	s_setprio 1
	s_waitcnt lgkmcnt(0)
	v_mfma_f32_16x16x32_bf16 v[126:129], v[154:157], v[186:189], v[126:129]
	v_mfma_f32_16x16x32_bf16 v[122:125], v[162:165], v[186:189], v[122:125]
	v_mfma_f32_16x16x32_bf16 v[118:121], v[154:157], v[194:197], v[118:121]
	v_mfma_f32_16x16x32_bf16 v[114:117], v[162:165], v[194:197], v[114:117]
	v_mfma_f32_16x16x32_bf16 v[102:105], v[154:157], v[212:215], v[102:105]
	v_mfma_f32_16x16x32_bf16 v[98:101], v[162:165], v[212:215], v[98:101]
	v_mfma_f32_16x16x32_bf16 v[86:89], v[154:157], v[220:223], v[86:89]
	v_mfma_f32_16x16x32_bf16 v[82:85], v[162:165], v[220:223], v[82:85]
	v_mfma_f32_16x16x32_bf16 v[126:129], v[158:161], v[190:193], v[126:129]
	v_mfma_f32_16x16x32_bf16 v[122:125], v[166:169], v[190:193], v[122:125]
	v_mfma_f32_16x16x32_bf16 v[118:121], v[158:161], v[208:211], v[118:121]
	v_mfma_f32_16x16x32_bf16 v[114:117], v[166:169], v[208:211], v[114:117]
	v_mfma_f32_16x16x32_bf16 v[102:105], v[158:161], v[216:219], v[102:105]
	v_mfma_f32_16x16x32_bf16 v[98:101], v[166:169], v[216:219], v[98:101]
	v_mfma_f32_16x16x32_bf16 v[86:89], v[158:161], v[224:227], v[86:89]
	v_mfma_f32_16x16x32_bf16 v[82:85], v[166:169], v[224:227], v[82:85]
	s_setprio 0
	s_setprio 1
	v_mfma_f32_16x16x32_bf16 v[110:113], v[170:173], v[186:189], v[110:113]
	v_mfma_f32_16x16x32_bf16 v[106:109], v[178:181], v[186:189], v[106:109]
	v_mfma_f32_16x16x32_bf16 v[94:97], v[170:173], v[194:197], v[94:97]
	v_mfma_f32_16x16x32_bf16 v[90:93], v[178:181], v[194:197], v[90:93]
	v_mfma_f32_16x16x32_bf16 v[78:81], v[170:173], v[212:215], v[78:81]
	v_mfma_f32_16x16x32_bf16 v[74:77], v[178:181], v[212:215], v[74:77]
	v_mfma_f32_16x16x32_bf16 v[70:73], v[170:173], v[220:223], v[70:73]
	v_mfma_f32_16x16x32_bf16 v[66:69], v[178:181], v[220:223], v[66:69]
	v_mfma_f32_16x16x32_bf16 v[110:113], v[174:177], v[190:193], v[110:113]
	v_mfma_f32_16x16x32_bf16 v[106:109], v[182:185], v[190:193], v[106:109]
	v_mfma_f32_16x16x32_bf16 v[94:97], v[174:177], v[208:211], v[94:97]
	v_mfma_f32_16x16x32_bf16 v[90:93], v[182:185], v[208:211], v[90:93]
	v_mfma_f32_16x16x32_bf16 v[78:81], v[174:177], v[216:219], v[78:81]
	v_mfma_f32_16x16x32_bf16 v[74:77], v[182:185], v[216:219], v[74:77]
	v_mfma_f32_16x16x32_bf16 v[70:73], v[174:177], v[224:227], v[70:73]
	v_mfma_f32_16x16x32_bf16 v[66:69], v[182:185], v[224:227], v[66:69]
	s_setprio 0
	s_barrier
	s_add_i32 s47, s37, s2
	v_lshl_add_u64 v[146:147], s[24:25], 0, v[134:135]
	s_mov_b32 m0, s47
	ds_read_b128 v[186:189], v152 offset:16384
	ds_read_b128 v[190:193], v152 offset:17408
	ds_read_b128 v[194:197], v152 offset:18432
	ds_read_b128 v[208:211], v152 offset:19456
	ds_read_b128 v[212:215], v152 offset:20480
	ds_read_b128 v[216:219], v152 offset:21504
	ds_read_b128 v[220:223], v152 offset:22528
	ds_read_b128 v[224:227], v152 offset:23552
	global_load_lds_dwordx4 v[146:147], off
	s_add_i32 m0, s47, 0x2000
	s_add_u32 s48, s24, 0x40000
	v_lshl_add_u64 v[228:229], s[24:25], 0, v[130:131]
	s_addc_u32 s49, s25, 0
	s_add_i32 s47, s38, s2
	global_load_lds_dwordx4 v[228:229], off
	v_lshl_add_u64 v[236:237], s[48:49], 0, v[134:135]
	s_mov_b32 m0, s47
	v_lshl_add_u64 v[238:239], s[26:27], 0, v[132:133]
	global_load_lds_dwordx4 v[236:237], off
	v_lshl_add_u64 v[236:237], s[48:49], 0, v[130:131]
	s_add_i32 m0, s47, 0x2000
	s_nop 0
	global_load_lds_dwordx4 v[236:237], off
	v_lshl_add_u64 v[236:237], s[26:27], 0, v[136:137]
	s_mov_b32 m0, s21
	s_nop 0
	global_load_lds_dwordx4 v[236:237], off
	s_mov_b32 m0, s28
	s_nop 0
	global_load_lds_dwordx4 v[238:239], off
	s_waitcnt vmcnt(8)
	s_waitcnt lgkmcnt(0)
	s_barrier
; #define PG8_STAGE(bufoff, gbase, voff) do { _Pragma("unroll") for (int _i = 0; _i < 2; ++_i) \
;         __builtin_amdgcn_global_load_lds((const unsigned*)((const char*)(gbase) + (voff)[_i]), (PG8_LAS unsigned*)(lds + (bufoff) + ldsw + _i * 8192), 16, 0, 0); } while (0)
; #define PG8_LDA(dst, b, h) do { _Pragma("unroll") for (int m = 0; m < 4; ++m) _Pragma("unroll") for (int k = 0; k < 2; ++k) dst[m][k] = *(const PG8_LAS bf16x8*)(lds + PG8_SA(b, h) + aoff + m * 2048 + k * 1024); } while (0)
; #define PG8_LDB(dst, b, h) do { _Pragma("unroll") for (int n = 0; n < 2; ++n) _Pragma("unroll") for (int k = 0; k < 2; ++k) dst[n][k] = *(const PG8_LAS bf16x8*)(lds + PG8_SB(b, h) + boff + n * 2048 + k * 1024); } while (0)
; #define PG8_MMA(ai, bj, At, Bt) do { __builtin_amdgcn_s_setprio(1); _Pragma("unroll") for (int m = 0; m < 4; ++m) _Pragma("unroll") for (int n = 0; n < 2; ++n) _Pragma("unroll") for (int k = 0; k < 2; ++k) \
;         acc[ai][bj][m][n] = __builtin_amdgcn_mfma_f32_16x16x32_bf16(Bt[n][k], At[m][k], acc[ai][bj][m][n], 0, 0, 0); __builtin_amdgcn_s_setprio(0); } while (0)
; #define PG8_WAIT_V(n) asm volatile("s_waitcnt vmcnt(" #n ")" ::: "memory")
; #define PG8_WAIT_L(n) asm volatile("s_waitcnt lgkmcnt(" #n ")" ::: "memory")
; #define PG8_BAR __builtin_amdgcn_s_barrier()
; #define PG8_SCHED __builtin_amdgcn_sched_barrier(0)
; template <class Epi, class Sched, bool ALIGN_EPI = false, bool SP2 = false>
; __device__ __forceinline__ void gemm_phase(PG8_LAS unsigned char* lds, const Gemm g, const Sched& S, const Epi& E) {
;     ...
;             PG8_WAIT_V(8); PG8_WAIT_L(0); PG8_BAR; PG8_MMA(1, 0, At, B0); PG8_MMA(1, 1, At, B1); PG8_BAR; PG8_SCHED;
;             PG8_LDB(B0, 1, 0); PG8_LDB(B1, 1, 1); PG8_SCHED; PG8_LDA(At, 1, 0); PG8_STAGE(PG8_SA(0, 1), a2 + hstep, voffA);
;             PG8_WAIT_V(8); PG8_WAIT_L(0); PG8_BAR; PG8_MMA(0, 0, At, B0); PG8_MMA(0, 1, At, B1); PG8_BAR; PG8_SCHED;
	s_setprio 1
	s_waitcnt lgkmcnt(0)
	v_mfma_f32_16x16x32_bf16 v[62:65], v[154:157], v[186:189], v[62:65]
	v_mfma_f32_16x16x32_bf16 v[58:61], v[162:165], v[186:189], v[58:61]
	v_mfma_f32_16x16x32_bf16 v[54:57], v[154:157], v[194:197], v[54:57]
	v_mfma_f32_16x16x32_bf16 v[50:53], v[162:165], v[194:197], v[50:53]
	v_mfma_f32_16x16x32_bf16 v[38:41], v[154:157], v[212:215], v[38:41]
	v_mfma_f32_16x16x32_bf16 v[34:37], v[162:165], v[212:215], v[34:37]
	v_mfma_f32_16x16x32_bf16 v[22:25], v[154:157], v[220:223], v[22:25]
	v_mfma_f32_16x16x32_bf16 v[18:21], v[162:165], v[220:223], v[18:21]
	v_mfma_f32_16x16x32_bf16 v[62:65], v[158:161], v[190:193], v[62:65]
	v_mfma_f32_16x16x32_bf16 v[58:61], v[166:169], v[190:193], v[58:61]
	v_mfma_f32_16x16x32_bf16 v[54:57], v[158:161], v[208:211], v[54:57]
	v_mfma_f32_16x16x32_bf16 v[50:53], v[166:169], v[208:211], v[50:53]
	v_mfma_f32_16x16x32_bf16 v[38:41], v[158:161], v[216:219], v[38:41]
	v_mfma_f32_16x16x32_bf16 v[34:37], v[166:169], v[216:219], v[34:37]
	v_mfma_f32_16x16x32_bf16 v[22:25], v[158:161], v[224:227], v[22:25]
	v_mfma_f32_16x16x32_bf16 v[18:21], v[166:169], v[224:227], v[18:21]
	s_setprio 0
	s_setprio 1
	v_mfma_f32_16x16x32_bf16 v[46:49], v[170:173], v[186:189], v[46:49]
	v_mfma_f32_16x16x32_bf16 v[42:45], v[178:181], v[186:189], v[42:45]
	v_mfma_f32_16x16x32_bf16 v[30:33], v[170:173], v[194:197], v[30:33]
	v_mfma_f32_16x16x32_bf16 v[26:29], v[178:181], v[194:197], v[26:29]
	v_mfma_f32_16x16x32_bf16 v[14:17], v[170:173], v[212:215], v[14:17]
	v_mfma_f32_16x16x32_bf16 v[10:13], v[178:181], v[212:215], v[10:13]
	v_mfma_f32_16x16x32_bf16 v[6:9], v[170:173], v[220:223], v[6:9]
	v_mfma_f32_16x16x32_bf16 v[2:5], v[178:181], v[220:223], v[2:5]
	v_mfma_f32_16x16x32_bf16 v[46:49], v[174:177], v[190:193], v[46:49]
	v_mfma_f32_16x16x32_bf16 v[42:45], v[182:185], v[190:193], v[42:45]
	v_mfma_f32_16x16x32_bf16 v[30:33], v[174:177], v[208:211], v[30:33]
	v_mfma_f32_16x16x32_bf16 v[26:29], v[182:185], v[208:211], v[26:29]
	v_mfma_f32_16x16x32_bf16 v[14:17], v[174:177], v[216:219], v[14:17]
	v_mfma_f32_16x16x32_bf16 v[10:13], v[182:185], v[216:219], v[10:13]
	v_mfma_f32_16x16x32_bf16 v[6:9], v[174:177], v[224:227], v[6:9]
	v_mfma_f32_16x16x32_bf16 v[2:5], v[182:185], v[224:227], v[2:5]
	s_setprio 0
	s_barrier
	s_add_i32 s47, s36, 0x100
	v_add_u32_e32 v166, s47, v148
	ds_read_b128 v[154:157], v166
	ds_read_b128 v[158:161], v166 offset:1024
	ds_read_b128 v[162:165], v166 offset:2048
	ds_read_b128 v[166:169], v166 offset:3072
	ds_read_b128 v[170:173], v153
	ds_read_b128 v[174:177], v153 offset:1024
	ds_read_b128 v[178:181], v153 offset:2048
	ds_read_b128 v[182:185], v153 offset:3072
	s_add_u32 s26, s26, 0x40000
	s_addc_u32 s27, s27, 0
	s_mov_b32 m0, s29
	v_lshl_add_u64 v[240:241], s[26:27], 0, v[136:137]
	ds_read_b128 v[186:189], v152 offset:32768
	ds_read_b128 v[190:193], v152 offset:33792
	ds_read_b128 v[194:197], v152 offset:34816
	ds_read_b128 v[208:211], v152 offset:35840
	ds_read_b128 v[212:215], v152 offset:36864
	ds_read_b128 v[216:219], v152 offset:37888
	ds_read_b128 v[220:223], v152 offset:38912
	ds_read_b128 v[224:227], v152 offset:39936
	global_load_lds_dwordx4 v[240:241], off
	v_lshl_add_u64 v[240:241], s[26:27], 0, v[132:133]
	s_mov_b32 m0, s30
	s_nop 0
	global_load_lds_dwordx4 v[240:241], off
	s_waitcnt vmcnt(8)
	s_waitcnt lgkmcnt(0)
	s_barrier
	s_setprio 1
	s_waitcnt lgkmcnt(0)
	v_mfma_f32_16x16x32_bf16 v[126:129], v[154:157], v[186:189], v[126:129]
	v_mfma_f32_16x16x32_bf16 v[122:125], v[162:165], v[186:189], v[122:125]
	v_mfma_f32_16x16x32_bf16 v[118:121], v[154:157], v[194:197], v[118:121]
	v_mfma_f32_16x16x32_bf16 v[114:117], v[162:165], v[194:197], v[114:117]
	v_mfma_f32_16x16x32_bf16 v[102:105], v[154:157], v[212:215], v[102:105]
	v_mfma_f32_16x16x32_bf16 v[98:101], v[162:165], v[212:215], v[98:101]
	v_mfma_f32_16x16x32_bf16 v[86:89], v[154:157], v[220:223], v[86:89]
	v_mfma_f32_16x16x32_bf16 v[82:85], v[162:165], v[220:223], v[82:85]
	v_mfma_f32_16x16x32_bf16 v[126:129], v[158:161], v[190:193], v[126:129]
	v_mfma_f32_16x16x32_bf16 v[122:125], v[166:169], v[190:193], v[122:125]
	v_mfma_f32_16x16x32_bf16 v[118:121], v[158:161], v[208:211], v[118:121]
	v_mfma_f32_16x16x32_bf16 v[114:117], v[166:169], v[208:211], v[114:117]
	v_mfma_f32_16x16x32_bf16 v[102:105], v[158:161], v[216:219], v[102:105]
	v_mfma_f32_16x16x32_bf16 v[98:101], v[166:169], v[216:219], v[98:101]
	v_mfma_f32_16x16x32_bf16 v[86:89], v[158:161], v[224:227], v[86:89]
	v_mfma_f32_16x16x32_bf16 v[82:85], v[166:169], v[224:227], v[82:85]
	s_setprio 0
	s_setprio 1
	v_mfma_f32_16x16x32_bf16 v[110:113], v[170:173], v[186:189], v[110:113]
	v_mfma_f32_16x16x32_bf16 v[106:109], v[178:181], v[186:189], v[106:109]
	v_mfma_f32_16x16x32_bf16 v[94:97], v[170:173], v[194:197], v[94:97]
	v_mfma_f32_16x16x32_bf16 v[90:93], v[178:181], v[194:197], v[90:93]
	v_mfma_f32_16x16x32_bf16 v[78:81], v[170:173], v[212:215], v[78:81]
	v_mfma_f32_16x16x32_bf16 v[74:77], v[178:181], v[212:215], v[74:77]
	v_mfma_f32_16x16x32_bf16 v[70:73], v[170:173], v[220:223], v[70:73]
	v_mfma_f32_16x16x32_bf16 v[66:69], v[178:181], v[220:223], v[66:69]
	v_mfma_f32_16x16x32_bf16 v[110:113], v[174:177], v[190:193], v[110:113]
	v_mfma_f32_16x16x32_bf16 v[106:109], v[182:185], v[190:193], v[106:109]
	v_mfma_f32_16x16x32_bf16 v[94:97], v[174:177], v[208:211], v[94:97]
	v_mfma_f32_16x16x32_bf16 v[90:93], v[182:185], v[208:211], v[90:93]
	v_mfma_f32_16x16x32_bf16 v[78:81], v[174:177], v[216:219], v[78:81]
	v_mfma_f32_16x16x32_bf16 v[74:77], v[182:185], v[216:219], v[74:77]
	v_mfma_f32_16x16x32_bf16 v[70:73], v[174:177], v[224:227], v[70:73]
	v_mfma_f32_16x16x32_bf16 v[66:69], v[182:185], v[224:227], v[66:69]
	s_setprio 0
	s_barrier
; #define PG8_STAGE(bufoff, gbase, voff) do { _Pragma("unroll") for (int _i = 0; _i < 2; ++_i) \
;         __builtin_amdgcn_global_load_lds((const unsigned*)((const char*)(gbase) + (voff)[_i]), (PG8_LAS unsigned*)(lds + (bufoff) + ldsw + _i * 8192), 16, 0, 0); } while (0)
; #define PG8_LDA(dst, b, h) do { _Pragma("unroll") for (int m = 0; m < 4; ++m) _Pragma("unroll") for (int k = 0; k < 2; ++k) dst[m][k] = *(const PG8_LAS bf16x8*)(lds + PG8_SA(b, h) + aoff + m * 2048 + k * 1024); } while (0)
; #define PG8_MMA(ai, bj, At, Bt) do { __builtin_amdgcn_s_setprio(1); _Pragma("unroll") for (int m = 0; m < 4; ++m) _Pragma("unroll") for (int n = 0; n < 2; ++n) _Pragma("unroll") for (int k = 0; k < 2; ++k) \
;         acc[ai][bj][m][n] = __builtin_amdgcn_mfma_f32_16x16x32_bf16(Bt[n][k], At[m][k], acc[ai][bj][m][n], 0, 0, 0); __builtin_amdgcn_s_setprio(0); } while (0)
; #define PG8_WAIT_V(n) asm volatile("s_waitcnt vmcnt(" #n ")" ::: "memory")
; #define PG8_WAIT_L(n) asm volatile("s_waitcnt lgkmcnt(" #n ")" ::: "memory")
; #define PG8_BAR __builtin_amdgcn_s_barrier()
; #define PG8_SCHED __builtin_amdgcn_sched_barrier(0)
; template <class Epi, class Sched, bool ALIGN_EPI = false, bool SP2 = false>
; __device__ __forceinline__ void gemm_phase(PG8_LAS unsigned char* lds, const Gemm g, const Sched& S, const Epi& E) {
;     ...
;         for (int t = 0; t < nt; t += 2) {
;     ...
;             PG8_LDA(At, 1, 1); PG8_STAGE(PG8_SB(1, 0), b3, voffB); PG8_STAGE(PG8_SB(1, 1), b3 + hstep, voffB); PG8_STAGE(PG8_SA(1, 0), a3, voffA);
;             PG8_WAIT_V(8); PG8_WAIT_L(0); PG8_BAR; PG8_MMA(1, 0, At, B0); PG8_MMA(1, 1, At, B1); PG8_BAR; PG8_SCHED;
	s_add_i32 s26, s47, s2
	v_lshl_add_u64 v[146:147], v[146:147], 0, s[8:9]
	s_mov_b32 m0, s26
	ds_read_b128 v[186:189], v152 offset:49152
	ds_read_b128 v[190:193], v152 offset:50176
	ds_read_b128 v[194:197], v152 offset:51200
	ds_read_b128 v[208:211], v152 offset:52224
	ds_read_b128 v[212:215], v152 offset:53248
	ds_read_b128 v[216:219], v152 offset:54272
	ds_read_b128 v[220:223], v152 offset:55296
	ds_read_b128 v[224:227], v152 offset:56320
	global_load_lds_dwordx4 v[146:147], off
	s_add_i32 m0, s26, 0x2000
	s_add_u32 s24, s24, 0x40080
	v_lshl_add_u64 v[146:147], v[228:229], 0, s[8:9]
	s_addc_u32 s25, s25, 0
	s_add_i32 s26, s40, s2
	global_load_lds_dwordx4 v[146:147], off
	v_lshl_add_u64 v[146:147], s[24:25], 0, v[134:135]
	s_mov_b32 m0, s26
	s_nop 0
	global_load_lds_dwordx4 v[146:147], off
	v_lshl_add_u64 v[146:147], s[24:25], 0, v[130:131]
	s_add_i32 m0, s26, 0x2000
	s_nop 0
	global_load_lds_dwordx4 v[146:147], off
	v_lshl_add_u64 v[146:147], v[236:237], 0, s[8:9]
	s_mov_b32 m0, s34
	s_nop 0
	global_load_lds_dwordx4 v[146:147], off
	v_lshl_add_u64 v[146:147], v[238:239], 0, s[8:9]
	s_mov_b32 m0, s35
	s_nop 0
	global_load_lds_dwordx4 v[146:147], off
	s_waitcnt vmcnt(8)
	s_waitcnt lgkmcnt(0)
	s_barrier
	s_setprio 1
	s_waitcnt lgkmcnt(0)
	v_mfma_f32_16x16x32_bf16 v[62:65], v[154:157], v[186:189], v[62:65]
	v_mfma_f32_16x16x32_bf16 v[58:61], v[162:165], v[186:189], v[58:61]
	v_mfma_f32_16x16x32_bf16 v[54:57], v[154:157], v[194:197], v[54:57]
	v_mfma_f32_16x16x32_bf16 v[50:53], v[162:165], v[194:197], v[50:53]
	v_mfma_f32_16x16x32_bf16 v[38:41], v[154:157], v[212:215], v[38:41]
	v_mfma_f32_16x16x32_bf16 v[34:37], v[162:165], v[212:215], v[34:37]
	v_mfma_f32_16x16x32_bf16 v[22:25], v[154:157], v[220:223], v[22:25]
	v_mfma_f32_16x16x32_bf16 v[18:21], v[162:165], v[220:223], v[18:21]
	v_mfma_f32_16x16x32_bf16 v[62:65], v[158:161], v[190:193], v[62:65]
	v_mfma_f32_16x16x32_bf16 v[58:61], v[166:169], v[190:193], v[58:61]
	v_mfma_f32_16x16x32_bf16 v[54:57], v[158:161], v[208:211], v[54:57]
	v_mfma_f32_16x16x32_bf16 v[50:53], v[166:169], v[208:211], v[50:53]
	v_mfma_f32_16x16x32_bf16 v[38:41], v[158:161], v[216:219], v[38:41]
	v_mfma_f32_16x16x32_bf16 v[34:37], v[166:169], v[216:219], v[34:37]
	v_mfma_f32_16x16x32_bf16 v[22:25], v[158:161], v[224:227], v[22:25]
	v_mfma_f32_16x16x32_bf16 v[18:21], v[166:169], v[224:227], v[18:21]
	s_setprio 0
	s_setprio 1
	v_mfma_f32_16x16x32_bf16 v[46:49], v[170:173], v[186:189], v[46:49]
	v_mfma_f32_16x16x32_bf16 v[42:45], v[178:181], v[186:189], v[42:45]
	v_mfma_f32_16x16x32_bf16 v[30:33], v[170:173], v[194:197], v[30:33]
	v_mfma_f32_16x16x32_bf16 v[26:29], v[178:181], v[194:197], v[26:29]
	v_mfma_f32_16x16x32_bf16 v[14:17], v[170:173], v[212:215], v[14:17]
	v_mfma_f32_16x16x32_bf16 v[10:13], v[178:181], v[212:215], v[10:13]
	v_mfma_f32_16x16x32_bf16 v[6:9], v[170:173], v[220:223], v[6:9]
	v_mfma_f32_16x16x32_bf16 v[2:5], v[178:181], v[220:223], v[2:5]
	v_mfma_f32_16x16x32_bf16 v[46:49], v[174:177], v[190:193], v[46:49]
	v_mfma_f32_16x16x32_bf16 v[42:45], v[182:185], v[190:193], v[42:45]
	v_mfma_f32_16x16x32_bf16 v[30:33], v[174:177], v[208:211], v[30:33]
	v_mfma_f32_16x16x32_bf16 v[26:29], v[182:185], v[208:211], v[26:29]
	v_mfma_f32_16x16x32_bf16 v[14:17], v[174:177], v[216:219], v[14:17]
	v_mfma_f32_16x16x32_bf16 v[10:13], v[182:185], v[216:219], v[10:13]
	v_mfma_f32_16x16x32_bf16 v[6:9], v[174:177], v[224:227], v[6:9]
	v_mfma_f32_16x16x32_bf16 v[2:5], v[182:185], v[224:227], v[2:5]
	s_setprio 0
	s_barrier
	s_add_i32 s46, s46, 2
	s_add_u32 s22, s22, 0x100
	s_addc_u32 s23, s23, 0
	s_add_u32 s44, s44, 0x100
	s_addc_u32 s45, s45, 0
	s_cmp_gt_u32 s46, 13
	s_cbranch_scc0 .LBB0_1274
	s_and_b64 vcc, exec, s[10:11]
	s_cbranch_vccz .LBB0_1277
	s_barrier

; #define PG8_STAGE(bufoff, gbase, voff) do { _Pragma("unroll") for (int _i = 0; _i < 2; ++_i) \
;         __builtin_amdgcn_global_load_lds((const unsigned*)((const char*)(gbase) + (voff)[_i]), (PG8_LAS unsigned*)(lds + (bufoff) + ldsw + _i * 8192), 16, 0, 0); } while (0)
; #define PG8_WAIT_V(n) asm volatile("s_waitcnt vmcnt(" #n ")" ::: "memory")
; #define PG8_BAR __builtin_amdgcn_s_barrier()
; template <class Epi, class Sched, bool ALIGN_EPI = false, bool SP2 = false>
; __device__ __forceinline__ void gemm_phase(PG8_LAS unsigned char* lds, const Gemm g, const Sched& S, const Epi& E) {
;     ...
;     const int K = g.K, LD = g.ld, nt = K / BK;
;     unsigned voffA[2], voffB[2];
; #pragma unroll
;     for (int i = 0; i < 2; ++i) { int R, C; stage_rc(tid * 16 + i * 8192, R, C); const int Rb = Epi::PERM ? ((R & ~31) + perm32(R & 31)) : R;
;         voffA[i] = (unsigned)(R * LD + C) * 2u; voffB[i] = (unsigned)(Rb * LD + C) * 2u; }
;     const size_t kstep = (size_t)(BK * 2);
;     const size_t hstep = (size_t)HALF * LD * 2;
;     const size_t tstep = 2 * hstep;
;     const unsigned ldsw = (unsigned)wid * 1024u;
;     const int aoff = lds_byte(wr * 64 + fr, fq * 8), boff = lds_byte(wc * 32 + fr, fq * 8);
;     ...
;         PG8_STAGE(PG8_SB(0, 0), cB, voffB); PG8_STAGE(PG8_SB(0, 1), cB + hstep, voffB); PG8_STAGE(PG8_SA(0, 0), cA, voffA); PG8_STAGE(PG8_SA(0, 1), cA + hstep, voffA);
;         if (wr == 1) PG8_BAR;
;         PG8_WAIT_V(2); PG8_BAR;
;         PG8_STAGE(PG8_SB(1, 0), cB + kstep, voffB); PG8_STAGE(PG8_SA(1, 0), cA + kstep, voffA); PG8_STAGE(PG8_SB(1, 1), cB + hstep + kstep, voffB);
;         PG8_WAIT_V(6); PG8_BAR;
.LBB0_1438:
	s_lshl_b32 s10, s10, 5
	s_and_b32 s17, s10, 0x60
	s_mov_b64 s[10:11], 0x80
	s_add_i32 m0, s3, 0x18000
	v_lshl_add_u64 v[4:5], v[4:5], 0, s[10:11]
	s_lshl_b32 s13, s5, 13
	s_lshl_b32 s20, s17, 7
	s_waitcnt vmcnt(2)
	s_barrier
	global_load_lds_dwordx4 v[4:5], off
	v_lshl_add_u64 v[0:1], v[0:1], 0, s[10:11]
	s_add_i32 m0, s3, 0x1a000
	s_add_i32 s40, s3, 0x8000
	s_add_i32 s41, s3, 0xa000
	global_load_lds_dwordx4 v[0:1], off
	v_lshl_add_u64 v[0:1], v[2:3], 0, s[10:11]
	s_mov_b32 m0, s40
	s_add_u32 s18, s36, 0x40080
	global_load_lds_dwordx4 v[0:1], off
	v_lshl_add_u64 v[0:1], v[6:7], 0, s[10:11]
	s_mov_b32 m0, s41
	s_addc_u32 s19, s37, 0
	global_load_lds_dwordx4 v[0:1], off
	s_add_i32 m0, s3, 0x1c000
	v_lshl_add_u64 v[0:1], s[18:19], 0, v[132:133]
	global_load_lds_dwordx4 v[0:1], off
	v_lshl_add_u64 v[0:1], s[18:19], 0, v[134:135]
	s_add_i32 m0, s3, 0x1e000
	v_lshlrev_b32_e32 v3, 2, v204
	global_load_lds_dwordx4 v[0:1], off
	v_lshrrev_b32_e32 v0, 1, v198
	v_and_b32_e32 v0, 24, v0
	v_lshlrev_b32_e32 v1, 1, v0
	v_lshl_or_b32 v2, v204, 6, v1
	v_and_b32_e32 v3, 32, v3
	v_or_b32_e32 v153, s17, v0
	v_lshlrev_b32_e32 v0, 8, v198
	v_bitop3_b32 v2, v2, s13, v3 bitop3:0xde
	v_and_b32_e32 v0, 0x38000, v0
	v_lshlrev_b32_e32 v3, 11, v230
	v_or3_b32 v0, v8, v0, v3
	v_add_u32_e32 v136, v0, v205
	v_lshlrev_b32_e32 v0, 4, v9
	s_sext_i32_i8 s47, s4
	v_lshl_or_b32 v152, s5, 6, v204
	v_or_b32_e32 v1, v1, v150
	s_mov_b32 s4, 0x18000
	s_mov_b32 s5, 0x1c000
	s_waitcnt vmcnt(6)
	s_cmpk_lt_u32 s12, 0x100
	v_and_b32_e32 v0, 0x78000, v0
	v_bitop3_b32 v1, s20, v1, v151 bitop3:0xf6
	s_cselect_b64 s[12:13], -1, 0
	v_or3_b32 v0, v8, v0, v3
	s_add_i32 s43, s14, 0x100
	s_add_i32 s44, s16, 0x100
	s_add_i32 s45, s4, 0x100
	s_add_i32 s46, s5, 0x100
	v_mov_b32_e32 v137, v133
	v_add_u32_e32 v138, v0, v205
	v_mov_b32_e32 v139, v133
	s_mov_b32 s42, 0
	v_mov_b64_e32 v[140:141], 0x200
	v_mov_b64_e32 v[142:143], 0x1ff
	v_add_u32_e32 v154, s43, v1
	v_add_u32_e32 v155, s44, v1
	v_add_u32_e32 v156, 0x100, v2
	s_mov_b32 s14, 0x3fb504f3
	s_mov_b64 s[16:17], 0x48000
	s_mov_b64 s[18:19], 0x50000
	s_mov_b64 s[20:21], 0x58000
	v_add_u32_e32 v157, s45, v1
	v_add_u32_e32 v158, s46, v1
	s_barrier
	s_branch .LBB0_1441

; #define PG8_STAGE(bufoff, gbase, voff) do { _Pragma("unroll") for (int _i = 0; _i < 2; ++_i) \
;         __builtin_amdgcn_global_load_lds((const unsigned*)((const char*)(gbase) + (voff)[_i]), (PG8_LAS unsigned*)(lds + (bufoff) + ldsw + _i * 8192), 16, 0, 0); } while (0)
; #define PG8_LDA(dst, b, h) do { _Pragma("unroll") for (int m = 0; m < 4; ++m) _Pragma("unroll") for (int k = 0; k < 2; ++k) dst[m][k] = *(const PG8_LAS bf16x8*)(lds + PG8_SA(b, h) + aoff + m * 2048 + k * 1024); } while (0)
; #define PG8_LDB(dst, b, h) do { _Pragma("unroll") for (int n = 0; n < 2; ++n) _Pragma("unroll") for (int k = 0; k < 2; ++k) dst[n][k] = *(const PG8_LAS bf16x8*)(lds + PG8_SB(b, h) + boff + n * 2048 + k * 1024); } while (0)
; #define PG8_MMA(ai, bj, At, Bt) do { __builtin_amdgcn_s_setprio(1); _Pragma("unroll") for (int m = 0; m < 4; ++m) _Pragma("unroll") for (int n = 0; n < 2; ++n) _Pragma("unroll") for (int k = 0; k < 2; ++k) \
;         acc[ai][bj][m][n] = __builtin_amdgcn_mfma_f32_16x16x32_bf16(Bt[n][k], At[m][k], acc[ai][bj][m][n], 0, 0, 0); __builtin_amdgcn_s_setprio(0); } while (0)
; #define PG8_WAIT_V(n) asm volatile("s_waitcnt vmcnt(" #n ")" ::: "memory")
; #define PG8_WAIT_L(n) asm volatile("s_waitcnt lgkmcnt(" #n ")" ::: "memory")
; template <class Epi, class Sched, bool ALIGN_EPI = false, bool SP2 = false>
; __device__ __forceinline__ void gemm_phase(PG8_LAS unsigned char* lds, const Gemm g, const Sched& S, const Epi& E) {
;     ...
;             const bool last = (t == nt - 2);
;             const char* a1 = cA + (size_t)(t + 1) * kstep;
;             const char* a2 = last ? nA : cA + (size_t)(t + 2) * kstep; const char* b2 = last ? nB : cB + (size_t)(t + 2) * kstep;
;             const char* a3 = a2 + kstep; const char* b3 = b2 + kstep;
;             if (last && has_next) S.a_ready(nxt);
;             if constexpr (SP2) {
;             PG8_LDB(B0, 0, 0); PG8_LDB(B1, 0, 1); PG8_SCHED; PG8_LDA(At, 0, 0); PG8_STAGE(PG8_SA(1, 1), a1 + hstep, voffA);
;             PG8_WAIT_V(8); PG8_WAIT_L(0); PG8_BAR; PG8_MMA(0, 0, At, B0); PG8_MMA(0, 1, At, B1); PG8_BAR; PG8_SCHED;
;             PG8_LDA(At, 0, 1); PG8_STAGE(PG8_SB(0, 0), b2, voffB); PG8_STAGE(PG8_SB(0, 1), b2 + hstep, voffB); PG8_STAGE(PG8_SA(0, 0), a2, voffA);
;             PG8_WAIT_V(8); PG8_WAIT_L(0); PG8_BAR; PG8_MMA(1, 0, At, B0); PG8_MMA(1, 1, At, B1); PG8_BAR; PG8_SCHED;
.LBB0_1448:
	ds_read_b128 v[144:147], v154
	ds_read_b128 v[160:163], v154 offset:1024
	ds_read_b128 v[164:167], v154 offset:2048
	ds_read_b128 v[168:171], v154 offset:3072
	ds_read_b128 v[172:175], v155
	ds_read_b128 v[176:179], v155 offset:1024
	ds_read_b128 v[180:183], v155 offset:2048
	ds_read_b128 v[184:187], v155 offset:3072
	s_add_u32 s36, s34, 0xfffc0080
	s_addc_u32 s37, s35, -1
	s_cmp_eq_u32 s52, 12
	s_cselect_b32 s39, s25, s37
	s_cselect_b32 s38, s48, s36
	s_cselect_b32 s37, s23, s51
	s_cselect_b32 s36, s49, s50
	v_lshl_add_u64 v[148:149], s[34:35], 0, v[136:137]
	s_add_i32 m0, s3, 0xc000
	ds_read_b128 v[188:191], v156
	ds_read_b128 v[192:195], v156 offset:1024
	ds_read_b128 v[206:209], v156 offset:2048
	ds_read_b128 v[210:213], v156 offset:3072
	ds_read_b128 v[214:217], v156 offset:4096
	ds_read_b128 v[218:221], v156 offset:5120
	ds_read_b128 v[222:225], v156 offset:6144
	ds_read_b128 v[226:229], v156 offset:7168
	global_load_lds_dwordx4 v[148:149], off
	v_lshl_add_u64 v[148:149], s[34:35], 0, v[138:139]
	s_add_i32 m0, s3, 0xe000
	s_nop 0
	global_load_lds_dwordx4 v[148:149], off
	s_waitcnt vmcnt(8)
	s_waitcnt lgkmcnt(0)
	s_barrier
	s_setprio 1
	s_waitcnt lgkmcnt(0)
	v_mfma_f32_16x16x32_bf16 v[124:127], v[144:147], v[188:191], v[124:127]
	v_mfma_f32_16x16x32_bf16 v[120:123], v[164:167], v[188:191], v[120:123]
	v_mfma_f32_16x16x32_bf16 v[108:111], v[144:147], v[206:209], v[108:111]
	v_mfma_f32_16x16x32_bf16 v[104:107], v[164:167], v[206:209], v[104:107]
	v_mfma_f32_16x16x32_bf16 v[92:95], v[144:147], v[214:217], v[92:95]
	v_mfma_f32_16x16x32_bf16 v[88:91], v[164:167], v[214:217], v[88:91]
	v_mfma_f32_16x16x32_bf16 v[76:79], v[144:147], v[222:225], v[76:79]
	v_mfma_f32_16x16x32_bf16 v[72:75], v[164:167], v[222:225], v[72:75]
	v_mfma_f32_16x16x32_bf16 v[124:127], v[160:163], v[192:195], v[124:127]
	v_mfma_f32_16x16x32_bf16 v[120:123], v[168:171], v[192:195], v[120:123]
	v_mfma_f32_16x16x32_bf16 v[108:111], v[160:163], v[210:213], v[108:111]
	v_mfma_f32_16x16x32_bf16 v[104:107], v[168:171], v[210:213], v[104:107]
	v_mfma_f32_16x16x32_bf16 v[92:95], v[160:163], v[218:221], v[92:95]
	v_mfma_f32_16x16x32_bf16 v[88:91], v[168:171], v[218:221], v[88:91]
	v_mfma_f32_16x16x32_bf16 v[76:79], v[160:163], v[226:229], v[76:79]
	v_mfma_f32_16x16x32_bf16 v[72:75], v[168:171], v[226:229], v[72:75]
	s_setprio 0
	s_setprio 1
	v_mfma_f32_16x16x32_bf16 v[116:119], v[172:175], v[188:191], v[116:119]
	v_mfma_f32_16x16x32_bf16 v[112:115], v[180:183], v[188:191], v[112:115]
	v_mfma_f32_16x16x32_bf16 v[100:103], v[172:175], v[206:209], v[100:103]
	v_mfma_f32_16x16x32_bf16 v[96:99], v[180:183], v[206:209], v[96:99]
	v_mfma_f32_16x16x32_bf16 v[84:87], v[172:175], v[214:217], v[84:87]
	v_mfma_f32_16x16x32_bf16 v[80:83], v[180:183], v[214:217], v[80:83]
	v_mfma_f32_16x16x32_bf16 v[68:71], v[172:175], v[222:225], v[68:71]
	v_mfma_f32_16x16x32_bf16 v[64:67], v[180:183], v[222:225], v[64:67]
	v_mfma_f32_16x16x32_bf16 v[116:119], v[176:179], v[192:195], v[116:119]
	v_mfma_f32_16x16x32_bf16 v[112:115], v[184:187], v[192:195], v[112:115]
	v_mfma_f32_16x16x32_bf16 v[100:103], v[176:179], v[210:213], v[100:103]
	v_mfma_f32_16x16x32_bf16 v[96:99], v[184:187], v[210:213], v[96:99]
	v_mfma_f32_16x16x32_bf16 v[84:87], v[176:179], v[218:221], v[84:87]
	v_mfma_f32_16x16x32_bf16 v[80:83], v[184:187], v[218:221], v[80:83]
	v_mfma_f32_16x16x32_bf16 v[68:71], v[176:179], v[226:229], v[68:71]
	v_mfma_f32_16x16x32_bf16 v[64:67], v[184:187], v[226:229], v[64:67]
	s_setprio 0
	s_barrier
	s_add_i32 s53, s43, s2
	v_lshl_add_u64 v[148:149], s[36:37], 0, v[132:133]
	s_mov_b32 m0, s53
	ds_read_b128 v[188:191], v156 offset:16384
	ds_read_b128 v[192:195], v156 offset:17408
	ds_read_b128 v[206:209], v156 offset:18432
	ds_read_b128 v[210:213], v156 offset:19456
	ds_read_b128 v[214:217], v156 offset:20480
	ds_read_b128 v[218:221], v156 offset:21504
	ds_read_b128 v[222:225], v156 offset:22528
	ds_read_b128 v[226:229], v156 offset:23552
	global_load_lds_dwordx4 v[148:149], off
	s_add_i32 m0, s53, 0x2000
	s_add_u32 s54, s36, 0x40000
	v_lshl_add_u64 v[196:197], s[36:37], 0, v[134:135]
	s_addc_u32 s55, s37, 0
	s_add_i32 s53, s44, s2
	global_load_lds_dwordx4 v[196:197], off
	v_lshl_add_u64 v[236:237], s[54:55], 0, v[132:133]
	s_mov_b32 m0, s53
	v_lshl_add_u64 v[238:239], s[38:39], 0, v[130:131]
	global_load_lds_dwordx4 v[236:237], off
	v_lshl_add_u64 v[236:237], s[54:55], 0, v[134:135]
	s_add_i32 m0, s53, 0x2000
	s_nop 0
	global_load_lds_dwordx4 v[236:237], off
	v_lshl_add_u64 v[236:237], s[38:39], 0, v[128:129]
	s_mov_b32 m0, s3
	s_nop 0
	global_load_lds_dwordx4 v[236:237], off
	s_mov_b32 m0, s15
	s_nop 0
	global_load_lds_dwordx4 v[238:239], off
	s_waitcnt vmcnt(8)
	s_waitcnt lgkmcnt(0)
	s_barrier
; #define PG8_STAGE(bufoff, gbase, voff) do { _Pragma("unroll") for (int _i = 0; _i < 2; ++_i) \
;         __builtin_amdgcn_global_load_lds((const unsigned*)((const char*)(gbase) + (voff)[_i]), (PG8_LAS unsigned*)(lds + (bufoff) + ldsw + _i * 8192), 16, 0, 0); } while (0)
; #define PG8_LDA(dst, b, h) do { _Pragma("unroll") for (int m = 0; m < 4; ++m) _Pragma("unroll") for (int k = 0; k < 2; ++k) dst[m][k] = *(const PG8_LAS bf16x8*)(lds + PG8_SA(b, h) + aoff + m * 2048 + k * 1024); } while (0)
; #define PG8_LDB(dst, b, h) do { _Pragma("unroll") for (int n = 0; n < 2; ++n) _Pragma("unroll") for (int k = 0; k < 2; ++k) dst[n][k] = *(const PG8_LAS bf16x8*)(lds + PG8_SB(b, h) + boff + n * 2048 + k * 1024); } while (0)
; #define PG8_MMA(ai, bj, At, Bt) do { __builtin_amdgcn_s_setprio(1); _Pragma("unroll") for (int m = 0; m < 4; ++m) _Pragma("unroll") for (int n = 0; n < 2; ++n) _Pragma("unroll") for (int k = 0; k < 2; ++k) \
;         acc[ai][bj][m][n] = __builtin_amdgcn_mfma_f32_16x16x32_bf16(Bt[n][k], At[m][k], acc[ai][bj][m][n], 0, 0, 0); __builtin_amdgcn_s_setprio(0); } while (0)
; #define PG8_WAIT_V(n) asm volatile("s_waitcnt vmcnt(" #n ")" ::: "memory")
; #define PG8_WAIT_L(n) asm volatile("s_waitcnt lgkmcnt(" #n ")" ::: "memory")
; #define PG8_BAR __builtin_amdgcn_s_barrier()
; #define PG8_SCHED __builtin_amdgcn_sched_barrier(0)
; template <class Epi, class Sched, bool ALIGN_EPI = false, bool SP2 = false>
; __device__ __forceinline__ void gemm_phase(PG8_LAS unsigned char* lds, const Gemm g, const Sched& S, const Epi& E) {
;     ...
;             PG8_WAIT_V(8); PG8_WAIT_L(0); PG8_BAR; PG8_MMA(1, 0, At, B0); PG8_MMA(1, 1, At, B1); PG8_BAR; PG8_SCHED;
;             PG8_LDB(B0, 1, 0); PG8_LDB(B1, 1, 1); PG8_SCHED; PG8_LDA(At, 1, 0); PG8_STAGE(PG8_SA(0, 1), a2 + hstep, voffA);
;             PG8_WAIT_V(8); PG8_WAIT_L(0); PG8_BAR; PG8_MMA(0, 0, At, B0); PG8_MMA(0, 1, At, B1); PG8_BAR; PG8_SCHED;
	s_setprio 1
	s_waitcnt lgkmcnt(0)
	v_mfma_f32_16x16x32_bf16 v[60:63], v[144:147], v[188:191], v[60:63]
	v_mfma_f32_16x16x32_bf16 v[56:59], v[164:167], v[188:191], v[56:59]
	v_mfma_f32_16x16x32_bf16 v[44:47], v[144:147], v[206:209], v[44:47]
	v_mfma_f32_16x16x32_bf16 v[40:43], v[164:167], v[206:209], v[40:43]
	v_mfma_f32_16x16x32_bf16 v[28:31], v[144:147], v[214:217], v[28:31]
	v_mfma_f32_16x16x32_bf16 v[24:27], v[164:167], v[214:217], v[24:27]
	v_mfma_f32_16x16x32_bf16 v[12:15], v[144:147], v[222:225], v[12:15]
	v_mfma_f32_16x16x32_bf16 v[8:11], v[164:167], v[222:225], v[8:11]
	v_mfma_f32_16x16x32_bf16 v[60:63], v[160:163], v[192:195], v[60:63]
	v_mfma_f32_16x16x32_bf16 v[56:59], v[168:171], v[192:195], v[56:59]
	v_mfma_f32_16x16x32_bf16 v[44:47], v[160:163], v[210:213], v[44:47]
	v_mfma_f32_16x16x32_bf16 v[40:43], v[168:171], v[210:213], v[40:43]
	v_mfma_f32_16x16x32_bf16 v[28:31], v[160:163], v[218:221], v[28:31]
	v_mfma_f32_16x16x32_bf16 v[24:27], v[168:171], v[218:221], v[24:27]
	v_mfma_f32_16x16x32_bf16 v[12:15], v[160:163], v[226:229], v[12:15]
	v_mfma_f32_16x16x32_bf16 v[8:11], v[168:171], v[226:229], v[8:11]
	s_setprio 0
	s_setprio 1
	v_mfma_f32_16x16x32_bf16 v[52:55], v[172:175], v[188:191], v[52:55]
	v_mfma_f32_16x16x32_bf16 v[48:51], v[180:183], v[188:191], v[48:51]
	v_mfma_f32_16x16x32_bf16 v[36:39], v[172:175], v[206:209], v[36:39]
	v_mfma_f32_16x16x32_bf16 v[32:35], v[180:183], v[206:209], v[32:35]
	v_mfma_f32_16x16x32_bf16 v[20:23], v[172:175], v[214:217], v[20:23]
	v_mfma_f32_16x16x32_bf16 v[16:19], v[180:183], v[214:217], v[16:19]
	v_mfma_f32_16x16x32_bf16 v[4:7], v[172:175], v[222:225], v[4:7]
	v_mfma_f32_16x16x32_bf16 v[0:3], v[180:183], v[222:225], v[0:3]
	v_mfma_f32_16x16x32_bf16 v[52:55], v[176:179], v[192:195], v[52:55]
	v_mfma_f32_16x16x32_bf16 v[48:51], v[184:187], v[192:195], v[48:51]
	v_mfma_f32_16x16x32_bf16 v[36:39], v[176:179], v[210:213], v[36:39]
	v_mfma_f32_16x16x32_bf16 v[32:35], v[184:187], v[210:213], v[32:35]
	v_mfma_f32_16x16x32_bf16 v[20:23], v[176:179], v[218:221], v[20:23]
	v_mfma_f32_16x16x32_bf16 v[16:19], v[184:187], v[218:221], v[16:19]
	v_mfma_f32_16x16x32_bf16 v[4:7], v[176:179], v[226:229], v[4:7]
	v_mfma_f32_16x16x32_bf16 v[0:3], v[184:187], v[226:229], v[0:3]
	s_setprio 0
	s_barrier
	ds_read_b128 v[144:147], v157
	ds_read_b128 v[160:163], v157 offset:1024
	ds_read_b128 v[164:167], v157 offset:2048
	ds_read_b128 v[168:171], v157 offset:3072
	ds_read_b128 v[172:175], v158
	ds_read_b128 v[176:179], v158 offset:1024
	ds_read_b128 v[180:183], v158 offset:2048
	ds_read_b128 v[184:187], v158 offset:3072
	s_add_u32 s38, s38, 0x40000
	s_addc_u32 s39, s39, 0
	s_mov_b32 m0, s31
	v_lshl_add_u64 v[240:241], s[38:39], 0, v[128:129]
	ds_read_b128 v[188:191], v156 offset:32768
	ds_read_b128 v[192:195], v156 offset:33792
	ds_read_b128 v[206:209], v156 offset:34816
	ds_read_b128 v[210:213], v156 offset:35840
	ds_read_b128 v[214:217], v156 offset:36864
	ds_read_b128 v[218:221], v156 offset:37888
	ds_read_b128 v[222:225], v156 offset:38912
	ds_read_b128 v[226:229], v156 offset:39936
	global_load_lds_dwordx4 v[240:241], off
	v_lshl_add_u64 v[240:241], s[38:39], 0, v[130:131]
	s_mov_b32 m0, s33
	s_nop 0
	global_load_lds_dwordx4 v[240:241], off
	s_waitcnt vmcnt(8)
	s_waitcnt lgkmcnt(0)
	s_barrier
	s_setprio 1
	s_waitcnt lgkmcnt(0)
	v_mfma_f32_16x16x32_bf16 v[124:127], v[144:147], v[188:191], v[124:127]
	v_mfma_f32_16x16x32_bf16 v[120:123], v[164:167], v[188:191], v[120:123]
	v_mfma_f32_16x16x32_bf16 v[108:111], v[144:147], v[206:209], v[108:111]
	v_mfma_f32_16x16x32_bf16 v[104:107], v[164:167], v[206:209], v[104:107]
	v_mfma_f32_16x16x32_bf16 v[92:95], v[144:147], v[214:217], v[92:95]
	v_mfma_f32_16x16x32_bf16 v[88:91], v[164:167], v[214:217], v[88:91]
	v_mfma_f32_16x16x32_bf16 v[76:79], v[144:147], v[222:225], v[76:79]
	v_mfma_f32_16x16x32_bf16 v[72:75], v[164:167], v[222:225], v[72:75]
	v_mfma_f32_16x16x32_bf16 v[124:127], v[160:163], v[192:195], v[124:127]
	v_mfma_f32_16x16x32_bf16 v[120:123], v[168:171], v[192:195], v[120:123]
	v_mfma_f32_16x16x32_bf16 v[108:111], v[160:163], v[210:213], v[108:111]
	v_mfma_f32_16x16x32_bf16 v[104:107], v[168:171], v[210:213], v[104:107]
	v_mfma_f32_16x16x32_bf16 v[92:95], v[160:163], v[218:221], v[92:95]
	v_mfma_f32_16x16x32_bf16 v[88:91], v[168:171], v[218:221], v[88:91]
	v_mfma_f32_16x16x32_bf16 v[76:79], v[160:163], v[226:229], v[76:79]
	v_mfma_f32_16x16x32_bf16 v[72:75], v[168:171], v[226:229], v[72:75]
	s_setprio 0
	s_setprio 1
	v_mfma_f32_16x16x32_bf16 v[116:119], v[172:175], v[188:191], v[116:119]
	v_mfma_f32_16x16x32_bf16 v[112:115], v[180:183], v[188:191], v[112:115]
	v_mfma_f32_16x16x32_bf16 v[100:103], v[172:175], v[206:209], v[100:103]
	v_mfma_f32_16x16x32_bf16 v[96:99], v[180:183], v[206:209], v[96:99]
	v_mfma_f32_16x16x32_bf16 v[84:87], v[172:175], v[214:217], v[84:87]
	v_mfma_f32_16x16x32_bf16 v[80:83], v[180:183], v[214:217], v[80:83]
	v_mfma_f32_16x16x32_bf16 v[68:71], v[172:175], v[222:225], v[68:71]
	v_mfma_f32_16x16x32_bf16 v[64:67], v[180:183], v[222:225], v[64:67]
	v_mfma_f32_16x16x32_bf16 v[116:119], v[176:179], v[192:195], v[116:119]
	v_mfma_f32_16x16x32_bf16 v[112:115], v[184:187], v[192:195], v[112:115]
	v_mfma_f32_16x16x32_bf16 v[100:103], v[176:179], v[210:213], v[100:103]
	v_mfma_f32_16x16x32_bf16 v[96:99], v[184:187], v[210:213], v[96:99]
	v_mfma_f32_16x16x32_bf16 v[84:87], v[176:179], v[218:221], v[84:87]
	v_mfma_f32_16x16x32_bf16 v[80:83], v[184:187], v[218:221], v[80:83]
	v_mfma_f32_16x16x32_bf16 v[68:71], v[176:179], v[226:229], v[68:71]
	v_mfma_f32_16x16x32_bf16 v[64:67], v[184:187], v[226:229], v[64:67]
	s_setprio 0
	s_barrier
; #define PG8_STAGE(bufoff, gbase, voff) do { _Pragma("unroll") for (int _i = 0; _i < 2; ++_i) \
;         __builtin_amdgcn_global_load_lds((const unsigned*)((const char*)(gbase) + (voff)[_i]), (PG8_LAS unsigned*)(lds + (bufoff) + ldsw + _i * 8192), 16, 0, 0); } while (0)
; #define PG8_LDA(dst, b, h) do { _Pragma("unroll") for (int m = 0; m < 4; ++m) _Pragma("unroll") for (int k = 0; k < 2; ++k) dst[m][k] = *(const PG8_LAS bf16x8*)(lds + PG8_SA(b, h) + aoff + m * 2048 + k * 1024); } while (0)
; #define PG8_MMA(ai, bj, At, Bt) do { __builtin_amdgcn_s_setprio(1); _Pragma("unroll") for (int m = 0; m < 4; ++m) _Pragma("unroll") for (int n = 0; n < 2; ++n) _Pragma("unroll") for (int k = 0; k < 2; ++k) \
;         acc[ai][bj][m][n] = __builtin_amdgcn_mfma_f32_16x16x32_bf16(Bt[n][k], At[m][k], acc[ai][bj][m][n], 0, 0, 0); __builtin_amdgcn_s_setprio(0); } while (0)
; #define PG8_WAIT_V(n) asm volatile("s_waitcnt vmcnt(" #n ")" ::: "memory")
; #define PG8_WAIT_L(n) asm volatile("s_waitcnt lgkmcnt(" #n ")" ::: "memory")
; #define PG8_BAR __builtin_amdgcn_s_barrier()
; #define PG8_SCHED __builtin_amdgcn_sched_barrier(0)
; template <class Epi, class Sched, bool ALIGN_EPI = false, bool SP2 = false>
; __device__ __forceinline__ void gemm_phase(PG8_LAS unsigned char* lds, const Gemm g, const Sched& S, const Epi& E) {
;     ...
;         for (int t = 0; t < nt; t += 2) {
;     ...
;             PG8_LDA(At, 1, 1); PG8_STAGE(PG8_SB(1, 0), b3, voffB); PG8_STAGE(PG8_SB(1, 1), b3 + hstep, voffB); PG8_STAGE(PG8_SA(1, 0), a3, voffA);
;             PG8_WAIT_V(8); PG8_WAIT_L(0); PG8_BAR; PG8_MMA(1, 0, At, B0); PG8_MMA(1, 1, At, B1); PG8_BAR; PG8_SCHED;
	s_add_i32 s38, s45, s2
	v_lshl_add_u64 v[148:149], v[148:149], 0, s[10:11]
	s_mov_b32 m0, s38
	ds_read_b128 v[188:191], v156 offset:49152
	ds_read_b128 v[192:195], v156 offset:50176
	ds_read_b128 v[206:209], v156 offset:51200
	ds_read_b128 v[210:213], v156 offset:52224
	ds_read_b128 v[214:217], v156 offset:53248
	ds_read_b128 v[218:221], v156 offset:54272
	ds_read_b128 v[222:225], v156 offset:55296
	ds_read_b128 v[226:229], v156 offset:56320
	global_load_lds_dwordx4 v[148:149], off
	s_add_i32 m0, s38, 0x2000
	s_add_u32 s36, s36, 0x40080
	v_lshl_add_u64 v[148:149], v[196:197], 0, s[10:11]
	s_addc_u32 s37, s37, 0
	s_add_i32 s38, s46, s2
	global_load_lds_dwordx4 v[148:149], off
	v_lshl_add_u64 v[148:149], s[36:37], 0, v[132:133]
	s_mov_b32 m0, s38
	s_nop 0
	global_load_lds_dwordx4 v[148:149], off
	v_lshl_add_u64 v[148:149], s[36:37], 0, v[134:135]
	s_add_i32 m0, s38, 0x2000
	s_nop 0
	global_load_lds_dwordx4 v[148:149], off
	v_lshl_add_u64 v[148:149], v[236:237], 0, s[10:11]
	s_mov_b32 m0, s40
	s_nop 0
	global_load_lds_dwordx4 v[148:149], off
	v_lshl_add_u64 v[148:149], v[238:239], 0, s[10:11]
	s_mov_b32 m0, s41
	s_nop 0
	global_load_lds_dwordx4 v[148:149], off
	s_waitcnt vmcnt(8)
	s_waitcnt lgkmcnt(0)
	s_barrier
	s_setprio 1
	s_waitcnt lgkmcnt(0)
	v_mfma_f32_16x16x32_bf16 v[60:63], v[144:147], v[188:191], v[60:63]
	v_mfma_f32_16x16x32_bf16 v[56:59], v[164:167], v[188:191], v[56:59]
	v_mfma_f32_16x16x32_bf16 v[44:47], v[144:147], v[206:209], v[44:47]
	v_mfma_f32_16x16x32_bf16 v[40:43], v[164:167], v[206:209], v[40:43]
	v_mfma_f32_16x16x32_bf16 v[28:31], v[144:147], v[214:217], v[28:31]
	v_mfma_f32_16x16x32_bf16 v[24:27], v[164:167], v[214:217], v[24:27]
	v_mfma_f32_16x16x32_bf16 v[12:15], v[144:147], v[222:225], v[12:15]
	v_mfma_f32_16x16x32_bf16 v[8:11], v[164:167], v[222:225], v[8:11]
	v_mfma_f32_16x16x32_bf16 v[60:63], v[160:163], v[192:195], v[60:63]
	v_mfma_f32_16x16x32_bf16 v[56:59], v[168:171], v[192:195], v[56:59]
	v_mfma_f32_16x16x32_bf16 v[44:47], v[160:163], v[210:213], v[44:47]
	v_mfma_f32_16x16x32_bf16 v[40:43], v[168:171], v[210:213], v[40:43]
	v_mfma_f32_16x16x32_bf16 v[28:31], v[160:163], v[218:221], v[28:31]
	v_mfma_f32_16x16x32_bf16 v[24:27], v[168:171], v[218:221], v[24:27]
	v_mfma_f32_16x16x32_bf16 v[12:15], v[160:163], v[226:229], v[12:15]
	v_mfma_f32_16x16x32_bf16 v[8:11], v[168:171], v[226:229], v[8:11]
	s_setprio 0
	s_setprio 1
	v_mfma_f32_16x16x32_bf16 v[52:55], v[172:175], v[188:191], v[52:55]
	v_mfma_f32_16x16x32_bf16 v[48:51], v[180:183], v[188:191], v[48:51]
	v_mfma_f32_16x16x32_bf16 v[36:39], v[172:175], v[206:209], v[36:39]
	v_mfma_f32_16x16x32_bf16 v[32:35], v[180:183], v[206:209], v[32:35]
	v_mfma_f32_16x16x32_bf16 v[20:23], v[172:175], v[214:217], v[20:23]
	v_mfma_f32_16x16x32_bf16 v[16:19], v[180:183], v[214:217], v[16:19]
	v_mfma_f32_16x16x32_bf16 v[4:7], v[172:175], v[222:225], v[4:7]
	v_mfma_f32_16x16x32_bf16 v[0:3], v[180:183], v[222:225], v[0:3]
	v_mfma_f32_16x16x32_bf16 v[52:55], v[176:179], v[192:195], v[52:55]
	v_mfma_f32_16x16x32_bf16 v[48:51], v[184:187], v[192:195], v[48:51]
	v_mfma_f32_16x16x32_bf16 v[36:39], v[176:179], v[210:213], v[36:39]
	v_mfma_f32_16x16x32_bf16 v[32:35], v[184:187], v[210:213], v[32:35]
	v_mfma_f32_16x16x32_bf16 v[20:23], v[176:179], v[218:221], v[20:23]
	v_mfma_f32_16x16x32_bf16 v[16:19], v[184:187], v[218:221], v[16:19]
	v_mfma_f32_16x16x32_bf16 v[4:7], v[176:179], v[226:229], v[4:7]
	v_mfma_f32_16x16x32_bf16 v[0:3], v[184:187], v[226:229], v[0:3]
	s_setprio 0
	s_barrier
	s_add_i32 s52, s52, 2
	s_add_u32 s34, s34, 0x100
	s_addc_u32 s35, s35, 0
	s_add_u32 s50, s50, 0x100
	s_addc_u32 s51, s51, 0
	s_cmp_gt_u32 s52, 13
	s_cbranch_scc0 .LBB0_1448
	s_and_b64 vcc, exec, s[12:13]
	s_cbranch_vccz .LBB0_1451
	s_barrier

; #define PG8_STAGE(bufoff, gbase, voff) do { _Pragma("unroll") for (int _i = 0; _i < 2; ++_i) \
;         __builtin_amdgcn_global_load_lds((const unsigned*)((const char*)(gbase) + (voff)[_i]), (PG8_LAS unsigned*)(lds + (bufoff) + ldsw + _i * 8192), 16, 0, 0); } while (0)
; #define PG8_WAIT_V(n) asm volatile("s_waitcnt vmcnt(" #n ")" ::: "memory")
; #define PG8_BAR __builtin_amdgcn_s_barrier()
; template <class Epi, class Sched, bool ALIGN_EPI = false, bool SP2 = false>
; __device__ __forceinline__ void gemm_phase(PG8_LAS unsigned char* lds, const Gemm g, const Sched& S, const Epi& E) {
;     ...
;     const int K = g.K, LD = g.ld, nt = K / BK;
;     unsigned voffA[2], voffB[2];
; #pragma unroll
;     for (int i = 0; i < 2; ++i) { int R, C; stage_rc(tid * 16 + i * 8192, R, C); const int Rb = Epi::PERM ? ((R & ~31) + perm32(R & 31)) : R;
;         voffA[i] = (unsigned)(R * LD + C) * 2u; voffB[i] = (unsigned)(Rb * LD + C) * 2u; }
;     const size_t kstep = (size_t)(BK * 2);
;     const size_t hstep = (size_t)HALF * LD * 2;
;     const size_t tstep = 2 * hstep;
;     const unsigned ldsw = (unsigned)wid * 1024u;
;     const int aoff = lds_byte(wr * 64 + fr, fq * 8), boff = lds_byte(wc * 32 + fr, fq * 8);
;     ...
;         PG8_STAGE(PG8_SB(0, 0), cB, voffB); PG8_STAGE(PG8_SB(0, 1), cB + hstep, voffB); PG8_STAGE(PG8_SA(0, 0), cA, voffA); PG8_STAGE(PG8_SA(0, 1), cA + hstep, voffA);
;         if (wr == 1) PG8_BAR;
;         PG8_WAIT_V(2); PG8_BAR;
;         PG8_STAGE(PG8_SB(1, 0), cB + kstep, voffB); PG8_STAGE(PG8_SA(1, 0), cA + kstep, voffA); PG8_STAGE(PG8_SB(1, 1), cB + hstep + kstep, voffB);
;         PG8_WAIT_V(6); PG8_BAR;
.LBB0_1458:
	s_lshl_b32 s14, s14, 5
	s_and_b32 s24, s14, 0x60
	s_mov_b64 s[14:15], 0x80
	s_add_i32 m0, s3, 0x18000
	v_lshl_add_u64 v[6:7], v[6:7], 0, s[14:15]
	s_lshl_b32 s23, s5, 13
	s_lshl_b32 s25, s24, 7
	s_waitcnt vmcnt(2)
	s_barrier
	global_load_lds_dwordx4 v[6:7], off
	v_lshl_add_u64 v[4:5], v[4:5], 0, s[14:15]
	s_add_i32 m0, s3, 0x1a000
	s_add_i32 s48, s3, 0x8000
	s_add_i32 s49, s3, 0xa000
	global_load_lds_dwordx4 v[4:5], off
	v_lshl_add_u64 v[0:1], v[0:1], 0, s[14:15]
	s_mov_b32 m0, s48
	s_add_u32 s18, s16, 0x40080
	global_load_lds_dwordx4 v[0:1], off
	v_lshl_add_u64 v[0:1], v[2:3], 0, s[14:15]
	s_mov_b32 m0, s49
	s_addc_u32 s19, s17, 0
	global_load_lds_dwordx4 v[0:1], off
	s_add_i32 m0, s3, 0x1c000
	v_lshl_add_u64 v[0:1], s[18:19], 0, v[128:129]
	global_load_lds_dwordx4 v[0:1], off
	v_lshl_add_u64 v[0:1], s[18:19], 0, v[130:131]
	s_add_i32 m0, s3, 0x1e000
	v_bfe_u32 v16, v198, 4, 2
	global_load_lds_dwordx4 v[0:1], off
	v_lshlrev_b32_e32 v1, 4, v16
	v_lshlrev_b32_e32 v3, 2, v204
	v_lshl_or_b32 v2, v204, 6, v1
	v_and_b32_e32 v3, 32, v3
	v_or_b32_e32 v1, v1, v150
	s_cmpk_lt_u32 s4, 0x100
	v_lshl_or_b32 v0, s5, 6, v204
	v_bitop3_b32 v17, v2, s23, v3 bitop3:0xde
	v_bitop3_b32 v18, s25, v1, v151 bitop3:0xf6
	s_mov_b32 s5, 0x18000
	s_mov_b32 s23, 0x1c000
	s_waitcnt vmcnt(6)
	s_cselect_b64 s[18:19], -1, 0
	s_add_i32 s53, s7, 0x100
	s_add_i32 s55, s22, 0x100
	v_mov_b32_e32 v1, v129
	v_or_b32_e32 v2, 16, v0
	v_mov_b32_e32 v3, v129
	v_or_b32_e32 v4, 32, v0
	v_mov_b32_e32 v5, v129
	v_or_b32_e32 v6, 48, v0
	v_mov_b32_e32 v7, v129
	v_add_u32_e32 v8, 0x80, v0
	v_mov_b32_e32 v9, v129
	v_add_u32_e32 v10, 0x90, v0
	v_mov_b32_e32 v11, v129
	v_add_u32_e32 v12, 0xa0, v0
	v_mov_b32_e32 v13, v129
	v_add_u32_e32 v14, 0xb0, v0
	v_mov_b32_e32 v15, v129
	v_add_u32_e32 v149, s53, v18
	v_add_u32_e32 v150, s55, v18
	s_add_i32 s53, s53, s2
	s_add_i32 s55, s55, s2
	s_add_i32 s57, s5, 0x100
	s_add_i32 s58, s23, 0x100
	v_lshlrev_b64 v[132:133], 12, v[0:1]
	v_lshlrev_b64 v[134:135], 12, v[2:3]
	v_lshlrev_b64 v[136:137], 12, v[4:5]
	v_lshlrev_b64 v[138:139], 12, v[6:7]
	v_lshlrev_b64 v[140:141], 12, v[8:9]
	v_lshlrev_b64 v[142:143], 12, v[10:11]
	v_lshlrev_b64 v[144:145], 12, v[12:13]
	v_lshlrev_b64 v[146:147], 12, v[14:15]
	v_lshl_or_b32 v148, v16, 2, s24
	s_mov_b32 s50, 0
	v_add_u32_e32 v151, 0x100, v17
	s_add_i32 s51, s3, 0xc000
	s_add_i32 s52, s3, 0xe000
	s_add_i32 s54, s53, 0x2000
	s_add_i32 s56, s55, 0x2000
	v_add_u32_e32 v152, s57, v18
	v_add_u32_e32 v153, s58, v18
	s_barrier
	s_branch .LBB0_1461

; #define PG8_STAGE(bufoff, gbase, voff) do { _Pragma("unroll") for (int _i = 0; _i < 2; ++_i) \
;         __builtin_amdgcn_global_load_lds((const unsigned*)((const char*)(gbase) + (voff)[_i]), (PG8_LAS unsigned*)(lds + (bufoff) + ldsw + _i * 8192), 16, 0, 0); } while (0)
; #define PG8_LDA(dst, b, h) do { _Pragma("unroll") for (int m = 0; m < 4; ++m) _Pragma("unroll") for (int k = 0; k < 2; ++k) dst[m][k] = *(const PG8_LAS bf16x8*)(lds + PG8_SA(b, h) + aoff + m * 2048 + k * 1024); } while (0)
; #define PG8_LDB(dst, b, h) do { _Pragma("unroll") for (int n = 0; n < 2; ++n) _Pragma("unroll") for (int k = 0; k < 2; ++k) dst[n][k] = *(const PG8_LAS bf16x8*)(lds + PG8_SB(b, h) + boff + n * 2048 + k * 1024); } while (0)
; #define PG8_WAIT_V(n) asm volatile("s_waitcnt vmcnt(" #n ")" ::: "memory")
; #define PG8_WAIT_L(n) asm volatile("s_waitcnt lgkmcnt(" #n ")" ::: "memory")
; #define PG8_BAR __builtin_amdgcn_s_barrier()
; #define PG8_SCHED __builtin_amdgcn_sched_barrier(0)
; template <class Epi, class Sched, bool ALIGN_EPI = false, bool SP2 = false>
; __device__ __forceinline__ void gemm_phase(PG8_LAS unsigned char* lds, const Gemm g, const Sched& S, const Epi& E) {
;     ...
;         const char* nA = has_next ? (const char*)g.A + (size_t)nxt.pm * tstep + (size_t)nxt.ko * 2 : cA; const char* nB = has_next ? (const char*)g.Bt + (size_t)nxt.pn * tstep + (size_t)nxt.ko * 2 : cB;
;         for (int t = 0; t < nt; t += 2) {
;             const bool last = (t == nt - 2);
;             const char* a1 = cA + (size_t)(t + 1) * kstep;
;             const char* a2 = last ? nA : cA + (size_t)(t + 2) * kstep; const char* b2 = last ? nB : cB + (size_t)(t + 2) * kstep;
;             const char* a3 = a2 + kstep; const char* b3 = b2 + kstep;
;             if (last && has_next) S.a_ready(nxt);
;             if constexpr (SP2) {
;             PG8_LDB(B0, 0, 0); PG8_LDB(B1, 0, 1); PG8_SCHED; PG8_LDA(At, 0, 0); PG8_STAGE(PG8_SA(1, 1), a1 + hstep, voffA);
;             PG8_WAIT_V(8); PG8_WAIT_L(0); PG8_BAR; PG8_MMA(0, 0, At, B0); PG8_MMA(0, 1, At, B1); PG8_BAR; PG8_SCHED;
;             PG8_LDA(At, 0, 1); PG8_STAGE(PG8_SB(0, 0), b2, voffB); PG8_STAGE(PG8_SB(0, 1), b2 + hstep, voffB); PG8_STAGE(PG8_SA(0, 0), a2, voffA);
;             PG8_WAIT_V(8); PG8_WAIT_L(0); PG8_BAR; PG8_MMA(1, 0, At, B0); PG8_MMA(1, 1, At, B1); PG8_BAR; PG8_SCHED;
.LBB0_1468:
	s_add_u32 s23, s20, s7
	s_addc_u32 s25, s21, 0
	s_add_u32 s27, s23, 0x100
	s_addc_u32 s40, s25, 0
	s_and_b64 s[38:39], s[36:37], exec
	s_cselect_b32 s41, s29, s40
	s_cselect_b32 s40, s28, s27
	s_add_u32 s7, s16, s7
	s_addc_u32 s27, s17, 0
	s_add_u32 s7, s7, 0x100
	s_addc_u32 s27, s27, 0
	s_and_b64 s[36:37], s[36:37], exec
	ds_read_b128 v[154:157], v149
	ds_read_b128 v[158:161], v149 offset:1024
	ds_read_b128 v[162:165], v149 offset:2048
	ds_read_b128 v[166:169], v149 offset:3072
	ds_read_b128 v[170:173], v150
	ds_read_b128 v[174:177], v150 offset:1024
	ds_read_b128 v[178:181], v150 offset:2048
	ds_read_b128 v[182:185], v150 offset:3072
	s_cselect_b32 s43, s31, s27
	s_cselect_b32 s42, s30, s7
	s_add_u32 s46, s23, 0x40080
	s_addc_u32 s47, s25, 0
	s_add_u32 s44, s42, 0x40000
	s_addc_u32 s45, s43, 0
	s_add_u32 s38, s40, 0x40000
	s_addc_u32 s39, s41, 0
	s_add_i32 s27, s57, s2
	s_add_i32 s23, s27, 0x2000
	s_add_u32 s36, s42, 0x40080
	s_addc_u32 s37, s43, 0
	s_add_i32 s25, s58, s2
	s_add_i32 s7, s25, 0x2000
	s_mov_b32 m0, s51
	v_lshl_add_u64 v[226:227], s[46:47], 0, v[128:129]
	ds_read_b128 v[186:189], v151
	ds_read_b128 v[190:193], v151 offset:1024
	ds_read_b128 v[194:197], v151 offset:2048
	ds_read_b128 v[206:209], v151 offset:3072
	ds_read_b128 v[210:213], v151 offset:4096
	ds_read_b128 v[214:217], v151 offset:5120
	ds_read_b128 v[218:221], v151 offset:6144
	ds_read_b128 v[222:225], v151 offset:7168
	global_load_lds_dwordx4 v[226:227], off
	v_lshl_add_u64 v[226:227], s[46:47], 0, v[130:131]
	s_mov_b32 m0, s52
	s_nop 0
	global_load_lds_dwordx4 v[226:227], off
	s_waitcnt vmcnt(8)
	s_waitcnt lgkmcnt(0)
	s_barrier
	s_setprio 1
	s_waitcnt lgkmcnt(0)
	v_mfma_f32_16x16x32_bf16 v[124:127], v[154:157], v[186:189], v[124:127]
	v_mfma_f32_16x16x32_bf16 v[120:123], v[162:165], v[186:189], v[120:123]
	v_mfma_f32_16x16x32_bf16 v[116:119], v[154:157], v[194:197], v[116:119]
	v_mfma_f32_16x16x32_bf16 v[112:115], v[162:165], v[194:197], v[112:115]
	v_mfma_f32_16x16x32_bf16 v[108:111], v[154:157], v[210:213], v[108:111]
	v_mfma_f32_16x16x32_bf16 v[104:107], v[162:165], v[210:213], v[104:107]
	v_mfma_f32_16x16x32_bf16 v[96:99], v[154:157], v[218:221], v[96:99]
	v_mfma_f32_16x16x32_bf16 v[88:91], v[162:165], v[218:221], v[88:91]
	v_mfma_f32_16x16x32_bf16 v[124:127], v[158:161], v[190:193], v[124:127]
	v_mfma_f32_16x16x32_bf16 v[120:123], v[166:169], v[190:193], v[120:123]
	v_mfma_f32_16x16x32_bf16 v[116:119], v[158:161], v[206:209], v[116:119]
	v_mfma_f32_16x16x32_bf16 v[112:115], v[166:169], v[206:209], v[112:115]
	v_mfma_f32_16x16x32_bf16 v[108:111], v[158:161], v[214:217], v[108:111]
	v_mfma_f32_16x16x32_bf16 v[104:107], v[166:169], v[214:217], v[104:107]
	v_mfma_f32_16x16x32_bf16 v[96:99], v[158:161], v[222:225], v[96:99]
	v_mfma_f32_16x16x32_bf16 v[88:91], v[166:169], v[222:225], v[88:91]
	s_setprio 0
	s_setprio 1
	v_mfma_f32_16x16x32_bf16 v[100:103], v[170:173], v[186:189], v[100:103]
	v_mfma_f32_16x16x32_bf16 v[92:95], v[178:181], v[186:189], v[92:95]
	v_mfma_f32_16x16x32_bf16 v[84:87], v[170:173], v[194:197], v[84:87]
	v_mfma_f32_16x16x32_bf16 v[80:83], v[178:181], v[194:197], v[80:83]
	v_mfma_f32_16x16x32_bf16 v[76:79], v[170:173], v[210:213], v[76:79]
	v_mfma_f32_16x16x32_bf16 v[72:75], v[178:181], v[210:213], v[72:75]
	v_mfma_f32_16x16x32_bf16 v[68:71], v[170:173], v[218:221], v[68:71]
	v_mfma_f32_16x16x32_bf16 v[64:67], v[178:181], v[218:221], v[64:67]
	v_mfma_f32_16x16x32_bf16 v[100:103], v[174:177], v[190:193], v[100:103]
	v_mfma_f32_16x16x32_bf16 v[92:95], v[182:185], v[190:193], v[92:95]
	v_mfma_f32_16x16x32_bf16 v[84:87], v[174:177], v[206:209], v[84:87]
	v_mfma_f32_16x16x32_bf16 v[80:83], v[182:185], v[206:209], v[80:83]
	v_mfma_f32_16x16x32_bf16 v[76:79], v[174:177], v[214:217], v[76:79]
	v_mfma_f32_16x16x32_bf16 v[72:75], v[182:185], v[214:217], v[72:75]
	v_mfma_f32_16x16x32_bf16 v[68:71], v[174:177], v[222:225], v[68:71]
	v_mfma_f32_16x16x32_bf16 v[64:67], v[182:185], v[222:225], v[64:67]
	s_setprio 0
	s_barrier
	s_mov_b32 m0, s53
	v_lshl_add_u64 v[226:227], s[42:43], 0, v[128:129]
	ds_read_b128 v[186:189], v151 offset:16384
	ds_read_b128 v[190:193], v151 offset:17408
	ds_read_b128 v[194:197], v151 offset:18432
	ds_read_b128 v[206:209], v151 offset:19456
	ds_read_b128 v[210:213], v151 offset:20480
	ds_read_b128 v[214:217], v151 offset:21504
	ds_read_b128 v[218:221], v151 offset:22528
	ds_read_b128 v[222:225], v151 offset:23552
	global_load_lds_dwordx4 v[226:227], off
	v_lshl_add_u64 v[228:229], s[42:43], 0, v[130:131]
	s_mov_b32 m0, s54
	v_lshl_add_u64 v[236:237], s[44:45], 0, v[128:129]
	global_load_lds_dwordx4 v[228:229], off
	s_mov_b32 m0, s55
	v_lshl_add_u64 v[238:239], s[40:41], 0, v[130:131]
	global_load_lds_dwordx4 v[236:237], off
	v_lshl_add_u64 v[236:237], s[44:45], 0, v[130:131]
	s_mov_b32 m0, s56
	s_nop 0
	global_load_lds_dwordx4 v[236:237], off
	v_lshl_add_u64 v[236:237], s[40:41], 0, v[128:129]
	s_mov_b32 m0, s3
	s_nop 0
	global_load_lds_dwordx4 v[236:237], off
	s_mov_b32 m0, s11
	s_nop 0
	global_load_lds_dwordx4 v[238:239], off
	s_waitcnt vmcnt(8)
	s_waitcnt lgkmcnt(0)
	s_barrier
; #define PG8_STAGE(bufoff, gbase, voff) do { _Pragma("unroll") for (int _i = 0; _i < 2; ++_i) \
;         __builtin_amdgcn_global_load_lds((const unsigned*)((const char*)(gbase) + (voff)[_i]), (PG8_LAS unsigned*)(lds + (bufoff) + ldsw + _i * 8192), 16, 0, 0); } while (0)
; #define PG8_LDA(dst, b, h) do { _Pragma("unroll") for (int m = 0; m < 4; ++m) _Pragma("unroll") for (int k = 0; k < 2; ++k) dst[m][k] = *(const PG8_LAS bf16x8*)(lds + PG8_SA(b, h) + aoff + m * 2048 + k * 1024); } while (0)
; #define PG8_LDB(dst, b, h) do { _Pragma("unroll") for (int n = 0; n < 2; ++n) _Pragma("unroll") for (int k = 0; k < 2; ++k) dst[n][k] = *(const PG8_LAS bf16x8*)(lds + PG8_SB(b, h) + boff + n * 2048 + k * 1024); } while (0)
; #define PG8_MMA(ai, bj, At, Bt) do { __builtin_amdgcn_s_setprio(1); _Pragma("unroll") for (int m = 0; m < 4; ++m) _Pragma("unroll") for (int n = 0; n < 2; ++n) _Pragma("unroll") for (int k = 0; k < 2; ++k) \
;         acc[ai][bj][m][n] = __builtin_amdgcn_mfma_f32_16x16x32_bf16(Bt[n][k], At[m][k], acc[ai][bj][m][n], 0, 0, 0); __builtin_amdgcn_s_setprio(0); } while (0)
; #define PG8_WAIT_V(n) asm volatile("s_waitcnt vmcnt(" #n ")" ::: "memory")
; #define PG8_WAIT_L(n) asm volatile("s_waitcnt lgkmcnt(" #n ")" ::: "memory")
; #define PG8_BAR __builtin_amdgcn_s_barrier()
; #define PG8_SCHED __builtin_amdgcn_sched_barrier(0)
; template <class Epi, class Sched, bool ALIGN_EPI = false, bool SP2 = false>
; __device__ __forceinline__ void gemm_phase(PG8_LAS unsigned char* lds, const Gemm g, const Sched& S, const Epi& E) {
;     ...
;             PG8_WAIT_V(8); PG8_WAIT_L(0); PG8_BAR; PG8_MMA(1, 0, At, B0); PG8_MMA(1, 1, At, B1); PG8_BAR; PG8_SCHED;
;             PG8_LDB(B0, 1, 0); PG8_LDB(B1, 1, 1); PG8_SCHED; PG8_LDA(At, 1, 0); PG8_STAGE(PG8_SA(0, 1), a2 + hstep, voffA);
;             PG8_WAIT_V(8); PG8_WAIT_L(0); PG8_BAR; PG8_MMA(0, 0, At, B0); PG8_MMA(0, 1, At, B1); PG8_BAR; PG8_SCHED;
	s_setprio 1
	s_waitcnt lgkmcnt(0)
	v_mfma_f32_16x16x32_bf16 v[60:63], v[154:157], v[186:189], v[60:63]
	v_mfma_f32_16x16x32_bf16 v[56:59], v[162:165], v[186:189], v[56:59]
	v_mfma_f32_16x16x32_bf16 v[52:55], v[154:157], v[194:197], v[52:55]
	v_mfma_f32_16x16x32_bf16 v[48:51], v[162:165], v[194:197], v[48:51]
	v_mfma_f32_16x16x32_bf16 v[44:47], v[154:157], v[210:213], v[44:47]
	v_mfma_f32_16x16x32_bf16 v[40:43], v[162:165], v[210:213], v[40:43]
	v_mfma_f32_16x16x32_bf16 v[32:35], v[154:157], v[218:221], v[32:35]
	v_mfma_f32_16x16x32_bf16 v[24:27], v[162:165], v[218:221], v[24:27]
	v_mfma_f32_16x16x32_bf16 v[60:63], v[158:161], v[190:193], v[60:63]
	v_mfma_f32_16x16x32_bf16 v[56:59], v[166:169], v[190:193], v[56:59]
	v_mfma_f32_16x16x32_bf16 v[52:55], v[158:161], v[206:209], v[52:55]
	v_mfma_f32_16x16x32_bf16 v[48:51], v[166:169], v[206:209], v[48:51]
	v_mfma_f32_16x16x32_bf16 v[44:47], v[158:161], v[214:217], v[44:47]
	v_mfma_f32_16x16x32_bf16 v[40:43], v[166:169], v[214:217], v[40:43]
	v_mfma_f32_16x16x32_bf16 v[32:35], v[158:161], v[222:225], v[32:35]
	v_mfma_f32_16x16x32_bf16 v[24:27], v[166:169], v[222:225], v[24:27]
	s_setprio 0
	s_setprio 1
	v_mfma_f32_16x16x32_bf16 v[36:39], v[170:173], v[186:189], v[36:39]
	v_mfma_f32_16x16x32_bf16 v[28:31], v[178:181], v[186:189], v[28:31]
	v_mfma_f32_16x16x32_bf16 v[20:23], v[170:173], v[194:197], v[20:23]
	v_mfma_f32_16x16x32_bf16 v[16:19], v[178:181], v[194:197], v[16:19]
	v_mfma_f32_16x16x32_bf16 v[12:15], v[170:173], v[210:213], v[12:15]
	v_mfma_f32_16x16x32_bf16 v[8:11], v[178:181], v[210:213], v[8:11]
	v_mfma_f32_16x16x32_bf16 v[4:7], v[170:173], v[218:221], v[4:7]
	v_mfma_f32_16x16x32_bf16 v[0:3], v[178:181], v[218:221], v[0:3]
	v_mfma_f32_16x16x32_bf16 v[36:39], v[174:177], v[190:193], v[36:39]
	v_mfma_f32_16x16x32_bf16 v[28:31], v[182:185], v[190:193], v[28:31]
	v_mfma_f32_16x16x32_bf16 v[20:23], v[174:177], v[206:209], v[20:23]
	v_mfma_f32_16x16x32_bf16 v[16:19], v[182:185], v[206:209], v[16:19]
	v_mfma_f32_16x16x32_bf16 v[12:15], v[174:177], v[214:217], v[12:15]
	v_mfma_f32_16x16x32_bf16 v[8:11], v[182:185], v[214:217], v[8:11]
	v_mfma_f32_16x16x32_bf16 v[4:7], v[174:177], v[222:225], v[4:7]
	v_mfma_f32_16x16x32_bf16 v[0:3], v[182:185], v[222:225], v[0:3]
	s_setprio 0
	s_barrier
	ds_read_b128 v[154:157], v152
	ds_read_b128 v[158:161], v152 offset:1024
	ds_read_b128 v[162:165], v152 offset:2048
	ds_read_b128 v[166:169], v152 offset:3072
	ds_read_b128 v[170:173], v153
	ds_read_b128 v[174:177], v153 offset:1024
	ds_read_b128 v[178:181], v153 offset:2048
	ds_read_b128 v[182:185], v153 offset:3072
	s_mov_b32 m0, s13
	v_lshl_add_u64 v[240:241], s[38:39], 0, v[128:129]
	ds_read_b128 v[186:189], v151 offset:32768
	ds_read_b128 v[190:193], v151 offset:33792
	ds_read_b128 v[194:197], v151 offset:34816
	ds_read_b128 v[206:209], v151 offset:35840
	ds_read_b128 v[210:213], v151 offset:36864
	ds_read_b128 v[214:217], v151 offset:37888
	ds_read_b128 v[218:221], v151 offset:38912
	ds_read_b128 v[222:225], v151 offset:39936
	global_load_lds_dwordx4 v[240:241], off
	v_lshl_add_u64 v[240:241], s[38:39], 0, v[130:131]
	s_mov_b32 m0, s33
	s_nop 0
	global_load_lds_dwordx4 v[240:241], off
	s_waitcnt vmcnt(8)
	s_waitcnt lgkmcnt(0)
	s_barrier
	s_setprio 1
	s_waitcnt lgkmcnt(0)
	v_mfma_f32_16x16x32_bf16 v[124:127], v[154:157], v[186:189], v[124:127]
	v_mfma_f32_16x16x32_bf16 v[120:123], v[162:165], v[186:189], v[120:123]
	v_mfma_f32_16x16x32_bf16 v[116:119], v[154:157], v[194:197], v[116:119]
	v_mfma_f32_16x16x32_bf16 v[112:115], v[162:165], v[194:197], v[112:115]
	v_mfma_f32_16x16x32_bf16 v[108:111], v[154:157], v[210:213], v[108:111]
	v_mfma_f32_16x16x32_bf16 v[104:107], v[162:165], v[210:213], v[104:107]
	v_mfma_f32_16x16x32_bf16 v[96:99], v[154:157], v[218:221], v[96:99]
	v_mfma_f32_16x16x32_bf16 v[88:91], v[162:165], v[218:221], v[88:91]
	v_mfma_f32_16x16x32_bf16 v[124:127], v[158:161], v[190:193], v[124:127]
	v_mfma_f32_16x16x32_bf16 v[120:123], v[166:169], v[190:193], v[120:123]
	v_mfma_f32_16x16x32_bf16 v[116:119], v[158:161], v[206:209], v[116:119]
	v_mfma_f32_16x16x32_bf16 v[112:115], v[166:169], v[206:209], v[112:115]
	v_mfma_f32_16x16x32_bf16 v[108:111], v[158:161], v[214:217], v[108:111]
	v_mfma_f32_16x16x32_bf16 v[104:107], v[166:169], v[214:217], v[104:107]
	v_mfma_f32_16x16x32_bf16 v[96:99], v[158:161], v[222:225], v[96:99]
	v_mfma_f32_16x16x32_bf16 v[88:91], v[166:169], v[222:225], v[88:91]
	s_setprio 0
	s_setprio 1
	v_mfma_f32_16x16x32_bf16 v[100:103], v[170:173], v[186:189], v[100:103]
	v_mfma_f32_16x16x32_bf16 v[92:95], v[178:181], v[186:189], v[92:95]
	v_mfma_f32_16x16x32_bf16 v[84:87], v[170:173], v[194:197], v[84:87]
	v_mfma_f32_16x16x32_bf16 v[80:83], v[178:181], v[194:197], v[80:83]
	v_mfma_f32_16x16x32_bf16 v[76:79], v[170:173], v[210:213], v[76:79]
	v_mfma_f32_16x16x32_bf16 v[72:75], v[178:181], v[210:213], v[72:75]
	v_mfma_f32_16x16x32_bf16 v[68:71], v[170:173], v[218:221], v[68:71]
	v_mfma_f32_16x16x32_bf16 v[64:67], v[178:181], v[218:221], v[64:67]
	v_mfma_f32_16x16x32_bf16 v[100:103], v[174:177], v[190:193], v[100:103]
	v_mfma_f32_16x16x32_bf16 v[92:95], v[182:185], v[190:193], v[92:95]
	v_mfma_f32_16x16x32_bf16 v[84:87], v[174:177], v[206:209], v[84:87]
	v_mfma_f32_16x16x32_bf16 v[80:83], v[182:185], v[206:209], v[80:83]
	v_mfma_f32_16x16x32_bf16 v[76:79], v[174:177], v[214:217], v[76:79]
	v_mfma_f32_16x16x32_bf16 v[72:75], v[182:185], v[214:217], v[72:75]
	v_mfma_f32_16x16x32_bf16 v[68:71], v[174:177], v[222:225], v[68:71]
	v_mfma_f32_16x16x32_bf16 v[64:67], v[182:185], v[222:225], v[64:67]
	s_setprio 0
	s_barrier
; #define PG8_STAGE(bufoff, gbase, voff) do { _Pragma("unroll") for (int _i = 0; _i < 2; ++_i) \
;         __builtin_amdgcn_global_load_lds((const unsigned*)((const char*)(gbase) + (voff)[_i]), (PG8_LAS unsigned*)(lds + (bufoff) + ldsw + _i * 8192), 16, 0, 0); } while (0)
; #define PG8_LDA(dst, b, h) do { _Pragma("unroll") for (int m = 0; m < 4; ++m) _Pragma("unroll") for (int k = 0; k < 2; ++k) dst[m][k] = *(const PG8_LAS bf16x8*)(lds + PG8_SA(b, h) + aoff + m * 2048 + k * 1024); } while (0)
; #define PG8_MMA(ai, bj, At, Bt) do { __builtin_amdgcn_s_setprio(1); _Pragma("unroll") for (int m = 0; m < 4; ++m) _Pragma("unroll") for (int n = 0; n < 2; ++n) _Pragma("unroll") for (int k = 0; k < 2; ++k) \
;         acc[ai][bj][m][n] = __builtin_amdgcn_mfma_f32_16x16x32_bf16(Bt[n][k], At[m][k], acc[ai][bj][m][n], 0, 0, 0); __builtin_amdgcn_s_setprio(0); } while (0)
; #define PG8_WAIT_V(n) asm volatile("s_waitcnt vmcnt(" #n ")" ::: "memory")
; #define PG8_WAIT_L(n) asm volatile("s_waitcnt lgkmcnt(" #n ")" ::: "memory")
; #define PG8_BAR __builtin_amdgcn_s_barrier()
; #define PG8_SCHED __builtin_amdgcn_sched_barrier(0)
; template <class Epi, class Sched, bool ALIGN_EPI = false, bool SP2 = false>
; __device__ __forceinline__ void gemm_phase(PG8_LAS unsigned char* lds, const Gemm g, const Sched& S, const Epi& E) {
;     ...
;         for (int t = 0; t < nt; t += 2) {
;     ...
;             PG8_LDA(At, 1, 1); PG8_STAGE(PG8_SB(1, 0), b3, voffB); PG8_STAGE(PG8_SB(1, 1), b3 + hstep, voffB); PG8_STAGE(PG8_SA(1, 0), a3, voffA);
;             PG8_WAIT_V(8); PG8_WAIT_L(0); PG8_BAR; PG8_MMA(1, 0, At, B0); PG8_MMA(1, 1, At, B1); PG8_BAR; PG8_SCHED;
	s_mov_b32 m0, s27
	v_lshl_add_u64 v[226:227], v[226:227], 0, s[14:15]
	ds_read_b128 v[186:189], v151 offset:49152
	ds_read_b128 v[190:193], v151 offset:50176
	ds_read_b128 v[194:197], v151 offset:51200
	ds_read_b128 v[206:209], v151 offset:52224
	ds_read_b128 v[210:213], v151 offset:53248
	ds_read_b128 v[214:217], v151 offset:54272
	ds_read_b128 v[218:221], v151 offset:55296
	ds_read_b128 v[222:225], v151 offset:56320
	global_load_lds_dwordx4 v[226:227], off
	v_lshl_add_u64 v[226:227], v[228:229], 0, s[14:15]
	s_mov_b32 m0, s23
	s_nop 0
	global_load_lds_dwordx4 v[226:227], off
	v_lshl_add_u64 v[226:227], s[36:37], 0, v[128:129]
	s_mov_b32 m0, s25
	s_nop 0
	global_load_lds_dwordx4 v[226:227], off
	v_lshl_add_u64 v[226:227], s[36:37], 0, v[130:131]
	s_mov_b32 m0, s7
	s_nop 0
	global_load_lds_dwordx4 v[226:227], off
	v_lshl_add_u64 v[226:227], v[236:237], 0, s[14:15]
	s_mov_b32 m0, s48
	s_nop 0
	global_load_lds_dwordx4 v[226:227], off
	v_lshl_add_u64 v[226:227], v[238:239], 0, s[14:15]
	s_mov_b32 m0, s49
	s_nop 0
	global_load_lds_dwordx4 v[226:227], off
	s_waitcnt vmcnt(8)
	s_waitcnt lgkmcnt(0)
	s_barrier
	s_setprio 1
	s_waitcnt lgkmcnt(0)
	v_mfma_f32_16x16x32_bf16 v[60:63], v[154:157], v[186:189], v[60:63]
	v_mfma_f32_16x16x32_bf16 v[56:59], v[162:165], v[186:189], v[56:59]
	v_mfma_f32_16x16x32_bf16 v[52:55], v[154:157], v[194:197], v[52:55]
	v_mfma_f32_16x16x32_bf16 v[48:51], v[162:165], v[194:197], v[48:51]
	v_mfma_f32_16x16x32_bf16 v[44:47], v[154:157], v[210:213], v[44:47]
	v_mfma_f32_16x16x32_bf16 v[40:43], v[162:165], v[210:213], v[40:43]
	v_mfma_f32_16x16x32_bf16 v[32:35], v[154:157], v[218:221], v[32:35]
	v_mfma_f32_16x16x32_bf16 v[24:27], v[162:165], v[218:221], v[24:27]
	v_mfma_f32_16x16x32_bf16 v[60:63], v[158:161], v[190:193], v[60:63]
	v_mfma_f32_16x16x32_bf16 v[56:59], v[166:169], v[190:193], v[56:59]
	v_mfma_f32_16x16x32_bf16 v[52:55], v[158:161], v[206:209], v[52:55]
	v_mfma_f32_16x16x32_bf16 v[48:51], v[166:169], v[206:209], v[48:51]
	v_mfma_f32_16x16x32_bf16 v[44:47], v[158:161], v[214:217], v[44:47]
	v_mfma_f32_16x16x32_bf16 v[40:43], v[166:169], v[214:217], v[40:43]
	v_mfma_f32_16x16x32_bf16 v[32:35], v[158:161], v[222:225], v[32:35]
	v_mfma_f32_16x16x32_bf16 v[24:27], v[166:169], v[222:225], v[24:27]
	s_setprio 0
	s_setprio 1
	v_mfma_f32_16x16x32_bf16 v[36:39], v[170:173], v[186:189], v[36:39]
	v_mfma_f32_16x16x32_bf16 v[28:31], v[178:181], v[186:189], v[28:31]
	v_mfma_f32_16x16x32_bf16 v[20:23], v[170:173], v[194:197], v[20:23]
	v_mfma_f32_16x16x32_bf16 v[16:19], v[178:181], v[194:197], v[16:19]
	v_mfma_f32_16x16x32_bf16 v[12:15], v[170:173], v[210:213], v[12:15]
	v_mfma_f32_16x16x32_bf16 v[8:11], v[178:181], v[210:213], v[8:11]
	v_mfma_f32_16x16x32_bf16 v[4:7], v[170:173], v[218:221], v[4:7]
	v_mfma_f32_16x16x32_bf16 v[0:3], v[178:181], v[218:221], v[0:3]
	v_mfma_f32_16x16x32_bf16 v[36:39], v[174:177], v[190:193], v[36:39]
	v_mfma_f32_16x16x32_bf16 v[28:31], v[182:185], v[190:193], v[28:31]
	v_mfma_f32_16x16x32_bf16 v[20:23], v[174:177], v[206:209], v[20:23]
	v_mfma_f32_16x16x32_bf16 v[16:19], v[182:185], v[206:209], v[16:19]
	v_mfma_f32_16x16x32_bf16 v[12:15], v[174:177], v[214:217], v[12:15]
	v_mfma_f32_16x16x32_bf16 v[8:11], v[182:185], v[214:217], v[8:11]
	v_mfma_f32_16x16x32_bf16 v[4:7], v[174:177], v[222:225], v[4:7]
	v_mfma_f32_16x16x32_bf16 v[0:3], v[182:185], v[222:225], v[0:3]
	s_setprio 0
	s_barrier
	s_movk_i32 s7, 0x100
	s_andn2_b64 vcc, exec, s[34:35]
	s_mov_b64 s[36:37], -1
	s_mov_b64 s[34:35], 0
	s_cbranch_vccz .LBB0_1468
	s_and_b64 vcc, exec, s[18:19]
	s_cbranch_vccz .LBB0_1471
	s_barrier

; #define PG8_STAGE(bufoff, gbase, voff) do { _Pragma("unroll") for (int _i = 0; _i < 2; ++_i) \
;         __builtin_amdgcn_global_load_lds((const unsigned*)((const char*)(gbase) + (voff)[_i]), (PG8_LAS unsigned*)(lds + (bufoff) + ldsw + _i * 8192), 16, 0, 0); } while (0)
; #define PG8_WAIT_V(n) asm volatile("s_waitcnt vmcnt(" #n ")" ::: "memory")
; #define PG8_BAR __builtin_amdgcn_s_barrier()
; template <class Epi, class Sched, bool ALIGN_EPI = false, bool SP2 = false>
; __device__ __forceinline__ void gemm_phase(PG8_LAS unsigned char* lds, const Gemm g, const Sched& S, const Epi& E) {
;     ...
;     const int K = g.K, LD = g.ld, nt = K / BK;
;     unsigned voffA[2], voffB[2];
; #pragma unroll
;     for (int i = 0; i < 2; ++i) { int R, C; stage_rc(tid * 16 + i * 8192, R, C); const int Rb = Epi::PERM ? ((R & ~31) + perm32(R & 31)) : R;
;         voffA[i] = (unsigned)(R * LD + C) * 2u; voffB[i] = (unsigned)(Rb * LD + C) * 2u; }
;     const size_t kstep = (size_t)(BK * 2);
;     const size_t hstep = (size_t)HALF * LD * 2;
;     const size_t tstep = 2 * hstep;
;     const unsigned ldsw = (unsigned)wid * 1024u;
;     const int aoff = lds_byte(wr * 64 + fr, fq * 8), boff = lds_byte(wc * 32 + fr, fq * 8);
;     ...
;         PG8_STAGE(PG8_SB(0, 0), cB, voffB); PG8_STAGE(PG8_SB(0, 1), cB + hstep, voffB); PG8_STAGE(PG8_SA(0, 0), cA, voffA); PG8_STAGE(PG8_SA(0, 1), cA + hstep, voffA);
;         if (wr == 1) PG8_BAR;
;         PG8_WAIT_V(2); PG8_BAR;
;         PG8_STAGE(PG8_SB(1, 0), cB + kstep, voffB); PG8_STAGE(PG8_SA(1, 0), cA + kstep, voffA); PG8_STAGE(PG8_SB(1, 1), cB + hstep + kstep, voffB);
;         PG8_WAIT_V(6); PG8_BAR;
.LBB0_1618:
	s_lshl_b32 s8, s8, 5
	s_and_b32 s16, s8, 0x60
	s_mov_b64 s[8:9], 0x80
	s_add_i32 m0, s29, 0x18000
	v_lshl_add_u64 v[6:7], v[6:7], 0, s[8:9]
	s_lshl_b32 s11, s10, 13
	s_lshl_b32 s17, s16, 7
	s_waitcnt vmcnt(2)
	s_barrier
	global_load_lds_dwordx4 v[6:7], off
	v_lshl_add_u64 v[2:3], v[2:3], 0, s[8:9]
	s_add_i32 m0, s29, 0x1a000
	s_add_i32 s43, s29, 0x8000
	s_add_i32 s44, s29, 0xa000
	global_load_lds_dwordx4 v[2:3], off
	v_lshl_add_u64 v[0:1], v[0:1], 0, s[8:9]
	s_mov_b32 m0, s43
	s_add_u32 s14, s34, 0x40080
	global_load_lds_dwordx4 v[0:1], off
	v_lshl_add_u64 v[0:1], v[4:5], 0, s[8:9]
	s_mov_b32 m0, s44
	s_addc_u32 s15, s35, 0
	global_load_lds_dwordx4 v[0:1], off
	s_add_i32 m0, s29, 0x1c000
	v_lshl_add_u64 v[0:1], s[14:15], 0, v[132:133]
	global_load_lds_dwordx4 v[0:1], off
	v_lshl_add_u64 v[0:1], s[14:15], 0, v[128:129]
	s_add_i32 m0, s29, 0x1e000
	s_sext_i32_i8 s53, s4
	global_load_lds_dwordx4 v[0:1], off
	v_lshlrev_b32_e32 v0, 1, v10
	s_movk_i32 s4, 0x3c0
	v_lshl_or_b32 v1, v204, 6, v0
	v_and_b32_e32 v2, 32, v232
	v_and_or_b32 v0, v234, s4, v0
	v_bitop3_b32 v1, v1, s11, v2 bitop3:0xde
	v_bitop3_b32 v0, s17, v0, v2 bitop3:0xf6
	v_lshlrev_b32_e32 v2, 8, v198
	v_and_b32_e32 v2, 0x38000, v2
	v_lshlrev_b32_e32 v3, 11, v230
	v_or3_b32 v2, v9, v2, v3
	v_add_u32_e32 v136, v2, v205
	v_lshlrev_b32_e32 v2, 4, v8
	s_mov_b32 s4, 0x18000
	s_mov_b32 s20, 0x1c000
	s_waitcnt vmcnt(6)
	s_cmpk_lt_u32 s5, 0x100
	v_and_b32_e32 v2, 0x78000, v2
	v_lshl_or_b32 v146, s10, 6, v204
	s_cselect_b64 s[10:11], -1, 0
	v_or3_b32 v2, v9, v2, v3
	s_add_i32 s45, s12, 0x100
	s_add_i32 s46, s13, 0x100
	s_add_i32 s51, s4, 0x100
	s_add_i32 s52, s20, 0x100
	v_or_b32_e32 v147, s16, v10
	v_mov_b32_e32 v137, v133
	v_add_u32_e32 v138, v2, v205
	v_mov_b32_e32 v139, v133
	v_mov_b64_e32 v[140:141], 0x880
	v_mov_b64_e32 v[142:143], 0x87f
	v_add_u32_e32 v148, s45, v0
	v_add_u32_e32 v149, s46, v0
	v_add_u32_e32 v150, 0x100, v1
	s_mov_b64 s[12:13], 0x100000
	s_mov_b32 s47, 0x100000
	s_mov_b64 s[14:15], 0x120000
	s_mov_b32 s48, 0x120000
	s_mov_b64 s[16:17], 0x140000
	s_mov_b32 s49, 0x140000
	s_mov_b64 s[18:19], 0x160000
	s_mov_b32 s50, 0x160000
	v_add_u32_e32 v151, s51, v0
	v_add_u32_e32 v152, s52, v0
	s_barrier
	s_branch .LBB0_1621

; #define PG8_STAGE(bufoff, gbase, voff) do { _Pragma("unroll") for (int _i = 0; _i < 2; ++_i) \
;         __builtin_amdgcn_global_load_lds((const unsigned*)((const char*)(gbase) + (voff)[_i]), (PG8_LAS unsigned*)(lds + (bufoff) + ldsw + _i * 8192), 16, 0, 0); } while (0)
; #define PG8_LDA(dst, b, h) do { _Pragma("unroll") for (int m = 0; m < 4; ++m) _Pragma("unroll") for (int k = 0; k < 2; ++k) dst[m][k] = *(const PG8_LAS bf16x8*)(lds + PG8_SA(b, h) + aoff + m * 2048 + k * 1024); } while (0)
; #define PG8_LDB(dst, b, h) do { _Pragma("unroll") for (int n = 0; n < 2; ++n) _Pragma("unroll") for (int k = 0; k < 2; ++k) dst[n][k] = *(const PG8_LAS bf16x8*)(lds + PG8_SB(b, h) + boff + n * 2048 + k * 1024); } while (0)
; #define PG8_MMA(ai, bj, At, Bt) do { __builtin_amdgcn_s_setprio(1); _Pragma("unroll") for (int m = 0; m < 4; ++m) _Pragma("unroll") for (int n = 0; n < 2; ++n) _Pragma("unroll") for (int k = 0; k < 2; ++k) \
;         acc[ai][bj][m][n] = __builtin_amdgcn_mfma_f32_16x16x32_bf16(Bt[n][k], At[m][k], acc[ai][bj][m][n], 0, 0, 0); __builtin_amdgcn_s_setprio(0); } while (0)
; #define PG8_WAIT_V(n) asm volatile("s_waitcnt vmcnt(" #n ")" ::: "memory")
; #define PG8_WAIT_L(n) asm volatile("s_waitcnt lgkmcnt(" #n ")" ::: "memory")
; template <class Epi, class Sched, bool ALIGN_EPI = false, bool SP2 = false>
; __device__ __forceinline__ void gemm_phase(PG8_LAS unsigned char* lds, const Gemm g, const Sched& S, const Epi& E) {
;     ...
;             const bool last = (t == nt - 2);
;             const char* a1 = cA + (size_t)(t + 1) * kstep;
;             const char* a2 = last ? nA : cA + (size_t)(t + 2) * kstep; const char* b2 = last ? nB : cB + (size_t)(t + 2) * kstep;
;             const char* a3 = a2 + kstep; const char* b3 = b2 + kstep;
;             if (last && has_next) S.a_ready(nxt);
;             if constexpr (SP2) {
;             PG8_LDB(B0, 0, 0); PG8_LDB(B1, 0, 1); PG8_SCHED; PG8_LDA(At, 0, 0); PG8_STAGE(PG8_SA(1, 1), a1 + hstep, voffA);
;             PG8_WAIT_V(8); PG8_WAIT_L(0); PG8_BAR; PG8_MMA(0, 0, At, B0); PG8_MMA(0, 1, At, B1); PG8_BAR; PG8_SCHED;
;             PG8_LDA(At, 0, 1); PG8_STAGE(PG8_SB(0, 0), b2, voffB); PG8_STAGE(PG8_SB(0, 1), b2 + hstep, voffB); PG8_STAGE(PG8_SA(0, 0), a2, voffA);
;             PG8_WAIT_V(8); PG8_WAIT_L(0); PG8_BAR; PG8_MMA(1, 0, At, B0); PG8_MMA(1, 1, At, B1); PG8_BAR; PG8_SCHED;
.LBB0_1624:
	ds_read_b128 v[154:157], v148
	ds_read_b128 v[158:161], v148 offset:1024
	ds_read_b128 v[162:165], v148 offset:2048
	ds_read_b128 v[166:169], v148 offset:3072
	ds_read_b128 v[170:173], v149
	ds_read_b128 v[174:177], v149 offset:1024
	ds_read_b128 v[178:181], v149 offset:2048
	ds_read_b128 v[182:185], v149 offset:3072
	s_add_u32 s34, s30, 0xfffc0080
	s_addc_u32 s35, s31, -1
	s_cmp_eq_u32 s58, 12
	s_cselect_b32 s37, s23, s35
	s_cselect_b32 s36, s54, s34
	s_cselect_b32 s35, s21, s57
	s_cselect_b32 s34, s55, s56
	v_lshl_add_u64 v[144:145], s[30:31], 0, v[136:137]
	s_add_i32 m0, s29, 0xc000
	ds_read_b128 v[186:189], v150
	ds_read_b128 v[190:193], v150 offset:1024
	ds_read_b128 v[194:197], v150 offset:2048
	ds_read_b128 v[206:209], v150 offset:3072
	ds_read_b128 v[210:213], v150 offset:4096
	ds_read_b128 v[214:217], v150 offset:5120
	ds_read_b128 v[218:221], v150 offset:6144
	ds_read_b128 v[222:225], v150 offset:7168
	global_load_lds_dwordx4 v[144:145], off
	v_lshl_add_u64 v[144:145], s[30:31], 0, v[138:139]
	s_add_i32 m0, s29, 0xe000
	s_nop 0
	global_load_lds_dwordx4 v[144:145], off
	s_waitcnt vmcnt(8)
	s_waitcnt lgkmcnt(0)
	s_barrier
	s_setprio 1
	s_waitcnt lgkmcnt(0)
	v_mfma_f32_16x16x32_bf16 v[124:127], v[154:157], v[186:189], v[124:127]
	v_mfma_f32_16x16x32_bf16 v[120:123], v[162:165], v[186:189], v[120:123]
	v_mfma_f32_16x16x32_bf16 v[108:111], v[154:157], v[194:197], v[108:111]
	v_mfma_f32_16x16x32_bf16 v[104:107], v[162:165], v[194:197], v[104:107]
	v_mfma_f32_16x16x32_bf16 v[92:95], v[154:157], v[210:213], v[92:95]
	v_mfma_f32_16x16x32_bf16 v[88:91], v[162:165], v[210:213], v[88:91]
	v_mfma_f32_16x16x32_bf16 v[76:79], v[154:157], v[218:221], v[76:79]
	v_mfma_f32_16x16x32_bf16 v[72:75], v[162:165], v[218:221], v[72:75]
	v_mfma_f32_16x16x32_bf16 v[124:127], v[158:161], v[190:193], v[124:127]
	v_mfma_f32_16x16x32_bf16 v[120:123], v[166:169], v[190:193], v[120:123]
	v_mfma_f32_16x16x32_bf16 v[108:111], v[158:161], v[206:209], v[108:111]
	v_mfma_f32_16x16x32_bf16 v[104:107], v[166:169], v[206:209], v[104:107]
	v_mfma_f32_16x16x32_bf16 v[92:95], v[158:161], v[214:217], v[92:95]
	v_mfma_f32_16x16x32_bf16 v[88:91], v[166:169], v[214:217], v[88:91]
	v_mfma_f32_16x16x32_bf16 v[76:79], v[158:161], v[222:225], v[76:79]
	v_mfma_f32_16x16x32_bf16 v[72:75], v[166:169], v[222:225], v[72:75]
	s_setprio 0
	s_setprio 1
	v_mfma_f32_16x16x32_bf16 v[116:119], v[170:173], v[186:189], v[116:119]
	v_mfma_f32_16x16x32_bf16 v[112:115], v[178:181], v[186:189], v[112:115]
	v_mfma_f32_16x16x32_bf16 v[100:103], v[170:173], v[194:197], v[100:103]
	v_mfma_f32_16x16x32_bf16 v[96:99], v[178:181], v[194:197], v[96:99]
	v_mfma_f32_16x16x32_bf16 v[84:87], v[170:173], v[210:213], v[84:87]
	v_mfma_f32_16x16x32_bf16 v[80:83], v[178:181], v[210:213], v[80:83]
	v_mfma_f32_16x16x32_bf16 v[68:71], v[170:173], v[218:221], v[68:71]
	v_mfma_f32_16x16x32_bf16 v[64:67], v[178:181], v[218:221], v[64:67]
	v_mfma_f32_16x16x32_bf16 v[116:119], v[174:177], v[190:193], v[116:119]
	v_mfma_f32_16x16x32_bf16 v[112:115], v[182:185], v[190:193], v[112:115]
	v_mfma_f32_16x16x32_bf16 v[100:103], v[174:177], v[206:209], v[100:103]
	v_mfma_f32_16x16x32_bf16 v[96:99], v[182:185], v[206:209], v[96:99]
	v_mfma_f32_16x16x32_bf16 v[84:87], v[174:177], v[214:217], v[84:87]
	v_mfma_f32_16x16x32_bf16 v[80:83], v[182:185], v[214:217], v[80:83]
	v_mfma_f32_16x16x32_bf16 v[68:71], v[174:177], v[222:225], v[68:71]
	v_mfma_f32_16x16x32_bf16 v[64:67], v[182:185], v[222:225], v[64:67]
	s_setprio 0
	s_barrier
	s_add_i32 s59, s45, s33
	v_lshl_add_u64 v[144:145], s[34:35], 0, v[132:133]
	s_mov_b32 m0, s59
	ds_read_b128 v[186:189], v150 offset:16384
	ds_read_b128 v[190:193], v150 offset:17408
	ds_read_b128 v[194:197], v150 offset:18432
	ds_read_b128 v[206:209], v150 offset:19456
	ds_read_b128 v[210:213], v150 offset:20480
	ds_read_b128 v[214:217], v150 offset:21504
	ds_read_b128 v[218:221], v150 offset:22528
	ds_read_b128 v[222:225], v150 offset:23552
	global_load_lds_dwordx4 v[144:145], off
	s_add_i32 m0, s59, 0x2000
	s_add_u32 s60, s34, 0x40000
	v_lshl_add_u64 v[226:227], s[34:35], 0, v[128:129]
	s_addc_u32 s61, s35, 0
	s_add_i32 s59, s46, s33
	global_load_lds_dwordx4 v[226:227], off
	v_lshl_add_u64 v[228:229], s[60:61], 0, v[132:133]
	s_mov_b32 m0, s59
	v_lshl_add_u64 v[236:237], s[36:37], 0, v[130:131]
	global_load_lds_dwordx4 v[228:229], off
	v_lshl_add_u64 v[228:229], s[60:61], 0, v[128:129]
	s_add_i32 m0, s59, 0x2000
	s_nop 0
	global_load_lds_dwordx4 v[228:229], off
	v_lshl_add_u64 v[228:229], s[36:37], 0, v[134:135]
	s_mov_b32 m0, s29
	s_nop 0
	global_load_lds_dwordx4 v[228:229], off
	s_mov_b32 m0, s39
	s_nop 0
	global_load_lds_dwordx4 v[236:237], off
	s_waitcnt vmcnt(8)
	s_waitcnt lgkmcnt(0)
	s_barrier
; #define PG8_STAGE(bufoff, gbase, voff) do { _Pragma("unroll") for (int _i = 0; _i < 2; ++_i) \
;         __builtin_amdgcn_global_load_lds((const unsigned*)((const char*)(gbase) + (voff)[_i]), (PG8_LAS unsigned*)(lds + (bufoff) + ldsw + _i * 8192), 16, 0, 0); } while (0)
; #define PG8_LDA(dst, b, h) do { _Pragma("unroll") for (int m = 0; m < 4; ++m) _Pragma("unroll") for (int k = 0; k < 2; ++k) dst[m][k] = *(const PG8_LAS bf16x8*)(lds + PG8_SA(b, h) + aoff + m * 2048 + k * 1024); } while (0)
; #define PG8_LDB(dst, b, h) do { _Pragma("unroll") for (int n = 0; n < 2; ++n) _Pragma("unroll") for (int k = 0; k < 2; ++k) dst[n][k] = *(const PG8_LAS bf16x8*)(lds + PG8_SB(b, h) + boff + n * 2048 + k * 1024); } while (0)
; #define PG8_MMA(ai, bj, At, Bt) do { __builtin_amdgcn_s_setprio(1); _Pragma("unroll") for (int m = 0; m < 4; ++m) _Pragma("unroll") for (int n = 0; n < 2; ++n) _Pragma("unroll") for (int k = 0; k < 2; ++k) \
;         acc[ai][bj][m][n] = __builtin_amdgcn_mfma_f32_16x16x32_bf16(Bt[n][k], At[m][k], acc[ai][bj][m][n], 0, 0, 0); __builtin_amdgcn_s_setprio(0); } while (0)
; #define PG8_WAIT_V(n) asm volatile("s_waitcnt vmcnt(" #n ")" ::: "memory")
; #define PG8_WAIT_L(n) asm volatile("s_waitcnt lgkmcnt(" #n ")" ::: "memory")
; #define PG8_BAR __builtin_amdgcn_s_barrier()
; #define PG8_SCHED __builtin_amdgcn_sched_barrier(0)
; template <class Epi, class Sched, bool ALIGN_EPI = false, bool SP2 = false>
; __device__ __forceinline__ void gemm_phase(PG8_LAS unsigned char* lds, const Gemm g, const Sched& S, const Epi& E) {
;     ...
;             PG8_WAIT_V(8); PG8_WAIT_L(0); PG8_BAR; PG8_MMA(1, 0, At, B0); PG8_MMA(1, 1, At, B1); PG8_BAR; PG8_SCHED;
;             PG8_LDB(B0, 1, 0); PG8_LDB(B1, 1, 1); PG8_SCHED; PG8_LDA(At, 1, 0); PG8_STAGE(PG8_SA(0, 1), a2 + hstep, voffA);
;             PG8_WAIT_V(8); PG8_WAIT_L(0); PG8_BAR; PG8_MMA(0, 0, At, B0); PG8_MMA(0, 1, At, B1); PG8_BAR; PG8_SCHED;
	s_setprio 1
	s_waitcnt lgkmcnt(0)
	v_mfma_f32_16x16x32_bf16 v[60:63], v[154:157], v[186:189], v[60:63]
	v_mfma_f32_16x16x32_bf16 v[56:59], v[162:165], v[186:189], v[56:59]
	v_mfma_f32_16x16x32_bf16 v[44:47], v[154:157], v[194:197], v[44:47]
	v_mfma_f32_16x16x32_bf16 v[40:43], v[162:165], v[194:197], v[40:43]
	v_mfma_f32_16x16x32_bf16 v[28:31], v[154:157], v[210:213], v[28:31]
	v_mfma_f32_16x16x32_bf16 v[24:27], v[162:165], v[210:213], v[24:27]
	v_mfma_f32_16x16x32_bf16 v[12:15], v[154:157], v[218:221], v[12:15]
	v_mfma_f32_16x16x32_bf16 v[8:11], v[162:165], v[218:221], v[8:11]
	v_mfma_f32_16x16x32_bf16 v[60:63], v[158:161], v[190:193], v[60:63]
	v_mfma_f32_16x16x32_bf16 v[56:59], v[166:169], v[190:193], v[56:59]
	v_mfma_f32_16x16x32_bf16 v[44:47], v[158:161], v[206:209], v[44:47]
	v_mfma_f32_16x16x32_bf16 v[40:43], v[166:169], v[206:209], v[40:43]
	v_mfma_f32_16x16x32_bf16 v[28:31], v[158:161], v[214:217], v[28:31]
	v_mfma_f32_16x16x32_bf16 v[24:27], v[166:169], v[214:217], v[24:27]
	v_mfma_f32_16x16x32_bf16 v[12:15], v[158:161], v[222:225], v[12:15]
	v_mfma_f32_16x16x32_bf16 v[8:11], v[166:169], v[222:225], v[8:11]
	s_setprio 0
	s_setprio 1
	v_mfma_f32_16x16x32_bf16 v[52:55], v[170:173], v[186:189], v[52:55]
	v_mfma_f32_16x16x32_bf16 v[48:51], v[178:181], v[186:189], v[48:51]
	v_mfma_f32_16x16x32_bf16 v[36:39], v[170:173], v[194:197], v[36:39]
	v_mfma_f32_16x16x32_bf16 v[32:35], v[178:181], v[194:197], v[32:35]
	v_mfma_f32_16x16x32_bf16 v[20:23], v[170:173], v[210:213], v[20:23]
	v_mfma_f32_16x16x32_bf16 v[16:19], v[178:181], v[210:213], v[16:19]
	v_mfma_f32_16x16x32_bf16 v[4:7], v[170:173], v[218:221], v[4:7]
	v_mfma_f32_16x16x32_bf16 v[0:3], v[178:181], v[218:221], v[0:3]
	v_mfma_f32_16x16x32_bf16 v[52:55], v[174:177], v[190:193], v[52:55]
	v_mfma_f32_16x16x32_bf16 v[48:51], v[182:185], v[190:193], v[48:51]
	v_mfma_f32_16x16x32_bf16 v[36:39], v[174:177], v[206:209], v[36:39]
	v_mfma_f32_16x16x32_bf16 v[32:35], v[182:185], v[206:209], v[32:35]
	v_mfma_f32_16x16x32_bf16 v[20:23], v[174:177], v[214:217], v[20:23]
	v_mfma_f32_16x16x32_bf16 v[16:19], v[182:185], v[214:217], v[16:19]
	v_mfma_f32_16x16x32_bf16 v[4:7], v[174:177], v[222:225], v[4:7]
	v_mfma_f32_16x16x32_bf16 v[0:3], v[182:185], v[222:225], v[0:3]
	s_setprio 0
	s_barrier
	ds_read_b128 v[154:157], v151
	ds_read_b128 v[158:161], v151 offset:1024
	ds_read_b128 v[162:165], v151 offset:2048
	ds_read_b128 v[166:169], v151 offset:3072
	ds_read_b128 v[170:173], v152
	ds_read_b128 v[174:177], v152 offset:1024
	ds_read_b128 v[178:181], v152 offset:2048
	ds_read_b128 v[182:185], v152 offset:3072
	s_add_u32 s36, s36, 0x40000
	s_addc_u32 s37, s37, 0
	s_mov_b32 m0, s40
	v_lshl_add_u64 v[238:239], s[36:37], 0, v[134:135]
	ds_read_b128 v[186:189], v150 offset:32768
	ds_read_b128 v[190:193], v150 offset:33792
	ds_read_b128 v[194:197], v150 offset:34816
	ds_read_b128 v[206:209], v150 offset:35840
	ds_read_b128 v[210:213], v150 offset:36864
	ds_read_b128 v[214:217], v150 offset:37888
	ds_read_b128 v[218:221], v150 offset:38912
	ds_read_b128 v[222:225], v150 offset:39936
	global_load_lds_dwordx4 v[238:239], off
	v_lshl_add_u64 v[238:239], s[36:37], 0, v[130:131]
	s_mov_b32 m0, s41
	s_nop 0
	global_load_lds_dwordx4 v[238:239], off
	s_waitcnt vmcnt(8)
	s_waitcnt lgkmcnt(0)
	s_barrier
	s_setprio 1
	s_waitcnt lgkmcnt(0)
	v_mfma_f32_16x16x32_bf16 v[124:127], v[154:157], v[186:189], v[124:127]
	v_mfma_f32_16x16x32_bf16 v[120:123], v[162:165], v[186:189], v[120:123]
	v_mfma_f32_16x16x32_bf16 v[108:111], v[154:157], v[194:197], v[108:111]
	v_mfma_f32_16x16x32_bf16 v[104:107], v[162:165], v[194:197], v[104:107]
	v_mfma_f32_16x16x32_bf16 v[92:95], v[154:157], v[210:213], v[92:95]
	v_mfma_f32_16x16x32_bf16 v[88:91], v[162:165], v[210:213], v[88:91]
	v_mfma_f32_16x16x32_bf16 v[76:79], v[154:157], v[218:221], v[76:79]
	v_mfma_f32_16x16x32_bf16 v[72:75], v[162:165], v[218:221], v[72:75]
	v_mfma_f32_16x16x32_bf16 v[124:127], v[158:161], v[190:193], v[124:127]
	v_mfma_f32_16x16x32_bf16 v[120:123], v[166:169], v[190:193], v[120:123]
	v_mfma_f32_16x16x32_bf16 v[108:111], v[158:161], v[206:209], v[108:111]
	v_mfma_f32_16x16x32_bf16 v[104:107], v[166:169], v[206:209], v[104:107]
	v_mfma_f32_16x16x32_bf16 v[92:95], v[158:161], v[214:217], v[92:95]
	v_mfma_f32_16x16x32_bf16 v[88:91], v[166:169], v[214:217], v[88:91]
	v_mfma_f32_16x16x32_bf16 v[76:79], v[158:161], v[222:225], v[76:79]
	v_mfma_f32_16x16x32_bf16 v[72:75], v[166:169], v[222:225], v[72:75]
	s_setprio 0
	s_setprio 1
	v_mfma_f32_16x16x32_bf16 v[116:119], v[170:173], v[186:189], v[116:119]
	v_mfma_f32_16x16x32_bf16 v[112:115], v[178:181], v[186:189], v[112:115]
	v_mfma_f32_16x16x32_bf16 v[100:103], v[170:173], v[194:197], v[100:103]
	v_mfma_f32_16x16x32_bf16 v[96:99], v[178:181], v[194:197], v[96:99]
	v_mfma_f32_16x16x32_bf16 v[84:87], v[170:173], v[210:213], v[84:87]
	v_mfma_f32_16x16x32_bf16 v[80:83], v[178:181], v[210:213], v[80:83]
	v_mfma_f32_16x16x32_bf16 v[68:71], v[170:173], v[218:221], v[68:71]
	v_mfma_f32_16x16x32_bf16 v[64:67], v[178:181], v[218:221], v[64:67]
	v_mfma_f32_16x16x32_bf16 v[116:119], v[174:177], v[190:193], v[116:119]
	v_mfma_f32_16x16x32_bf16 v[112:115], v[182:185], v[190:193], v[112:115]
	v_mfma_f32_16x16x32_bf16 v[100:103], v[174:177], v[206:209], v[100:103]
	v_mfma_f32_16x16x32_bf16 v[96:99], v[182:185], v[206:209], v[96:99]
	v_mfma_f32_16x16x32_bf16 v[84:87], v[174:177], v[214:217], v[84:87]
	v_mfma_f32_16x16x32_bf16 v[80:83], v[182:185], v[214:217], v[80:83]
	v_mfma_f32_16x16x32_bf16 v[68:71], v[174:177], v[222:225], v[68:71]
	v_mfma_f32_16x16x32_bf16 v[64:67], v[182:185], v[222:225], v[64:67]
	s_setprio 0
	s_barrier
; #define PG8_STAGE(bufoff, gbase, voff) do { _Pragma("unroll") for (int _i = 0; _i < 2; ++_i) \
;         __builtin_amdgcn_global_load_lds((const unsigned*)((const char*)(gbase) + (voff)[_i]), (PG8_LAS unsigned*)(lds + (bufoff) + ldsw + _i * 8192), 16, 0, 0); } while (0)
; #define PG8_LDA(dst, b, h) do { _Pragma("unroll") for (int m = 0; m < 4; ++m) _Pragma("unroll") for (int k = 0; k < 2; ++k) dst[m][k] = *(const PG8_LAS bf16x8*)(lds + PG8_SA(b, h) + aoff + m * 2048 + k * 1024); } while (0)
; #define PG8_MMA(ai, bj, At, Bt) do { __builtin_amdgcn_s_setprio(1); _Pragma("unroll") for (int m = 0; m < 4; ++m) _Pragma("unroll") for (int n = 0; n < 2; ++n) _Pragma("unroll") for (int k = 0; k < 2; ++k) \
;         acc[ai][bj][m][n] = __builtin_amdgcn_mfma_f32_16x16x32_bf16(Bt[n][k], At[m][k], acc[ai][bj][m][n], 0, 0, 0); __builtin_amdgcn_s_setprio(0); } while (0)
; #define PG8_WAIT_V(n) asm volatile("s_waitcnt vmcnt(" #n ")" ::: "memory")
; #define PG8_WAIT_L(n) asm volatile("s_waitcnt lgkmcnt(" #n ")" ::: "memory")
; #define PG8_BAR __builtin_amdgcn_s_barrier()
; #define PG8_SCHED __builtin_amdgcn_sched_barrier(0)
; template <class Epi, class Sched, bool ALIGN_EPI = false, bool SP2 = false>
; __device__ __forceinline__ void gemm_phase(PG8_LAS unsigned char* lds, const Gemm g, const Sched& S, const Epi& E) {
;     ...
;         for (int t = 0; t < nt; t += 2) {
;     ...
;             PG8_LDA(At, 1, 1); PG8_STAGE(PG8_SB(1, 0), b3, voffB); PG8_STAGE(PG8_SB(1, 1), b3 + hstep, voffB); PG8_STAGE(PG8_SA(1, 0), a3, voffA);
;             PG8_WAIT_V(8); PG8_WAIT_L(0); PG8_BAR; PG8_MMA(1, 0, At, B0); PG8_MMA(1, 1, At, B1); PG8_BAR; PG8_SCHED;
	s_add_i32 s36, s51, s33
	v_lshl_add_u64 v[144:145], v[144:145], 0, s[8:9]
	s_mov_b32 m0, s36
	ds_read_b128 v[186:189], v150 offset:49152
	ds_read_b128 v[190:193], v150 offset:50176
	ds_read_b128 v[194:197], v150 offset:51200
	ds_read_b128 v[206:209], v150 offset:52224
	ds_read_b128 v[210:213], v150 offset:53248
	ds_read_b128 v[214:217], v150 offset:54272
	ds_read_b128 v[218:221], v150 offset:55296
	ds_read_b128 v[222:225], v150 offset:56320
	global_load_lds_dwordx4 v[144:145], off
	s_add_i32 m0, s36, 0x2000
	s_add_u32 s34, s34, 0x40080
	v_lshl_add_u64 v[144:145], v[226:227], 0, s[8:9]
	s_addc_u32 s35, s35, 0
	s_add_i32 s36, s52, s33
	global_load_lds_dwordx4 v[144:145], off
	v_lshl_add_u64 v[144:145], s[34:35], 0, v[132:133]
	s_mov_b32 m0, s36
	s_nop 0
	global_load_lds_dwordx4 v[144:145], off
	v_lshl_add_u64 v[144:145], s[34:35], 0, v[128:129]
	s_add_i32 m0, s36, 0x2000
	s_nop 0
	global_load_lds_dwordx4 v[144:145], off
	v_lshl_add_u64 v[144:145], v[228:229], 0, s[8:9]
	s_mov_b32 m0, s43
	s_nop 0
	global_load_lds_dwordx4 v[144:145], off
	v_lshl_add_u64 v[144:145], v[236:237], 0, s[8:9]
	s_mov_b32 m0, s44
	s_nop 0
	global_load_lds_dwordx4 v[144:145], off
	s_waitcnt vmcnt(8)
	s_waitcnt lgkmcnt(0)
	s_barrier
	s_setprio 1
	s_waitcnt lgkmcnt(0)
	v_mfma_f32_16x16x32_bf16 v[60:63], v[154:157], v[186:189], v[60:63]
	v_mfma_f32_16x16x32_bf16 v[56:59], v[162:165], v[186:189], v[56:59]
	v_mfma_f32_16x16x32_bf16 v[44:47], v[154:157], v[194:197], v[44:47]
	v_mfma_f32_16x16x32_bf16 v[40:43], v[162:165], v[194:197], v[40:43]
	v_mfma_f32_16x16x32_bf16 v[28:31], v[154:157], v[210:213], v[28:31]
	v_mfma_f32_16x16x32_bf16 v[24:27], v[162:165], v[210:213], v[24:27]
	v_mfma_f32_16x16x32_bf16 v[12:15], v[154:157], v[218:221], v[12:15]
	v_mfma_f32_16x16x32_bf16 v[8:11], v[162:165], v[218:221], v[8:11]
	v_mfma_f32_16x16x32_bf16 v[60:63], v[158:161], v[190:193], v[60:63]
	v_mfma_f32_16x16x32_bf16 v[56:59], v[166:169], v[190:193], v[56:59]
	v_mfma_f32_16x16x32_bf16 v[44:47], v[158:161], v[206:209], v[44:47]
	v_mfma_f32_16x16x32_bf16 v[40:43], v[166:169], v[206:209], v[40:43]
	v_mfma_f32_16x16x32_bf16 v[28:31], v[158:161], v[214:217], v[28:31]
	v_mfma_f32_16x16x32_bf16 v[24:27], v[166:169], v[214:217], v[24:27]
	v_mfma_f32_16x16x32_bf16 v[12:15], v[158:161], v[222:225], v[12:15]
	v_mfma_f32_16x16x32_bf16 v[8:11], v[166:169], v[222:225], v[8:11]
	s_setprio 0
	s_setprio 1
	v_mfma_f32_16x16x32_bf16 v[52:55], v[170:173], v[186:189], v[52:55]
	v_mfma_f32_16x16x32_bf16 v[48:51], v[178:181], v[186:189], v[48:51]
	v_mfma_f32_16x16x32_bf16 v[36:39], v[170:173], v[194:197], v[36:39]
	v_mfma_f32_16x16x32_bf16 v[32:35], v[178:181], v[194:197], v[32:35]
	v_mfma_f32_16x16x32_bf16 v[20:23], v[170:173], v[210:213], v[20:23]
	v_mfma_f32_16x16x32_bf16 v[16:19], v[178:181], v[210:213], v[16:19]
	v_mfma_f32_16x16x32_bf16 v[4:7], v[170:173], v[218:221], v[4:7]
	v_mfma_f32_16x16x32_bf16 v[0:3], v[178:181], v[218:221], v[0:3]
	v_mfma_f32_16x16x32_bf16 v[52:55], v[174:177], v[190:193], v[52:55]
	v_mfma_f32_16x16x32_bf16 v[48:51], v[182:185], v[190:193], v[48:51]
	v_mfma_f32_16x16x32_bf16 v[36:39], v[174:177], v[206:209], v[36:39]
	v_mfma_f32_16x16x32_bf16 v[32:35], v[182:185], v[206:209], v[32:35]
	v_mfma_f32_16x16x32_bf16 v[20:23], v[174:177], v[214:217], v[20:23]
	v_mfma_f32_16x16x32_bf16 v[16:19], v[182:185], v[214:217], v[16:19]
	v_mfma_f32_16x16x32_bf16 v[4:7], v[174:177], v[222:225], v[4:7]
	v_mfma_f32_16x16x32_bf16 v[0:3], v[182:185], v[222:225], v[0:3]
	s_setprio 0
	s_barrier
	s_add_i32 s58, s58, 2
	s_add_u32 s30, s30, 0x100
	s_addc_u32 s31, s31, 0
	s_add_u32 s56, s56, 0x100
	s_addc_u32 s57, s57, 0
	s_cmp_gt_u32 s58, 13
	s_cbranch_scc0 .LBB0_1624
	s_and_b64 vcc, exec, s[10:11]
	s_cbranch_vccz .LBB0_1627
	s_barrier

; #define PG8_STAGE(bufoff, gbase, voff) do { _Pragma("unroll") for (int _i = 0; _i < 2; ++_i) \
;         __builtin_amdgcn_global_load_lds((const unsigned*)((const char*)(gbase) + (voff)[_i]), (PG8_LAS unsigned*)(lds + (bufoff) + ldsw + _i * 8192), 16, 0, 0); } while (0)
; #define PG8_WAIT_V(n) asm volatile("s_waitcnt vmcnt(" #n ")" ::: "memory")
; #define PG8_BAR __builtin_amdgcn_s_barrier()
; template <class Epi, class Sched, bool ALIGN_EPI = false, bool SP2 = false>
; __device__ __forceinline__ void gemm_phase(PG8_LAS unsigned char* lds, const Gemm g, const Sched& S, const Epi& E) {
;     ...
;     const int K = g.K, LD = g.ld, nt = K / BK;
;     unsigned voffA[2], voffB[2];
; #pragma unroll
;     for (int i = 0; i < 2; ++i) { int R, C; stage_rc(tid * 16 + i * 8192, R, C); const int Rb = Epi::PERM ? ((R & ~31) + perm32(R & 31)) : R;
;         voffA[i] = (unsigned)(R * LD + C) * 2u; voffB[i] = (unsigned)(Rb * LD + C) * 2u; }
;     const size_t kstep = (size_t)(BK * 2);
;     const size_t hstep = (size_t)HALF * LD * 2;
;     const size_t tstep = 2 * hstep;
;     const unsigned ldsw = (unsigned)wid * 1024u;
;     const int aoff = lds_byte(wr * 64 + fr, fq * 8), boff = lds_byte(wc * 32 + fr, fq * 8);
;     ...
;         PG8_STAGE(PG8_SB(0, 0), cB, voffB); PG8_STAGE(PG8_SB(0, 1), cB + hstep, voffB); PG8_STAGE(PG8_SA(0, 0), cA, voffA); PG8_STAGE(PG8_SA(0, 1), cA + hstep, voffA);
;         if (wr == 1) PG8_BAR;
;         PG8_WAIT_V(2); PG8_BAR;
;         PG8_STAGE(PG8_SB(1, 0), cB + kstep, voffB); PG8_STAGE(PG8_SA(1, 0), cA + kstep, voffA); PG8_STAGE(PG8_SB(1, 1), cB + hstep + kstep, voffB);
;         PG8_WAIT_V(6); PG8_BAR;
.LBB0_1693:
	s_lshl_b32 s8, s8, 5
	s_and_b32 s15, s8, 0x60
	s_mov_b64 s[8:9], 0x80
	s_add_i32 m0, s31, 0x18000
	v_lshl_add_u64 v[6:7], v[6:7], 0, s[8:9]
	s_lshl_b32 s11, s5, 13
	s_lshl_b32 s18, s15, 7
	s_waitcnt vmcnt(2)
	s_barrier
	global_load_lds_dwordx4 v[6:7], off
	v_lshl_add_u64 v[2:3], v[2:3], 0, s[8:9]
	s_add_i32 m0, s31, 0x1a000
	s_add_i32 s42, s31, 0x8000
	s_add_i32 s43, s31, 0xa000
	global_load_lds_dwordx4 v[2:3], off
	v_lshl_add_u64 v[0:1], v[0:1], 0, s[8:9]
	s_mov_b32 m0, s42
	s_add_u32 s16, s36, 0x100080
	global_load_lds_dwordx4 v[0:1], off
	v_lshl_add_u64 v[0:1], v[4:5], 0, s[8:9]
	s_mov_b32 m0, s43
	s_addc_u32 s17, s37, 0
	global_load_lds_dwordx4 v[0:1], off
	s_add_i32 m0, s31, 0x1c000
	v_lshl_add_u64 v[0:1], s[16:17], 0, v[132:133]
	global_load_lds_dwordx4 v[0:1], off
	v_lshl_add_u64 v[0:1], s[16:17], 0, v[134:135]
	s_add_i32 m0, s31, 0x1e000
	v_lshlrev_b32_e32 v3, 2, v204
	global_load_lds_dwordx4 v[0:1], off
	v_lshrrev_b32_e32 v0, 1, v198
	v_and_b32_e32 v0, 24, v0
	v_lshlrev_b32_e32 v1, 1, v0
	v_lshl_or_b32 v2, v204, 6, v1
	v_and_b32_e32 v3, 32, v3
	v_or_b32_e32 v155, s15, v0
	v_lshlrev_b32_e32 v0, 10, v198
	v_bitop3_b32 v2, v2, s11, v3 bitop3:0xde
	v_and_b32_e32 v0, 0xe0000, v0
	v_lshlrev_b32_e32 v3, 13, v230
	v_or3_b32 v0, v150, v0, v3
	v_add_u32_e32 v136, v0, v205
	v_lshlrev_b32_e32 v0, 6, v151
	s_sext_i32_i8 s49, s4
	v_lshl_or_b32 v154, s5, 6, v204
	v_or_b32_e32 v1, v1, v152
	s_mov_b32 s4, 0x18000
	s_mov_b32 s5, 0x1c000
	s_waitcnt vmcnt(6)
	s_cmpk_lt_u32 s10, 0x100
	v_and_b32_e32 v0, 0x1e0000, v0
	v_bitop3_b32 v1, s18, v1, v153 bitop3:0xf6
	s_cselect_b64 s[10:11], -1, 0
	v_or3_b32 v0, v150, v0, v3
	s_add_i32 s45, s12, 0x100
	s_add_i32 s46, s14, 0x100
	s_add_i32 s47, s4, 0x100
	s_add_i32 s48, s5, 0x100
	v_mov_b32_e32 v137, v133
	v_add_u32_e32 v138, v0, v205
	v_mov_b32_e32 v139, v133
	s_mov_b32 s44, 0
	v_mov_b64_e32 v[140:141], 0x200
	v_mov_b64_e32 v[142:143], 0x1ff
	v_add_u32_e32 v156, s45, v1
	v_add_u32_e32 v157, s46, v1
	v_add_u32_e32 v158, 0x100, v2
	s_mov_b32 s12, 0x3fb504f3
	s_mov_b64 s[14:15], 0x40000
	s_mov_b64 s[16:17], 0x48000
	s_mov_b64 s[18:19], 0x50000
	s_mov_b64 s[20:21], 0x58000
	v_add_u32_e32 v159, s47, v1
	v_add_u32_e32 v160, s48, v1
	s_barrier
	s_branch .LBB0_1696

; #define PG8_STAGE(bufoff, gbase, voff) do { _Pragma("unroll") for (int _i = 0; _i < 2; ++_i) \
;         __builtin_amdgcn_global_load_lds((const unsigned*)((const char*)(gbase) + (voff)[_i]), (PG8_LAS unsigned*)(lds + (bufoff) + ldsw + _i * 8192), 16, 0, 0); } while (0)
; #define PG8_LDA(dst, b, h) do { _Pragma("unroll") for (int m = 0; m < 4; ++m) _Pragma("unroll") for (int k = 0; k < 2; ++k) dst[m][k] = *(const PG8_LAS bf16x8*)(lds + PG8_SA(b, h) + aoff + m * 2048 + k * 1024); } while (0)
; #define PG8_LDB(dst, b, h) do { _Pragma("unroll") for (int n = 0; n < 2; ++n) _Pragma("unroll") for (int k = 0; k < 2; ++k) dst[n][k] = *(const PG8_LAS bf16x8*)(lds + PG8_SB(b, h) + boff + n * 2048 + k * 1024); } while (0)
; #define PG8_MMA(ai, bj, At, Bt) do { __builtin_amdgcn_s_setprio(1); _Pragma("unroll") for (int m = 0; m < 4; ++m) _Pragma("unroll") for (int n = 0; n < 2; ++n) _Pragma("unroll") for (int k = 0; k < 2; ++k) \
;         acc[ai][bj][m][n] = __builtin_amdgcn_mfma_f32_16x16x32_bf16(Bt[n][k], At[m][k], acc[ai][bj][m][n], 0, 0, 0); __builtin_amdgcn_s_setprio(0); } while (0)
; #define PG8_WAIT_V(n) asm volatile("s_waitcnt vmcnt(" #n ")" ::: "memory")
; #define PG8_WAIT_L(n) asm volatile("s_waitcnt lgkmcnt(" #n ")" ::: "memory")
; template <class Epi, class Sched, bool ALIGN_EPI = false, bool SP2 = false>
; __device__ __forceinline__ void gemm_phase(PG8_LAS unsigned char* lds, const Gemm g, const Sched& S, const Epi& E) {
;     ...
;             const bool last = (t == nt - 2);
;             const char* a1 = cA + (size_t)(t + 1) * kstep;
;             const char* a2 = last ? nA : cA + (size_t)(t + 2) * kstep; const char* b2 = last ? nB : cB + (size_t)(t + 2) * kstep;
;             const char* a3 = a2 + kstep; const char* b3 = b2 + kstep;
;             if (last && has_next) S.a_ready(nxt);
;             if constexpr (SP2) {
;             PG8_LDB(B0, 0, 0); PG8_LDB(B1, 0, 1); PG8_SCHED; PG8_LDA(At, 0, 0); PG8_STAGE(PG8_SA(1, 1), a1 + hstep, voffA);
;             PG8_WAIT_V(8); PG8_WAIT_L(0); PG8_BAR; PG8_MMA(0, 0, At, B0); PG8_MMA(0, 1, At, B1); PG8_BAR; PG8_SCHED;
;             PG8_LDA(At, 0, 1); PG8_STAGE(PG8_SB(0, 0), b2, voffB); PG8_STAGE(PG8_SB(0, 1), b2 + hstep, voffB); PG8_STAGE(PG8_SA(0, 0), a2, voffA);
;             PG8_WAIT_V(8); PG8_WAIT_L(0); PG8_BAR; PG8_MMA(1, 0, At, B0); PG8_MMA(1, 1, At, B1); PG8_BAR; PG8_SCHED;
.LBB0_1703:
	ds_read_b128 v[144:147], v156
	ds_read_b128 v[162:165], v156 offset:1024
	ds_read_b128 v[166:169], v156 offset:2048
	ds_read_b128 v[170:173], v156 offset:3072
	ds_read_b128 v[174:177], v157
	ds_read_b128 v[178:181], v157 offset:1024
	ds_read_b128 v[182:185], v157 offset:2048
	ds_read_b128 v[186:189], v157 offset:3072
	s_add_u32 s36, s34, 0xfff00080
	s_addc_u32 s37, s35, -1
	s_cmp_eq_u32 s54, 60
	s_cselect_b32 s39, s25, s37
	s_cselect_b32 s38, s50, s36
	s_cselect_b32 s37, s23, s53
	s_cselect_b32 s36, s51, s52
	v_lshl_add_u64 v[148:149], s[34:35], 0, v[136:137]
	s_add_i32 m0, s31, 0xc000
	ds_read_b128 v[190:193], v158
	ds_read_b128 v[194:197], v158 offset:1024
	ds_read_b128 v[206:209], v158 offset:2048
	ds_read_b128 v[210:213], v158 offset:3072
	ds_read_b128 v[214:217], v158 offset:4096
	ds_read_b128 v[218:221], v158 offset:5120
	ds_read_b128 v[222:225], v158 offset:6144
	ds_read_b128 v[226:229], v158 offset:7168
	global_load_lds_dwordx4 v[148:149], off
	v_lshl_add_u64 v[148:149], s[34:35], 0, v[138:139]
	s_add_i32 m0, s31, 0xe000
	s_nop 0
	global_load_lds_dwordx4 v[148:149], off
	s_waitcnt vmcnt(8)
	s_waitcnt lgkmcnt(0)
	s_barrier
	s_setprio 1
	s_waitcnt lgkmcnt(0)
	v_mfma_f32_16x16x32_bf16 v[124:127], v[144:147], v[190:193], v[124:127]
	v_mfma_f32_16x16x32_bf16 v[120:123], v[166:169], v[190:193], v[120:123]
	v_mfma_f32_16x16x32_bf16 v[108:111], v[144:147], v[206:209], v[108:111]
	v_mfma_f32_16x16x32_bf16 v[104:107], v[166:169], v[206:209], v[104:107]
	v_mfma_f32_16x16x32_bf16 v[92:95], v[144:147], v[214:217], v[92:95]
	v_mfma_f32_16x16x32_bf16 v[88:91], v[166:169], v[214:217], v[88:91]
	v_mfma_f32_16x16x32_bf16 v[76:79], v[144:147], v[222:225], v[76:79]
	v_mfma_f32_16x16x32_bf16 v[72:75], v[166:169], v[222:225], v[72:75]
	v_mfma_f32_16x16x32_bf16 v[124:127], v[162:165], v[194:197], v[124:127]
	v_mfma_f32_16x16x32_bf16 v[120:123], v[170:173], v[194:197], v[120:123]
	v_mfma_f32_16x16x32_bf16 v[108:111], v[162:165], v[210:213], v[108:111]
	v_mfma_f32_16x16x32_bf16 v[104:107], v[170:173], v[210:213], v[104:107]
	v_mfma_f32_16x16x32_bf16 v[92:95], v[162:165], v[218:221], v[92:95]
	v_mfma_f32_16x16x32_bf16 v[88:91], v[170:173], v[218:221], v[88:91]
	v_mfma_f32_16x16x32_bf16 v[76:79], v[162:165], v[226:229], v[76:79]
	v_mfma_f32_16x16x32_bf16 v[72:75], v[170:173], v[226:229], v[72:75]
	s_setprio 0
	s_setprio 1
	v_mfma_f32_16x16x32_bf16 v[116:119], v[174:177], v[190:193], v[116:119]
	v_mfma_f32_16x16x32_bf16 v[112:115], v[182:185], v[190:193], v[112:115]
	v_mfma_f32_16x16x32_bf16 v[100:103], v[174:177], v[206:209], v[100:103]
	v_mfma_f32_16x16x32_bf16 v[96:99], v[182:185], v[206:209], v[96:99]
	v_mfma_f32_16x16x32_bf16 v[84:87], v[174:177], v[214:217], v[84:87]
	v_mfma_f32_16x16x32_bf16 v[80:83], v[182:185], v[214:217], v[80:83]
	v_mfma_f32_16x16x32_bf16 v[68:71], v[174:177], v[222:225], v[68:71]
	v_mfma_f32_16x16x32_bf16 v[64:67], v[182:185], v[222:225], v[64:67]
	v_mfma_f32_16x16x32_bf16 v[116:119], v[178:181], v[194:197], v[116:119]
	v_mfma_f32_16x16x32_bf16 v[112:115], v[186:189], v[194:197], v[112:115]
	v_mfma_f32_16x16x32_bf16 v[100:103], v[178:181], v[210:213], v[100:103]
	v_mfma_f32_16x16x32_bf16 v[96:99], v[186:189], v[210:213], v[96:99]
	v_mfma_f32_16x16x32_bf16 v[84:87], v[178:181], v[218:221], v[84:87]
	v_mfma_f32_16x16x32_bf16 v[80:83], v[186:189], v[218:221], v[80:83]
	v_mfma_f32_16x16x32_bf16 v[68:71], v[178:181], v[226:229], v[68:71]
	v_mfma_f32_16x16x32_bf16 v[64:67], v[186:189], v[226:229], v[64:67]
	s_setprio 0
	s_barrier
	s_add_i32 s55, s45, s13
	v_lshl_add_u64 v[148:149], s[36:37], 0, v[132:133]
	s_mov_b32 m0, s55
	ds_read_b128 v[190:193], v158 offset:16384
	ds_read_b128 v[194:197], v158 offset:17408
	ds_read_b128 v[206:209], v158 offset:18432
	ds_read_b128 v[210:213], v158 offset:19456
	ds_read_b128 v[214:217], v158 offset:20480
	ds_read_b128 v[218:221], v158 offset:21504
	ds_read_b128 v[222:225], v158 offset:22528
	ds_read_b128 v[226:229], v158 offset:23552
	global_load_lds_dwordx4 v[148:149], off
	s_add_i32 m0, s55, 0x2000
	s_add_u32 s56, s36, 0x100000
	v_lshl_add_u64 v[232:233], s[36:37], 0, v[134:135]
	s_addc_u32 s57, s37, 0
	s_add_i32 s55, s46, s13
	global_load_lds_dwordx4 v[232:233], off
	v_lshl_add_u64 v[234:235], s[56:57], 0, v[132:133]
	s_mov_b32 m0, s55
	v_lshl_add_u64 v[236:237], s[38:39], 0, v[130:131]
	global_load_lds_dwordx4 v[234:235], off
	v_lshl_add_u64 v[234:235], s[56:57], 0, v[134:135]
	s_add_i32 m0, s55, 0x2000
	s_nop 0
	global_load_lds_dwordx4 v[234:235], off
	v_lshl_add_u64 v[234:235], s[38:39], 0, v[128:129]
	s_mov_b32 m0, s31
	s_nop 0
	global_load_lds_dwordx4 v[234:235], off
	s_mov_b32 m0, s33
	s_nop 0
	global_load_lds_dwordx4 v[236:237], off
	s_waitcnt vmcnt(8)
	s_waitcnt lgkmcnt(0)
	s_barrier
; #define PG8_STAGE(bufoff, gbase, voff) do { _Pragma("unroll") for (int _i = 0; _i < 2; ++_i) \
;         __builtin_amdgcn_global_load_lds((const unsigned*)((const char*)(gbase) + (voff)[_i]), (PG8_LAS unsigned*)(lds + (bufoff) + ldsw + _i * 8192), 16, 0, 0); } while (0)
; #define PG8_LDA(dst, b, h) do { _Pragma("unroll") for (int m = 0; m < 4; ++m) _Pragma("unroll") for (int k = 0; k < 2; ++k) dst[m][k] = *(const PG8_LAS bf16x8*)(lds + PG8_SA(b, h) + aoff + m * 2048 + k * 1024); } while (0)
; #define PG8_LDB(dst, b, h) do { _Pragma("unroll") for (int n = 0; n < 2; ++n) _Pragma("unroll") for (int k = 0; k < 2; ++k) dst[n][k] = *(const PG8_LAS bf16x8*)(lds + PG8_SB(b, h) + boff + n * 2048 + k * 1024); } while (0)
; #define PG8_MMA(ai, bj, At, Bt) do { __builtin_amdgcn_s_setprio(1); _Pragma("unroll") for (int m = 0; m < 4; ++m) _Pragma("unroll") for (int n = 0; n < 2; ++n) _Pragma("unroll") for (int k = 0; k < 2; ++k) \
;         acc[ai][bj][m][n] = __builtin_amdgcn_mfma_f32_16x16x32_bf16(Bt[n][k], At[m][k], acc[ai][bj][m][n], 0, 0, 0); __builtin_amdgcn_s_setprio(0); } while (0)
; #define PG8_WAIT_V(n) asm volatile("s_waitcnt vmcnt(" #n ")" ::: "memory")
; #define PG8_WAIT_L(n) asm volatile("s_waitcnt lgkmcnt(" #n ")" ::: "memory")
; #define PG8_BAR __builtin_amdgcn_s_barrier()
; #define PG8_SCHED __builtin_amdgcn_sched_barrier(0)
; template <class Epi, class Sched, bool ALIGN_EPI = false, bool SP2 = false>
; __device__ __forceinline__ void gemm_phase(PG8_LAS unsigned char* lds, const Gemm g, const Sched& S, const Epi& E) {
;     ...
;             PG8_WAIT_V(8); PG8_WAIT_L(0); PG8_BAR; PG8_MMA(1, 0, At, B0); PG8_MMA(1, 1, At, B1); PG8_BAR; PG8_SCHED;
;             PG8_LDB(B0, 1, 0); PG8_LDB(B1, 1, 1); PG8_SCHED; PG8_LDA(At, 1, 0); PG8_STAGE(PG8_SA(0, 1), a2 + hstep, voffA);
;             PG8_WAIT_V(8); PG8_WAIT_L(0); PG8_BAR; PG8_MMA(0, 0, At, B0); PG8_MMA(0, 1, At, B1); PG8_BAR; PG8_SCHED;
	s_setprio 1
	s_waitcnt lgkmcnt(0)
	v_mfma_f32_16x16x32_bf16 v[60:63], v[144:147], v[190:193], v[60:63]
	v_mfma_f32_16x16x32_bf16 v[56:59], v[166:169], v[190:193], v[56:59]
	v_mfma_f32_16x16x32_bf16 v[44:47], v[144:147], v[206:209], v[44:47]
	v_mfma_f32_16x16x32_bf16 v[40:43], v[166:169], v[206:209], v[40:43]
	v_mfma_f32_16x16x32_bf16 v[28:31], v[144:147], v[214:217], v[28:31]
	v_mfma_f32_16x16x32_bf16 v[24:27], v[166:169], v[214:217], v[24:27]
	v_mfma_f32_16x16x32_bf16 v[12:15], v[144:147], v[222:225], v[12:15]
	v_mfma_f32_16x16x32_bf16 v[8:11], v[166:169], v[222:225], v[8:11]
	v_mfma_f32_16x16x32_bf16 v[60:63], v[162:165], v[194:197], v[60:63]
	v_mfma_f32_16x16x32_bf16 v[56:59], v[170:173], v[194:197], v[56:59]
	v_mfma_f32_16x16x32_bf16 v[44:47], v[162:165], v[210:213], v[44:47]
	v_mfma_f32_16x16x32_bf16 v[40:43], v[170:173], v[210:213], v[40:43]
	v_mfma_f32_16x16x32_bf16 v[28:31], v[162:165], v[218:221], v[28:31]
	v_mfma_f32_16x16x32_bf16 v[24:27], v[170:173], v[218:221], v[24:27]
	v_mfma_f32_16x16x32_bf16 v[12:15], v[162:165], v[226:229], v[12:15]
	v_mfma_f32_16x16x32_bf16 v[8:11], v[170:173], v[226:229], v[8:11]
	s_setprio 0
	s_setprio 1
	v_mfma_f32_16x16x32_bf16 v[52:55], v[174:177], v[190:193], v[52:55]
	v_mfma_f32_16x16x32_bf16 v[48:51], v[182:185], v[190:193], v[48:51]
	v_mfma_f32_16x16x32_bf16 v[36:39], v[174:177], v[206:209], v[36:39]
	v_mfma_f32_16x16x32_bf16 v[32:35], v[182:185], v[206:209], v[32:35]
	v_mfma_f32_16x16x32_bf16 v[20:23], v[174:177], v[214:217], v[20:23]
	v_mfma_f32_16x16x32_bf16 v[16:19], v[182:185], v[214:217], v[16:19]
	v_mfma_f32_16x16x32_bf16 v[4:7], v[174:177], v[222:225], v[4:7]
	v_mfma_f32_16x16x32_bf16 v[0:3], v[182:185], v[222:225], v[0:3]
	v_mfma_f32_16x16x32_bf16 v[52:55], v[178:181], v[194:197], v[52:55]
	v_mfma_f32_16x16x32_bf16 v[48:51], v[186:189], v[194:197], v[48:51]
	v_mfma_f32_16x16x32_bf16 v[36:39], v[178:181], v[210:213], v[36:39]
	v_mfma_f32_16x16x32_bf16 v[32:35], v[186:189], v[210:213], v[32:35]
	v_mfma_f32_16x16x32_bf16 v[20:23], v[178:181], v[218:221], v[20:23]
	v_mfma_f32_16x16x32_bf16 v[16:19], v[186:189], v[218:221], v[16:19]
	v_mfma_f32_16x16x32_bf16 v[4:7], v[178:181], v[226:229], v[4:7]
	v_mfma_f32_16x16x32_bf16 v[0:3], v[186:189], v[226:229], v[0:3]
	s_setprio 0
	s_barrier
	ds_read_b128 v[144:147], v159
	ds_read_b128 v[162:165], v159 offset:1024
	ds_read_b128 v[166:169], v159 offset:2048
	ds_read_b128 v[170:173], v159 offset:3072
	ds_read_b128 v[174:177], v160
	ds_read_b128 v[178:181], v160 offset:1024
	ds_read_b128 v[182:185], v160 offset:2048
	ds_read_b128 v[186:189], v160 offset:3072
	s_add_u32 s38, s38, 0x100000
	s_addc_u32 s39, s39, 0
	s_mov_b32 m0, s40
	v_lshl_add_u64 v[238:239], s[38:39], 0, v[128:129]
	ds_read_b128 v[190:193], v158 offset:32768
	ds_read_b128 v[194:197], v158 offset:33792
	ds_read_b128 v[206:209], v158 offset:34816
	ds_read_b128 v[210:213], v158 offset:35840
	ds_read_b128 v[214:217], v158 offset:36864
	ds_read_b128 v[218:221], v158 offset:37888
	ds_read_b128 v[222:225], v158 offset:38912
	ds_read_b128 v[226:229], v158 offset:39936
	global_load_lds_dwordx4 v[238:239], off
	v_lshl_add_u64 v[238:239], s[38:39], 0, v[130:131]
	s_mov_b32 m0, s41
	s_nop 0
	global_load_lds_dwordx4 v[238:239], off
	s_waitcnt vmcnt(8)
	s_waitcnt lgkmcnt(0)
	s_barrier
	s_setprio 1
	s_waitcnt lgkmcnt(0)
	v_mfma_f32_16x16x32_bf16 v[124:127], v[144:147], v[190:193], v[124:127]
	v_mfma_f32_16x16x32_bf16 v[120:123], v[166:169], v[190:193], v[120:123]
	v_mfma_f32_16x16x32_bf16 v[108:111], v[144:147], v[206:209], v[108:111]
	v_mfma_f32_16x16x32_bf16 v[104:107], v[166:169], v[206:209], v[104:107]
	v_mfma_f32_16x16x32_bf16 v[92:95], v[144:147], v[214:217], v[92:95]
	v_mfma_f32_16x16x32_bf16 v[88:91], v[166:169], v[214:217], v[88:91]
	v_mfma_f32_16x16x32_bf16 v[76:79], v[144:147], v[222:225], v[76:79]
	v_mfma_f32_16x16x32_bf16 v[72:75], v[166:169], v[222:225], v[72:75]
	v_mfma_f32_16x16x32_bf16 v[124:127], v[162:165], v[194:197], v[124:127]
	v_mfma_f32_16x16x32_bf16 v[120:123], v[170:173], v[194:197], v[120:123]
	v_mfma_f32_16x16x32_bf16 v[108:111], v[162:165], v[210:213], v[108:111]
	v_mfma_f32_16x16x32_bf16 v[104:107], v[170:173], v[210:213], v[104:107]
	v_mfma_f32_16x16x32_bf16 v[92:95], v[162:165], v[218:221], v[92:95]
	v_mfma_f32_16x16x32_bf16 v[88:91], v[170:173], v[218:221], v[88:91]
	v_mfma_f32_16x16x32_bf16 v[76:79], v[162:165], v[226:229], v[76:79]
	v_mfma_f32_16x16x32_bf16 v[72:75], v[170:173], v[226:229], v[72:75]
	s_setprio 0
	s_setprio 1
	v_mfma_f32_16x16x32_bf16 v[116:119], v[174:177], v[190:193], v[116:119]
	v_mfma_f32_16x16x32_bf16 v[112:115], v[182:185], v[190:193], v[112:115]
	v_mfma_f32_16x16x32_bf16 v[100:103], v[174:177], v[206:209], v[100:103]
	v_mfma_f32_16x16x32_bf16 v[96:99], v[182:185], v[206:209], v[96:99]
	v_mfma_f32_16x16x32_bf16 v[84:87], v[174:177], v[214:217], v[84:87]
	v_mfma_f32_16x16x32_bf16 v[80:83], v[182:185], v[214:217], v[80:83]
	v_mfma_f32_16x16x32_bf16 v[68:71], v[174:177], v[222:225], v[68:71]
	v_mfma_f32_16x16x32_bf16 v[64:67], v[182:185], v[222:225], v[64:67]
	v_mfma_f32_16x16x32_bf16 v[116:119], v[178:181], v[194:197], v[116:119]
	v_mfma_f32_16x16x32_bf16 v[112:115], v[186:189], v[194:197], v[112:115]
	v_mfma_f32_16x16x32_bf16 v[100:103], v[178:181], v[210:213], v[100:103]
	v_mfma_f32_16x16x32_bf16 v[96:99], v[186:189], v[210:213], v[96:99]
	v_mfma_f32_16x16x32_bf16 v[84:87], v[178:181], v[218:221], v[84:87]
	v_mfma_f32_16x16x32_bf16 v[80:83], v[186:189], v[218:221], v[80:83]
	v_mfma_f32_16x16x32_bf16 v[68:71], v[178:181], v[226:229], v[68:71]
	v_mfma_f32_16x16x32_bf16 v[64:67], v[186:189], v[226:229], v[64:67]
	s_setprio 0
	s_barrier
; #define PG8_STAGE(bufoff, gbase, voff) do { _Pragma("unroll") for (int _i = 0; _i < 2; ++_i) \
;         __builtin_amdgcn_global_load_lds((const unsigned*)((const char*)(gbase) + (voff)[_i]), (PG8_LAS unsigned*)(lds + (bufoff) + ldsw + _i * 8192), 16, 0, 0); } while (0)
; #define PG8_LDA(dst, b, h) do { _Pragma("unroll") for (int m = 0; m < 4; ++m) _Pragma("unroll") for (int k = 0; k < 2; ++k) dst[m][k] = *(const PG8_LAS bf16x8*)(lds + PG8_SA(b, h) + aoff + m * 2048 + k * 1024); } while (0)
; #define PG8_MMA(ai, bj, At, Bt) do { __builtin_amdgcn_s_setprio(1); _Pragma("unroll") for (int m = 0; m < 4; ++m) _Pragma("unroll") for (int n = 0; n < 2; ++n) _Pragma("unroll") for (int k = 0; k < 2; ++k) \
;         acc[ai][bj][m][n] = __builtin_amdgcn_mfma_f32_16x16x32_bf16(Bt[n][k], At[m][k], acc[ai][bj][m][n], 0, 0, 0); __builtin_amdgcn_s_setprio(0); } while (0)
; #define PG8_WAIT_V(n) asm volatile("s_waitcnt vmcnt(" #n ")" ::: "memory")
; #define PG8_WAIT_L(n) asm volatile("s_waitcnt lgkmcnt(" #n ")" ::: "memory")
; #define PG8_BAR __builtin_amdgcn_s_barrier()
; #define PG8_SCHED __builtin_amdgcn_sched_barrier(0)
; template <class Epi, class Sched, bool ALIGN_EPI = false, bool SP2 = false>
; __device__ __forceinline__ void gemm_phase(PG8_LAS unsigned char* lds, const Gemm g, const Sched& S, const Epi& E) {
;     ...
;         for (int t = 0; t < nt; t += 2) {
;     ...
;             PG8_LDA(At, 1, 1); PG8_STAGE(PG8_SB(1, 0), b3, voffB); PG8_STAGE(PG8_SB(1, 1), b3 + hstep, voffB); PG8_STAGE(PG8_SA(1, 0), a3, voffA);
;             PG8_WAIT_V(8); PG8_WAIT_L(0); PG8_BAR; PG8_MMA(1, 0, At, B0); PG8_MMA(1, 1, At, B1); PG8_BAR; PG8_SCHED;
	s_add_i32 s38, s47, s13
	v_lshl_add_u64 v[148:149], v[148:149], 0, s[8:9]
	s_mov_b32 m0, s38
	ds_read_b128 v[190:193], v158 offset:49152
	ds_read_b128 v[194:197], v158 offset:50176
	ds_read_b128 v[206:209], v158 offset:51200
	ds_read_b128 v[210:213], v158 offset:52224
	ds_read_b128 v[214:217], v158 offset:53248
	ds_read_b128 v[218:221], v158 offset:54272
	ds_read_b128 v[222:225], v158 offset:55296
	ds_read_b128 v[226:229], v158 offset:56320
	global_load_lds_dwordx4 v[148:149], off
	s_add_i32 m0, s38, 0x2000
	s_add_u32 s36, s36, 0x100080
	v_lshl_add_u64 v[148:149], v[232:233], 0, s[8:9]
	s_addc_u32 s37, s37, 0
	s_add_i32 s38, s48, s13
	global_load_lds_dwordx4 v[148:149], off
	v_lshl_add_u64 v[148:149], s[36:37], 0, v[132:133]
	s_mov_b32 m0, s38
	s_nop 0
	global_load_lds_dwordx4 v[148:149], off
	v_lshl_add_u64 v[148:149], s[36:37], 0, v[134:135]
	s_add_i32 m0, s38, 0x2000
	s_nop 0
	global_load_lds_dwordx4 v[148:149], off
	v_lshl_add_u64 v[148:149], v[234:235], 0, s[8:9]
	s_mov_b32 m0, s42
	s_nop 0
	global_load_lds_dwordx4 v[148:149], off
	v_lshl_add_u64 v[148:149], v[236:237], 0, s[8:9]
	s_mov_b32 m0, s43
	s_nop 0
	global_load_lds_dwordx4 v[148:149], off
	s_waitcnt vmcnt(8)
	s_waitcnt lgkmcnt(0)
	s_barrier
	s_setprio 1
	s_waitcnt lgkmcnt(0)
	v_mfma_f32_16x16x32_bf16 v[60:63], v[144:147], v[190:193], v[60:63]
	v_mfma_f32_16x16x32_bf16 v[56:59], v[166:169], v[190:193], v[56:59]
	v_mfma_f32_16x16x32_bf16 v[44:47], v[144:147], v[206:209], v[44:47]
	v_mfma_f32_16x16x32_bf16 v[40:43], v[166:169], v[206:209], v[40:43]
	v_mfma_f32_16x16x32_bf16 v[28:31], v[144:147], v[214:217], v[28:31]
	v_mfma_f32_16x16x32_bf16 v[24:27], v[166:169], v[214:217], v[24:27]
	v_mfma_f32_16x16x32_bf16 v[12:15], v[144:147], v[222:225], v[12:15]
	v_mfma_f32_16x16x32_bf16 v[8:11], v[166:169], v[222:225], v[8:11]
	v_mfma_f32_16x16x32_bf16 v[60:63], v[162:165], v[194:197], v[60:63]
	v_mfma_f32_16x16x32_bf16 v[56:59], v[170:173], v[194:197], v[56:59]
	v_mfma_f32_16x16x32_bf16 v[44:47], v[162:165], v[210:213], v[44:47]
	v_mfma_f32_16x16x32_bf16 v[40:43], v[170:173], v[210:213], v[40:43]
	v_mfma_f32_16x16x32_bf16 v[28:31], v[162:165], v[218:221], v[28:31]
	v_mfma_f32_16x16x32_bf16 v[24:27], v[170:173], v[218:221], v[24:27]
	v_mfma_f32_16x16x32_bf16 v[12:15], v[162:165], v[226:229], v[12:15]
	v_mfma_f32_16x16x32_bf16 v[8:11], v[170:173], v[226:229], v[8:11]
	s_setprio 0
	s_setprio 1
	v_mfma_f32_16x16x32_bf16 v[52:55], v[174:177], v[190:193], v[52:55]
	v_mfma_f32_16x16x32_bf16 v[48:51], v[182:185], v[190:193], v[48:51]
	v_mfma_f32_16x16x32_bf16 v[36:39], v[174:177], v[206:209], v[36:39]
	v_mfma_f32_16x16x32_bf16 v[32:35], v[182:185], v[206:209], v[32:35]
	v_mfma_f32_16x16x32_bf16 v[20:23], v[174:177], v[214:217], v[20:23]
	v_mfma_f32_16x16x32_bf16 v[16:19], v[182:185], v[214:217], v[16:19]
	v_mfma_f32_16x16x32_bf16 v[4:7], v[174:177], v[222:225], v[4:7]
	v_mfma_f32_16x16x32_bf16 v[0:3], v[182:185], v[222:225], v[0:3]
	v_mfma_f32_16x16x32_bf16 v[52:55], v[178:181], v[194:197], v[52:55]
	v_mfma_f32_16x16x32_bf16 v[48:51], v[186:189], v[194:197], v[48:51]
	v_mfma_f32_16x16x32_bf16 v[36:39], v[178:181], v[210:213], v[36:39]
	v_mfma_f32_16x16x32_bf16 v[32:35], v[186:189], v[210:213], v[32:35]
	v_mfma_f32_16x16x32_bf16 v[20:23], v[178:181], v[218:221], v[20:23]
	v_mfma_f32_16x16x32_bf16 v[16:19], v[186:189], v[218:221], v[16:19]
	v_mfma_f32_16x16x32_bf16 v[4:7], v[178:181], v[226:229], v[4:7]
	v_mfma_f32_16x16x32_bf16 v[0:3], v[186:189], v[226:229], v[0:3]
	s_setprio 0
	s_barrier
	s_add_i32 s54, s54, 2
	s_add_u32 s34, s34, 0x100
	s_addc_u32 s35, s35, 0
	s_add_u32 s52, s52, 0x100
	s_addc_u32 s53, s53, 0
	s_cmp_gt_u32 s54, 61
	s_cbranch_scc0 .LBB0_1703
	s_and_b64 vcc, exec, s[10:11]
	s_cbranch_vccz .LBB0_1706
	s_barrier

; #define PG8_STAGE(bufoff, gbase, voff) do { _Pragma("unroll") for (int _i = 0; _i < 2; ++_i) \
;         __builtin_amdgcn_global_load_lds((const unsigned*)((const char*)(gbase) + (voff)[_i]), (PG8_LAS unsigned*)(lds + (bufoff) + ldsw + _i * 8192), 16, 0, 0); } while (0)
; #define PG8_WAIT_V(n) asm volatile("s_waitcnt vmcnt(" #n ")" ::: "memory")
; #define PG8_BAR __builtin_amdgcn_s_barrier()
; template <class Epi, class Sched, bool ALIGN_EPI = false, bool SP2 = false>
; __device__ __forceinline__ void gemm_phase(PG8_LAS unsigned char* lds, const Gemm g, const Sched& S, const Epi& E) {
;     ...
;     const int K = g.K, LD = g.ld, nt = K / BK;
;     unsigned voffA[2], voffB[2];
; #pragma unroll
;     for (int i = 0; i < 2; ++i) { int R, C; stage_rc(tid * 16 + i * 8192, R, C); const int Rb = Epi::PERM ? ((R & ~31) + perm32(R & 31)) : R;
;         voffA[i] = (unsigned)(R * LD + C) * 2u; voffB[i] = (unsigned)(Rb * LD + C) * 2u; }
;     const size_t kstep = (size_t)(BK * 2);
;     const size_t hstep = (size_t)HALF * LD * 2;
;     const size_t tstep = 2 * hstep;
;     const unsigned ldsw = (unsigned)wid * 1024u;
;     const int aoff = lds_byte(wr * 64 + fr, fq * 8), boff = lds_byte(wc * 32 + fr, fq * 8);
;     ...
;         PG8_STAGE(PG8_SB(0, 0), cB, voffB); PG8_STAGE(PG8_SB(0, 1), cB + hstep, voffB); PG8_STAGE(PG8_SA(0, 0), cA, voffA); PG8_STAGE(PG8_SA(0, 1), cA + hstep, voffA);
;         if (wr == 1) PG8_BAR;
;         PG8_WAIT_V(2); PG8_BAR;
;         PG8_STAGE(PG8_SB(1, 0), cB + kstep, voffB); PG8_STAGE(PG8_SA(1, 0), cA + kstep, voffA); PG8_STAGE(PG8_SB(1, 1), cB + hstep + kstep, voffB);
;         PG8_WAIT_V(6); PG8_BAR;
.LBB0_1713:
	s_lshl_b32 s14, s14, 5
	s_and_b32 s20, s14, 0x60
	s_mov_b64 s[14:15], 0x80
	s_add_i32 m0, s11, 0x18000
	v_lshl_add_u64 v[6:7], v[6:7], 0, s[14:15]
	s_lshl_b32 s19, s5, 13
	s_lshl_b32 s21, s20, 7
	s_waitcnt vmcnt(2)
	s_barrier
	global_load_lds_dwordx4 v[6:7], off
	v_lshl_add_u64 v[4:5], v[4:5], 0, s[14:15]
	s_add_i32 m0, s11, 0x1a000
	s_add_i32 s40, s11, 0x8000
	s_add_i32 s41, s11, 0xa000
	global_load_lds_dwordx4 v[4:5], off
	v_lshl_add_u64 v[0:1], v[0:1], 0, s[14:15]
	s_mov_b32 m0, s40
	s_add_u32 s16, s34, 0x100080
	global_load_lds_dwordx4 v[0:1], off
	v_lshl_add_u64 v[0:1], v[2:3], 0, s[14:15]
	s_mov_b32 m0, s41
	s_addc_u32 s17, s35, 0
	global_load_lds_dwordx4 v[0:1], off
	s_add_i32 m0, s11, 0x1c000
	v_lshl_add_u64 v[0:1], s[16:17], 0, v[128:129]
	global_load_lds_dwordx4 v[0:1], off
	v_lshl_add_u64 v[0:1], s[16:17], 0, v[130:131]
	s_add_i32 m0, s11, 0x1e000
	v_bfe_u32 v16, v198, 4, 2
	global_load_lds_dwordx4 v[0:1], off
	v_lshlrev_b32_e32 v1, 4, v16
	v_lshl_or_b32 v2, v204, 6, v1
	v_lshlrev_b32_e32 v3, 2, v204
	v_or_b32_e32 v1, v1, v152
	v_lshl_or_b32 v0, s5, 6, v204
	v_and_b32_e32 v3, 32, v3
	v_bitop3_b32 v18, s21, v1, v153 bitop3:0xf6
	v_mov_b32_e32 v1, v129
	v_bitop3_b32 v17, v2, s19, v3 bitop3:0xde
	v_or_b32_e32 v2, 16, v0
	v_or_b32_e32 v4, 32, v0
	v_or_b32_e32 v6, 48, v0
	v_add_u32_e32 v8, 0x80, v0
	v_add_u32_e32 v10, 0x90, v0
	v_add_u32_e32 v12, 0xa0, v0
	v_add_u32_e32 v14, 0xb0, v0
	v_lshlrev_b64 v[132:133], 12, v[0:1]
	v_lshlrev_b32_e32 v0, 10, v198
	v_and_b32_e32 v0, 0xe0000, v0
	v_lshlrev_b32_e32 v1, 13, v230
	v_or3_b32 v0, v150, v0, v1
	s_cmpk_lt_u32 s4, 0x100
	v_add_u32_e32 v148, v0, v205
	v_lshlrev_b32_e32 v0, 6, v151
	s_mov_b32 s5, 0x18000
	s_mov_b32 s21, 0x1c000
	s_waitcnt vmcnt(6)
	s_cselect_b64 s[16:17], -1, 0
	v_and_b32_e32 v0, 0x1e0000, v0
	s_add_i32 s46, s7, 0x100
	v_mov_b32_e32 v3, v129
	v_mov_b32_e32 v5, v129
	v_mov_b32_e32 v7, v129
	v_mov_b32_e32 v9, v129
	v_mov_b32_e32 v11, v129
	v_mov_b32_e32 v13, v129
	v_mov_b32_e32 v15, v129
	v_or3_b32 v0, v150, v0, v1
	v_add_u32_e32 v153, s46, v18
	s_add_i32 s43, s18, 0x100
	s_brev_b32 s18, 31
	s_add_i32 s46, s46, s33
	s_add_i32 s48, s5, 0x100
	s_add_i32 s49, s21, 0x100
	v_lshlrev_b64 v[134:135], 12, v[2:3]
	v_lshlrev_b64 v[136:137], 12, v[4:5]
	v_lshlrev_b64 v[138:139], 12, v[6:7]
	v_lshlrev_b64 v[140:141], 12, v[8:9]
	v_lshlrev_b64 v[142:143], 12, v[10:11]
	v_lshlrev_b64 v[144:145], 12, v[12:13]
	v_lshlrev_b64 v[146:147], 12, v[14:15]
	v_lshl_or_b32 v152, v16, 2, s20
	v_mov_b32_e32 v149, v129
	v_add_u32_e32 v150, v0, v205
	v_mov_b32_e32 v151, v129
	s_mov_b32 s42, 0
	v_add_u32_e32 v154, s43, v18
	v_add_u32_e32 v155, 0x100, v17
	s_mov_b32 s19, -1
	s_add_i32 s44, s11, 0xc000
	s_add_i32 s45, s11, 0xe000
	s_add_i32 s47, s46, 0x2000
	v_add_u32_e32 v156, s48, v18
	v_add_u32_e32 v157, s49, v18
	s_barrier
	s_branch .LBB0_1716

; #define PG8_STAGE(bufoff, gbase, voff) do { _Pragma("unroll") for (int _i = 0; _i < 2; ++_i) \
;         __builtin_amdgcn_global_load_lds((const unsigned*)((const char*)(gbase) + (voff)[_i]), (PG8_LAS unsigned*)(lds + (bufoff) + ldsw + _i * 8192), 16, 0, 0); } while (0)
; #define PG8_LDA(dst, b, h) do { _Pragma("unroll") for (int m = 0; m < 4; ++m) _Pragma("unroll") for (int k = 0; k < 2; ++k) dst[m][k] = *(const PG8_LAS bf16x8*)(lds + PG8_SA(b, h) + aoff + m * 2048 + k * 1024); } while (0)
; #define PG8_LDB(dst, b, h) do { _Pragma("unroll") for (int n = 0; n < 2; ++n) _Pragma("unroll") for (int k = 0; k < 2; ++k) dst[n][k] = *(const PG8_LAS bf16x8*)(lds + PG8_SB(b, h) + boff + n * 2048 + k * 1024); } while (0)
; #define PG8_MMA(ai, bj, At, Bt) do { __builtin_amdgcn_s_setprio(1); _Pragma("unroll") for (int m = 0; m < 4; ++m) _Pragma("unroll") for (int n = 0; n < 2; ++n) _Pragma("unroll") for (int k = 0; k < 2; ++k) \
;         acc[ai][bj][m][n] = __builtin_amdgcn_mfma_f32_16x16x32_bf16(Bt[n][k], At[m][k], acc[ai][bj][m][n], 0, 0, 0); __builtin_amdgcn_s_setprio(0); } while (0)
; #define PG8_WAIT_V(n) asm volatile("s_waitcnt vmcnt(" #n ")" ::: "memory")
; #define PG8_WAIT_L(n) asm volatile("s_waitcnt lgkmcnt(" #n ")" ::: "memory")
; template <class Epi, class Sched, bool ALIGN_EPI = false, bool SP2 = false>
; __device__ __forceinline__ void gemm_phase(PG8_LAS unsigned char* lds, const Gemm g, const Sched& S, const Epi& E) {
;     ...
;             const bool last = (t == nt - 2);
;             const char* a1 = cA + (size_t)(t + 1) * kstep;
;             const char* a2 = last ? nA : cA + (size_t)(t + 2) * kstep; const char* b2 = last ? nB : cB + (size_t)(t + 2) * kstep;
;             const char* a3 = a2 + kstep; const char* b3 = b2 + kstep;
;             if (last && has_next) S.a_ready(nxt);
;             if constexpr (SP2) {
;             PG8_LDB(B0, 0, 0); PG8_LDB(B1, 0, 1); PG8_SCHED; PG8_LDA(At, 0, 0); PG8_STAGE(PG8_SA(1, 1), a1 + hstep, voffA);
;             PG8_WAIT_V(8); PG8_WAIT_L(0); PG8_BAR; PG8_MMA(0, 0, At, B0); PG8_MMA(0, 1, At, B1); PG8_BAR; PG8_SCHED;
;             PG8_LDA(At, 0, 1); PG8_STAGE(PG8_SB(0, 0), b2, voffB); PG8_STAGE(PG8_SB(0, 1), b2 + hstep, voffB); PG8_STAGE(PG8_SA(0, 0), a2, voffA);
;             PG8_WAIT_V(8); PG8_WAIT_L(0); PG8_BAR; PG8_MMA(1, 0, At, B0); PG8_MMA(1, 1, At, B1); PG8_BAR; PG8_SCHED;
.LBB0_1723:
	ds_read_b128 v[158:161], v153
	ds_read_b128 v[162:165], v153 offset:1024
	ds_read_b128 v[166:169], v153 offset:2048
	ds_read_b128 v[170:173], v153 offset:3072
	ds_read_b128 v[174:177], v154
	ds_read_b128 v[178:181], v154 offset:1024
	ds_read_b128 v[182:185], v154 offset:2048
	ds_read_b128 v[186:189], v154 offset:3072
	s_add_u32 s25, s30, 0xfff00080
	s_addc_u32 s34, s31, -1
	s_cmp_eq_u32 s23, 4
	s_cselect_b32 s37, s27, s34
	s_cselect_b32 s36, s26, s25
	s_cselect_b32 s35, s29, s21
	s_cselect_b32 s34, s28, s7
	s_mov_b32 m0, s44
	v_lshl_add_u64 v[198:199], s[30:31], 0, v[148:149]
	ds_read_b128 v[190:193], v155
	ds_read_b128 v[194:197], v155 offset:1024
	ds_read_b128 v[204:207], v155 offset:2048
	ds_read_b128 v[208:211], v155 offset:3072
	ds_read_b128 v[212:215], v155 offset:4096
	ds_read_b128 v[216:219], v155 offset:5120
	ds_read_b128 v[220:223], v155 offset:6144
	ds_read_b128 v[224:227], v155 offset:7168
	global_load_lds_dwordx4 v[198:199], off
	v_lshl_add_u64 v[198:199], s[30:31], 0, v[150:151]
	s_mov_b32 m0, s45
	s_nop 0
	global_load_lds_dwordx4 v[198:199], off
	s_waitcnt vmcnt(8)
	s_waitcnt lgkmcnt(0)
	s_barrier
	s_setprio 1
	s_waitcnt lgkmcnt(0)
	v_mfma_f32_16x16x32_bf16 v[124:127], v[158:161], v[190:193], v[124:127]
	v_mfma_f32_16x16x32_bf16 v[120:123], v[166:169], v[190:193], v[120:123]
	v_mfma_f32_16x16x32_bf16 v[116:119], v[158:161], v[204:207], v[116:119]
	v_mfma_f32_16x16x32_bf16 v[112:115], v[166:169], v[204:207], v[112:115]
	v_mfma_f32_16x16x32_bf16 v[108:111], v[158:161], v[212:215], v[108:111]
	v_mfma_f32_16x16x32_bf16 v[104:107], v[166:169], v[212:215], v[104:107]
	v_mfma_f32_16x16x32_bf16 v[96:99], v[158:161], v[220:223], v[96:99]
	v_mfma_f32_16x16x32_bf16 v[88:91], v[166:169], v[220:223], v[88:91]
	v_mfma_f32_16x16x32_bf16 v[124:127], v[162:165], v[194:197], v[124:127]
	v_mfma_f32_16x16x32_bf16 v[120:123], v[170:173], v[194:197], v[120:123]
	v_mfma_f32_16x16x32_bf16 v[116:119], v[162:165], v[208:211], v[116:119]
	v_mfma_f32_16x16x32_bf16 v[112:115], v[170:173], v[208:211], v[112:115]
	v_mfma_f32_16x16x32_bf16 v[108:111], v[162:165], v[216:219], v[108:111]
	v_mfma_f32_16x16x32_bf16 v[104:107], v[170:173], v[216:219], v[104:107]
	v_mfma_f32_16x16x32_bf16 v[96:99], v[162:165], v[224:227], v[96:99]
	v_mfma_f32_16x16x32_bf16 v[88:91], v[170:173], v[224:227], v[88:91]
	s_setprio 0
	s_setprio 1
	v_mfma_f32_16x16x32_bf16 v[100:103], v[174:177], v[190:193], v[100:103]
	v_mfma_f32_16x16x32_bf16 v[92:95], v[182:185], v[190:193], v[92:95]
	v_mfma_f32_16x16x32_bf16 v[84:87], v[174:177], v[204:207], v[84:87]
	v_mfma_f32_16x16x32_bf16 v[80:83], v[182:185], v[204:207], v[80:83]
	v_mfma_f32_16x16x32_bf16 v[76:79], v[174:177], v[212:215], v[76:79]
	v_mfma_f32_16x16x32_bf16 v[72:75], v[182:185], v[212:215], v[72:75]
	v_mfma_f32_16x16x32_bf16 v[68:71], v[174:177], v[220:223], v[68:71]
	v_mfma_f32_16x16x32_bf16 v[64:67], v[182:185], v[220:223], v[64:67]
	v_mfma_f32_16x16x32_bf16 v[100:103], v[178:181], v[194:197], v[100:103]
	v_mfma_f32_16x16x32_bf16 v[92:95], v[186:189], v[194:197], v[92:95]
	v_mfma_f32_16x16x32_bf16 v[84:87], v[178:181], v[208:211], v[84:87]
	v_mfma_f32_16x16x32_bf16 v[80:83], v[186:189], v[208:211], v[80:83]
	v_mfma_f32_16x16x32_bf16 v[76:79], v[178:181], v[216:219], v[76:79]
	v_mfma_f32_16x16x32_bf16 v[72:75], v[186:189], v[216:219], v[72:75]
	v_mfma_f32_16x16x32_bf16 v[68:71], v[178:181], v[224:227], v[68:71]
	v_mfma_f32_16x16x32_bf16 v[64:67], v[186:189], v[224:227], v[64:67]
	s_setprio 0
	s_barrier
	s_mov_b32 m0, s46
	v_lshl_add_u64 v[198:199], s[34:35], 0, v[128:129]
	s_add_u32 s50, s34, 0x100000
	ds_read_b128 v[190:193], v155 offset:16384
	ds_read_b128 v[194:197], v155 offset:17408
	ds_read_b128 v[204:207], v155 offset:18432
	ds_read_b128 v[208:211], v155 offset:19456
	ds_read_b128 v[212:215], v155 offset:20480
	ds_read_b128 v[216:219], v155 offset:21504
	ds_read_b128 v[220:223], v155 offset:22528
	ds_read_b128 v[224:227], v155 offset:23552
	global_load_lds_dwordx4 v[198:199], off
	v_lshl_add_u64 v[228:229], s[34:35], 0, v[130:131]
	s_mov_b32 m0, s47
	s_addc_u32 s51, s35, 0
	s_add_i32 s25, s43, s33
	global_load_lds_dwordx4 v[228:229], off
	v_lshl_add_u64 v[230:231], s[50:51], 0, v[128:129]
	s_mov_b32 m0, s25
	v_lshl_add_u64 v[232:233], s[36:37], 0, v[130:131]
	global_load_lds_dwordx4 v[230:231], off
	v_lshl_add_u64 v[230:231], s[50:51], 0, v[130:131]
	s_add_i32 m0, s25, 0x2000
	s_nop 0
	global_load_lds_dwordx4 v[230:231], off
	v_lshl_add_u64 v[230:231], s[36:37], 0, v[128:129]
	s_mov_b32 m0, s11
	s_nop 0
	global_load_lds_dwordx4 v[230:231], off
	s_mov_b32 m0, s13
	s_nop 0
	global_load_lds_dwordx4 v[232:233], off
	s_waitcnt vmcnt(8)
	s_waitcnt lgkmcnt(0)
	s_barrier
; #define PG8_STAGE(bufoff, gbase, voff) do { _Pragma("unroll") for (int _i = 0; _i < 2; ++_i) \
;         __builtin_amdgcn_global_load_lds((const unsigned*)((const char*)(gbase) + (voff)[_i]), (PG8_LAS unsigned*)(lds + (bufoff) + ldsw + _i * 8192), 16, 0, 0); } while (0)
; #define PG8_LDA(dst, b, h) do { _Pragma("unroll") for (int m = 0; m < 4; ++m) _Pragma("unroll") for (int k = 0; k < 2; ++k) dst[m][k] = *(const PG8_LAS bf16x8*)(lds + PG8_SA(b, h) + aoff + m * 2048 + k * 1024); } while (0)
; #define PG8_LDB(dst, b, h) do { _Pragma("unroll") for (int n = 0; n < 2; ++n) _Pragma("unroll") for (int k = 0; k < 2; ++k) dst[n][k] = *(const PG8_LAS bf16x8*)(lds + PG8_SB(b, h) + boff + n * 2048 + k * 1024); } while (0)
; #define PG8_MMA(ai, bj, At, Bt) do { __builtin_amdgcn_s_setprio(1); _Pragma("unroll") for (int m = 0; m < 4; ++m) _Pragma("unroll") for (int n = 0; n < 2; ++n) _Pragma("unroll") for (int k = 0; k < 2; ++k) \
;         acc[ai][bj][m][n] = __builtin_amdgcn_mfma_f32_16x16x32_bf16(Bt[n][k], At[m][k], acc[ai][bj][m][n], 0, 0, 0); __builtin_amdgcn_s_setprio(0); } while (0)
; #define PG8_WAIT_V(n) asm volatile("s_waitcnt vmcnt(" #n ")" ::: "memory")
; #define PG8_WAIT_L(n) asm volatile("s_waitcnt lgkmcnt(" #n ")" ::: "memory")
; #define PG8_BAR __builtin_amdgcn_s_barrier()
; #define PG8_SCHED __builtin_amdgcn_sched_barrier(0)
; template <class Epi, class Sched, bool ALIGN_EPI = false, bool SP2 = false>
; __device__ __forceinline__ void gemm_phase(PG8_LAS unsigned char* lds, const Gemm g, const Sched& S, const Epi& E) {
;     ...
;             PG8_WAIT_V(8); PG8_WAIT_L(0); PG8_BAR; PG8_MMA(1, 0, At, B0); PG8_MMA(1, 1, At, B1); PG8_BAR; PG8_SCHED;
;             PG8_LDB(B0, 1, 0); PG8_LDB(B1, 1, 1); PG8_SCHED; PG8_LDA(At, 1, 0); PG8_STAGE(PG8_SA(0, 1), a2 + hstep, voffA);
;             PG8_WAIT_V(8); PG8_WAIT_L(0); PG8_BAR; PG8_MMA(0, 0, At, B0); PG8_MMA(0, 1, At, B1); PG8_BAR; PG8_SCHED;
	s_setprio 1
	s_waitcnt lgkmcnt(0)
	v_mfma_f32_16x16x32_bf16 v[60:63], v[158:161], v[190:193], v[60:63]
	v_mfma_f32_16x16x32_bf16 v[56:59], v[166:169], v[190:193], v[56:59]
	v_mfma_f32_16x16x32_bf16 v[52:55], v[158:161], v[204:207], v[52:55]
	v_mfma_f32_16x16x32_bf16 v[48:51], v[166:169], v[204:207], v[48:51]
	v_mfma_f32_16x16x32_bf16 v[44:47], v[158:161], v[212:215], v[44:47]
	v_mfma_f32_16x16x32_bf16 v[40:43], v[166:169], v[212:215], v[40:43]
	v_mfma_f32_16x16x32_bf16 v[32:35], v[158:161], v[220:223], v[32:35]
	v_mfma_f32_16x16x32_bf16 v[24:27], v[166:169], v[220:223], v[24:27]
	v_mfma_f32_16x16x32_bf16 v[60:63], v[162:165], v[194:197], v[60:63]
	v_mfma_f32_16x16x32_bf16 v[56:59], v[170:173], v[194:197], v[56:59]
	v_mfma_f32_16x16x32_bf16 v[52:55], v[162:165], v[208:211], v[52:55]
	v_mfma_f32_16x16x32_bf16 v[48:51], v[170:173], v[208:211], v[48:51]
	v_mfma_f32_16x16x32_bf16 v[44:47], v[162:165], v[216:219], v[44:47]
	v_mfma_f32_16x16x32_bf16 v[40:43], v[170:173], v[216:219], v[40:43]
	v_mfma_f32_16x16x32_bf16 v[32:35], v[162:165], v[224:227], v[32:35]
	v_mfma_f32_16x16x32_bf16 v[24:27], v[170:173], v[224:227], v[24:27]
	s_setprio 0
	s_setprio 1
	v_mfma_f32_16x16x32_bf16 v[36:39], v[174:177], v[190:193], v[36:39]
	v_mfma_f32_16x16x32_bf16 v[28:31], v[182:185], v[190:193], v[28:31]
	v_mfma_f32_16x16x32_bf16 v[20:23], v[174:177], v[204:207], v[20:23]
	v_mfma_f32_16x16x32_bf16 v[16:19], v[182:185], v[204:207], v[16:19]
	v_mfma_f32_16x16x32_bf16 v[12:15], v[174:177], v[212:215], v[12:15]
	v_mfma_f32_16x16x32_bf16 v[8:11], v[182:185], v[212:215], v[8:11]
	v_mfma_f32_16x16x32_bf16 v[4:7], v[174:177], v[220:223], v[4:7]
	v_mfma_f32_16x16x32_bf16 v[0:3], v[182:185], v[220:223], v[0:3]
	v_mfma_f32_16x16x32_bf16 v[36:39], v[178:181], v[194:197], v[36:39]
	v_mfma_f32_16x16x32_bf16 v[28:31], v[186:189], v[194:197], v[28:31]
	v_mfma_f32_16x16x32_bf16 v[20:23], v[178:181], v[208:211], v[20:23]
	v_mfma_f32_16x16x32_bf16 v[16:19], v[186:189], v[208:211], v[16:19]
	v_mfma_f32_16x16x32_bf16 v[12:15], v[178:181], v[216:219], v[12:15]
	v_mfma_f32_16x16x32_bf16 v[8:11], v[186:189], v[216:219], v[8:11]
	v_mfma_f32_16x16x32_bf16 v[4:7], v[178:181], v[224:227], v[4:7]
	v_mfma_f32_16x16x32_bf16 v[0:3], v[186:189], v[224:227], v[0:3]
	s_setprio 0
	s_barrier
	ds_read_b128 v[158:161], v156
	ds_read_b128 v[162:165], v156 offset:1024
	ds_read_b128 v[166:169], v156 offset:2048
	ds_read_b128 v[170:173], v156 offset:3072
	ds_read_b128 v[174:177], v157
	ds_read_b128 v[178:181], v157 offset:1024
	ds_read_b128 v[182:185], v157 offset:2048
	ds_read_b128 v[186:189], v157 offset:3072
	s_add_u32 s36, s36, 0x100000
	s_addc_u32 s37, s37, 0
	s_mov_b32 m0, s38
	v_lshl_add_u64 v[234:235], s[36:37], 0, v[128:129]
	ds_read_b128 v[190:193], v155 offset:32768
	ds_read_b128 v[194:197], v155 offset:33792
	ds_read_b128 v[204:207], v155 offset:34816
	ds_read_b128 v[208:211], v155 offset:35840
	ds_read_b128 v[212:215], v155 offset:36864
	ds_read_b128 v[216:219], v155 offset:37888
	ds_read_b128 v[220:223], v155 offset:38912
	ds_read_b128 v[224:227], v155 offset:39936
	global_load_lds_dwordx4 v[234:235], off
	v_lshl_add_u64 v[234:235], s[36:37], 0, v[130:131]
	s_mov_b32 m0, s39
	s_nop 0
	global_load_lds_dwordx4 v[234:235], off
	s_waitcnt vmcnt(8)
	s_waitcnt lgkmcnt(0)
	s_barrier
	s_setprio 1
	s_waitcnt lgkmcnt(0)
	v_mfma_f32_16x16x32_bf16 v[124:127], v[158:161], v[190:193], v[124:127]
	v_mfma_f32_16x16x32_bf16 v[120:123], v[166:169], v[190:193], v[120:123]
	v_mfma_f32_16x16x32_bf16 v[116:119], v[158:161], v[204:207], v[116:119]
	v_mfma_f32_16x16x32_bf16 v[112:115], v[166:169], v[204:207], v[112:115]
	v_mfma_f32_16x16x32_bf16 v[108:111], v[158:161], v[212:215], v[108:111]
	v_mfma_f32_16x16x32_bf16 v[104:107], v[166:169], v[212:215], v[104:107]
	v_mfma_f32_16x16x32_bf16 v[96:99], v[158:161], v[220:223], v[96:99]
	v_mfma_f32_16x16x32_bf16 v[88:91], v[166:169], v[220:223], v[88:91]
	v_mfma_f32_16x16x32_bf16 v[124:127], v[162:165], v[194:197], v[124:127]
	v_mfma_f32_16x16x32_bf16 v[120:123], v[170:173], v[194:197], v[120:123]
	v_mfma_f32_16x16x32_bf16 v[116:119], v[162:165], v[208:211], v[116:119]
	v_mfma_f32_16x16x32_bf16 v[112:115], v[170:173], v[208:211], v[112:115]
	v_mfma_f32_16x16x32_bf16 v[108:111], v[162:165], v[216:219], v[108:111]
	v_mfma_f32_16x16x32_bf16 v[104:107], v[170:173], v[216:219], v[104:107]
	v_mfma_f32_16x16x32_bf16 v[96:99], v[162:165], v[224:227], v[96:99]
	v_mfma_f32_16x16x32_bf16 v[88:91], v[170:173], v[224:227], v[88:91]
	s_setprio 0
	s_setprio 1
	v_mfma_f32_16x16x32_bf16 v[100:103], v[174:177], v[190:193], v[100:103]
	v_mfma_f32_16x16x32_bf16 v[92:95], v[182:185], v[190:193], v[92:95]
	v_mfma_f32_16x16x32_bf16 v[84:87], v[174:177], v[204:207], v[84:87]
	v_mfma_f32_16x16x32_bf16 v[80:83], v[182:185], v[204:207], v[80:83]
	v_mfma_f32_16x16x32_bf16 v[76:79], v[174:177], v[212:215], v[76:79]
	v_mfma_f32_16x16x32_bf16 v[72:75], v[182:185], v[212:215], v[72:75]
	v_mfma_f32_16x16x32_bf16 v[68:71], v[174:177], v[220:223], v[68:71]
	v_mfma_f32_16x16x32_bf16 v[64:67], v[182:185], v[220:223], v[64:67]
	v_mfma_f32_16x16x32_bf16 v[100:103], v[178:181], v[194:197], v[100:103]
	v_mfma_f32_16x16x32_bf16 v[92:95], v[186:189], v[194:197], v[92:95]
	v_mfma_f32_16x16x32_bf16 v[84:87], v[178:181], v[208:211], v[84:87]
	v_mfma_f32_16x16x32_bf16 v[80:83], v[186:189], v[208:211], v[80:83]
	v_mfma_f32_16x16x32_bf16 v[76:79], v[178:181], v[216:219], v[76:79]
	v_mfma_f32_16x16x32_bf16 v[72:75], v[186:189], v[216:219], v[72:75]
	v_mfma_f32_16x16x32_bf16 v[68:71], v[178:181], v[224:227], v[68:71]
	v_mfma_f32_16x16x32_bf16 v[64:67], v[186:189], v[224:227], v[64:67]
	s_setprio 0
	s_barrier
; #define PG8_STAGE(bufoff, gbase, voff) do { _Pragma("unroll") for (int _i = 0; _i < 2; ++_i) \
;         __builtin_amdgcn_global_load_lds((const unsigned*)((const char*)(gbase) + (voff)[_i]), (PG8_LAS unsigned*)(lds + (bufoff) + ldsw + _i * 8192), 16, 0, 0); } while (0)
; #define PG8_LDA(dst, b, h) do { _Pragma("unroll") for (int m = 0; m < 4; ++m) _Pragma("unroll") for (int k = 0; k < 2; ++k) dst[m][k] = *(const PG8_LAS bf16x8*)(lds + PG8_SA(b, h) + aoff + m * 2048 + k * 1024); } while (0)
; #define PG8_LDB(dst, b, h) do { _Pragma("unroll") for (int n = 0; n < 2; ++n) _Pragma("unroll") for (int k = 0; k < 2; ++k) dst[n][k] = *(const PG8_LAS bf16x8*)(lds + PG8_SB(b, h) + boff + n * 2048 + k * 1024); } while (0)
; template <class Epi, class Sched, bool ALIGN_EPI = false, bool SP2 = false>
; __device__ __forceinline__ void gemm_phase(PG8_LAS unsigned char* lds, const Gemm g, const Sched& S, const Epi& E) {
;     ...
;         for (int t = 0; t < nt; t += 2) {
;             const bool last = (t == nt - 2);
;             const char* a1 = cA + (size_t)(t + 1) * kstep;
;             const char* a2 = last ? nA : cA + (size_t)(t + 2) * kstep; const char* b2 = last ? nB : cB + (size_t)(t + 2) * kstep;
;             const char* a3 = a2 + kstep; const char* b3 = b2 + kstep;
;             if (last && has_next) S.a_ready(nxt);
;             if constexpr (SP2) {
;             PG8_LDB(B0, 0, 0); PG8_LDB(B1, 0, 1); PG8_SCHED; PG8_LDA(At, 0, 0); PG8_STAGE(PG8_SA(1, 1), a1 + hstep, voffA);
;             PG8_WAIT_V(8); PG8_WAIT_L(0); PG8_BAR; PG8_MMA(0, 0, At, B0); PG8_MMA(0, 1, At, B1); PG8_BAR; PG8_SCHED;
;             PG8_LDA(At, 0, 1); PG8_STAGE(PG8_SB(0, 0), b2, voffB); PG8_STAGE(PG8_SB(0, 1), b2 + hstep, voffB); PG8_STAGE(PG8_SA(0, 0), a2, voffA);
;             PG8_WAIT_V(8); PG8_WAIT_L(0); PG8_BAR; PG8_MMA(1, 0, At, B0); PG8_MMA(1, 1, At, B1); PG8_BAR; PG8_SCHED;
;             PG8_LDB(B0, 1, 0); PG8_LDB(B1, 1, 1); PG8_SCHED; PG8_LDA(At, 1, 0); PG8_STAGE(PG8_SA(0, 1), a2 + hstep, voffA);
;             PG8_WAIT_V(8); PG8_WAIT_L(0); PG8_BAR; PG8_MMA(0, 0, At, B0); PG8_MMA(0, 1, At, B1); PG8_BAR; PG8_SCHED;
;             PG8_LDA(At, 1, 1); PG8_STAGE(PG8_SB(1, 0), b3, voffB); PG8_STAGE(PG8_SB(1, 1), b3 + hstep, voffB); PG8_STAGE(PG8_SA(1, 0), a3, voffA);
;             PG8_WAIT_V(8); PG8_WAIT_L(0); PG8_BAR; PG8_MMA(1, 0, At, B0); PG8_MMA(1, 1, At, B1); PG8_BAR; PG8_SCHED;
	s_add_i32 s25, s48, s33
	v_lshl_add_u64 v[198:199], v[198:199], 0, s[14:15]
	s_mov_b32 m0, s25
	ds_read_b128 v[190:193], v155 offset:49152
	ds_read_b128 v[194:197], v155 offset:50176
	ds_read_b128 v[204:207], v155 offset:51200
	ds_read_b128 v[208:211], v155 offset:52224
	ds_read_b128 v[212:215], v155 offset:53248
	ds_read_b128 v[216:219], v155 offset:54272
	ds_read_b128 v[220:223], v155 offset:55296
	ds_read_b128 v[224:227], v155 offset:56320
	global_load_lds_dwordx4 v[198:199], off
	s_add_i32 m0, s25, 0x2000
	s_add_u32 s34, s34, 0x100080
	v_lshl_add_u64 v[198:199], v[228:229], 0, s[14:15]
	s_addc_u32 s35, s35, 0
	s_add_i32 s25, s49, s33
	global_load_lds_dwordx4 v[198:199], off
	v_lshl_add_u64 v[198:199], s[34:35], 0, v[128:129]
	s_mov_b32 m0, s25
	s_nop 0
	global_load_lds_dwordx4 v[198:199], off
	v_lshl_add_u64 v[198:199], s[34:35], 0, v[130:131]
	s_add_i32 m0, s25, 0x2000
	s_nop 0
	global_load_lds_dwordx4 v[198:199], off
	v_lshl_add_u64 v[198:199], v[230:231], 0, s[14:15]
	s_mov_b32 m0, s40
	s_nop 0
	global_load_lds_dwordx4 v[198:199], off
	v_lshl_add_u64 v[198:199], v[232:233], 0, s[14:15]
	s_mov_b32 m0, s41
	s_nop 0
	global_load_lds_dwordx4 v[198:199], off
	s_waitcnt vmcnt(8)
	s_waitcnt lgkmcnt(0)
	s_barrier
	s_setprio 1
	s_waitcnt lgkmcnt(0)
	v_mfma_f32_16x16x32_bf16 v[60:63], v[158:161], v[190:193], v[60:63]
	v_mfma_f32_16x16x32_bf16 v[56:59], v[166:169], v[190:193], v[56:59]
	v_mfma_f32_16x16x32_bf16 v[52:55], v[158:161], v[204:207], v[52:55]
	v_mfma_f32_16x16x32_bf16 v[48:51], v[166:169], v[204:207], v[48:51]
	v_mfma_f32_16x16x32_bf16 v[44:47], v[158:161], v[212:215], v[44:47]
	v_mfma_f32_16x16x32_bf16 v[40:43], v[166:169], v[212:215], v[40:43]
	v_mfma_f32_16x16x32_bf16 v[32:35], v[158:161], v[220:223], v[32:35]
	v_mfma_f32_16x16x32_bf16 v[24:27], v[166:169], v[220:223], v[24:27]
	v_mfma_f32_16x16x32_bf16 v[60:63], v[162:165], v[194:197], v[60:63]
	v_mfma_f32_16x16x32_bf16 v[56:59], v[170:173], v[194:197], v[56:59]
	v_mfma_f32_16x16x32_bf16 v[52:55], v[162:165], v[208:211], v[52:55]
	v_mfma_f32_16x16x32_bf16 v[48:51], v[170:173], v[208:211], v[48:51]
	v_mfma_f32_16x16x32_bf16 v[44:47], v[162:165], v[216:219], v[44:47]
	v_mfma_f32_16x16x32_bf16 v[40:43], v[170:173], v[216:219], v[40:43]
	v_mfma_f32_16x16x32_bf16 v[32:35], v[162:165], v[224:227], v[32:35]
	v_mfma_f32_16x16x32_bf16 v[24:27], v[170:173], v[224:227], v[24:27]
	s_setprio 0
	s_setprio 1
	v_mfma_f32_16x16x32_bf16 v[36:39], v[174:177], v[190:193], v[36:39]
	v_mfma_f32_16x16x32_bf16 v[28:31], v[182:185], v[190:193], v[28:31]
	v_mfma_f32_16x16x32_bf16 v[20:23], v[174:177], v[204:207], v[20:23]
	v_mfma_f32_16x16x32_bf16 v[16:19], v[182:185], v[204:207], v[16:19]
	v_mfma_f32_16x16x32_bf16 v[12:15], v[174:177], v[212:215], v[12:15]
	v_mfma_f32_16x16x32_bf16 v[8:11], v[182:185], v[212:215], v[8:11]
	v_mfma_f32_16x16x32_bf16 v[4:7], v[174:177], v[220:223], v[4:7]
	v_mfma_f32_16x16x32_bf16 v[0:3], v[182:185], v[220:223], v[0:3]
	v_mfma_f32_16x16x32_bf16 v[36:39], v[178:181], v[194:197], v[36:39]
	v_mfma_f32_16x16x32_bf16 v[28:31], v[186:189], v[194:197], v[28:31]
	v_mfma_f32_16x16x32_bf16 v[20:23], v[178:181], v[208:211], v[20:23]
	v_mfma_f32_16x16x32_bf16 v[16:19], v[186:189], v[208:211], v[16:19]
	v_mfma_f32_16x16x32_bf16 v[12:15], v[178:181], v[216:219], v[12:15]
	v_mfma_f32_16x16x32_bf16 v[8:11], v[186:189], v[216:219], v[8:11]
	v_mfma_f32_16x16x32_bf16 v[4:7], v[178:181], v[224:227], v[4:7]
	v_mfma_f32_16x16x32_bf16 v[0:3], v[186:189], v[224:227], v[0:3]
	s_setprio 0
	s_barrier
	s_add_i32 s23, s23, 2
	s_add_u32 s30, s30, 0x100
	s_addc_u32 s31, s31, 0
	s_add_u32 s7, s7, 0x100
	s_addc_u32 s21, s21, 0
	s_cmp_gt_u32 s23, 5
	s_cbranch_scc0 .LBB0_1723
	s_and_b64 vcc, exec, s[16:17]
	s_cbranch_vccz .LBB0_1726
	s_barrier

; __global__ void __launch_bounds__(512, 2) fwd(Args args) {
	.amdhsa_kernel _Z3fwd4Args
		.amdhsa_group_segment_fixed_size 256
		.amdhsa_private_segment_fixed_size 0
		.amdhsa_kernarg_size 464
		.amdhsa_user_sgpr_count 2
		.amdhsa_user_sgpr_dispatch_ptr 0
		.amdhsa_user_sgpr_queue_ptr 0
		.amdhsa_user_sgpr_kernarg_segment_ptr 1
		.amdhsa_user_sgpr_dispatch_id 0
		.amdhsa_user_sgpr_kernarg_preload_length 0
		.amdhsa_user_sgpr_kernarg_preload_offset 0
		.amdhsa_user_sgpr_private_segment_size 0
		.amdhsa_uses_dynamic_stack 0
		.amdhsa_enable_private_segment 0
		.amdhsa_system_sgpr_workgroup_id_x 1
		.amdhsa_system_sgpr_workgroup_id_y 0
		.amdhsa_system_sgpr_workgroup_id_z 0
		.amdhsa_system_sgpr_workgroup_info 0
		.amdhsa_system_vgpr_workitem_id 2
		.amdhsa_next_free_vgpr 252
		.amdhsa_next_free_sgpr 98
		.amdhsa_accum_offset 252
		.amdhsa_reserve_vcc 1
		.amdhsa_float_round_mode_32 0
		.amdhsa_float_round_mode_16_64 0
		.amdhsa_float_denorm_mode_32 3
		.amdhsa_float_denorm_mode_16_64 3
		.amdhsa_dx10_clamp 1
		.amdhsa_ieee_mode 1
		.amdhsa_fp16_overflow 0
		.amdhsa_tg_split 0
		.amdhsa_exception_fp_ieee_invalid_op 0
		.amdhsa_exception_fp_denorm_src 0
		.amdhsa_exception_fp_ieee_div_zero 0
		.amdhsa_exception_fp_ieee_overflow 0
		.amdhsa_exception_fp_ieee_underflow 0
		.amdhsa_exception_fp_ieee_inexact 0
		.amdhsa_exception_int_div_zero 0
	.end_amdhsa_kernel

; __global__ void __launch_bounds__(512, 2) fwd(Args args) {
amdhsa.kernels:
  - .agpr_count:     0
    .args:
      - .offset:         0
        .size:           208
        .value_kind:     by_value
      - .offset:         208
        .size:           4
        .value_kind:     hidden_block_count_x
      - .offset:         212
        .size:           4
        .value_kind:     hidden_block_count_y
      - .offset:         216
        .size:           4
        .value_kind:     hidden_block_count_z
      - .offset:         220
        .size:           2
        .value_kind:     hidden_group_size_x
      - .offset:         222
        .size:           2
        .value_kind:     hidden_group_size_y
      - .offset:         224
        .size:           2
        .value_kind:     hidden_group_size_z
      - .offset:         226
        .size:           2
        .value_kind:     hidden_remainder_x
      - .offset:         228
        .size:           2
        .value_kind:     hidden_remainder_y
      - .offset:         230
        .size:           2
        .value_kind:     hidden_remainder_z
      - .offset:         248
        .size:           8
        .value_kind:     hidden_global_offset_x
      - .offset:         256
        .size:           8
        .value_kind:     hidden_global_offset_y
      - .offset:         264
        .size:           8
        .value_kind:     hidden_global_offset_z
      - .offset:         272
        .size:           2
        .value_kind:     hidden_grid_dims
      - .offset:         296
        .size:           8
        .value_kind:     hidden_multigrid_sync_arg
      - .offset:         328
        .size:           4
        .value_kind:     hidden_dynamic_lds_size
    .group_segment_fixed_size: 256
    .kernarg_segment_align: 8
    .kernarg_segment_size: 464
    .language:       OpenCL C
    .language_version:
      - 2
      - 0
    .max_flat_workgroup_size: 512
    .name:           _Z3fwd4Args
    .private_segment_fixed_size: 0
    .sgpr_count:     104
    .sgpr_spill_count: 127
    .symbol:         _Z3fwd4Args.kd
    .uniform_work_group_size: 1
    .uses_dynamic_stack: false
    .vgpr_count:     252
    .vgpr_spill_count: 0
    .wavefront_size: 64
